# wait for next-tile LDS-DMA at the end of the last K-step instead of at tile start (epilogue store drain overlaps step 0)
# speedup vs baseline: 1.0685x; 1.0070x over previous
.LBB0_298:
	v_mbcnt_hi_u32_b32 v188, -1, v210
	s_load_dwordx2 s[2:3], s[0:1], 0x158
	s_load_dwordx2 s[4:5], s[0:1], 0xc0
	s_ashr_i32 s7, s6, 31
	v_mov_b32_e32 v1, v188
	s_and_b32 s7, s7, s42
	s_add_i32 s68, s7, s6
	v_add_u32_e32 v0, s70, v1
	v_ashrrev_i32_e32 v189, 3, v0
	v_readfirstlane_b32 s8, v0
	v_lshlrev_b32_e32 v0, 3, v1
	v_and_b32_e32 v0, 56, v0
	s_cmpk_lt_i32 s68, 0x300
	s_cselect_b64 s[6:7], -1, 0
	s_cmpk_gt_i32 s68, 0x2ff
	v_lshlrev_b32_e32 v160, 1, v0
	v_add_u32_e32 v190, 64, v189
	s_cbranch_scc1 .LBB0_300
	s_mul_hi_i32 s9, s68, 0x2aaaaaab
	s_lshr_b32 s10, s9, 31
	s_add_i32 s9, s9, s10
	s_mul_i32 s10, s9, -6
	s_lshl_b32 s9, s9, 8
	v_add_u32_e32 v2, s9, v189
	v_min_i32_e32 v2, 0x7fff, v2
	v_ashrrev_i32_e32 v3, 31, v2
	v_lshlrev_b64 v[2:3], 11, v[2:3]
	s_add_i32 s10, s10, s68
	s_waitcnt lgkmcnt(0)
	v_lshl_add_u64 v[2:3], s[2:3], 0, v[2:3]
	v_mov_b32_e32 v161, 0
	s_lshl_b32 s10, s10, 8
	v_lshl_add_u64 v[2:3], v[2:3], 0, v[160:161]
	v_mbcnt_hi_u32_b32 v158, -1, v210
	s_and_b32 s90, s70, 0x40
	v_and_b32_e32 v159, 48, v158
	v_or_b32_e32 v159, s90, v159
	s_lshl_b32 s88, s70, 4
	s_lshl_b32 s92, s22, 4
	s_and_b32 s92, s92, 0x780
	s_mov_b32 s93, 0
	s_add_u32 m0, s88, 0
	v_lshl_add_u64 v[2:3], v[2:3], 0, s[92:93]
	v_xor_b32_e32 v2, v159, v2
	global_load_lds_dwordx4 v[2:3], off
	v_add_u32_e32 v2, s10, v189
	v_ashrrev_i32_e32 v3, 31, v2
	v_lshlrev_b64 v[2:3], 11, v[2:3]
	v_lshl_add_u64 v[2:3], s[4:5], 0, v[2:3]
	v_lshl_add_u64 v[2:3], v[2:3], 0, v[160:161]
	s_add_u32 m0, s88, 32768
	v_lshl_add_u64 v[2:3], v[2:3], 0, s[92:93]
	v_xor_b32_e32 v2, v159, v2
	global_load_lds_dwordx4 v[2:3], off
	v_add_u32_e32 v2, s9, v190
	v_min_i32_e32 v2, 0x7fff, v2
	v_ashrrev_i32_e32 v3, 31, v2
	v_lshlrev_b64 v[2:3], 11, v[2:3]
	v_lshl_add_u64 v[2:3], s[2:3], 0, v[2:3]
	v_lshl_add_u64 v[2:3], v[2:3], 0, v[160:161]
	s_add_u32 m0, s88, 8192
	v_lshl_add_u64 v[2:3], v[2:3], 0, s[92:93]
	v_xor_b32_e32 v2, v159, v2
	global_load_lds_dwordx4 v[2:3], off
	v_add_u32_e32 v2, s10, v190
	v_ashrrev_i32_e32 v3, 31, v2
	v_lshlrev_b64 v[2:3], 11, v[2:3]
	v_lshl_add_u64 v[2:3], s[4:5], 0, v[2:3]
	v_lshl_add_u64 v[2:3], v[2:3], 0, v[160:161]
	v_add_u32_e32 v4, 0x80, v189
	s_add_u32 m0, s88, 40960
	v_lshl_add_u64 v[2:3], v[2:3], 0, s[92:93]
	v_xor_b32_e32 v2, v159, v2
	global_load_lds_dwordx4 v[2:3], off
	v_add_u32_e32 v2, s9, v4
	v_min_i32_e32 v2, 0x7fff, v2
	v_ashrrev_i32_e32 v3, 31, v2
	v_lshlrev_b64 v[2:3], 11, v[2:3]
	v_lshl_add_u64 v[2:3], s[2:3], 0, v[2:3]
	v_lshl_add_u64 v[2:3], v[2:3], 0, v[160:161]
	s_add_u32 m0, s88, 16384
	v_lshl_add_u64 v[2:3], v[2:3], 0, s[92:93]
	v_xor_b32_e32 v2, v159, v2
	global_load_lds_dwordx4 v[2:3], off
	v_add_u32_e32 v2, s10, v4
	v_ashrrev_i32_e32 v3, 31, v2
	v_lshlrev_b64 v[2:3], 11, v[2:3]
	v_lshl_add_u64 v[2:3], s[4:5], 0, v[2:3]
	v_lshl_add_u64 v[2:3], v[2:3], 0, v[160:161]
	v_add_u32_e32 v4, 0xc0, v189
	s_add_u32 m0, s88, 49152
	v_lshl_add_u64 v[2:3], v[2:3], 0, s[92:93]
	v_xor_b32_e32 v2, v159, v2
	global_load_lds_dwordx4 v[2:3], off
	v_add_u32_e32 v2, s9, v4
	v_min_i32_e32 v2, 0x7fff, v2
	v_ashrrev_i32_e32 v3, 31, v2
	v_lshlrev_b64 v[2:3], 11, v[2:3]
	v_lshl_add_u64 v[2:3], s[2:3], 0, v[2:3]
	v_lshl_add_u64 v[2:3], v[2:3], 0, v[160:161]
	s_add_u32 m0, s88, 24576
	v_lshl_add_u64 v[2:3], v[2:3], 0, s[92:93]
	v_xor_b32_e32 v2, v159, v2
	global_load_lds_dwordx4 v[2:3], off
	v_add_u32_e32 v2, s10, v4
	v_ashrrev_i32_e32 v3, 31, v2
	v_lshlrev_b64 v[2:3], 11, v[2:3]
	v_lshl_add_u64 v[2:3], s[4:5], 0, v[2:3]
	v_lshl_add_u64 v[2:3], v[2:3], 0, v[160:161]
	s_add_u32 m0, s88, 57344
	v_lshl_add_u64 v[2:3], v[2:3], 0, s[92:93]
	v_xor_b32_e32 v2, v159, v2
	global_load_lds_dwordx4 v[2:3], off
	s_waitcnt vmcnt(0)

.LBB0_303:
	s_mul_hi_i32 s5, s68, 0x2aaaaaab
	s_lshr_b32 s2, s5, 31
	s_add_i32 s5, s5, s2
	s_lshl_b32 s69, s5, 8
	s_waitcnt lgkmcnt(0)
	v_add_u32_e32 v0, s69, v189
	v_min_i32_e32 v0, 0x7fff, v0
	v_ashrrev_i32_e32 v1, 31, v0
	v_lshlrev_b64 v[0:1], 11, v[0:1]
	s_mul_i32 s2, s5, 0x600
	v_lshl_add_u64 v[172:173], v[168:169], 0, v[0:1]
	v_subrev_u32_e32 v0, s2, v200
	v_ashrrev_i32_e32 v1, 31, v0
	v_lshlrev_b64 v[0:1], 11, v[0:1]
	v_lshl_add_u64 v[180:181], v[170:171], 0, v[0:1]
	v_subrev_u32_e32 v0, s2, v201
	v_ashrrev_i32_e32 v1, 31, v0
	v_lshlrev_b64 v[0:1], 11, v[0:1]
	v_lshl_add_u64 v[182:183], v[170:171], 0, v[0:1]
	v_subrev_u32_e32 v0, s2, v202
	v_ashrrev_i32_e32 v1, 31, v0
	v_add_u32_e32 v2, s69, v190
	v_add_u32_e32 v4, s69, v163
	v_add_u32_e32 v6, s69, v192
	v_lshlrev_b64 v[0:1], 11, v[0:1]
	v_min_i32_e32 v2, 0x7fff, v2
	v_min_i32_e32 v4, 0x7fff, v4
	v_min_i32_e32 v6, 0x7fff, v6
	v_lshl_add_u64 v[184:185], v[170:171], 0, v[0:1]
	v_subrev_u32_e32 v0, s2, v203
	v_ashrrev_i32_e32 v3, 31, v2
	v_ashrrev_i32_e32 v5, 31, v4
	v_ashrrev_i32_e32 v7, 31, v6
	v_ashrrev_i32_e32 v1, 31, v0
	v_lshlrev_b64 v[2:3], 11, v[2:3]
	v_lshlrev_b64 v[4:5], 11, v[4:5]
	v_lshlrev_b64 v[6:7], 11, v[6:7]
	v_lshlrev_b64 v[0:1], 11, v[0:1]
	s_mov_b32 s4, s68
	v_lshl_add_u64 v[174:175], v[168:169], 0, v[2:3]
	v_lshl_add_u64 v[176:177], v[168:169], 0, v[4:5]
	v_lshl_add_u64 v[178:179], v[168:169], 0, v[6:7]
	v_lshl_add_u64 v[186:187], v[170:171], 0, v[0:1]
	s_mov_b64 s[2:3], 0
	s_mov_b32 s6, s25
	v_mov_b32_e32 v0, v161
	v_mov_b32_e32 v1, v161
	v_mov_b32_e32 v2, v161
	v_mov_b32_e32 v3, v161
	v_mov_b32_e32 v4, v161
	v_mov_b32_e32 v5, v161
	v_mov_b32_e32 v6, v161
	v_mov_b32_e32 v7, v161
	v_mov_b32_e32 v8, v161
	v_mov_b32_e32 v9, v161
	v_mov_b32_e32 v10, v161
	v_mov_b32_e32 v11, v161
	v_mov_b32_e32 v12, v161
	v_mov_b32_e32 v13, v161
	v_mov_b32_e32 v14, v161
	v_mov_b32_e32 v15, v161
	v_mov_b32_e32 v16, v161
	v_mov_b32_e32 v17, v161
	v_mov_b32_e32 v18, v161
	v_mov_b32_e32 v19, v161
	v_mov_b32_e32 v20, v161
	v_mov_b32_e32 v21, v161
	v_mov_b32_e32 v22, v161
	v_mov_b32_e32 v23, v161
	v_mov_b32_e32 v24, v161
	v_mov_b32_e32 v25, v161
	v_mov_b32_e32 v26, v161
	v_mov_b32_e32 v27, v161
	v_mov_b32_e32 v28, v161
	v_mov_b32_e32 v29, v161
	v_mov_b32_e32 v30, v161
	v_mov_b32_e32 v31, v161
	v_mov_b32_e32 v32, v161
	v_mov_b32_e32 v33, v161
	v_mov_b32_e32 v34, v161
	v_mov_b32_e32 v35, v161
	v_mov_b32_e32 v36, v161
	v_mov_b32_e32 v37, v161
	v_mov_b32_e32 v38, v161
	v_mov_b32_e32 v39, v161
	v_mov_b32_e32 v40, v161
	v_mov_b32_e32 v41, v161
	v_mov_b32_e32 v42, v161
	v_mov_b32_e32 v43, v161
	v_mov_b32_e32 v44, v161
	v_mov_b32_e32 v45, v161
	v_mov_b32_e32 v46, v161
	v_mov_b32_e32 v47, v161
	v_mov_b32_e32 v48, v161
	v_mov_b32_e32 v49, v161
	v_mov_b32_e32 v50, v161
	v_mov_b32_e32 v51, v161
	v_mov_b32_e32 v52, v161
	v_mov_b32_e32 v53, v161
	v_mov_b32_e32 v54, v161
	v_mov_b32_e32 v55, v161
	v_mov_b32_e32 v56, v161
	v_mov_b32_e32 v57, v161
	v_mov_b32_e32 v58, v161
	v_mov_b32_e32 v59, v161
	v_mov_b32_e32 v60, v161
	v_mov_b32_e32 v61, v161
	v_mov_b32_e32 v62, v161
	v_mov_b32_e32 v63, v161
	v_mov_b32_e32 v64, v161
	v_mov_b32_e32 v65, v161
	v_mov_b32_e32 v66, v161
	v_mov_b32_e32 v67, v161
	v_mov_b32_e32 v68, v161
	v_mov_b32_e32 v69, v161
	v_mov_b32_e32 v70, v161
	v_mov_b32_e32 v71, v161
	v_mov_b32_e32 v72, v161
	v_mov_b32_e32 v73, v161
	v_mov_b32_e32 v74, v161
	v_mov_b32_e32 v75, v161
	v_mov_b32_e32 v76, v161
	v_mov_b32_e32 v77, v161
	v_mov_b32_e32 v78, v161
	v_mov_b32_e32 v79, v161
	v_mov_b32_e32 v80, v161
	v_mov_b32_e32 v81, v161
	v_mov_b32_e32 v82, v161
	v_mov_b32_e32 v83, v161
	v_mov_b32_e32 v84, v161
	v_mov_b32_e32 v85, v161
	v_mov_b32_e32 v86, v161
	v_mov_b32_e32 v87, v161
	v_mov_b32_e32 v88, v161
	v_mov_b32_e32 v89, v161
	v_mov_b32_e32 v90, v161
	v_mov_b32_e32 v91, v161
	v_mov_b32_e32 v92, v161
	v_mov_b32_e32 v93, v161
	v_mov_b32_e32 v94, v161
	v_mov_b32_e32 v95, v161
	v_mov_b32_e32 v96, v161
	v_mov_b32_e32 v97, v161
	v_mov_b32_e32 v98, v161
	v_mov_b32_e32 v99, v161
	v_mov_b32_e32 v100, v161
	v_mov_b32_e32 v101, v161
	v_mov_b32_e32 v102, v161
	v_mov_b32_e32 v103, v161
	v_mov_b32_e32 v104, v161
	v_mov_b32_e32 v105, v161
	v_mov_b32_e32 v106, v161
	v_mov_b32_e32 v107, v161
	v_mov_b32_e32 v108, v161
	v_mov_b32_e32 v109, v161
	v_mov_b32_e32 v110, v161
	v_mov_b32_e32 v111, v161
	v_mov_b32_e32 v112, v161
	v_mov_b32_e32 v113, v161
	v_mov_b32_e32 v114, v161
	v_mov_b32_e32 v115, v161
	v_mov_b32_e32 v116, v161
	v_mov_b32_e32 v117, v161
	v_mov_b32_e32 v118, v161
	v_mov_b32_e32 v119, v161
	v_mov_b32_e32 v120, v161
	v_mov_b32_e32 v121, v161
	v_mov_b32_e32 v122, v161
	v_mov_b32_e32 v123, v161
	v_mov_b32_e32 v124, v161
	v_mov_b32_e32 v125, v161
	v_mov_b32_e32 v126, v161
	v_mov_b32_e32 v127, v161
	v_mbcnt_hi_u32_b32 v128, -1, v210
	s_and_b32 s90, s70, 0x40
	v_and_b32_e32 v159, 48, v128
	v_or_b32_e32 v159, s90, v159
	v_and_b32_e32 v129, 31, v128
	v_lshrrev_b32_e32 v130, 5, v128
	v_bfe_u32 v131, v128, 1, 3
	v_lshlrev_b32_e32 v132, 7, v129
	s_lshr_b32 s91, s70, 7
	s_lshl_b32 s91, s91, 13
	s_lshl_b32 s90, s90, 8
	s_add_u32 s90, s90, 0x8000
	s_lshl_b32 s88, s70, 4
	s_mov_b32 s89, 0x10000
	s_lshl_b32 s92, s22, 4
	s_and_b32 s92, s92, 0x780
	s_mov_b32 s93, 0
	v_xor_b32_e32 v133, v130, v131
	v_lshl_add_u32 v133, v133, 4, v132
	v_add_u32_e32 v232, s91, v133
	v_add_u32_e32 v236, s90, v133
	v_or_b32_e32 v133, 2, v130
	v_xor_b32_e32 v133, v133, v131
	v_lshl_add_u32 v133, v133, 4, v132
	v_add_u32_e32 v233, s91, v133
	v_add_u32_e32 v237, s90, v133
	v_or_b32_e32 v133, 4, v130
	v_xor_b32_e32 v133, v133, v131
	v_lshl_add_u32 v133, v133, 4, v132
	v_add_u32_e32 v234, s91, v133
	v_add_u32_e32 v238, s90, v133
	v_or_b32_e32 v133, 6, v130
	v_xor_b32_e32 v133, v133, v131
	v_lshl_add_u32 v133, v133, 4, v132
	v_add_u32_e32 v235, s91, v133
	v_add_u32_e32 v239, s90, v133
	s_barrier
	ds_read_b128 v[206:209], v232
	ds_read_b128 v[216:219], v236
	ds_read_b128 v[212:215], v232 offset:4096
	ds_read_b128 v[220:223], v236 offset:4096
	ds_read_b128 v[224:227], v236 offset:8192
	ds_read_b128 v[228:231], v236 offset:12288
	s_add_u32 s94, s2, s92
	s_add_u32 s94, s94, 0x80
	s_and_b32 s94, s94, 0x780
	s_sub_u32 s94, s94, 0x80
	s_subb_u32 s95, 0, 0
	s_add_u32 s90, s88, s89
	s_add_u32 m0, s90, 0
	v_lshl_add_u64 v[152:153], v[172:173], 0, s[94:95]
	v_xor_b32_e32 v152, v159, v152
	global_load_lds_dwordx4 v[152:153], off
	s_add_u32 m0, s90, 32768
	v_lshl_add_u64 v[154:155], v[180:181], 0, s[94:95]
	v_xor_b32_e32 v154, v159, v154
	global_load_lds_dwordx4 v[154:155], off
	s_add_u32 m0, s90, 8192
	v_lshl_add_u64 v[156:157], v[174:175], 0, s[94:95]
	v_xor_b32_e32 v156, v159, v156
	global_load_lds_dwordx4 v[156:157], off
	s_add_u32 m0, s90, 40960
	v_lshl_add_u64 v[152:153], v[182:183], 0, s[94:95]
	v_xor_b32_e32 v152, v159, v152
	global_load_lds_dwordx4 v[152:153], off
	s_add_u32 m0, s90, 16384
	v_lshl_add_u64 v[154:155], v[176:177], 0, s[94:95]
	v_xor_b32_e32 v154, v159, v154
	global_load_lds_dwordx4 v[154:155], off
	s_add_u32 m0, s90, 49152
	v_lshl_add_u64 v[156:157], v[184:185], 0, s[94:95]
	v_xor_b32_e32 v156, v159, v156
	global_load_lds_dwordx4 v[156:157], off
	s_add_u32 m0, s90, 24576
	v_lshl_add_u64 v[152:153], v[178:179], 0, s[94:95]
	v_xor_b32_e32 v152, v159, v152
	global_load_lds_dwordx4 v[152:153], off
	s_add_u32 m0, s90, 57344
	v_lshl_add_u64 v[154:155], v[186:187], 0, s[94:95]
	v_xor_b32_e32 v154, v159, v154
	global_load_lds_dwordx4 v[154:155], off
	s_xor_b32 s89, s89, 0x10000

.LBB0_307:
	ds_read_b128 v[128:131], v233
	ds_read_b128 v[136:139], v237
	ds_read_b128 v[132:135], v233 offset:4096
	ds_read_b128 v[140:143], v237 offset:4096
	ds_read_b128 v[144:147], v237 offset:8192
	ds_read_b128 v[148:151], v237 offset:12288
	s_waitcnt lgkmcnt(6)
	v_mfma_f32_32x32x16_bf16 v[112:127], v[206:209], v[216:219], v[112:127]
	v_mfma_f32_32x32x16_bf16 v[48:63], v[212:215], v[216:219], v[48:63]
	v_mfma_f32_32x32x16_bf16 v[96:111], v[206:209], v[220:223], v[96:111]
	v_mfma_f32_32x32x16_bf16 v[32:47], v[212:215], v[220:223], v[32:47]
	v_mfma_f32_32x32x16_bf16 v[80:95], v[206:209], v[224:227], v[80:95]
	v_mfma_f32_32x32x16_bf16 v[16:31], v[212:215], v[224:227], v[16:31]
	v_mfma_f32_32x32x16_bf16 v[64:79], v[206:209], v[228:231], v[64:79]
	v_mfma_f32_32x32x16_bf16 v[0:15], v[212:215], v[228:231], v[0:15]
	ds_read_b128 v[206:209], v234
	ds_read_b128 v[216:219], v238
	ds_read_b128 v[212:215], v234 offset:4096
	ds_read_b128 v[220:223], v238 offset:4096
	ds_read_b128 v[224:227], v238 offset:8192
	ds_read_b128 v[228:231], v238 offset:12288
	s_waitcnt lgkmcnt(6)
	v_mfma_f32_32x32x16_bf16 v[112:127], v[128:131], v[136:139], v[112:127]
	v_mfma_f32_32x32x16_bf16 v[48:63], v[132:135], v[136:139], v[48:63]
	v_mfma_f32_32x32x16_bf16 v[96:111], v[128:131], v[140:143], v[96:111]
	v_mfma_f32_32x32x16_bf16 v[32:47], v[132:135], v[140:143], v[32:47]
	v_mfma_f32_32x32x16_bf16 v[80:95], v[128:131], v[144:147], v[80:95]
	v_mfma_f32_32x32x16_bf16 v[16:31], v[132:135], v[144:147], v[16:31]
	v_mfma_f32_32x32x16_bf16 v[64:79], v[128:131], v[148:151], v[64:79]
	v_mfma_f32_32x32x16_bf16 v[0:15], v[132:135], v[148:151], v[0:15]
	ds_read_b128 v[128:131], v235
	ds_read_b128 v[136:139], v239
	ds_read_b128 v[132:135], v235 offset:4096
	ds_read_b128 v[140:143], v239 offset:4096
	ds_read_b128 v[144:147], v239 offset:8192
	ds_read_b128 v[148:151], v239 offset:12288
	s_waitcnt lgkmcnt(6)
	v_mfma_f32_32x32x16_bf16 v[112:127], v[206:209], v[216:219], v[112:127]
	v_mfma_f32_32x32x16_bf16 v[48:63], v[212:215], v[216:219], v[48:63]
	v_mfma_f32_32x32x16_bf16 v[96:111], v[206:209], v[220:223], v[96:111]
	v_mfma_f32_32x32x16_bf16 v[32:47], v[212:215], v[220:223], v[32:47]
	v_mfma_f32_32x32x16_bf16 v[80:95], v[206:209], v[224:227], v[80:95]
	v_mfma_f32_32x32x16_bf16 v[16:31], v[212:215], v[224:227], v[16:31]
	v_mfma_f32_32x32x16_bf16 v[64:79], v[206:209], v[228:231], v[64:79]
	v_mfma_f32_32x32x16_bf16 v[0:15], v[212:215], v[228:231], v[0:15]
	s_waitcnt vmcnt(0) lgkmcnt(0)
	s_barrier
	v_xor_b32_e32 v232, 0x10000, v232
	v_xor_b32_e32 v236, 0x10000, v236
	v_mfma_f32_32x32x16_bf16 v[112:127], v[128:131], v[136:139], v[112:127]
	v_xor_b32_e32 v233, 0x10000, v233
	v_xor_b32_e32 v237, 0x10000, v237
	v_mfma_f32_32x32x16_bf16 v[48:63], v[132:135], v[136:139], v[48:63]
	v_xor_b32_e32 v234, 0x10000, v234
	v_xor_b32_e32 v238, 0x10000, v238
	v_mfma_f32_32x32x16_bf16 v[96:111], v[128:131], v[140:143], v[96:111]
	v_xor_b32_e32 v235, 0x10000, v235
	v_xor_b32_e32 v239, 0x10000, v239
	v_mfma_f32_32x32x16_bf16 v[32:47], v[132:135], v[140:143], v[32:47]
	v_mfma_f32_32x32x16_bf16 v[80:95], v[128:131], v[144:147], v[80:95]
	v_mfma_f32_32x32x16_bf16 v[16:31], v[132:135], v[144:147], v[16:31]
	v_mfma_f32_32x32x16_bf16 v[64:79], v[128:131], v[148:151], v[64:79]
	v_mfma_f32_32x32x16_bf16 v[0:15], v[132:135], v[148:151], v[0:15]
	s_mul_i32 s2, s5, -6
	s_add_i32 s2, s2, s4
	s_lshl_b32 s2, s2, 8
	s_or_b32 s24, s2, s56
	s_cmpk_lg_i32 s24, 0x180
	s_cselect_b64 s[8:9], -1, 0
	s_cmpk_gt_i32 s24, 0x180
	s_cselect_b64 s[4:5], -1, 0
	v_cndmask_b32_e64 v160, 0, 1, s[4:5]
	s_mov_b64 s[2:3], -1
	s_and_b64 vcc, exec, s[8:9]
	v_cmp_ne_u32_e64 s[6:7], 1, v160
	s_nop 3
	v_mov_b32_e32 v177, v191
	s_cbranch_vccz .LBB0_311
	s_and_b64 vcc, exec, s[6:7]
	s_nop 4
	v_mov_b32_e32 v175, v96
	v_mov_b32_e32 v174, v112
	s_cbranch_vccnz .LBB0_310
	v_mul_f32_e32 v160, 0xbfb8aa3b, v112
	v_mul_f32_e32 v172, 0xbfb8aa3b, v96
	v_exp_f32_e32 v160, v160
	v_exp_f32_e32 v172, v172
	v_mov_b32_e32 v174, v112
	v_mov_b32_e32 v175, v96
	v_add_f32_e32 v160, 1.0, v160
	v_add_f32_e32 v173, 1.0, v172
	v_rcp_f32_e32 v172, v160
	v_rcp_f32_e32 v173, v173
	s_nop 0
	v_pk_mul_f32 v[174:175], v[174:175], v[172:173]

.LBB0_877:
	v_or_b32_e32 v96, 1, v204
	v_min_i32_e32 v180, 0x7fff, v96
	v_ashrrev_i32_e32 v181, 31, v180
	v_lshl_add_u64 v[174:175], v[180:181], 2, s[18:19]
	v_mov_b32_e32 v112, v243
	v_mov_b32_e32 v96, v113
	v_cndmask_b32_e64 v113, 0, 1, s[6:7]
	v_cmp_ne_u32_e64 s[2:3], 1, v113
	v_mul_lo_u32 v179, v220, s29
	v_or_b32_e32 v178, v179, v178
	v_cvt_pk_bf16_f32 v177, v177, s0
	v_lshl_add_u32 v217, v178, 1, s31
	s_andn2_b64 vcc, exec, s[6:7]
	v_cvt_pk_bf16_f32 v176, v176, s0
	ds_write_b16 v217, v177
	ds_write_b16 v217, v176 offset:64
	s_waitcnt vmcnt(0)
	v_fmamk_f32 v112, v112, 0x3b800000, v216
	v_mul_f32_e32 v113, 0x4b800000, v112
	v_cmp_gt_f32_e64 s[4:5], s38, v112
	s_nop 1
	v_cndmask_b32_e64 v112, v112, v113, s[4:5]
	v_rsq_f32_e32 v112, v112
	s_nop 0
	v_mul_f32_e32 v113, 0x45800000, v112
	v_cndmask_b32_e64 v112, v112, v113, s[4:5]
	v_mul_f32_e32 v112, 0x3dd53b94, v112
	v_pk_mul_f32 v[96:97], v[96:97], v[112:113] op_sel_hi:[1,0]
	v_lshlrev_b64 v[112:113], 8, v[180:181]
	s_cbranch_vccnz .LBB0_879
	s_waitcnt lgkmcnt(0)
	v_lshl_add_u64 v[176:177], s[4:5], 0, v[112:113]
	v_lshl_add_u64 v[176:177], v[176:177], 0, v[160:161]
	v_mov_b32_e32 v176, v248
	v_mov_b32_e32 v177, v249
	s_waitcnt vmcnt(0)
	v_pk_mul_f32 v[178:179], v[96:97], v[176:177] op_sel_hi:[0,1]
	v_pk_mul_f32 v[180:181], v[96:97], v[176:177] op_sel:[1,1] op_sel_hi:[1,0]
	v_pk_fma_f32 v[96:97], v[96:97], v[176:177], v[178:179] op_sel:[1,1,0] op_sel_hi:[1,0,1] neg_lo:[0,0,1] neg_hi:[0,0,1]
	s_nop 0
	v_add_f32_e32 v96, v180, v178
.LBB0_879:
	v_or_b32_e32 v176, 2, v204
	v_min_i32_e32 v176, 0x7fff, v176
	v_ashrrev_i32_e32 v177, 31, v176
	v_lshl_add_u64 v[178:179], v[176:177], 2, s[18:19]
	v_mov_b32_e32 v180, v244
	v_cvt_pk_bf16_f32 v181, v97, s0
	v_mov_b32_e32 v97, v98
	v_cvt_pk_bf16_f32 v182, v96, s0
	v_mov_b32_e32 v96, v114
	s_and_b64 vcc, exec, s[2:3]
	v_lshlrev_b64 v[176:177], 8, v[176:177]
	ds_write_b16 v217, v181 offset:144
	ds_write_b16 v217, v182 offset:208
	s_waitcnt vmcnt(0)
	v_fmamk_f32 v98, v180, 0x3b800000, v216
	v_mul_f32_e32 v114, 0x4b800000, v98
	v_cmp_gt_f32_e64 s[4:5], s38, v98
	s_nop 1
	v_cndmask_b32_e64 v98, v98, v114, s[4:5]
	v_rsq_f32_e32 v98, v98
	s_nop 0
	v_mul_f32_e32 v114, 0x45800000, v98
	v_cndmask_b32_e64 v98, v98, v114, s[4:5]
	v_mul_f32_e32 v98, 0x3dd53b94, v98
	v_pk_mul_f32 v[96:97], v[96:97], v[98:99] op_sel_hi:[1,0]
	s_cbranch_vccnz .LBB0_881
	s_waitcnt lgkmcnt(0)
	v_lshl_add_u64 v[180:181], s[4:5], 0, v[176:177]
	v_lshl_add_u64 v[180:181], v[180:181], 0, v[160:161]
	v_mov_b32_e32 v180, v250
	v_mov_b32_e32 v181, v251
	s_waitcnt vmcnt(0)
	v_pk_mul_f32 v[182:183], v[96:97], v[180:181] op_sel_hi:[0,1]
	v_pk_mul_f32 v[184:185], v[96:97], v[180:181] op_sel:[1,1] op_sel_hi:[1,0]
	v_pk_fma_f32 v[96:97], v[96:97], v[180:181], v[182:183] op_sel:[1,1,0] op_sel_hi:[1,0,1] neg_lo:[0,0,1] neg_hi:[0,0,1]
	s_nop 0
	v_add_f32_e32 v96, v184, v182
.LBB0_881:
	v_or_b32_e32 v98, 3, v204
	v_min_i32_e32 v182, 0x7fff, v98
	v_ashrrev_i32_e32 v183, 31, v182
	v_lshl_add_u64 v[180:181], v[182:183], 2, s[18:19]
	v_mov_b32_e32 v114, v245
	v_mov_b32_e32 v98, v115
	v_cvt_pk_bf16_f32 v97, v97, s0
	v_cvt_pk_bf16_f32 v96, v96, s0
	ds_write_b16 v217, v97 offset:288
	ds_write_b16 v217, v96 offset:352
	s_and_b64 vcc, exec, s[2:3]
	s_waitcnt vmcnt(0)
	v_fmamk_f32 v114, v114, 0x3b800000, v216
	v_mul_f32_e32 v115, 0x4b800000, v114
	v_cmp_gt_f32_e64 s[4:5], s38, v114
	s_nop 1
	v_cndmask_b32_e64 v114, v114, v115, s[4:5]
	v_rsq_f32_e32 v114, v114
	s_nop 0
	v_mul_f32_e32 v96, 0x45800000, v114
	v_cndmask_b32_e64 v96, v114, v96, s[4:5]
	v_mul_f32_e32 v96, 0x3dd53b94, v96
	v_pk_mul_f32 v[96:97], v[98:99], v[96:97] op_sel_hi:[1,0]
	v_lshlrev_b64 v[98:99], 8, v[182:183]
	s_cbranch_vccnz .LBB0_883
	s_waitcnt lgkmcnt(0)
	v_lshl_add_u64 v[114:115], s[4:5], 0, v[98:99]
	v_lshl_add_u64 v[114:115], v[114:115], 0, v[160:161]
	v_mov_b32_e32 v114, v252
	v_mov_b32_e32 v115, v253
	s_waitcnt vmcnt(0)
	v_pk_mul_f32 v[182:183], v[96:97], v[114:115] op_sel_hi:[0,1]
	v_pk_mul_f32 v[184:185], v[96:97], v[114:115] op_sel:[1,1] op_sel_hi:[1,0]
	v_pk_fma_f32 v[96:97], v[96:97], v[114:115], v[182:183] op_sel:[1,1,0] op_sel_hi:[1,0,1] neg_lo:[0,0,1] neg_hi:[0,0,1]
	s_nop 0
	v_add_f32_e32 v96, v184, v182

.LBB0_885:
	v_add_u32_e32 v100, 9, v204
	v_min_i32_e32 v186, 0x7fff, v100
	v_ashrrev_i32_e32 v187, 31, v186
	v_lshl_add_u64 v[184:185], v[186:187], 2, s[18:19]
	v_mov_b32_e32 v116, v243
	v_mov_b32_e32 v100, v117
	v_cvt_pk_bf16_f32 v97, v97, s0
	v_cvt_pk_bf16_f32 v96, v96, s0
	ds_write_b16 v217, v97 offset:1152
	ds_write_b16 v217, v96 offset:1216
	s_and_b64 vcc, exec, s[2:3]
	s_waitcnt vmcnt(0)
	v_fmamk_f32 v116, v116, 0x3b800000, v216
	v_mul_f32_e32 v117, 0x4b800000, v116
	v_cmp_gt_f32_e64 s[4:5], s38, v116
	s_nop 1
	v_cndmask_b32_e64 v116, v116, v117, s[4:5]
	v_rsq_f32_e32 v116, v116
	s_nop 0
	v_mul_f32_e32 v96, 0x45800000, v116
	v_cndmask_b32_e64 v96, v116, v96, s[4:5]
	v_mul_f32_e32 v96, 0x3dd53b94, v96
	v_pk_mul_f32 v[96:97], v[100:101], v[96:97] op_sel_hi:[1,0]
	v_lshlrev_b64 v[100:101], 8, v[186:187]
	s_cbranch_vccnz .LBB0_887
	s_waitcnt lgkmcnt(0)
	v_lshl_add_u64 v[116:117], s[4:5], 0, v[100:101]
	v_lshl_add_u64 v[116:117], v[116:117], 0, v[160:161]
	v_mov_b32_e32 v116, v248
	v_mov_b32_e32 v117, v249
	s_waitcnt vmcnt(0)
	v_pk_mul_f32 v[186:187], v[96:97], v[116:117] op_sel_hi:[0,1]
	v_pk_mul_f32 v[188:189], v[96:97], v[116:117] op_sel:[1,1] op_sel_hi:[1,0]
	v_pk_fma_f32 v[96:97], v[96:97], v[116:117], v[186:187] op_sel:[1,1,0] op_sel_hi:[1,0,1] neg_lo:[0,0,1] neg_hi:[0,0,1]
	s_nop 0
	v_add_f32_e32 v96, v188, v186
.LBB0_887:
	v_add_u32_e32 v116, 10, v204
	v_min_i32_e32 v116, 0x7fff, v116
	v_ashrrev_i32_e32 v117, 31, v116
	v_lshl_add_u64 v[186:187], v[116:117], 2, s[18:19]
	v_mov_b32_e32 v188, v244
	v_cvt_pk_bf16_f32 v189, v97, s0
	v_mov_b32_e32 v97, v102
	v_cvt_pk_bf16_f32 v190, v96, s0
	v_mov_b32_e32 v96, v118
	s_and_b64 vcc, exec, s[2:3]
	v_lshlrev_b64 v[116:117], 8, v[116:117]
	ds_write_b16 v217, v189 offset:1296
	ds_write_b16 v217, v190 offset:1360
	s_waitcnt vmcnt(0)
	v_fmamk_f32 v102, v188, 0x3b800000, v216
	v_mul_f32_e32 v118, 0x4b800000, v102
	v_cmp_gt_f32_e64 s[4:5], s38, v102
	s_nop 1
	v_cndmask_b32_e64 v102, v102, v118, s[4:5]
	v_rsq_f32_e32 v102, v102
	s_nop 0
	v_mul_f32_e32 v118, 0x45800000, v102
	v_cndmask_b32_e64 v102, v102, v118, s[4:5]
	v_mul_f32_e32 v102, 0x3dd53b94, v102
	v_pk_mul_f32 v[96:97], v[96:97], v[102:103] op_sel_hi:[1,0]
	s_cbranch_vccnz .LBB0_889
	s_waitcnt lgkmcnt(0)
	v_lshl_add_u64 v[188:189], s[4:5], 0, v[116:117]
	v_lshl_add_u64 v[188:189], v[188:189], 0, v[160:161]
	v_mov_b32_e32 v188, v250
	v_mov_b32_e32 v189, v251
	s_waitcnt vmcnt(0)
	v_pk_mul_f32 v[190:191], v[96:97], v[188:189] op_sel_hi:[0,1]
	v_pk_mul_f32 v[192:193], v[96:97], v[188:189] op_sel:[1,1] op_sel_hi:[1,0]
	v_pk_fma_f32 v[96:97], v[96:97], v[188:189], v[190:191] op_sel:[1,1,0] op_sel_hi:[1,0,1] neg_lo:[0,0,1] neg_hi:[0,0,1]
	s_nop 0
	v_add_f32_e32 v96, v192, v190
.LBB0_889:
	v_add_u32_e32 v102, 11, v204
	v_min_i32_e32 v190, 0x7fff, v102
	v_ashrrev_i32_e32 v191, 31, v190
	v_lshl_add_u64 v[188:189], v[190:191], 2, s[18:19]
	v_mov_b32_e32 v118, v245
	v_mov_b32_e32 v102, v119
	v_cvt_pk_bf16_f32 v97, v97, s0
	v_cvt_pk_bf16_f32 v96, v96, s0
	ds_write_b16 v217, v97 offset:1440
	ds_write_b16 v217, v96 offset:1504
	s_and_b64 vcc, exec, s[2:3]
	s_waitcnt vmcnt(0)
	v_fmamk_f32 v118, v118, 0x3b800000, v216
	v_mul_f32_e32 v119, 0x4b800000, v118
	v_cmp_gt_f32_e64 s[4:5], s38, v118
	s_nop 1
	v_cndmask_b32_e64 v118, v118, v119, s[4:5]
	v_rsq_f32_e32 v118, v118
	s_nop 0
	v_mul_f32_e32 v96, 0x45800000, v118
	v_cndmask_b32_e64 v96, v118, v96, s[4:5]
	v_mul_f32_e32 v96, 0x3dd53b94, v96
	v_pk_mul_f32 v[96:97], v[102:103], v[96:97] op_sel_hi:[1,0]
	v_lshlrev_b64 v[102:103], 8, v[190:191]
	s_cbranch_vccnz .LBB0_891
	s_waitcnt lgkmcnt(0)
	v_lshl_add_u64 v[118:119], s[4:5], 0, v[102:103]
	v_lshl_add_u64 v[118:119], v[118:119], 0, v[160:161]
	v_mov_b32_e32 v118, v252
	v_mov_b32_e32 v119, v253
	s_waitcnt vmcnt(0)
	v_pk_mul_f32 v[190:191], v[96:97], v[118:119] op_sel_hi:[0,1]
	v_pk_mul_f32 v[192:193], v[96:97], v[118:119] op_sel:[1,1] op_sel_hi:[1,0]
	v_pk_fma_f32 v[96:97], v[96:97], v[118:119], v[190:191] op_sel:[1,1,0] op_sel_hi:[1,0,1] neg_lo:[0,0,1] neg_hi:[0,0,1]
	s_nop 0
	v_add_f32_e32 v96, v192, v190

.LBB0_893:
	v_add_u32_e32 v104, 17, v204
	v_min_i32_e32 v194, 0x7fff, v104
	v_ashrrev_i32_e32 v195, 31, v194
	v_lshl_add_u64 v[192:193], v[194:195], 2, s[18:19]
	v_mov_b32_e32 v120, v243
	v_mov_b32_e32 v104, v121
	v_cvt_pk_bf16_f32 v97, v97, s0
	v_cvt_pk_bf16_f32 v96, v96, s0
	ds_write_b16 v217, v97 offset:2304
	ds_write_b16 v217, v96 offset:2368
	s_and_b64 vcc, exec, s[2:3]
	s_waitcnt vmcnt(0)
	v_fmamk_f32 v120, v120, 0x3b800000, v216
	v_mul_f32_e32 v121, 0x4b800000, v120
	v_cmp_gt_f32_e64 s[4:5], s38, v120
	s_nop 1
	v_cndmask_b32_e64 v120, v120, v121, s[4:5]
	v_rsq_f32_e32 v120, v120
	s_nop 0
	v_mul_f32_e32 v96, 0x45800000, v120
	v_cndmask_b32_e64 v96, v120, v96, s[4:5]
	v_mul_f32_e32 v96, 0x3dd53b94, v96
	v_pk_mul_f32 v[96:97], v[104:105], v[96:97] op_sel_hi:[1,0]
	v_lshlrev_b64 v[104:105], 8, v[194:195]
	s_cbranch_vccnz .LBB0_895
	s_waitcnt lgkmcnt(0)
	v_lshl_add_u64 v[120:121], s[4:5], 0, v[104:105]
	v_lshl_add_u64 v[120:121], v[120:121], 0, v[160:161]
	v_mov_b32_e32 v120, v248
	v_mov_b32_e32 v121, v249
	s_waitcnt vmcnt(0)
	v_pk_mul_f32 v[194:195], v[96:97], v[120:121] op_sel_hi:[0,1]
	v_pk_mul_f32 v[196:197], v[96:97], v[120:121] op_sel:[1,1] op_sel_hi:[1,0]
	v_pk_fma_f32 v[96:97], v[96:97], v[120:121], v[194:195] op_sel:[1,1,0] op_sel_hi:[1,0,1] neg_lo:[0,0,1] neg_hi:[0,0,1]
	s_nop 0
	v_add_f32_e32 v96, v196, v194
.LBB0_895:
	v_add_u32_e32 v120, 18, v204
	v_min_i32_e32 v120, 0x7fff, v120
	v_ashrrev_i32_e32 v121, 31, v120
	v_lshl_add_u64 v[194:195], v[120:121], 2, s[18:19]
	v_mov_b32_e32 v196, v244
	v_cvt_pk_bf16_f32 v197, v97, s0
	v_mov_b32_e32 v97, v106
	v_cvt_pk_bf16_f32 v198, v96, s0
	v_mov_b32_e32 v96, v122
	s_and_b64 vcc, exec, s[2:3]
	v_lshlrev_b64 v[120:121], 8, v[120:121]
	ds_write_b16 v217, v197 offset:2448
	ds_write_b16 v217, v198 offset:2512
	s_waitcnt vmcnt(0)
	v_fmamk_f32 v106, v196, 0x3b800000, v216
	v_mul_f32_e32 v122, 0x4b800000, v106
	v_cmp_gt_f32_e64 s[4:5], s38, v106
	s_nop 1
	v_cndmask_b32_e64 v106, v106, v122, s[4:5]
	v_rsq_f32_e32 v106, v106
	s_nop 0
	v_mul_f32_e32 v122, 0x45800000, v106
	v_cndmask_b32_e64 v106, v106, v122, s[4:5]
	v_mul_f32_e32 v106, 0x3dd53b94, v106
	v_pk_mul_f32 v[96:97], v[96:97], v[106:107] op_sel_hi:[1,0]
	s_cbranch_vccnz .LBB0_897
	s_waitcnt lgkmcnt(0)
	v_lshl_add_u64 v[196:197], s[4:5], 0, v[120:121]
	v_lshl_add_u64 v[196:197], v[196:197], 0, v[160:161]
	v_mov_b32_e32 v196, v250
	v_mov_b32_e32 v197, v251
	s_waitcnt vmcnt(0)
	v_pk_mul_f32 v[198:199], v[96:97], v[196:197] op_sel_hi:[0,1]
	v_pk_mul_f32 v[200:201], v[96:97], v[196:197] op_sel:[1,1] op_sel_hi:[1,0]
	v_pk_fma_f32 v[96:97], v[96:97], v[196:197], v[198:199] op_sel:[1,1,0] op_sel_hi:[1,0,1] neg_lo:[0,0,1] neg_hi:[0,0,1]
	s_nop 0
	v_add_f32_e32 v96, v200, v198
.LBB0_897:
	v_add_u32_e32 v106, 19, v204
	v_min_i32_e32 v198, 0x7fff, v106
	v_ashrrev_i32_e32 v199, 31, v198
	v_lshl_add_u64 v[196:197], v[198:199], 2, s[18:19]
	v_mov_b32_e32 v122, v245
	v_mov_b32_e32 v106, v123
	v_cvt_pk_bf16_f32 v97, v97, s0
	v_cvt_pk_bf16_f32 v96, v96, s0
	ds_write_b16 v217, v97 offset:2592
	ds_write_b16 v217, v96 offset:2656
	s_and_b64 vcc, exec, s[2:3]
	s_waitcnt vmcnt(0)
	v_fmamk_f32 v122, v122, 0x3b800000, v216
	v_mul_f32_e32 v123, 0x4b800000, v122
	v_cmp_gt_f32_e64 s[4:5], s38, v122
	s_nop 1
	v_cndmask_b32_e64 v122, v122, v123, s[4:5]
	v_rsq_f32_e32 v122, v122
	s_nop 0
	v_mul_f32_e32 v96, 0x45800000, v122
	v_cndmask_b32_e64 v96, v122, v96, s[4:5]
	v_mul_f32_e32 v96, 0x3dd53b94, v96
	v_pk_mul_f32 v[96:97], v[106:107], v[96:97] op_sel_hi:[1,0]
	v_lshlrev_b64 v[106:107], 8, v[198:199]
	s_cbranch_vccnz .LBB0_899
	s_waitcnt lgkmcnt(0)
	v_lshl_add_u64 v[122:123], s[4:5], 0, v[106:107]
	v_lshl_add_u64 v[122:123], v[122:123], 0, v[160:161]
	v_mov_b32_e32 v122, v252
	v_mov_b32_e32 v123, v253
	s_waitcnt vmcnt(0)
	v_pk_mul_f32 v[198:199], v[96:97], v[122:123] op_sel_hi:[0,1]
	v_pk_mul_f32 v[200:201], v[96:97], v[122:123] op_sel:[1,1] op_sel_hi:[1,0]
	v_pk_fma_f32 v[96:97], v[96:97], v[122:123], v[198:199] op_sel:[1,1,0] op_sel_hi:[1,0,1] neg_lo:[0,0,1] neg_hi:[0,0,1]
	s_nop 0
	v_add_f32_e32 v96, v200, v198

.LBB0_901:
	v_add_u32_e32 v108, 25, v204
	v_min_i32_e32 v202, 0x7fff, v108
	v_ashrrev_i32_e32 v203, 31, v202
	v_lshl_add_u64 v[200:201], v[202:203], 2, s[18:19]
	v_mov_b32_e32 v124, v243
	v_mov_b32_e32 v108, v125
	v_cvt_pk_bf16_f32 v97, v97, s0
	v_cvt_pk_bf16_f32 v96, v96, s0
	ds_write_b16 v217, v97 offset:3456
	ds_write_b16 v217, v96 offset:3520
	s_and_b64 vcc, exec, s[2:3]
	s_waitcnt vmcnt(0)
	v_fmamk_f32 v124, v124, 0x3b800000, v216
	v_mul_f32_e32 v125, 0x4b800000, v124
	v_cmp_gt_f32_e64 s[4:5], s38, v124
	s_nop 1
	v_cndmask_b32_e64 v124, v124, v125, s[4:5]
	v_rsq_f32_e32 v124, v124
	s_nop 0
	v_mul_f32_e32 v96, 0x45800000, v124
	v_cndmask_b32_e64 v96, v124, v96, s[4:5]
	v_mul_f32_e32 v96, 0x3dd53b94, v96
	v_pk_mul_f32 v[96:97], v[108:109], v[96:97] op_sel_hi:[1,0]
	v_lshlrev_b64 v[108:109], 8, v[202:203]
	s_cbranch_vccnz .LBB0_903
	s_waitcnt lgkmcnt(0)
	v_lshl_add_u64 v[124:125], s[4:5], 0, v[108:109]
	v_lshl_add_u64 v[124:125], v[124:125], 0, v[160:161]
	v_mov_b32_e32 v124, v248
	v_mov_b32_e32 v125, v249
	s_waitcnt vmcnt(0)
	v_pk_mul_f32 v[202:203], v[96:97], v[124:125] op_sel_hi:[0,1]
	v_pk_mul_f32 v[222:223], v[96:97], v[124:125] op_sel:[1,1] op_sel_hi:[1,0]
	v_pk_fma_f32 v[96:97], v[96:97], v[124:125], v[202:203] op_sel:[1,1,0] op_sel_hi:[1,0,1] neg_lo:[0,0,1] neg_hi:[0,0,1]
	s_nop 0
	v_add_f32_e32 v96, v222, v202
.LBB0_903:
	v_add_u32_e32 v124, 26, v204
	v_min_i32_e32 v124, 0x7fff, v124
	v_ashrrev_i32_e32 v125, 31, v124
	v_lshl_add_u64 v[202:203], v[124:125], 2, s[18:19]
	v_mov_b32_e32 v205, v244
	v_cvt_pk_bf16_f32 v221, v97, s0
	v_mov_b32_e32 v97, v110
	v_cvt_pk_bf16_f32 v222, v96, s0
	v_mov_b32_e32 v96, v126
	s_and_b64 vcc, exec, s[2:3]
	v_lshlrev_b64 v[124:125], 8, v[124:125]
	ds_write_b16 v217, v221 offset:3600
	ds_write_b16 v217, v222 offset:3664
	s_waitcnt vmcnt(0)
	v_fmamk_f32 v110, v205, 0x3b800000, v216
	v_mul_f32_e32 v126, 0x4b800000, v110
	v_cmp_gt_f32_e64 s[4:5], s38, v110
	s_nop 1
	v_cndmask_b32_e64 v110, v110, v126, s[4:5]
	v_rsq_f32_e32 v110, v110
	s_nop 0
	v_mul_f32_e32 v126, 0x45800000, v110
	v_cndmask_b32_e64 v110, v110, v126, s[4:5]
	v_mul_f32_e32 v110, 0x3dd53b94, v110
	v_pk_mul_f32 v[96:97], v[96:97], v[110:111] op_sel_hi:[1,0]
	s_cbranch_vccnz .LBB0_905
	s_waitcnt lgkmcnt(0)
	v_lshl_add_u64 v[222:223], s[4:5], 0, v[124:125]
	v_lshl_add_u64 v[222:223], v[222:223], 0, v[160:161]
	v_mov_b32_e32 v222, v250
	v_mov_b32_e32 v223, v251
	s_waitcnt vmcnt(0)
	v_pk_mul_f32 v[224:225], v[96:97], v[222:223] op_sel_hi:[0,1]
	v_pk_mul_f32 v[226:227], v[96:97], v[222:223] op_sel:[1,1] op_sel_hi:[1,0]
	v_pk_fma_f32 v[96:97], v[96:97], v[222:223], v[224:225] op_sel:[1,1,0] op_sel_hi:[1,0,1] neg_lo:[0,0,1] neg_hi:[0,0,1]
	s_nop 0
	v_add_f32_e32 v96, v226, v224
.LBB0_905:
	v_add_u32_e32 v110, 27, v204
	v_min_i32_e32 v222, 0x7fff, v110
	v_ashrrev_i32_e32 v223, 31, v222
	v_lshl_add_u64 v[204:205], v[222:223], 2, s[18:19]
	v_mov_b32_e32 v126, v245
	v_mov_b32_e32 v110, v127
	v_cvt_pk_bf16_f32 v97, v97, s0
	v_cvt_pk_bf16_f32 v96, v96, s0
	ds_write_b16 v217, v97 offset:3744
	ds_write_b16 v217, v96 offset:3808
	s_and_b64 vcc, exec, s[2:3]
	s_waitcnt vmcnt(0)
	v_fmamk_f32 v126, v126, 0x3b800000, v216
	v_mul_f32_e32 v127, 0x4b800000, v126
	v_cmp_gt_f32_e64 s[4:5], s38, v126
	s_nop 1
	v_cndmask_b32_e64 v126, v126, v127, s[4:5]
	v_rsq_f32_e32 v126, v126
	s_nop 0
	v_mul_f32_e32 v96, 0x45800000, v126
	v_cndmask_b32_e64 v96, v126, v96, s[4:5]
	v_mul_f32_e32 v96, 0x3dd53b94, v96
	v_pk_mul_f32 v[96:97], v[110:111], v[96:97] op_sel_hi:[1,0]
	v_lshlrev_b64 v[110:111], 8, v[222:223]
	s_cbranch_vccnz .LBB0_907
	s_waitcnt lgkmcnt(0)
	v_lshl_add_u64 v[126:127], s[4:5], 0, v[110:111]
	v_lshl_add_u64 v[126:127], v[126:127], 0, v[160:161]
	v_mov_b32_e32 v126, v252
	v_mov_b32_e32 v127, v253
	s_waitcnt vmcnt(0)
	v_pk_mul_f32 v[222:223], v[96:97], v[126:127] op_sel_hi:[0,1]
	v_pk_mul_f32 v[224:225], v[96:97], v[126:127] op_sel:[1,1] op_sel_hi:[1,0]
	v_pk_fma_f32 v[96:97], v[96:97], v[126:127], v[222:223] op_sel:[1,1,0] op_sel_hi:[1,0,1] neg_lo:[0,0,1] neg_hi:[0,0,1]
	s_nop 0
	v_add_f32_e32 v96, v224, v222

.LBB0_917:
	v_mov_b32_e32 v80, v243
	v_cvt_pk_bf16_f32 v97, v127, s0
	v_mov_b32_e32 v64, v81
	v_cndmask_b32_e64 v81, 0, 1, s[24:25]
	v_cmp_ne_u32_e64 s[4:5], 1, v81
	v_cvt_pk_bf16_f32 v126, v126, s0
	ds_write_b16 v217, v97
	ds_write_b16 v217, v126 offset:64
	s_waitcnt vmcnt(0)
	v_fmamk_f32 v80, v80, 0x3b800000, v216
	v_mul_f32_e32 v127, 0x4b800000, v80
	v_cmp_gt_f32_e32 vcc, s38, v80
	s_nop 1
	v_cndmask_b32_e32 v80, v80, v127, vcc
	v_rsq_f32_e32 v80, v80
	s_nop 0
	v_mul_f32_e32 v81, 0x45800000, v80
	v_cndmask_b32_e32 v80, v80, v81, vcc
	v_mul_f32_e32 v80, 0x3dd53b94, v80
	s_andn2_b64 vcc, exec, s[24:25]
	v_pk_mul_f32 v[64:65], v[64:65], v[80:81] op_sel_hi:[1,0]
	s_cbranch_vccnz .LBB0_919
	s_waitcnt lgkmcnt(0)
	v_lshl_add_u64 v[80:81], s[24:25], 0, v[112:113]
	v_lshl_add_u64 v[80:81], v[80:81], 0, v[160:161]
	v_mov_b32_e32 v80, v248
	v_mov_b32_e32 v81, v249
	s_waitcnt vmcnt(0)
	v_pk_mul_f32 v[112:113], v[64:65], v[80:81] op_sel_hi:[0,1]
	v_pk_mul_f32 v[126:127], v[64:65], v[80:81] op_sel:[1,1] op_sel_hi:[1,0]
	v_pk_fma_f32 v[64:65], v[64:65], v[80:81], v[112:113] op_sel:[1,1,0] op_sel_hi:[1,0,1] neg_lo:[0,0,1] neg_hi:[0,0,1]
	s_nop 0
	v_add_f32_e32 v64, v126, v112
.LBB0_919:
	v_mov_b32_e32 v80, v244
	v_cvt_pk_bf16_f32 v81, v65, s0
	v_cvt_pk_bf16_f32 v97, v64, s0
	v_mov_b32_e32 v64, v82
	ds_write_b16 v217, v81 offset:144
	ds_write_b16 v217, v97 offset:208
	s_waitcnt vmcnt(0)
	v_fmamk_f32 v65, v80, 0x3b800000, v216
	v_mul_f32_e32 v80, 0x4b800000, v65
	v_cmp_gt_f32_e32 vcc, s38, v65
	s_nop 1
	v_cndmask_b32_e32 v65, v65, v80, vcc
	v_rsq_f32_e32 v80, v65
	v_mov_b32_e32 v65, v66
	v_mul_f32_e32 v66, 0x45800000, v80
	v_cndmask_b32_e32 v66, v80, v66, vcc
	v_mul_f32_e32 v66, 0x3dd53b94, v66
	s_and_b64 vcc, exec, s[4:5]
	v_pk_mul_f32 v[64:65], v[64:65], v[66:67] op_sel_hi:[1,0]
	s_cbranch_vccnz .LBB0_921
	s_waitcnt lgkmcnt(0)
	v_lshl_add_u64 v[80:81], s[24:25], 0, v[176:177]
	v_lshl_add_u64 v[80:81], v[80:81], 0, v[160:161]
	v_mov_b32_e32 v80, v250
	v_mov_b32_e32 v81, v251
	s_waitcnt vmcnt(0)
	v_pk_mul_f32 v[112:113], v[64:65], v[80:81] op_sel_hi:[0,1]
	v_pk_mul_f32 v[126:127], v[64:65], v[80:81] op_sel:[1,1] op_sel_hi:[1,0]
	v_pk_fma_f32 v[64:65], v[64:65], v[80:81], v[112:113] op_sel:[1,1,0] op_sel_hi:[1,0,1] neg_lo:[0,0,1] neg_hi:[0,0,1]
	s_nop 0
	v_add_f32_e32 v64, v126, v112
.LBB0_921:
	v_mov_b32_e32 v66, v245
	v_cvt_pk_bf16_f32 v65, v65, s0
	v_cvt_pk_bf16_f32 v64, v64, s0
	ds_write_b16 v217, v65 offset:288
	ds_write_b16 v217, v64 offset:352
	s_waitcnt vmcnt(0)
	v_fmamk_f32 v66, v66, 0x3b800000, v216
	v_mul_f32_e32 v80, 0x4b800000, v66
	v_cmp_gt_f32_e32 vcc, s38, v66
	s_nop 1
	v_cndmask_b32_e32 v66, v66, v80, vcc
	v_rsq_f32_e32 v80, v66
	v_mov_b32_e32 v66, v83
	v_mul_f32_e32 v64, 0x45800000, v80
	v_cndmask_b32_e32 v64, v80, v64, vcc
	v_mul_f32_e32 v64, 0x3dd53b94, v64
	s_and_b64 vcc, exec, s[4:5]
	v_pk_mul_f32 v[64:65], v[66:67], v[64:65] op_sel_hi:[1,0]
	s_cbranch_vccnz .LBB0_923
	s_waitcnt lgkmcnt(0)
	v_lshl_add_u64 v[66:67], s[24:25], 0, v[98:99]
	v_lshl_add_u64 v[66:67], v[66:67], 0, v[160:161]
	v_mov_b32_e32 v66, v252
	v_mov_b32_e32 v67, v253
	s_waitcnt vmcnt(0)
	v_pk_mul_f32 v[80:81], v[64:65], v[66:67] op_sel_hi:[0,1]
	v_pk_mul_f32 v[82:83], v[64:65], v[66:67] op_sel:[1,1] op_sel_hi:[1,0]
	v_pk_fma_f32 v[64:65], v[64:65], v[66:67], v[80:81] op_sel:[1,1,0] op_sel_hi:[1,0,1] neg_lo:[0,0,1] neg_hi:[0,0,1]
	s_nop 0
	v_add_f32_e32 v64, v82, v80

.LBB0_925:
	v_mov_b32_e32 v66, v243
	v_cvt_pk_bf16_f32 v65, v65, s0
	v_cvt_pk_bf16_f32 v64, v64, s0
	ds_write_b16 v217, v65 offset:1152
	ds_write_b16 v217, v64 offset:1216
	v_mov_b32_e32 v68, v85
	s_waitcnt vmcnt(0)
	v_fmamk_f32 v66, v66, 0x3b800000, v216
	v_mul_f32_e32 v67, 0x4b800000, v66
	v_cmp_gt_f32_e32 vcc, s38, v66
	s_nop 1
	v_cndmask_b32_e32 v66, v66, v67, vcc
	v_rsq_f32_e32 v66, v66
	s_nop 0
	v_mul_f32_e32 v64, 0x45800000, v66
	v_cndmask_b32_e32 v64, v66, v64, vcc
	v_mul_f32_e32 v64, 0x3dd53b94, v64
	s_and_b64 vcc, exec, s[4:5]
	v_pk_mul_f32 v[64:65], v[68:69], v[64:65] op_sel_hi:[1,0]
	s_cbranch_vccnz .LBB0_927
	s_waitcnt lgkmcnt(0)
	v_lshl_add_u64 v[66:67], s[24:25], 0, v[100:101]
	v_lshl_add_u64 v[66:67], v[66:67], 0, v[160:161]
	v_mov_b32_e32 v66, v248
	v_mov_b32_e32 v67, v249
	s_waitcnt vmcnt(0)
	v_pk_mul_f32 v[68:69], v[64:65], v[66:67] op_sel_hi:[0,1]
	v_pk_mul_f32 v[80:81], v[64:65], v[66:67] op_sel:[1,1] op_sel_hi:[1,0]
	v_pk_fma_f32 v[64:65], v[64:65], v[66:67], v[68:69] op_sel:[1,1,0] op_sel_hi:[1,0,1] neg_lo:[0,0,1] neg_hi:[0,0,1]
	s_nop 0
	v_add_f32_e32 v64, v80, v68
.LBB0_927:
	v_mov_b32_e32 v66, v244
	v_cvt_pk_bf16_f32 v67, v65, s0
	v_cvt_pk_bf16_f32 v68, v64, s0
	ds_write_b16 v217, v67 offset:1296
	ds_write_b16 v217, v68 offset:1360
	v_mov_b32_e32 v64, v86
	s_waitcnt vmcnt(0)
	v_fmamk_f32 v65, v66, 0x3b800000, v216
	v_mul_f32_e32 v66, 0x4b800000, v65
	v_cmp_gt_f32_e32 vcc, s38, v65
	s_nop 1
	v_cndmask_b32_e32 v65, v65, v66, vcc
	v_rsq_f32_e32 v66, v65
	v_mov_b32_e32 v65, v70
	v_mul_f32_e32 v67, 0x45800000, v66
	v_cndmask_b32_e32 v66, v66, v67, vcc
	v_mul_f32_e32 v66, 0x3dd53b94, v66
	s_and_b64 vcc, exec, s[4:5]
	v_pk_mul_f32 v[64:65], v[64:65], v[66:67] op_sel_hi:[1,0]
	s_cbranch_vccnz .LBB0_929
	s_waitcnt lgkmcnt(0)
	v_lshl_add_u64 v[66:67], s[24:25], 0, v[116:117]
	v_lshl_add_u64 v[66:67], v[66:67], 0, v[160:161]
	v_mov_b32_e32 v66, v250
	v_mov_b32_e32 v67, v251
	s_waitcnt vmcnt(0)
	v_pk_mul_f32 v[68:69], v[64:65], v[66:67] op_sel_hi:[0,1]
	v_pk_mul_f32 v[80:81], v[64:65], v[66:67] op_sel:[1,1] op_sel_hi:[1,0]
	v_pk_fma_f32 v[64:65], v[64:65], v[66:67], v[68:69] op_sel:[1,1,0] op_sel_hi:[1,0,1] neg_lo:[0,0,1] neg_hi:[0,0,1]
	s_nop 0
	v_add_f32_e32 v64, v80, v68
.LBB0_929:
	v_mov_b32_e32 v66, v245
	v_cvt_pk_bf16_f32 v65, v65, s0
	v_cvt_pk_bf16_f32 v64, v64, s0
	ds_write_b16 v217, v65 offset:1440
	ds_write_b16 v217, v64 offset:1504
	v_mov_b32_e32 v70, v87
	s_waitcnt vmcnt(0)
	v_fmamk_f32 v66, v66, 0x3b800000, v216
	v_mul_f32_e32 v67, 0x4b800000, v66
	v_cmp_gt_f32_e32 vcc, s38, v66
	s_nop 1
	v_cndmask_b32_e32 v66, v66, v67, vcc
	v_rsq_f32_e32 v66, v66
	s_nop 0
	v_mul_f32_e32 v64, 0x45800000, v66
	v_cndmask_b32_e32 v64, v66, v64, vcc
	v_mul_f32_e32 v64, 0x3dd53b94, v64
	s_and_b64 vcc, exec, s[4:5]
	v_pk_mul_f32 v[64:65], v[70:71], v[64:65] op_sel_hi:[1,0]
	s_cbranch_vccnz .LBB0_931
	s_waitcnt lgkmcnt(0)
	v_lshl_add_u64 v[66:67], s[24:25], 0, v[102:103]
	v_lshl_add_u64 v[66:67], v[66:67], 0, v[160:161]
	v_mov_b32_e32 v66, v252
	v_mov_b32_e32 v67, v253
	s_waitcnt vmcnt(0)
	v_pk_mul_f32 v[68:69], v[64:65], v[66:67] op_sel_hi:[0,1]
	v_pk_mul_f32 v[70:71], v[64:65], v[66:67] op_sel:[1,1] op_sel_hi:[1,0]
	v_pk_fma_f32 v[64:65], v[64:65], v[66:67], v[68:69] op_sel:[1,1,0] op_sel_hi:[1,0,1] neg_lo:[0,0,1] neg_hi:[0,0,1]
	s_nop 0
	v_add_f32_e32 v64, v70, v68

.LBB0_933:
	v_mov_b32_e32 v66, v243
	v_cvt_pk_bf16_f32 v65, v65, s0
	v_cvt_pk_bf16_f32 v64, v64, s0
	ds_write_b16 v217, v65 offset:2304
	ds_write_b16 v217, v64 offset:2368
	v_mov_b32_e32 v72, v89
	s_waitcnt vmcnt(0)
	v_fmamk_f32 v66, v66, 0x3b800000, v216
	v_mul_f32_e32 v67, 0x4b800000, v66
	v_cmp_gt_f32_e32 vcc, s38, v66
	s_nop 1
	v_cndmask_b32_e32 v66, v66, v67, vcc
	v_rsq_f32_e32 v66, v66
	s_nop 0
	v_mul_f32_e32 v64, 0x45800000, v66
	v_cndmask_b32_e32 v64, v66, v64, vcc
	v_mul_f32_e32 v64, 0x3dd53b94, v64
	s_and_b64 vcc, exec, s[4:5]
	v_pk_mul_f32 v[64:65], v[72:73], v[64:65] op_sel_hi:[1,0]
	s_cbranch_vccnz .LBB0_935
	s_waitcnt lgkmcnt(0)
	v_lshl_add_u64 v[66:67], s[24:25], 0, v[104:105]
	v_lshl_add_u64 v[66:67], v[66:67], 0, v[160:161]
	v_mov_b32_e32 v66, v248
	v_mov_b32_e32 v67, v249
	s_waitcnt vmcnt(0)
	v_pk_mul_f32 v[68:69], v[64:65], v[66:67] op_sel_hi:[0,1]
	v_pk_mul_f32 v[70:71], v[64:65], v[66:67] op_sel:[1,1] op_sel_hi:[1,0]
	v_pk_fma_f32 v[64:65], v[64:65], v[66:67], v[68:69] op_sel:[1,1,0] op_sel_hi:[1,0,1] neg_lo:[0,0,1] neg_hi:[0,0,1]
	s_nop 0
	v_add_f32_e32 v64, v70, v68
.LBB0_935:
	v_mov_b32_e32 v66, v244
	v_cvt_pk_bf16_f32 v67, v65, s0
	v_cvt_pk_bf16_f32 v68, v64, s0
	ds_write_b16 v217, v67 offset:2448
	ds_write_b16 v217, v68 offset:2512
	v_mov_b32_e32 v64, v90
	s_waitcnt vmcnt(0)
	v_fmamk_f32 v65, v66, 0x3b800000, v216
	v_mul_f32_e32 v66, 0x4b800000, v65
	v_cmp_gt_f32_e32 vcc, s38, v65
	s_nop 1
	v_cndmask_b32_e32 v65, v65, v66, vcc
	v_rsq_f32_e32 v66, v65
	v_mov_b32_e32 v65, v74
	v_mul_f32_e32 v67, 0x45800000, v66
	v_cndmask_b32_e32 v66, v66, v67, vcc
	v_mul_f32_e32 v66, 0x3dd53b94, v66
	s_and_b64 vcc, exec, s[4:5]
	v_pk_mul_f32 v[64:65], v[64:65], v[66:67] op_sel_hi:[1,0]
	s_cbranch_vccnz .LBB0_937
	s_waitcnt lgkmcnt(0)
	v_lshl_add_u64 v[66:67], s[24:25], 0, v[120:121]
	v_lshl_add_u64 v[66:67], v[66:67], 0, v[160:161]
	v_mov_b32_e32 v66, v250
	v_mov_b32_e32 v67, v251
	s_waitcnt vmcnt(0)
	v_pk_mul_f32 v[68:69], v[64:65], v[66:67] op_sel_hi:[0,1]
	v_pk_mul_f32 v[70:71], v[64:65], v[66:67] op_sel:[1,1] op_sel_hi:[1,0]
	v_pk_fma_f32 v[64:65], v[64:65], v[66:67], v[68:69] op_sel:[1,1,0] op_sel_hi:[1,0,1] neg_lo:[0,0,1] neg_hi:[0,0,1]
	s_nop 0
	v_add_f32_e32 v64, v70, v68
.LBB0_937:
	v_mov_b32_e32 v66, v245
	v_cvt_pk_bf16_f32 v65, v65, s0
	v_cvt_pk_bf16_f32 v64, v64, s0
	ds_write_b16 v217, v65 offset:2592
	ds_write_b16 v217, v64 offset:2656
	v_mov_b32_e32 v74, v91
	s_waitcnt vmcnt(0)
	v_fmamk_f32 v66, v66, 0x3b800000, v216
	v_mul_f32_e32 v67, 0x4b800000, v66
	v_cmp_gt_f32_e32 vcc, s38, v66
	s_nop 1
	v_cndmask_b32_e32 v66, v66, v67, vcc
	v_rsq_f32_e32 v66, v66
	s_nop 0
	v_mul_f32_e32 v64, 0x45800000, v66
	v_cndmask_b32_e32 v64, v66, v64, vcc
	v_mul_f32_e32 v64, 0x3dd53b94, v64
	s_and_b64 vcc, exec, s[4:5]
	v_pk_mul_f32 v[64:65], v[74:75], v[64:65] op_sel_hi:[1,0]
	s_cbranch_vccnz .LBB0_939
	s_waitcnt lgkmcnt(0)
	v_lshl_add_u64 v[66:67], s[24:25], 0, v[106:107]
	v_lshl_add_u64 v[66:67], v[66:67], 0, v[160:161]
	v_mov_b32_e32 v66, v252
	v_mov_b32_e32 v67, v253
	s_waitcnt vmcnt(0)
	v_pk_mul_f32 v[68:69], v[64:65], v[66:67] op_sel_hi:[0,1]
	v_pk_mul_f32 v[70:71], v[64:65], v[66:67] op_sel:[1,1] op_sel_hi:[1,0]
	v_pk_fma_f32 v[64:65], v[64:65], v[66:67], v[68:69] op_sel:[1,1,0] op_sel_hi:[1,0,1] neg_lo:[0,0,1] neg_hi:[0,0,1]
	s_nop 0
	v_add_f32_e32 v64, v70, v68

.LBB0_941:
	v_mov_b32_e32 v66, v243
	v_cvt_pk_bf16_f32 v65, v65, s0
	v_cvt_pk_bf16_f32 v64, v64, s0
	ds_write_b16 v217, v65 offset:3456
	ds_write_b16 v217, v64 offset:3520
	v_mov_b32_e32 v76, v93
	s_waitcnt vmcnt(0)
	v_fmamk_f32 v66, v66, 0x3b800000, v216
	v_mul_f32_e32 v67, 0x4b800000, v66
	v_cmp_gt_f32_e32 vcc, s38, v66
	s_nop 1
	v_cndmask_b32_e32 v66, v66, v67, vcc
	v_rsq_f32_e32 v66, v66
	s_nop 0
	v_mul_f32_e32 v64, 0x45800000, v66
	v_cndmask_b32_e32 v64, v66, v64, vcc
	v_mul_f32_e32 v64, 0x3dd53b94, v64
	s_and_b64 vcc, exec, s[4:5]
	v_pk_mul_f32 v[64:65], v[76:77], v[64:65] op_sel_hi:[1,0]
	s_cbranch_vccnz .LBB0_943
	s_waitcnt lgkmcnt(0)
	v_lshl_add_u64 v[66:67], s[24:25], 0, v[108:109]
	v_lshl_add_u64 v[66:67], v[66:67], 0, v[160:161]
	v_mov_b32_e32 v66, v248
	v_mov_b32_e32 v67, v249
	s_waitcnt vmcnt(0)
	v_pk_mul_f32 v[68:69], v[64:65], v[66:67] op_sel_hi:[0,1]
	v_pk_mul_f32 v[70:71], v[64:65], v[66:67] op_sel:[1,1] op_sel_hi:[1,0]
	v_pk_fma_f32 v[64:65], v[64:65], v[66:67], v[68:69] op_sel:[1,1,0] op_sel_hi:[1,0,1] neg_lo:[0,0,1] neg_hi:[0,0,1]
	s_nop 0
	v_add_f32_e32 v64, v70, v68
.LBB0_943:
	v_mov_b32_e32 v66, v244
	v_cvt_pk_bf16_f32 v67, v65, s0
	v_cvt_pk_bf16_f32 v68, v64, s0
	ds_write_b16 v217, v67 offset:3600
	ds_write_b16 v217, v68 offset:3664
	v_mov_b32_e32 v64, v94
	s_waitcnt vmcnt(0)
	v_fmamk_f32 v65, v66, 0x3b800000, v216
	v_mul_f32_e32 v66, 0x4b800000, v65
	v_cmp_gt_f32_e32 vcc, s38, v65
	s_nop 1
	v_cndmask_b32_e32 v65, v65, v66, vcc
	v_rsq_f32_e32 v66, v65
	v_mov_b32_e32 v65, v78
	v_mul_f32_e32 v67, 0x45800000, v66
	v_cndmask_b32_e32 v66, v66, v67, vcc
	v_mul_f32_e32 v66, 0x3dd53b94, v66
	s_and_b64 vcc, exec, s[4:5]
	v_pk_mul_f32 v[64:65], v[64:65], v[66:67] op_sel_hi:[1,0]
	s_cbranch_vccnz .LBB0_945
	s_waitcnt lgkmcnt(0)
	v_lshl_add_u64 v[66:67], s[24:25], 0, v[124:125]
	v_lshl_add_u64 v[66:67], v[66:67], 0, v[160:161]
	v_mov_b32_e32 v66, v250
	v_mov_b32_e32 v67, v251
	s_waitcnt vmcnt(0)
	v_pk_mul_f32 v[68:69], v[64:65], v[66:67] op_sel_hi:[0,1]
	v_pk_mul_f32 v[70:71], v[64:65], v[66:67] op_sel:[1,1] op_sel_hi:[1,0]
	v_pk_fma_f32 v[64:65], v[64:65], v[66:67], v[68:69] op_sel:[1,1,0] op_sel_hi:[1,0,1] neg_lo:[0,0,1] neg_hi:[0,0,1]
	s_nop 0
	v_add_f32_e32 v64, v70, v68
.LBB0_945:
	v_mov_b32_e32 v66, v245
	v_cvt_pk_bf16_f32 v65, v65, s0
	v_cvt_pk_bf16_f32 v64, v64, s0
	ds_write_b16 v217, v65 offset:3744
	ds_write_b16 v217, v64 offset:3808
	v_mov_b32_e32 v78, v95
	s_waitcnt vmcnt(0)
	v_fmamk_f32 v66, v66, 0x3b800000, v216
	v_mul_f32_e32 v67, 0x4b800000, v66
	v_cmp_gt_f32_e32 vcc, s38, v66
	s_nop 1
	v_cndmask_b32_e32 v66, v66, v67, vcc
	v_rsq_f32_e32 v66, v66
	s_nop 0
	v_mul_f32_e32 v64, 0x45800000, v66
	v_cndmask_b32_e32 v64, v66, v64, vcc
	v_mul_f32_e32 v64, 0x3dd53b94, v64
	s_and_b64 vcc, exec, s[4:5]
	v_pk_mul_f32 v[64:65], v[78:79], v[64:65] op_sel_hi:[1,0]
	s_cbranch_vccnz .LBB0_947
	s_waitcnt lgkmcnt(0)
	v_lshl_add_u64 v[66:67], s[24:25], 0, v[110:111]
	v_lshl_add_u64 v[66:67], v[66:67], 0, v[160:161]
	v_mov_b32_e32 v66, v252
	v_mov_b32_e32 v67, v253
	s_waitcnt vmcnt(0)
	v_pk_mul_f32 v[68:69], v[64:65], v[66:67] op_sel_hi:[0,1]
	v_pk_mul_f32 v[70:71], v[64:65], v[66:67] op_sel:[1,1] op_sel_hi:[1,0]
	v_pk_fma_f32 v[64:65], v[64:65], v[66:67], v[68:69] op_sel:[1,1,0] op_sel_hi:[1,0,1] neg_lo:[0,0,1] neg_hi:[0,0,1]
	s_nop 0
	v_add_f32_e32 v64, v70, v68

.LBB0_957:
	v_or_b32_e32 v32, 1, v97
	v_min_i32_e32 v72, 0x7fff, v32
	v_ashrrev_i32_e32 v73, 31, v72
	v_lshl_add_u64 v[68:69], v[72:73], 2, s[18:19]
	v_mov_b32_e32 v48, v243
	v_mov_b32_e32 v32, v49
	v_cvt_pk_bf16_f32 v71, v71, s0
	s_and_b64 vcc, exec, s[2:3]
	v_cvt_pk_bf16_f32 v70, v70, s0
	ds_write_b16 v217, v71
	ds_write_b16 v217, v70 offset:64
	s_waitcnt vmcnt(0)
	v_fmamk_f32 v48, v48, 0x3b800000, v216
	v_mul_f32_e32 v49, 0x4b800000, v48
	v_cmp_gt_f32_e64 s[6:7], s38, v48
	s_nop 1
	v_cndmask_b32_e64 v48, v48, v49, s[6:7]
	v_rsq_f32_e32 v48, v48
	s_nop 0
	v_mul_f32_e32 v49, 0x45800000, v48
	v_cndmask_b32_e64 v48, v48, v49, s[6:7]
	v_mul_f32_e32 v48, 0x3dd53b94, v48
	v_pk_mul_f32 v[48:49], v[32:33], v[48:49] op_sel_hi:[1,0]
	v_lshlrev_b64 v[32:33], 8, v[72:73]
	s_cbranch_vccnz .LBB0_959
	s_waitcnt lgkmcnt(0)
	v_lshl_add_u64 v[70:71], s[6:7], 0, v[32:33]
	v_lshl_add_u64 v[70:71], v[70:71], 0, v[160:161]
	v_mov_b32_e32 v70, v248
	v_mov_b32_e32 v71, v249
	s_waitcnt vmcnt(0)
	v_pk_mul_f32 v[72:73], v[48:49], v[70:71] op_sel_hi:[0,1]
	v_pk_mul_f32 v[74:75], v[48:49], v[70:71] op_sel:[1,1] op_sel_hi:[1,0]
	v_pk_fma_f32 v[48:49], v[48:49], v[70:71], v[72:73] op_sel:[1,1,0] op_sel_hi:[1,0,1] neg_lo:[0,0,1] neg_hi:[0,0,1]
	s_nop 0
	v_add_f32_e32 v48, v74, v72
.LBB0_959:
	v_or_b32_e32 v70, 2, v97
	v_min_i32_e32 v72, 0x7fff, v70
	v_ashrrev_i32_e32 v73, 31, v72
	v_lshl_add_u64 v[70:71], v[72:73], 2, s[18:19]
	v_mov_b32_e32 v74, v244
	v_cvt_pk_bf16_f32 v75, v49, s0
	v_mov_b32_e32 v49, v34
	v_cvt_pk_bf16_f32 v76, v48, s0
	v_mov_b32_e32 v48, v50
	s_and_b64 vcc, exec, s[2:3]
	ds_write_b16 v217, v75 offset:144
	ds_write_b16 v217, v76 offset:208
	s_waitcnt vmcnt(0)
	v_fmamk_f32 v34, v74, 0x3b800000, v216
	v_mul_f32_e32 v50, 0x4b800000, v34
	v_cmp_gt_f32_e64 s[6:7], s38, v34
	s_nop 1
	v_cndmask_b32_e64 v34, v34, v50, s[6:7]
	v_rsq_f32_e32 v34, v34
	s_nop 0
	v_mul_f32_e32 v50, 0x45800000, v34
	v_cndmask_b32_e64 v34, v34, v50, s[6:7]
	v_mul_f32_e32 v34, 0x3dd53b94, v34
	v_pk_mul_f32 v[74:75], v[48:49], v[34:35] op_sel_hi:[1,0]
	v_lshlrev_b64 v[48:49], 8, v[72:73]
	s_cbranch_vccnz .LBB0_961
	s_waitcnt lgkmcnt(0)
	v_lshl_add_u64 v[72:73], s[6:7], 0, v[48:49]
	v_lshl_add_u64 v[72:73], v[72:73], 0, v[160:161]
	v_mov_b32_e32 v72, v250
	v_mov_b32_e32 v73, v251
	s_waitcnt vmcnt(0)
	v_pk_mul_f32 v[76:77], v[74:75], v[72:73] op_sel_hi:[0,1]
	v_pk_mul_f32 v[78:79], v[74:75], v[72:73] op_sel:[1,1] op_sel_hi:[1,0]
	v_pk_fma_f32 v[74:75], v[74:75], v[72:73], v[76:77] op_sel:[1,1,0] op_sel_hi:[1,0,1] neg_lo:[0,0,1] neg_hi:[0,0,1]
	s_nop 0
	v_add_f32_e32 v74, v78, v76
.LBB0_961:
	v_or_b32_e32 v34, 3, v97
	v_min_i32_e32 v76, 0x7fff, v34
	v_ashrrev_i32_e32 v77, 31, v76
	v_lshl_add_u64 v[72:73], v[76:77], 2, s[18:19]
	v_mov_b32_e32 v50, v245
	v_mov_b32_e32 v34, v51
	v_cvt_pk_bf16_f32 v75, v75, s0
	s_and_b64 vcc, exec, s[2:3]
	v_cvt_pk_bf16_f32 v74, v74, s0
	ds_write_b16 v217, v75 offset:288
	ds_write_b16 v217, v74 offset:352
	s_waitcnt vmcnt(0)
	v_fmamk_f32 v50, v50, 0x3b800000, v216
	v_mul_f32_e32 v51, 0x4b800000, v50
	v_cmp_gt_f32_e64 s[6:7], s38, v50
	s_nop 1
	v_cndmask_b32_e64 v50, v50, v51, s[6:7]
	v_rsq_f32_e32 v50, v50
	s_nop 0
	v_mul_f32_e32 v51, 0x45800000, v50
	v_cndmask_b32_e64 v50, v50, v51, s[6:7]
	v_mul_f32_e32 v50, 0x3dd53b94, v50
	v_pk_mul_f32 v[50:51], v[34:35], v[50:51] op_sel_hi:[1,0]
	v_lshlrev_b64 v[34:35], 8, v[76:77]
	s_cbranch_vccnz .LBB0_963
	s_waitcnt lgkmcnt(0)
	v_lshl_add_u64 v[74:75], s[6:7], 0, v[34:35]
	v_lshl_add_u64 v[74:75], v[74:75], 0, v[160:161]
	v_mov_b32_e32 v74, v252
	v_mov_b32_e32 v75, v253
	s_waitcnt vmcnt(0)
	v_pk_mul_f32 v[76:77], v[50:51], v[74:75] op_sel_hi:[0,1]
	v_pk_mul_f32 v[78:79], v[50:51], v[74:75] op_sel:[1,1] op_sel_hi:[1,0]
	v_pk_fma_f32 v[50:51], v[50:51], v[74:75], v[76:77] op_sel:[1,1,0] op_sel_hi:[1,0,1] neg_lo:[0,0,1] neg_hi:[0,0,1]
	s_nop 0
	v_add_f32_e32 v50, v78, v76

.LBB0_965:
	v_add_u32_e32 v36, 9, v97
	v_min_i32_e32 v80, 0x7fff, v36
	v_ashrrev_i32_e32 v81, 31, v80
	v_lshl_add_u64 v[76:77], v[80:81], 2, s[18:19]
	v_mov_b32_e32 v52, v243
	v_mov_b32_e32 v36, v53
	v_cvt_pk_bf16_f32 v79, v79, s0
	s_and_b64 vcc, exec, s[2:3]
	v_cvt_pk_bf16_f32 v78, v78, s0
	ds_write_b16 v217, v79 offset:1152
	ds_write_b16 v217, v78 offset:1216
	s_waitcnt vmcnt(0)
	v_fmamk_f32 v52, v52, 0x3b800000, v216
	v_mul_f32_e32 v53, 0x4b800000, v52
	v_cmp_gt_f32_e64 s[6:7], s38, v52
	s_nop 1
	v_cndmask_b32_e64 v52, v52, v53, s[6:7]
	v_rsq_f32_e32 v52, v52
	s_nop 0
	v_mul_f32_e32 v53, 0x45800000, v52
	v_cndmask_b32_e64 v52, v52, v53, s[6:7]
	v_mul_f32_e32 v52, 0x3dd53b94, v52
	v_pk_mul_f32 v[52:53], v[36:37], v[52:53] op_sel_hi:[1,0]
	v_lshlrev_b64 v[36:37], 8, v[80:81]
	s_cbranch_vccnz .LBB0_967
	s_waitcnt lgkmcnt(0)
	v_lshl_add_u64 v[78:79], s[6:7], 0, v[36:37]
	v_lshl_add_u64 v[78:79], v[78:79], 0, v[160:161]
	v_mov_b32_e32 v78, v248
	v_mov_b32_e32 v79, v249
	s_waitcnt vmcnt(0)
	v_pk_mul_f32 v[80:81], v[52:53], v[78:79] op_sel_hi:[0,1]
	v_pk_mul_f32 v[82:83], v[52:53], v[78:79] op_sel:[1,1] op_sel_hi:[1,0]
	v_pk_fma_f32 v[52:53], v[52:53], v[78:79], v[80:81] op_sel:[1,1,0] op_sel_hi:[1,0,1] neg_lo:[0,0,1] neg_hi:[0,0,1]
	s_nop 0
	v_add_f32_e32 v52, v82, v80
.LBB0_967:
	v_add_u32_e32 v78, 10, v97
	v_min_i32_e32 v80, 0x7fff, v78
	v_ashrrev_i32_e32 v81, 31, v80
	v_lshl_add_u64 v[78:79], v[80:81], 2, s[18:19]
	v_mov_b32_e32 v82, v244
	v_cvt_pk_bf16_f32 v83, v53, s0
	v_mov_b32_e32 v53, v38
	v_cvt_pk_bf16_f32 v84, v52, s0
	v_mov_b32_e32 v52, v54
	s_and_b64 vcc, exec, s[2:3]
	ds_write_b16 v217, v83 offset:1296
	ds_write_b16 v217, v84 offset:1360
	s_waitcnt vmcnt(0)
	v_fmamk_f32 v38, v82, 0x3b800000, v216
	v_mul_f32_e32 v54, 0x4b800000, v38
	v_cmp_gt_f32_e64 s[6:7], s38, v38
	s_nop 1
	v_cndmask_b32_e64 v38, v38, v54, s[6:7]
	v_rsq_f32_e32 v38, v38
	s_nop 0
	v_mul_f32_e32 v54, 0x45800000, v38
	v_cndmask_b32_e64 v38, v38, v54, s[6:7]
	v_mul_f32_e32 v38, 0x3dd53b94, v38
	v_pk_mul_f32 v[82:83], v[52:53], v[38:39] op_sel_hi:[1,0]
	v_lshlrev_b64 v[52:53], 8, v[80:81]
	s_cbranch_vccnz .LBB0_969
	s_waitcnt lgkmcnt(0)
	v_lshl_add_u64 v[80:81], s[6:7], 0, v[52:53]
	v_lshl_add_u64 v[80:81], v[80:81], 0, v[160:161]
	v_mov_b32_e32 v80, v250
	v_mov_b32_e32 v81, v251
	s_waitcnt vmcnt(0)
	v_pk_mul_f32 v[84:85], v[82:83], v[80:81] op_sel_hi:[0,1]
	v_pk_mul_f32 v[86:87], v[82:83], v[80:81] op_sel:[1,1] op_sel_hi:[1,0]
	v_pk_fma_f32 v[82:83], v[82:83], v[80:81], v[84:85] op_sel:[1,1,0] op_sel_hi:[1,0,1] neg_lo:[0,0,1] neg_hi:[0,0,1]
	s_nop 0
	v_add_f32_e32 v82, v86, v84
.LBB0_969:
	v_add_u32_e32 v38, 11, v97
	v_min_i32_e32 v84, 0x7fff, v38
	v_ashrrev_i32_e32 v85, 31, v84
	v_lshl_add_u64 v[80:81], v[84:85], 2, s[18:19]
	v_mov_b32_e32 v54, v245
	v_mov_b32_e32 v38, v55
	v_cvt_pk_bf16_f32 v83, v83, s0
	s_and_b64 vcc, exec, s[2:3]
	v_cvt_pk_bf16_f32 v82, v82, s0
	ds_write_b16 v217, v83 offset:1440
	ds_write_b16 v217, v82 offset:1504
	s_waitcnt vmcnt(0)
	v_fmamk_f32 v54, v54, 0x3b800000, v216
	v_mul_f32_e32 v55, 0x4b800000, v54
	v_cmp_gt_f32_e64 s[6:7], s38, v54
	s_nop 1
	v_cndmask_b32_e64 v54, v54, v55, s[6:7]
	v_rsq_f32_e32 v54, v54
	s_nop 0
	v_mul_f32_e32 v55, 0x45800000, v54
	v_cndmask_b32_e64 v54, v54, v55, s[6:7]
	v_mul_f32_e32 v54, 0x3dd53b94, v54
	v_pk_mul_f32 v[54:55], v[38:39], v[54:55] op_sel_hi:[1,0]
	v_lshlrev_b64 v[38:39], 8, v[84:85]
	s_cbranch_vccnz .LBB0_971
	s_waitcnt lgkmcnt(0)
	v_lshl_add_u64 v[82:83], s[6:7], 0, v[38:39]
	v_lshl_add_u64 v[82:83], v[82:83], 0, v[160:161]
	v_mov_b32_e32 v82, v252
	v_mov_b32_e32 v83, v253
	s_waitcnt vmcnt(0)
	v_pk_mul_f32 v[84:85], v[54:55], v[82:83] op_sel_hi:[0,1]
	v_pk_mul_f32 v[86:87], v[54:55], v[82:83] op_sel:[1,1] op_sel_hi:[1,0]
	v_pk_fma_f32 v[54:55], v[54:55], v[82:83], v[84:85] op_sel:[1,1,0] op_sel_hi:[1,0,1] neg_lo:[0,0,1] neg_hi:[0,0,1]
	s_nop 0
	v_add_f32_e32 v54, v86, v84

.LBB0_973:
	v_add_u32_e32 v40, 17, v97
	v_min_i32_e32 v88, 0x7fff, v40
	v_ashrrev_i32_e32 v89, 31, v88
	v_lshl_add_u64 v[84:85], v[88:89], 2, s[18:19]
	v_mov_b32_e32 v56, v243
	v_mov_b32_e32 v40, v57
	v_cvt_pk_bf16_f32 v87, v87, s0
	s_and_b64 vcc, exec, s[2:3]
	v_cvt_pk_bf16_f32 v86, v86, s0
	ds_write_b16 v217, v87 offset:2304
	ds_write_b16 v217, v86 offset:2368
	s_waitcnt vmcnt(0)
	v_fmamk_f32 v56, v56, 0x3b800000, v216
	v_mul_f32_e32 v57, 0x4b800000, v56
	v_cmp_gt_f32_e64 s[6:7], s38, v56
	s_nop 1
	v_cndmask_b32_e64 v56, v56, v57, s[6:7]
	v_rsq_f32_e32 v56, v56
	s_nop 0
	v_mul_f32_e32 v57, 0x45800000, v56
	v_cndmask_b32_e64 v56, v56, v57, s[6:7]
	v_mul_f32_e32 v56, 0x3dd53b94, v56
	v_pk_mul_f32 v[56:57], v[40:41], v[56:57] op_sel_hi:[1,0]
	v_lshlrev_b64 v[40:41], 8, v[88:89]
	s_cbranch_vccnz .LBB0_975
	s_waitcnt lgkmcnt(0)
	v_lshl_add_u64 v[86:87], s[6:7], 0, v[40:41]
	v_lshl_add_u64 v[86:87], v[86:87], 0, v[160:161]
	v_mov_b32_e32 v86, v248
	v_mov_b32_e32 v87, v249
	s_waitcnt vmcnt(0)
	v_pk_mul_f32 v[88:89], v[56:57], v[86:87] op_sel_hi:[0,1]
	v_pk_mul_f32 v[90:91], v[56:57], v[86:87] op_sel:[1,1] op_sel_hi:[1,0]
	v_pk_fma_f32 v[56:57], v[56:57], v[86:87], v[88:89] op_sel:[1,1,0] op_sel_hi:[1,0,1] neg_lo:[0,0,1] neg_hi:[0,0,1]
	s_nop 0
	v_add_f32_e32 v56, v90, v88
.LBB0_975:
	v_add_u32_e32 v86, 18, v97
	v_min_i32_e32 v88, 0x7fff, v86
	v_ashrrev_i32_e32 v89, 31, v88
	v_lshl_add_u64 v[86:87], v[88:89], 2, s[18:19]
	v_mov_b32_e32 v90, v244
	v_cvt_pk_bf16_f32 v91, v57, s0
	v_mov_b32_e32 v57, v42
	v_cvt_pk_bf16_f32 v92, v56, s0
	v_mov_b32_e32 v56, v58
	s_and_b64 vcc, exec, s[2:3]
	ds_write_b16 v217, v91 offset:2448
	ds_write_b16 v217, v92 offset:2512
	s_waitcnt vmcnt(0)
	v_fmamk_f32 v42, v90, 0x3b800000, v216
	v_mul_f32_e32 v58, 0x4b800000, v42
	v_cmp_gt_f32_e64 s[6:7], s38, v42
	s_nop 1
	v_cndmask_b32_e64 v42, v42, v58, s[6:7]
	v_rsq_f32_e32 v42, v42
	s_nop 0
	v_mul_f32_e32 v58, 0x45800000, v42
	v_cndmask_b32_e64 v42, v42, v58, s[6:7]
	v_mul_f32_e32 v42, 0x3dd53b94, v42
	v_pk_mul_f32 v[90:91], v[56:57], v[42:43] op_sel_hi:[1,0]
	v_lshlrev_b64 v[56:57], 8, v[88:89]
	s_cbranch_vccnz .LBB0_977
	s_waitcnt lgkmcnt(0)
	v_lshl_add_u64 v[88:89], s[6:7], 0, v[56:57]
	v_lshl_add_u64 v[88:89], v[88:89], 0, v[160:161]
	v_mov_b32_e32 v88, v250
	v_mov_b32_e32 v89, v251
	s_waitcnt vmcnt(0)
	v_pk_mul_f32 v[92:93], v[90:91], v[88:89] op_sel_hi:[0,1]
	v_pk_mul_f32 v[94:95], v[90:91], v[88:89] op_sel:[1,1] op_sel_hi:[1,0]
	v_pk_fma_f32 v[90:91], v[90:91], v[88:89], v[92:93] op_sel:[1,1,0] op_sel_hi:[1,0,1] neg_lo:[0,0,1] neg_hi:[0,0,1]
	s_nop 0
	v_add_f32_e32 v90, v94, v92
.LBB0_977:
	v_add_u32_e32 v42, 19, v97
	v_min_i32_e32 v92, 0x7fff, v42
	v_ashrrev_i32_e32 v93, 31, v92
	v_lshl_add_u64 v[88:89], v[92:93], 2, s[18:19]
	v_mov_b32_e32 v58, v245
	v_mov_b32_e32 v42, v59
	v_cvt_pk_bf16_f32 v91, v91, s0
	s_and_b64 vcc, exec, s[2:3]
	v_cvt_pk_bf16_f32 v90, v90, s0
	ds_write_b16 v217, v91 offset:2592
	ds_write_b16 v217, v90 offset:2656
	s_waitcnt vmcnt(0)
	v_fmamk_f32 v58, v58, 0x3b800000, v216
	v_mul_f32_e32 v59, 0x4b800000, v58
	v_cmp_gt_f32_e64 s[6:7], s38, v58
	s_nop 1
	v_cndmask_b32_e64 v58, v58, v59, s[6:7]
	v_rsq_f32_e32 v58, v58
	s_nop 0
	v_mul_f32_e32 v59, 0x45800000, v58
	v_cndmask_b32_e64 v58, v58, v59, s[6:7]
	v_mul_f32_e32 v58, 0x3dd53b94, v58
	v_pk_mul_f32 v[58:59], v[42:43], v[58:59] op_sel_hi:[1,0]
	v_lshlrev_b64 v[42:43], 8, v[92:93]
	s_cbranch_vccnz .LBB0_979
	s_waitcnt lgkmcnt(0)
	v_lshl_add_u64 v[90:91], s[6:7], 0, v[42:43]
	v_lshl_add_u64 v[90:91], v[90:91], 0, v[160:161]
	v_mov_b32_e32 v90, v252
	v_mov_b32_e32 v91, v253
	s_waitcnt vmcnt(0)
	v_pk_mul_f32 v[92:93], v[58:59], v[90:91] op_sel_hi:[0,1]
	v_pk_mul_f32 v[94:95], v[58:59], v[90:91] op_sel:[1,1] op_sel_hi:[1,0]
	v_pk_fma_f32 v[58:59], v[58:59], v[90:91], v[92:93] op_sel:[1,1,0] op_sel_hi:[1,0,1] neg_lo:[0,0,1] neg_hi:[0,0,1]
	s_nop 0
	v_add_f32_e32 v58, v94, v92

.LBB0_981:
	v_add_u32_e32 v44, 25, v97
	v_min_i32_e32 v98, 0x7fff, v44
	v_ashrrev_i32_e32 v99, 31, v98
	v_lshl_add_u64 v[92:93], v[98:99], 2, s[18:19]
	v_mov_b32_e32 v60, v243
	v_mov_b32_e32 v44, v61
	v_cvt_pk_bf16_f32 v95, v95, s0
	s_and_b64 vcc, exec, s[2:3]
	v_cvt_pk_bf16_f32 v94, v94, s0
	ds_write_b16 v217, v95 offset:3456
	ds_write_b16 v217, v94 offset:3520
	s_waitcnt vmcnt(0)
	v_fmamk_f32 v60, v60, 0x3b800000, v216
	v_mul_f32_e32 v61, 0x4b800000, v60
	v_cmp_gt_f32_e64 s[6:7], s38, v60
	s_nop 1
	v_cndmask_b32_e64 v60, v60, v61, s[6:7]
	v_rsq_f32_e32 v60, v60
	s_nop 0
	v_mul_f32_e32 v61, 0x45800000, v60
	v_cndmask_b32_e64 v60, v60, v61, s[6:7]
	v_mul_f32_e32 v60, 0x3dd53b94, v60
	v_pk_mul_f32 v[60:61], v[44:45], v[60:61] op_sel_hi:[1,0]
	v_lshlrev_b64 v[44:45], 8, v[98:99]
	s_cbranch_vccnz .LBB0_983
	s_waitcnt lgkmcnt(0)
	v_lshl_add_u64 v[94:95], s[6:7], 0, v[44:45]
	v_lshl_add_u64 v[94:95], v[94:95], 0, v[160:161]
	v_mov_b32_e32 v94, v248
	v_mov_b32_e32 v95, v249
	s_waitcnt vmcnt(0)
	v_pk_mul_f32 v[98:99], v[60:61], v[94:95] op_sel_hi:[0,1]
	v_pk_mul_f32 v[100:101], v[60:61], v[94:95] op_sel:[1,1] op_sel_hi:[1,0]
	v_pk_fma_f32 v[60:61], v[60:61], v[94:95], v[98:99] op_sel:[1,1,0] op_sel_hi:[1,0,1] neg_lo:[0,0,1] neg_hi:[0,0,1]
	s_nop 0
	v_add_f32_e32 v60, v100, v98
.LBB0_983:
	v_add_u32_e32 v94, 26, v97
	v_min_i32_e32 v98, 0x7fff, v94
	v_ashrrev_i32_e32 v99, 31, v98
	v_lshl_add_u64 v[94:95], v[98:99], 2, s[18:19]
	v_mov_b32_e32 v100, v244
	v_cvt_pk_bf16_f32 v101, v61, s0
	v_mov_b32_e32 v61, v46
	v_cvt_pk_bf16_f32 v102, v60, s0
	v_mov_b32_e32 v60, v62
	s_and_b64 vcc, exec, s[2:3]
	ds_write_b16 v217, v101 offset:3600
	ds_write_b16 v217, v102 offset:3664
	s_waitcnt vmcnt(0)
	v_fmamk_f32 v46, v100, 0x3b800000, v216
	v_mul_f32_e32 v62, 0x4b800000, v46
	v_cmp_gt_f32_e64 s[6:7], s38, v46
	s_nop 1
	v_cndmask_b32_e64 v46, v46, v62, s[6:7]
	v_rsq_f32_e32 v46, v46
	s_nop 0
	v_mul_f32_e32 v62, 0x45800000, v46
	v_cndmask_b32_e64 v46, v46, v62, s[6:7]
	v_mul_f32_e32 v46, 0x3dd53b94, v46
	v_pk_mul_f32 v[100:101], v[60:61], v[46:47] op_sel_hi:[1,0]
	v_lshlrev_b64 v[60:61], 8, v[98:99]
	s_cbranch_vccnz .LBB0_985
	s_waitcnt lgkmcnt(0)
	v_lshl_add_u64 v[98:99], s[6:7], 0, v[60:61]
	v_lshl_add_u64 v[98:99], v[98:99], 0, v[160:161]
	v_mov_b32_e32 v98, v250
	v_mov_b32_e32 v99, v251
	s_waitcnt vmcnt(0)
	v_pk_mul_f32 v[102:103], v[100:101], v[98:99] op_sel_hi:[0,1]
	v_pk_mul_f32 v[104:105], v[100:101], v[98:99] op_sel:[1,1] op_sel_hi:[1,0]
	v_pk_fma_f32 v[100:101], v[100:101], v[98:99], v[102:103] op_sel:[1,1,0] op_sel_hi:[1,0,1] neg_lo:[0,0,1] neg_hi:[0,0,1]
	s_nop 0
	v_add_f32_e32 v100, v104, v102
.LBB0_985:
	v_add_u32_e32 v46, 27, v97
	v_min_i32_e32 v102, 0x7fff, v46
	v_ashrrev_i32_e32 v103, 31, v102
	v_lshl_add_u64 v[98:99], v[102:103], 2, s[18:19]
	v_mov_b32_e32 v62, v245
	v_mov_b32_e32 v46, v63
	v_cvt_pk_bf16_f32 v97, v101, s0
	s_and_b64 vcc, exec, s[2:3]
	v_cvt_pk_bf16_f32 v100, v100, s0
	ds_write_b16 v217, v97 offset:3744
	ds_write_b16 v217, v100 offset:3808
	s_waitcnt vmcnt(0)
	v_fmamk_f32 v62, v62, 0x3b800000, v216
	v_mul_f32_e32 v63, 0x4b800000, v62
	v_cmp_gt_f32_e64 s[6:7], s38, v62
	s_nop 1
	v_cndmask_b32_e64 v62, v62, v63, s[6:7]
	v_rsq_f32_e32 v62, v62
	s_nop 0
	v_mul_f32_e32 v63, 0x45800000, v62
	v_cndmask_b32_e64 v62, v62, v63, s[6:7]
	v_mul_f32_e32 v62, 0x3dd53b94, v62
	v_pk_mul_f32 v[62:63], v[46:47], v[62:63] op_sel_hi:[1,0]
	v_lshlrev_b64 v[46:47], 8, v[102:103]
	s_cbranch_vccnz .LBB0_987
	s_waitcnt lgkmcnt(0)
	v_lshl_add_u64 v[100:101], s[2:3], 0, v[46:47]
	v_lshl_add_u64 v[100:101], v[100:101], 0, v[160:161]
	v_mov_b32_e32 v100, v252
	v_mov_b32_e32 v101, v253
	s_waitcnt vmcnt(0)
	v_pk_mul_f32 v[102:103], v[62:63], v[100:101] op_sel_hi:[0,1]
	v_pk_mul_f32 v[104:105], v[62:63], v[100:101] op_sel:[1,1] op_sel_hi:[1,0]
	v_pk_fma_f32 v[62:63], v[62:63], v[100:101], v[102:103] op_sel:[1,1,0] op_sel_hi:[1,0,1] neg_lo:[0,0,1] neg_hi:[0,0,1]
	s_nop 0
	v_add_f32_e32 v62, v104, v102

.LBB0_997:
	v_mov_b32_e32 v0, v243
	v_cvt_pk_bf16_f32 v16, v63, s0
	v_cvt_pk_bf16_f32 v62, v62, s0
	ds_write_b16 v217, v16
	ds_write_b16 v217, v62 offset:64
	s_waitcnt vmcnt(0)
	v_fmamk_f32 v0, v0, 0x3b800000, v216
	v_mul_f32_e32 v63, 0x4b800000, v0
	v_cmp_gt_f32_e32 vcc, s38, v0
	s_nop 1
	v_cndmask_b32_e32 v0, v0, v63, vcc
	v_rsq_f32_e32 v63, v0
	v_mov_b32_e32 v0, v17
	v_mul_f32_e32 v16, 0x45800000, v63
	v_cndmask_b32_e32 v16, v63, v16, vcc
	v_mul_f32_e32 v16, 0x3dd53b94, v16
	s_and_b64 vcc, exec, s[4:5]
	v_pk_mul_f32 v[0:1], v[0:1], v[16:17] op_sel_hi:[1,0]
	s_cbranch_vccnz .LBB0_999
	s_waitcnt lgkmcnt(0)
	v_lshl_add_u64 v[16:17], s[12:13], 0, v[32:33]
	v_lshl_add_u64 v[16:17], v[16:17], 0, v[160:161]
	v_mov_b32_e32 v16, v248
	v_mov_b32_e32 v17, v249
	s_waitcnt vmcnt(0)
	v_pk_mul_f32 v[32:33], v[0:1], v[16:17] op_sel_hi:[0,1]
	v_pk_mul_f32 v[62:63], v[0:1], v[16:17] op_sel:[1,1] op_sel_hi:[1,0]
	v_pk_fma_f32 v[0:1], v[0:1], v[16:17], v[32:33] op_sel:[1,1,0] op_sel_hi:[1,0,1] neg_lo:[0,0,1] neg_hi:[0,0,1]
	s_nop 0
	v_add_f32_e32 v0, v62, v32
.LBB0_999:
	v_mov_b32_e32 v16, v244
	v_cvt_pk_bf16_f32 v17, v1, s0
	v_cvt_pk_bf16_f32 v32, v0, s0
	v_mov_b32_e32 v0, v18
	ds_write_b16 v217, v17 offset:144
	ds_write_b16 v217, v32 offset:208
	s_waitcnt vmcnt(0)
	v_fmamk_f32 v1, v16, 0x3b800000, v216
	v_mul_f32_e32 v16, 0x4b800000, v1
	v_cmp_gt_f32_e32 vcc, s38, v1
	s_nop 1
	v_cndmask_b32_e32 v1, v1, v16, vcc
	v_rsq_f32_e32 v16, v1
	v_mov_b32_e32 v1, v2
	v_mul_f32_e32 v2, 0x45800000, v16
	v_cndmask_b32_e32 v2, v16, v2, vcc
	v_mul_f32_e32 v2, 0x3dd53b94, v2
	s_and_b64 vcc, exec, s[4:5]
	v_pk_mul_f32 v[0:1], v[0:1], v[2:3] op_sel_hi:[1,0]
	s_cbranch_vccnz .LBB0_1001
	s_waitcnt lgkmcnt(0)
	v_lshl_add_u64 v[16:17], s[12:13], 0, v[48:49]
	v_lshl_add_u64 v[16:17], v[16:17], 0, v[160:161]
	v_mov_b32_e32 v16, v250
	v_mov_b32_e32 v17, v251
	s_waitcnt vmcnt(0)
	v_pk_mul_f32 v[32:33], v[0:1], v[16:17] op_sel_hi:[0,1]
	v_pk_mul_f32 v[48:49], v[0:1], v[16:17] op_sel:[1,1] op_sel_hi:[1,0]
	v_pk_fma_f32 v[0:1], v[0:1], v[16:17], v[32:33] op_sel:[1,1,0] op_sel_hi:[1,0,1] neg_lo:[0,0,1] neg_hi:[0,0,1]
	s_nop 0
	v_add_f32_e32 v0, v48, v32
.LBB0_1001:
	v_mov_b32_e32 v2, v245
	v_cvt_pk_bf16_f32 v1, v1, s0
	v_cvt_pk_bf16_f32 v0, v0, s0
	ds_write_b16 v217, v1 offset:288
	ds_write_b16 v217, v0 offset:352
	s_waitcnt vmcnt(0)
	v_fmamk_f32 v2, v2, 0x3b800000, v216
	v_mul_f32_e32 v16, 0x4b800000, v2
	v_cmp_gt_f32_e32 vcc, s38, v2
	s_nop 1
	v_cndmask_b32_e32 v2, v2, v16, vcc
	v_rsq_f32_e32 v16, v2
	v_mov_b32_e32 v2, v19
	v_mul_f32_e32 v0, 0x45800000, v16
	v_cndmask_b32_e32 v0, v16, v0, vcc
	v_mul_f32_e32 v0, 0x3dd53b94, v0
	s_and_b64 vcc, exec, s[4:5]
	v_pk_mul_f32 v[0:1], v[2:3], v[0:1] op_sel_hi:[1,0]
	s_cbranch_vccnz .LBB0_1003
	s_waitcnt lgkmcnt(0)
	v_lshl_add_u64 v[2:3], s[12:13], 0, v[34:35]
	v_lshl_add_u64 v[2:3], v[2:3], 0, v[160:161]
	v_mov_b32_e32 v2, v252
	v_mov_b32_e32 v3, v253
	s_waitcnt vmcnt(0)
	v_pk_mul_f32 v[16:17], v[0:1], v[2:3] op_sel_hi:[0,1]
	v_pk_mul_f32 v[18:19], v[0:1], v[2:3] op_sel:[1,1] op_sel_hi:[1,0]
	v_pk_fma_f32 v[0:1], v[0:1], v[2:3], v[16:17] op_sel:[1,1,0] op_sel_hi:[1,0,1] neg_lo:[0,0,1] neg_hi:[0,0,1]
	s_nop 0
	v_add_f32_e32 v0, v18, v16

.LBB0_1005:
	v_mov_b32_e32 v2, v243
	v_cvt_pk_bf16_f32 v1, v1, s0
	v_cvt_pk_bf16_f32 v0, v0, s0
	ds_write_b16 v217, v1 offset:1152
	ds_write_b16 v217, v0 offset:1216
	v_mov_b32_e32 v4, v21
	s_waitcnt vmcnt(0)
	v_fmamk_f32 v2, v2, 0x3b800000, v216
	v_mul_f32_e32 v3, 0x4b800000, v2
	v_cmp_gt_f32_e32 vcc, s38, v2
	s_nop 1
	v_cndmask_b32_e32 v2, v2, v3, vcc
	v_rsq_f32_e32 v2, v2
	s_nop 0
	v_mul_f32_e32 v0, 0x45800000, v2
	v_cndmask_b32_e32 v0, v2, v0, vcc
	v_mul_f32_e32 v0, 0x3dd53b94, v0
	s_and_b64 vcc, exec, s[4:5]
	v_pk_mul_f32 v[0:1], v[4:5], v[0:1] op_sel_hi:[1,0]
	s_cbranch_vccnz .LBB0_1007
	s_waitcnt lgkmcnt(0)
	v_lshl_add_u64 v[2:3], s[12:13], 0, v[36:37]
	v_lshl_add_u64 v[2:3], v[2:3], 0, v[160:161]
	v_mov_b32_e32 v2, v248
	v_mov_b32_e32 v3, v249
	s_waitcnt vmcnt(0)
	v_pk_mul_f32 v[4:5], v[0:1], v[2:3] op_sel_hi:[0,1]
	v_pk_mul_f32 v[16:17], v[0:1], v[2:3] op_sel:[1,1] op_sel_hi:[1,0]
	v_pk_fma_f32 v[0:1], v[0:1], v[2:3], v[4:5] op_sel:[1,1,0] op_sel_hi:[1,0,1] neg_lo:[0,0,1] neg_hi:[0,0,1]
	s_nop 0
	v_add_f32_e32 v0, v16, v4
.LBB0_1007:
	v_mov_b32_e32 v2, v244
	v_cvt_pk_bf16_f32 v3, v1, s0
	v_cvt_pk_bf16_f32 v4, v0, s0
	ds_write_b16 v217, v3 offset:1296
	ds_write_b16 v217, v4 offset:1360
	v_mov_b32_e32 v0, v22
	s_waitcnt vmcnt(0)
	v_fmamk_f32 v1, v2, 0x3b800000, v216
	v_mul_f32_e32 v2, 0x4b800000, v1
	v_cmp_gt_f32_e32 vcc, s38, v1
	s_nop 1
	v_cndmask_b32_e32 v1, v1, v2, vcc
	v_rsq_f32_e32 v2, v1
	v_mov_b32_e32 v1, v6
	v_mul_f32_e32 v3, 0x45800000, v2
	v_cndmask_b32_e32 v2, v2, v3, vcc
	v_mul_f32_e32 v2, 0x3dd53b94, v2
	s_and_b64 vcc, exec, s[4:5]
	v_pk_mul_f32 v[0:1], v[0:1], v[2:3] op_sel_hi:[1,0]
	s_cbranch_vccnz .LBB0_1009
	s_waitcnt lgkmcnt(0)
	v_lshl_add_u64 v[2:3], s[12:13], 0, v[52:53]
	v_lshl_add_u64 v[2:3], v[2:3], 0, v[160:161]
	v_mov_b32_e32 v2, v250
	v_mov_b32_e32 v3, v251
	s_waitcnt vmcnt(0)
	v_pk_mul_f32 v[4:5], v[0:1], v[2:3] op_sel_hi:[0,1]
	v_pk_mul_f32 v[16:17], v[0:1], v[2:3] op_sel:[1,1] op_sel_hi:[1,0]
	v_pk_fma_f32 v[0:1], v[0:1], v[2:3], v[4:5] op_sel:[1,1,0] op_sel_hi:[1,0,1] neg_lo:[0,0,1] neg_hi:[0,0,1]
	s_nop 0
	v_add_f32_e32 v0, v16, v4
.LBB0_1009:
	v_mov_b32_e32 v2, v245
	v_cvt_pk_bf16_f32 v1, v1, s0
	v_cvt_pk_bf16_f32 v0, v0, s0
	ds_write_b16 v217, v1 offset:1440
	ds_write_b16 v217, v0 offset:1504
	v_mov_b32_e32 v6, v23
	s_waitcnt vmcnt(0)
	v_fmamk_f32 v2, v2, 0x3b800000, v216
	v_mul_f32_e32 v3, 0x4b800000, v2
	v_cmp_gt_f32_e32 vcc, s38, v2
	s_nop 1
	v_cndmask_b32_e32 v2, v2, v3, vcc
	v_rsq_f32_e32 v2, v2
	s_nop 0
	v_mul_f32_e32 v0, 0x45800000, v2
	v_cndmask_b32_e32 v0, v2, v0, vcc
	v_mul_f32_e32 v0, 0x3dd53b94, v0
	s_and_b64 vcc, exec, s[4:5]
	v_pk_mul_f32 v[0:1], v[6:7], v[0:1] op_sel_hi:[1,0]
	s_cbranch_vccnz .LBB0_1011
	s_waitcnt lgkmcnt(0)
	v_lshl_add_u64 v[2:3], s[12:13], 0, v[38:39]
	v_lshl_add_u64 v[2:3], v[2:3], 0, v[160:161]
	v_mov_b32_e32 v2, v252
	v_mov_b32_e32 v3, v253
	s_waitcnt vmcnt(0)
	v_pk_mul_f32 v[4:5], v[0:1], v[2:3] op_sel_hi:[0,1]
	v_pk_mul_f32 v[6:7], v[0:1], v[2:3] op_sel:[1,1] op_sel_hi:[1,0]
	v_pk_fma_f32 v[0:1], v[0:1], v[2:3], v[4:5] op_sel:[1,1,0] op_sel_hi:[1,0,1] neg_lo:[0,0,1] neg_hi:[0,0,1]
	s_nop 0
	v_add_f32_e32 v0, v6, v4

.LBB0_1013:
	v_mov_b32_e32 v2, v243
	v_cvt_pk_bf16_f32 v1, v1, s0
	v_cvt_pk_bf16_f32 v0, v0, s0
	ds_write_b16 v217, v1 offset:2304
	ds_write_b16 v217, v0 offset:2368
	v_mov_b32_e32 v8, v25
	s_waitcnt vmcnt(0)
	v_fmamk_f32 v2, v2, 0x3b800000, v216
	v_mul_f32_e32 v3, 0x4b800000, v2
	v_cmp_gt_f32_e32 vcc, s38, v2
	s_nop 1
	v_cndmask_b32_e32 v2, v2, v3, vcc
	v_rsq_f32_e32 v2, v2
	s_nop 0
	v_mul_f32_e32 v0, 0x45800000, v2
	v_cndmask_b32_e32 v0, v2, v0, vcc
	v_mul_f32_e32 v0, 0x3dd53b94, v0
	s_and_b64 vcc, exec, s[4:5]
	v_pk_mul_f32 v[0:1], v[8:9], v[0:1] op_sel_hi:[1,0]
	s_cbranch_vccnz .LBB0_1015
	s_waitcnt lgkmcnt(0)
	v_lshl_add_u64 v[2:3], s[12:13], 0, v[40:41]
	v_lshl_add_u64 v[2:3], v[2:3], 0, v[160:161]
	v_mov_b32_e32 v2, v248
	v_mov_b32_e32 v3, v249
	s_waitcnt vmcnt(0)
	v_pk_mul_f32 v[4:5], v[0:1], v[2:3] op_sel_hi:[0,1]
	v_pk_mul_f32 v[6:7], v[0:1], v[2:3] op_sel:[1,1] op_sel_hi:[1,0]
	v_pk_fma_f32 v[0:1], v[0:1], v[2:3], v[4:5] op_sel:[1,1,0] op_sel_hi:[1,0,1] neg_lo:[0,0,1] neg_hi:[0,0,1]
	s_nop 0
	v_add_f32_e32 v0, v6, v4
.LBB0_1015:
	v_mov_b32_e32 v2, v244
	v_cvt_pk_bf16_f32 v3, v1, s0
	v_cvt_pk_bf16_f32 v4, v0, s0
	ds_write_b16 v217, v3 offset:2448
	ds_write_b16 v217, v4 offset:2512
	v_mov_b32_e32 v0, v26
	s_waitcnt vmcnt(0)
	v_fmamk_f32 v1, v2, 0x3b800000, v216
	v_mul_f32_e32 v2, 0x4b800000, v1
	v_cmp_gt_f32_e32 vcc, s38, v1
	s_nop 1
	v_cndmask_b32_e32 v1, v1, v2, vcc
	v_rsq_f32_e32 v2, v1
	v_mov_b32_e32 v1, v10
	v_mul_f32_e32 v3, 0x45800000, v2
	v_cndmask_b32_e32 v2, v2, v3, vcc
	v_mul_f32_e32 v2, 0x3dd53b94, v2
	s_and_b64 vcc, exec, s[4:5]
	v_pk_mul_f32 v[0:1], v[0:1], v[2:3] op_sel_hi:[1,0]
	s_cbranch_vccnz .LBB0_1017
	s_waitcnt lgkmcnt(0)
	v_lshl_add_u64 v[2:3], s[12:13], 0, v[56:57]
	v_lshl_add_u64 v[2:3], v[2:3], 0, v[160:161]
	v_mov_b32_e32 v2, v250
	v_mov_b32_e32 v3, v251
	s_waitcnt vmcnt(0)
	v_pk_mul_f32 v[4:5], v[0:1], v[2:3] op_sel_hi:[0,1]
	v_pk_mul_f32 v[6:7], v[0:1], v[2:3] op_sel:[1,1] op_sel_hi:[1,0]
	v_pk_fma_f32 v[0:1], v[0:1], v[2:3], v[4:5] op_sel:[1,1,0] op_sel_hi:[1,0,1] neg_lo:[0,0,1] neg_hi:[0,0,1]
	s_nop 0
	v_add_f32_e32 v0, v6, v4
.LBB0_1017:
	v_mov_b32_e32 v2, v245
	v_cvt_pk_bf16_f32 v1, v1, s0
	v_cvt_pk_bf16_f32 v0, v0, s0
	ds_write_b16 v217, v1 offset:2592
	ds_write_b16 v217, v0 offset:2656
	v_mov_b32_e32 v10, v27
	s_waitcnt vmcnt(0)
	v_fmamk_f32 v2, v2, 0x3b800000, v216
	v_mul_f32_e32 v3, 0x4b800000, v2
	v_cmp_gt_f32_e32 vcc, s38, v2
	s_nop 1
	v_cndmask_b32_e32 v2, v2, v3, vcc
	v_rsq_f32_e32 v2, v2
	s_nop 0
	v_mul_f32_e32 v0, 0x45800000, v2
	v_cndmask_b32_e32 v0, v2, v0, vcc
	v_mul_f32_e32 v0, 0x3dd53b94, v0
	s_and_b64 vcc, exec, s[4:5]
	v_pk_mul_f32 v[0:1], v[10:11], v[0:1] op_sel_hi:[1,0]
	s_cbranch_vccnz .LBB0_1019
	s_waitcnt lgkmcnt(0)
	v_lshl_add_u64 v[2:3], s[12:13], 0, v[42:43]
	v_lshl_add_u64 v[2:3], v[2:3], 0, v[160:161]
	v_mov_b32_e32 v2, v252
	v_mov_b32_e32 v3, v253
	s_waitcnt vmcnt(0)
	v_pk_mul_f32 v[4:5], v[0:1], v[2:3] op_sel_hi:[0,1]
	v_pk_mul_f32 v[6:7], v[0:1], v[2:3] op_sel:[1,1] op_sel_hi:[1,0]
	v_pk_fma_f32 v[0:1], v[0:1], v[2:3], v[4:5] op_sel:[1,1,0] op_sel_hi:[1,0,1] neg_lo:[0,0,1] neg_hi:[0,0,1]
	s_nop 0
	v_add_f32_e32 v0, v6, v4

.LBB0_1021:
	v_mov_b32_e32 v2, v243
	v_cvt_pk_bf16_f32 v1, v1, s0
	v_cvt_pk_bf16_f32 v0, v0, s0
	ds_write_b16 v217, v1 offset:3456
	ds_write_b16 v217, v0 offset:3520
	v_mov_b32_e32 v12, v29
	s_waitcnt vmcnt(0)
	v_fmamk_f32 v2, v2, 0x3b800000, v216
	v_mul_f32_e32 v3, 0x4b800000, v2
	v_cmp_gt_f32_e32 vcc, s38, v2
	s_nop 1
	v_cndmask_b32_e32 v2, v2, v3, vcc
	v_rsq_f32_e32 v2, v2
	s_nop 0
	v_mul_f32_e32 v0, 0x45800000, v2
	v_cndmask_b32_e32 v0, v2, v0, vcc
	v_mul_f32_e32 v0, 0x3dd53b94, v0
	s_and_b64 vcc, exec, s[4:5]
	v_pk_mul_f32 v[0:1], v[12:13], v[0:1] op_sel_hi:[1,0]
	s_cbranch_vccnz .LBB0_1023
	s_waitcnt lgkmcnt(0)
	v_lshl_add_u64 v[2:3], s[12:13], 0, v[44:45]
	v_lshl_add_u64 v[2:3], v[2:3], 0, v[160:161]
	v_mov_b32_e32 v2, v248
	v_mov_b32_e32 v3, v249
	s_waitcnt vmcnt(0)
	v_pk_mul_f32 v[4:5], v[0:1], v[2:3] op_sel_hi:[0,1]
	v_pk_mul_f32 v[6:7], v[0:1], v[2:3] op_sel:[1,1] op_sel_hi:[1,0]
	v_pk_fma_f32 v[0:1], v[0:1], v[2:3], v[4:5] op_sel:[1,1,0] op_sel_hi:[1,0,1] neg_lo:[0,0,1] neg_hi:[0,0,1]
	s_nop 0
	v_add_f32_e32 v0, v6, v4
.LBB0_1023:
	v_mov_b32_e32 v2, v244
	v_cvt_pk_bf16_f32 v3, v1, s0
	v_cvt_pk_bf16_f32 v4, v0, s0
	ds_write_b16 v217, v3 offset:3600
	ds_write_b16 v217, v4 offset:3664
	v_mov_b32_e32 v0, v30
	s_waitcnt vmcnt(0)
	v_fmamk_f32 v1, v2, 0x3b800000, v216
	v_mul_f32_e32 v2, 0x4b800000, v1
	v_cmp_gt_f32_e32 vcc, s38, v1
	s_nop 1
	v_cndmask_b32_e32 v1, v1, v2, vcc
	v_rsq_f32_e32 v2, v1
	v_mov_b32_e32 v1, v14
	v_mul_f32_e32 v3, 0x45800000, v2
	v_cndmask_b32_e32 v2, v2, v3, vcc
	v_mul_f32_e32 v2, 0x3dd53b94, v2
	s_and_b64 vcc, exec, s[4:5]
	v_pk_mul_f32 v[0:1], v[0:1], v[2:3] op_sel_hi:[1,0]
	s_cbranch_vccnz .LBB0_1025
	s_waitcnt lgkmcnt(0)
	v_lshl_add_u64 v[2:3], s[12:13], 0, v[60:61]
	v_lshl_add_u64 v[2:3], v[2:3], 0, v[160:161]
	v_mov_b32_e32 v2, v250
	v_mov_b32_e32 v3, v251
	s_waitcnt vmcnt(0)
	v_pk_mul_f32 v[4:5], v[0:1], v[2:3] op_sel_hi:[0,1]
	v_pk_mul_f32 v[6:7], v[0:1], v[2:3] op_sel:[1,1] op_sel_hi:[1,0]
	v_pk_fma_f32 v[0:1], v[0:1], v[2:3], v[4:5] op_sel:[1,1,0] op_sel_hi:[1,0,1] neg_lo:[0,0,1] neg_hi:[0,0,1]
	s_nop 0
	v_add_f32_e32 v0, v6, v4
.LBB0_1025:
	v_mov_b32_e32 v2, v245
	v_cvt_pk_bf16_f32 v1, v1, s0
	v_cvt_pk_bf16_f32 v0, v0, s0
	ds_write_b16 v217, v1 offset:3744
	ds_write_b16 v217, v0 offset:3808
	v_mov_b32_e32 v14, v31
	s_waitcnt vmcnt(0)
	v_fmamk_f32 v2, v2, 0x3b800000, v216
	v_mul_f32_e32 v3, 0x4b800000, v2
	v_cmp_gt_f32_e32 vcc, s38, v2
	s_nop 1
	v_cndmask_b32_e32 v2, v2, v3, vcc
	v_rsq_f32_e32 v2, v2
	s_nop 0
	v_mul_f32_e32 v0, 0x45800000, v2
	v_cndmask_b32_e32 v0, v2, v0, vcc
	v_mul_f32_e32 v0, 0x3dd53b94, v0
	s_and_b64 vcc, exec, s[4:5]
	v_pk_mul_f32 v[0:1], v[14:15], v[0:1] op_sel_hi:[1,0]
	s_cbranch_vccnz .LBB0_1027
	s_waitcnt lgkmcnt(0)
	v_lshl_add_u64 v[2:3], s[4:5], 0, v[46:47]
	v_lshl_add_u64 v[2:3], v[2:3], 0, v[160:161]
	v_mov_b32_e32 v2, v252
	v_mov_b32_e32 v3, v253
	s_waitcnt vmcnt(0)
	v_pk_mul_f32 v[4:5], v[0:1], v[2:3] op_sel_hi:[0,1]
	v_pk_mul_f32 v[6:7], v[0:1], v[2:3] op_sel:[1,1] op_sel_hi:[1,0]
	v_pk_fma_f32 v[0:1], v[0:1], v[2:3], v[4:5] op_sel:[1,1,0] op_sel_hi:[1,0,1] neg_lo:[0,0,1] neg_hi:[0,0,1]
	s_nop 0
	v_add_f32_e32 v0, v6, v4

.LBB0_1270:
	v_mbcnt_hi_u32_b32 v211, -1, v210
	s_load_dwordx2 s[2:3], s[0:1], 0xf0
	s_load_dwordx2 s[4:5], s[0:1], 0x158
	s_ashr_i32 s7, s6, 31
	v_mov_b32_e32 v1, v211
	s_and_b32 s7, s7, s42
	s_add_i32 s54, s7, s6
	v_add_u32_e32 v0, s70, v1
	v_ashrrev_i32_e32 v212, 3, v0
	v_readfirstlane_b32 s8, v0
	v_lshlrev_b32_e32 v0, 3, v1
	v_and_b32_e32 v0, 56, v0
	s_cmpk_lt_i32 s54, 0x200
	s_cselect_b64 s[6:7], -1, 0
	s_cmpk_gt_i32 s54, 0x1ff
	v_lshlrev_b32_e32 v168, 1, v0
	v_add_u32_e32 v213, 64, v212
	s_cbranch_scc1 .LBB0_1272
	s_ashr_i32 s9, s54, 31
	s_lshr_b32 s9, s9, 30
	s_add_i32 s9, s54, s9
	s_ashr_i32 s9, s9, 2
	s_lshl_b32 s10, s9, 8
	v_add_u32_e32 v2, s10, v212
	v_min_i32_e32 v2, 0x7fff, v2
	v_ashrrev_i32_e32 v3, 31, v2
	v_lshlrev_b64 v[2:3], 11, v[2:3]
	s_lshl_b32 s9, s9, 10
	s_lshl_b32 s11, s54, 8
	s_waitcnt lgkmcnt(0)
	v_lshl_add_u64 v[2:3], s[4:5], 0, v[2:3]
	v_mov_b32_e32 v169, 0
	s_sub_i32 s9, s11, s9
	v_lshl_add_u64 v[2:3], v[2:3], 0, v[168:169]
	v_mbcnt_hi_u32_b32 v158, -1, v210
	s_and_b32 s90, s70, 0x40
	v_and_b32_e32 v159, 48, v158
	v_or_b32_e32 v159, s90, v159
	s_lshl_b32 s88, s70, 4
	s_lshl_b32 s92, s22, 4
	s_and_b32 s92, s92, 0x780
	s_mov_b32 s93, 0
	s_add_u32 m0, s88, 0
	v_lshl_add_u64 v[2:3], v[2:3], 0, s[92:93]
	v_xor_b32_e32 v2, v159, v2
	global_load_lds_dwordx4 v[2:3], off
	v_add_u32_e32 v2, s9, v212
	v_ashrrev_i32_e32 v3, 31, v2
	v_lshlrev_b64 v[2:3], 11, v[2:3]
	v_lshl_add_u64 v[2:3], s[2:3], 0, v[2:3]
	v_lshl_add_u64 v[2:3], v[2:3], 0, v[168:169]
	s_add_u32 m0, s88, 32768
	v_lshl_add_u64 v[2:3], v[2:3], 0, s[92:93]
	v_xor_b32_e32 v2, v159, v2
	global_load_lds_dwordx4 v[2:3], off
	v_add_u32_e32 v2, s10, v213
	v_min_i32_e32 v2, 0x7fff, v2
	v_ashrrev_i32_e32 v3, 31, v2
	v_lshlrev_b64 v[2:3], 11, v[2:3]
	v_lshl_add_u64 v[2:3], s[4:5], 0, v[2:3]
	v_lshl_add_u64 v[2:3], v[2:3], 0, v[168:169]
	s_add_u32 m0, s88, 8192
	v_lshl_add_u64 v[2:3], v[2:3], 0, s[92:93]
	v_xor_b32_e32 v2, v159, v2
	global_load_lds_dwordx4 v[2:3], off
	v_add_u32_e32 v2, s9, v213
	v_ashrrev_i32_e32 v3, 31, v2
	v_lshlrev_b64 v[2:3], 11, v[2:3]
	v_lshl_add_u64 v[2:3], s[2:3], 0, v[2:3]
	v_lshl_add_u64 v[2:3], v[2:3], 0, v[168:169]
	v_add_u32_e32 v4, 0x80, v212
	s_add_u32 m0, s88, 40960
	v_lshl_add_u64 v[2:3], v[2:3], 0, s[92:93]
	v_xor_b32_e32 v2, v159, v2
	global_load_lds_dwordx4 v[2:3], off
	v_add_u32_e32 v2, s10, v4
	v_min_i32_e32 v2, 0x7fff, v2
	v_ashrrev_i32_e32 v3, 31, v2
	v_lshlrev_b64 v[2:3], 11, v[2:3]
	v_lshl_add_u64 v[2:3], s[4:5], 0, v[2:3]
	v_lshl_add_u64 v[2:3], v[2:3], 0, v[168:169]
	s_add_u32 m0, s88, 16384
	v_lshl_add_u64 v[2:3], v[2:3], 0, s[92:93]
	v_xor_b32_e32 v2, v159, v2
	global_load_lds_dwordx4 v[2:3], off
	v_add_u32_e32 v2, s9, v4
	v_ashrrev_i32_e32 v3, 31, v2
	v_lshlrev_b64 v[2:3], 11, v[2:3]
	v_lshl_add_u64 v[2:3], s[2:3], 0, v[2:3]
	v_lshl_add_u64 v[2:3], v[2:3], 0, v[168:169]
	v_add_u32_e32 v4, 0xc0, v212
	s_add_u32 m0, s88, 49152
	v_lshl_add_u64 v[2:3], v[2:3], 0, s[92:93]
	v_xor_b32_e32 v2, v159, v2
	global_load_lds_dwordx4 v[2:3], off
	v_add_u32_e32 v2, s10, v4
	v_min_i32_e32 v2, 0x7fff, v2
	v_ashrrev_i32_e32 v3, 31, v2
	v_lshlrev_b64 v[2:3], 11, v[2:3]
	v_lshl_add_u64 v[2:3], s[4:5], 0, v[2:3]
	v_lshl_add_u64 v[2:3], v[2:3], 0, v[168:169]
	s_add_u32 m0, s88, 24576
	v_lshl_add_u64 v[2:3], v[2:3], 0, s[92:93]
	v_xor_b32_e32 v2, v159, v2
	global_load_lds_dwordx4 v[2:3], off
	v_add_u32_e32 v2, s9, v4
	v_ashrrev_i32_e32 v3, 31, v2
	v_lshlrev_b64 v[2:3], 11, v[2:3]
	v_lshl_add_u64 v[2:3], s[2:3], 0, v[2:3]
	v_lshl_add_u64 v[2:3], v[2:3], 0, v[168:169]
	s_add_u32 m0, s88, 57344
	v_lshl_add_u64 v[2:3], v[2:3], 0, s[92:93]
	v_xor_b32_e32 v2, v159, v2
	global_load_lds_dwordx4 v[2:3], off
	s_waitcnt vmcnt(0)

.LBB0_1275:
	s_ashr_i32 s2, s54, 31
	s_lshr_b32 s2, s2, 30
	s_add_i32 s2, s54, s2
	s_ashr_i32 s2, s2, 2
	s_lshl_b32 s4, s2, 8
	v_add_u32_e32 v0, s4, v212
	v_min_i32_e32 v0, 0x7fff, v0
	v_ashrrev_i32_e32 v1, 31, v0
	s_lshl_b32 s6, s2, 10
	v_lshlrev_b64 v[0:1], 11, v[0:1]
	v_lshl_add_u64 v[160:161], v[176:177], 0, v[0:1]
	v_subrev_u32_e32 v0, s6, v220
	v_ashrrev_i32_e32 v1, 31, v0
	v_lshlrev_b64 v[0:1], 11, v[0:1]
	v_lshl_add_u64 v[180:181], v[178:179], 0, v[0:1]
	v_subrev_u32_e32 v0, s6, v221
	v_ashrrev_i32_e32 v1, 31, v0
	v_lshlrev_b64 v[0:1], 11, v[0:1]
	v_lshl_add_u64 v[182:183], v[178:179], 0, v[0:1]
	v_subrev_u32_e32 v0, s6, v222
	v_ashrrev_i32_e32 v1, 31, v0
	v_add_u32_e32 v2, s4, v213
	v_add_u32_e32 v4, s4, v171
	v_add_u32_e32 v6, s4, v215
	v_lshlrev_b64 v[0:1], 11, v[0:1]
	v_min_i32_e32 v2, 0x7fff, v2
	v_min_i32_e32 v4, 0x7fff, v4
	v_min_i32_e32 v6, 0x7fff, v6
	v_lshl_add_u64 v[184:185], v[178:179], 0, v[0:1]
	v_subrev_u32_e32 v0, s6, v223
	v_ashrrev_i32_e32 v3, 31, v2
	v_ashrrev_i32_e32 v5, 31, v4
	v_ashrrev_i32_e32 v7, 31, v6
	v_ashrrev_i32_e32 v1, 31, v0
	v_lshlrev_b64 v[2:3], 11, v[2:3]
	v_lshlrev_b64 v[4:5], 11, v[4:5]
	v_lshlrev_b64 v[6:7], 11, v[6:7]
	v_lshlrev_b64 v[0:1], 11, v[0:1]
	s_mov_b32 s5, s54
	v_lshl_add_u64 v[162:163], v[176:177], 0, v[2:3]
	v_lshl_add_u64 v[164:165], v[176:177], 0, v[4:5]
	v_lshl_add_u64 v[166:167], v[176:177], 0, v[6:7]
	v_lshl_add_u64 v[186:187], v[178:179], 0, v[0:1]
	s_mov_b64 s[2:3], 0
	s_mov_b32 s7, 0
	v_mov_b32_e32 v0, 0
	v_mov_b32_e32 v1, v169
	v_mov_b32_e32 v2, v169
	v_mov_b32_e32 v3, v169
	v_mov_b32_e32 v4, v169
	v_mov_b32_e32 v5, v169
	v_mov_b32_e32 v6, v169
	v_mov_b32_e32 v7, v169
	v_mov_b32_e32 v8, v169
	v_mov_b32_e32 v9, v169
	v_mov_b32_e32 v10, v169
	v_mov_b32_e32 v11, v169
	v_mov_b32_e32 v12, v169
	v_mov_b32_e32 v13, v169
	v_mov_b32_e32 v14, v169
	v_mov_b32_e32 v15, v169
	v_mov_b32_e32 v16, 0
	v_mov_b32_e32 v17, v169
	v_mov_b32_e32 v18, v169
	v_mov_b32_e32 v19, v169
	v_mov_b32_e32 v20, v169
	v_mov_b32_e32 v21, v169
	v_mov_b32_e32 v22, v169
	v_mov_b32_e32 v23, v169
	v_mov_b32_e32 v24, v169
	v_mov_b32_e32 v25, v169
	v_mov_b32_e32 v26, v169
	v_mov_b32_e32 v27, v169
	v_mov_b32_e32 v28, v169
	v_mov_b32_e32 v29, v169
	v_mov_b32_e32 v30, v169
	v_mov_b32_e32 v31, v169
	v_mov_b32_e32 v32, 0
	v_mov_b32_e32 v33, v169
	v_mov_b32_e32 v34, v169
	v_mov_b32_e32 v35, v169
	v_mov_b32_e32 v36, v169
	v_mov_b32_e32 v37, v169
	v_mov_b32_e32 v38, v169
	v_mov_b32_e32 v39, v169
	v_mov_b32_e32 v40, v169
	v_mov_b32_e32 v41, v169
	v_mov_b32_e32 v42, v169
	v_mov_b32_e32 v43, v169
	v_mov_b32_e32 v44, v169
	v_mov_b32_e32 v45, v169
	v_mov_b32_e32 v46, v169
	v_mov_b32_e32 v47, v169
	v_mov_b32_e32 v48, 0
	v_mov_b32_e32 v49, v169
	v_mov_b32_e32 v50, v169
	v_mov_b32_e32 v51, v169
	v_mov_b32_e32 v52, v169
	v_mov_b32_e32 v53, v169
	v_mov_b32_e32 v54, v169
	v_mov_b32_e32 v55, v169
	v_mov_b32_e32 v56, v169
	v_mov_b32_e32 v57, v169
	v_mov_b32_e32 v58, v169
	v_mov_b32_e32 v59, v169
	v_mov_b32_e32 v60, v169
	v_mov_b32_e32 v61, v169
	v_mov_b32_e32 v62, v169
	v_mov_b32_e32 v63, v169
	v_mov_b32_e32 v64, 0
	v_mov_b32_e32 v65, v169
	v_mov_b32_e32 v66, v169
	v_mov_b32_e32 v67, v169
	v_mov_b32_e32 v68, v169
	v_mov_b32_e32 v69, v169
	v_mov_b32_e32 v70, v169
	v_mov_b32_e32 v71, v169
	v_mov_b32_e32 v72, v169
	v_mov_b32_e32 v73, v169
	v_mov_b32_e32 v74, v169
	v_mov_b32_e32 v75, v169
	v_mov_b32_e32 v76, v169
	v_mov_b32_e32 v77, v169
	v_mov_b32_e32 v78, v169
	v_mov_b32_e32 v79, v169
	v_mov_b32_e32 v80, 0
	v_mov_b32_e32 v81, v169
	v_mov_b32_e32 v82, v169
	v_mov_b32_e32 v83, v169
	v_mov_b32_e32 v84, v169
	v_mov_b32_e32 v85, v169
	v_mov_b32_e32 v86, v169
	v_mov_b32_e32 v87, v169
	v_mov_b32_e32 v88, v169
	v_mov_b32_e32 v89, v169
	v_mov_b32_e32 v90, v169
	v_mov_b32_e32 v91, v169
	v_mov_b32_e32 v92, v169
	v_mov_b32_e32 v93, v169
	v_mov_b32_e32 v94, v169
	v_mov_b32_e32 v95, v169
	v_mov_b32_e32 v96, 0
	v_mov_b32_e32 v97, v169
	v_mov_b32_e32 v98, v169
	v_mov_b32_e32 v99, v169
	v_mov_b32_e32 v100, v169
	v_mov_b32_e32 v101, v169
	v_mov_b32_e32 v102, v169
	v_mov_b32_e32 v103, v169
	v_mov_b32_e32 v104, v169
	v_mov_b32_e32 v105, v169
	v_mov_b32_e32 v106, v169
	v_mov_b32_e32 v107, v169
	v_mov_b32_e32 v108, v169
	v_mov_b32_e32 v109, v169
	v_mov_b32_e32 v110, v169
	v_mov_b32_e32 v111, v169
	v_mov_b32_e32 v112, 0
	v_mov_b32_e32 v113, v169
	v_mov_b32_e32 v114, v169
	v_mov_b32_e32 v115, v169
	v_mov_b32_e32 v116, v169
	v_mov_b32_e32 v117, v169
	v_mov_b32_e32 v118, v169
	v_mov_b32_e32 v119, v169
	v_mov_b32_e32 v120, v169
	v_mov_b32_e32 v121, v169
	v_mov_b32_e32 v122, v169
	v_mov_b32_e32 v123, v169
	v_mov_b32_e32 v124, v169
	v_mov_b32_e32 v125, v169
	v_mov_b32_e32 v126, v169
	v_mov_b32_e32 v127, v169
	v_mbcnt_hi_u32_b32 v128, -1, v210
	s_and_b32 s90, s70, 0x40
	v_and_b32_e32 v159, 48, v128
	v_or_b32_e32 v159, s90, v159
	v_and_b32_e32 v129, 31, v128
	v_lshrrev_b32_e32 v130, 5, v128
	v_bfe_u32 v131, v128, 1, 3
	v_lshlrev_b32_e32 v132, 7, v129
	s_lshr_b32 s91, s70, 7
	s_lshl_b32 s91, s91, 13
	s_lshl_b32 s90, s90, 8
	s_add_u32 s90, s90, 0x8000
	s_lshl_b32 s88, s70, 4
	s_mov_b32 s89, 0x10000
	s_lshl_b32 s92, s22, 4
	s_and_b32 s92, s92, 0x780
	s_mov_b32 s93, 0
	v_xor_b32_e32 v133, v130, v131
	v_lshl_add_u32 v133, v133, 4, v132
	v_add_u32_e32 v230, s91, v133
	v_add_u32_e32 v234, s90, v133
	v_or_b32_e32 v133, 2, v130
	v_xor_b32_e32 v133, v133, v131
	v_lshl_add_u32 v133, v133, 4, v132
	v_add_u32_e32 v231, s91, v133
	v_add_u32_e32 v235, s90, v133
	v_or_b32_e32 v133, 4, v130
	v_xor_b32_e32 v133, v133, v131
	v_lshl_add_u32 v133, v133, 4, v132
	v_add_u32_e32 v232, s91, v133
	v_add_u32_e32 v236, s90, v133
	v_or_b32_e32 v133, 6, v130
	v_xor_b32_e32 v133, v133, v131
	v_lshl_add_u32 v133, v133, 4, v132
	v_add_u32_e32 v233, s91, v133
	v_add_u32_e32 v237, s90, v133
	s_barrier
	ds_read_b128 v[188:191], v230
	ds_read_b128 v[196:199], v234
	ds_read_b128 v[192:195], v230 offset:4096
	ds_read_b128 v[200:203], v234 offset:4096
	ds_read_b128 v[204:207], v234 offset:8192
	ds_read_b128 v[226:229], v234 offset:12288
	s_add_u32 s94, s2, s92
	s_add_u32 s94, s94, 0x80
	s_and_b32 s94, s94, 0x780
	s_sub_u32 s94, s94, 0x80
	s_subb_u32 s95, 0, 0
	s_add_u32 s90, s88, s89
	s_add_u32 m0, s90, 0
	v_lshl_add_u64 v[152:153], v[160:161], 0, s[94:95]
	v_xor_b32_e32 v152, v159, v152
	global_load_lds_dwordx4 v[152:153], off
	s_add_u32 m0, s90, 32768
	v_lshl_add_u64 v[154:155], v[180:181], 0, s[94:95]
	v_xor_b32_e32 v154, v159, v154
	global_load_lds_dwordx4 v[154:155], off
	s_add_u32 m0, s90, 8192
	v_lshl_add_u64 v[156:157], v[162:163], 0, s[94:95]
	v_xor_b32_e32 v156, v159, v156
	global_load_lds_dwordx4 v[156:157], off
	s_add_u32 m0, s90, 40960
	v_lshl_add_u64 v[152:153], v[182:183], 0, s[94:95]
	v_xor_b32_e32 v152, v159, v152
	global_load_lds_dwordx4 v[152:153], off
	s_add_u32 m0, s90, 16384
	v_lshl_add_u64 v[154:155], v[164:165], 0, s[94:95]
	v_xor_b32_e32 v154, v159, v154
	global_load_lds_dwordx4 v[154:155], off
	s_add_u32 m0, s90, 49152
	v_lshl_add_u64 v[156:157], v[184:185], 0, s[94:95]
	v_xor_b32_e32 v156, v159, v156
	global_load_lds_dwordx4 v[156:157], off
	s_add_u32 m0, s90, 24576
	v_lshl_add_u64 v[152:153], v[166:167], 0, s[94:95]
	v_xor_b32_e32 v152, v159, v152
	global_load_lds_dwordx4 v[152:153], off
	s_add_u32 m0, s90, 57344
	v_lshl_add_u64 v[154:155], v[186:187], 0, s[94:95]
	v_xor_b32_e32 v154, v159, v154
	global_load_lds_dwordx4 v[154:155], off
	s_xor_b32 s89, s89, 0x10000

.LBB0_1279:
	ds_read_b128 v[128:131], v231
	ds_read_b128 v[136:139], v235
	ds_read_b128 v[132:135], v231 offset:4096
	ds_read_b128 v[140:143], v235 offset:4096
	ds_read_b128 v[144:147], v235 offset:8192
	ds_read_b128 v[148:151], v235 offset:12288
	s_waitcnt lgkmcnt(6)
	v_mfma_f32_32x32x16_bf16 v[112:127], v[188:191], v[196:199], v[112:127]
	v_mfma_f32_32x32x16_bf16 v[48:63], v[192:195], v[196:199], v[48:63]
	v_mfma_f32_32x32x16_bf16 v[96:111], v[188:191], v[200:203], v[96:111]
	v_mfma_f32_32x32x16_bf16 v[32:47], v[192:195], v[200:203], v[32:47]
	v_mfma_f32_32x32x16_bf16 v[80:95], v[188:191], v[204:207], v[80:95]
	v_mfma_f32_32x32x16_bf16 v[16:31], v[192:195], v[204:207], v[16:31]
	v_mfma_f32_32x32x16_bf16 v[64:79], v[188:191], v[226:229], v[64:79]
	v_mfma_f32_32x32x16_bf16 v[0:15], v[192:195], v[226:229], v[0:15]
	ds_read_b128 v[188:191], v232
	ds_read_b128 v[196:199], v236
	ds_read_b128 v[192:195], v232 offset:4096
	ds_read_b128 v[200:203], v236 offset:4096
	ds_read_b128 v[204:207], v236 offset:8192
	ds_read_b128 v[226:229], v236 offset:12288
	s_waitcnt lgkmcnt(6)
	v_mfma_f32_32x32x16_bf16 v[112:127], v[128:131], v[136:139], v[112:127]
	v_mfma_f32_32x32x16_bf16 v[48:63], v[132:135], v[136:139], v[48:63]
	v_mfma_f32_32x32x16_bf16 v[96:111], v[128:131], v[140:143], v[96:111]
	v_mfma_f32_32x32x16_bf16 v[32:47], v[132:135], v[140:143], v[32:47]
	v_mfma_f32_32x32x16_bf16 v[80:95], v[128:131], v[144:147], v[80:95]
	v_mfma_f32_32x32x16_bf16 v[16:31], v[132:135], v[144:147], v[16:31]
	v_mfma_f32_32x32x16_bf16 v[64:79], v[128:131], v[148:151], v[64:79]
	v_mfma_f32_32x32x16_bf16 v[0:15], v[132:135], v[148:151], v[0:15]
	ds_read_b128 v[128:131], v233
	ds_read_b128 v[136:139], v237
	ds_read_b128 v[132:135], v233 offset:4096
	ds_read_b128 v[140:143], v237 offset:4096
	ds_read_b128 v[144:147], v237 offset:8192
	ds_read_b128 v[148:151], v237 offset:12288
	s_waitcnt lgkmcnt(6)
	v_mfma_f32_32x32x16_bf16 v[112:127], v[188:191], v[196:199], v[112:127]
	v_mfma_f32_32x32x16_bf16 v[48:63], v[192:195], v[196:199], v[48:63]
	v_mfma_f32_32x32x16_bf16 v[96:111], v[188:191], v[200:203], v[96:111]
	v_mfma_f32_32x32x16_bf16 v[32:47], v[192:195], v[200:203], v[32:47]
	v_mfma_f32_32x32x16_bf16 v[80:95], v[188:191], v[204:207], v[80:95]
	v_mfma_f32_32x32x16_bf16 v[16:31], v[192:195], v[204:207], v[16:31]
	v_mfma_f32_32x32x16_bf16 v[64:79], v[188:191], v[226:229], v[64:79]
	v_mfma_f32_32x32x16_bf16 v[0:15], v[192:195], v[226:229], v[0:15]
	s_waitcnt vmcnt(0) lgkmcnt(0)
	s_barrier
	v_xor_b32_e32 v230, 0x10000, v230
	v_xor_b32_e32 v234, 0x10000, v234
	v_mfma_f32_32x32x16_bf16 v[112:127], v[128:131], v[136:139], v[112:127]
	v_xor_b32_e32 v231, 0x10000, v231
	v_xor_b32_e32 v235, 0x10000, v235
	v_mfma_f32_32x32x16_bf16 v[48:63], v[132:135], v[136:139], v[48:63]
	v_xor_b32_e32 v232, 0x10000, v232
	v_xor_b32_e32 v236, 0x10000, v236
	v_mfma_f32_32x32x16_bf16 v[96:111], v[128:131], v[140:143], v[96:111]
	v_xor_b32_e32 v233, 0x10000, v233
	v_xor_b32_e32 v237, 0x10000, v237
	v_mfma_f32_32x32x16_bf16 v[32:47], v[132:135], v[140:143], v[32:47]
	v_mfma_f32_32x32x16_bf16 v[80:95], v[128:131], v[144:147], v[80:95]
	v_mfma_f32_32x32x16_bf16 v[16:31], v[132:135], v[144:147], v[16:31]
	v_mfma_f32_32x32x16_bf16 v[64:79], v[128:131], v[148:151], v[64:79]
	v_mfma_f32_32x32x16_bf16 v[0:15], v[132:135], v[148:151], v[0:15]
	s_lshl_b32 s2, s5, 8
	s_sub_i32 s2, s2, s6
	v_mov_b32_e32 v168, v214
	s_add_i32 s55, s4, s30
	s_or_b32 s26, s2, s31
	s_ashr_i32 s27, s26, 31
	s_load_dwordx2 s[24:25], s[0:1], 0x140
	v_ashrrev_i32_e32 v180, 3, v168
	v_and_b32_e32 v183, -4, v180
	v_add_u32_e32 v225, s55, v183
	v_add_u32_e32 v190, 8, v225
	v_min_i32_e32 v190, 0x7fff, v190
	v_ashrrev_i32_e32 v190, 12, v190
	v_min_i32_e32 v184, 0x7fff, v225
	v_and_b32_e32 v182, 31, v168
	v_ashrrev_i32_e32 v184, 12, v184
	v_or_b32_e32 v180, s26, v182
	v_mul_hi_i32_i24_e32 v185, 0x3000, v184
	v_mul_i32_i24_e32 v184, 0x3000, v184
	v_ashrrev_i32_e32 v181, 31, v180
	s_waitcnt lgkmcnt(0)
	v_lshl_add_u64 v[184:185], s[24:25], 0, v[184:185]
	v_add_u32_e32 v188, 9, v225
	v_mul_hi_i32_i24_e32 v187, 0x3000, v190
	v_mul_i32_i24_e32 v186, 0x3000, v190
	v_min_i32_e32 v188, 0x7fff, v188
	v_add_u32_e32 v190, 10, v225
	v_ashrrev_i32_e32 v188, 12, v188
	v_min_i32_e32 v190, 0x7fff, v190
	v_mul_hi_i32_i24_e32 v189, 0x3000, v188
	v_mul_i32_i24_e32 v188, 0x3000, v188
	v_ashrrev_i32_e32 v190, 12, v190
	v_lshl_add_u64 v[188:189], s[24:25], 0, v[188:189]
	v_mul_hi_i32_i24_e32 v191, 0x3000, v190
	v_mul_i32_i24_e32 v190, 0x3000, v190
	v_lshl_add_u64 v[184:185], v[184:185], 0, s[18:19]
	v_lshlrev_b64 v[180:181], 2, v[180:181]
	v_lshl_add_u64 v[186:187], s[24:25], 0, v[186:187]
	v_lshl_add_u64 v[188:189], v[188:189], 0, s[18:19]
	v_lshl_add_u64 v[190:191], s[24:25], 0, v[190:191]
	v_lshl_add_u64 v[208:209], v[184:185], 0, v[180:181]
	v_lshl_add_u64 v[186:187], v[186:187], 0, s[18:19]
	v_lshl_add_u64 v[190:191], v[190:191], 0, s[18:19]
	v_lshl_add_u64 v[230:231], v[186:187], 0, v[180:181]
	v_lshl_add_u64 v[196:197], v[188:189], 0, v[180:181]
	v_lshl_add_u64 v[198:199], v[190:191], 0, v[180:181]
	global_load_dword v232, v[208:209], off
	global_load_dword v233, v[208:209], off offset:128
	global_load_dword v238, v[230:231], off
	global_load_dword v239, v[230:231], off offset:128
	global_load_dword v240, v[196:197], off
	global_load_dword v241, v[196:197], off offset:128
	global_load_dword v242, v[198:199], off
	global_load_dword v243, v[198:199], off offset:128
	v_add_u32_e32 v196, 17, v225
	v_min_i32_e32 v196, 0x7fff, v196
	v_add_u32_e32 v198, 18, v225
	v_ashrrev_i32_e32 v196, 12, v196
	v_min_i32_e32 v198, 0x7fff, v198
	v_mul_hi_i32_i24_e32 v197, 0x3000, v196
	v_mul_i32_i24_e32 v196, 0x3000, v196
	v_ashrrev_i32_e32 v198, 12, v198
	v_lshl_add_u64 v[196:197], s[24:25], 0, v[196:197]
	v_mul_hi_i32_i24_e32 v199, 0x3000, v198
	v_mul_i32_i24_e32 v198, 0x3000, v198
	v_add_u32_e32 v192, 11, v225
	v_add_u32_e32 v194, 16, v225
	v_min_i32_e32 v192, 0x7fff, v192
	v_min_i32_e32 v194, 0x7fff, v194
	v_ashrrev_i32_e32 v192, 12, v192
	v_ashrrev_i32_e32 v194, 12, v194
	v_mul_hi_i32_i24_e32 v193, 0x3000, v192
	v_mul_i32_i24_e32 v192, 0x3000, v192
	v_mul_hi_i32_i24_e32 v195, 0x3000, v194
	v_mul_i32_i24_e32 v194, 0x3000, v194
	v_lshl_add_u64 v[192:193], s[24:25], 0, v[192:193]
	v_lshl_add_u64 v[194:195], s[24:25], 0, v[194:195]
	v_lshl_add_u64 v[192:193], v[192:193], 0, s[18:19]
	v_lshl_add_u64 v[194:195], v[194:195], 0, s[18:19]
	v_lshl_add_u64 v[196:197], v[196:197], 0, s[18:19]
	v_lshl_add_u64 v[198:199], s[24:25], 0, v[198:199]
	v_lshl_add_u64 v[208:209], v[192:193], 0, v[180:181]
	v_lshl_add_u64 v[198:199], v[198:199], 0, s[18:19]
	v_lshl_add_u64 v[226:227], v[198:199], 0, v[180:181]
	s_waitcnt vmcnt(7)
	v_mul_f32_e32 v112, v112, v232
	v_lshl_add_u64 v[204:205], v[194:195], 0, v[180:181]
	v_lshl_add_u64 v[206:207], v[196:197], 0, v[180:181]
	s_waitcnt vmcnt(6)
	s_nop 2
	v_mul_f32_e32 v96, v96, v233
	v_mul_f32_e32 v97, v97, v233
	global_load_dword v234, v[208:209], off
	global_load_dword v235, v[208:209], off offset:128
	global_load_dword v236, v[204:205], off
	global_load_dword v237, v[204:205], off offset:128
	global_load_dword v244, v[206:207], off
	global_load_dword v245, v[206:207], off offset:128
	global_load_dword v246, v[226:227], off
	global_load_dword v247, v[226:227], off offset:128
	v_add_u32_e32 v204, 25, v225
	v_add_u32_e32 v206, 26, v225
	v_min_i32_e32 v204, 0x7fff, v204
	v_min_i32_e32 v206, 0x7fff, v206
	v_ashrrev_i32_e32 v204, 12, v204
	v_ashrrev_i32_e32 v206, 12, v206
	v_add_u32_e32 v200, 19, v225
	v_min_i32_e32 v200, 0x7fff, v200
	v_add_u32_e32 v202, 24, v225
	v_ashrrev_i32_e32 v200, 12, v200
	v_min_i32_e32 v202, 0x7fff, v202
	v_mul_hi_i32_i24_e32 v201, 0x3000, v200
	v_mul_i32_i24_e32 v200, 0x3000, v200
	v_ashrrev_i32_e32 v202, 12, v202
	v_mul_hi_i32_i24_e32 v205, 0x3000, v204
	v_mul_i32_i24_e32 v204, 0x3000, v204
	v_mul_hi_i32_i24_e32 v207, 0x3000, v206
	v_mul_i32_i24_e32 v206, 0x3000, v206
	v_lshl_add_u64 v[200:201], s[24:25], 0, v[200:201]
	v_mul_hi_i32_i24_e32 v203, 0x3000, v202
	v_mul_i32_i24_e32 v202, 0x3000, v202
	v_lshl_add_u64 v[204:205], s[24:25], 0, v[204:205]
	v_lshl_add_u64 v[206:207], s[24:25], 0, v[206:207]
	v_lshl_add_u64 v[200:201], v[200:201], 0, s[18:19]
	v_lshl_add_u64 v[202:203], s[24:25], 0, v[202:203]
	v_lshl_add_u64 v[204:205], v[204:205], 0, s[18:19]
	v_lshl_add_u64 v[206:207], v[206:207], 0, s[18:19]
	v_lshl_add_u64 v[208:209], v[200:201], 0, v[180:181]
	v_lshl_add_u64 v[202:203], v[202:203], 0, s[18:19]
	v_lshl_add_u64 v[228:229], v[204:205], 0, v[180:181]
	v_lshl_add_u64 v[230:231], v[206:207], 0, v[180:181]
	v_lshl_add_u64 v[226:227], v[202:203], 0, v[180:181]
	global_load_dword v248, v[208:209], off
	global_load_dword v249, v[208:209], off offset:128
	global_load_dword v250, v[226:227], off
	global_load_dword v251, v[226:227], off offset:128
	global_load_dword v252, v[228:229], off
	s_nop 0
	global_load_dword v228, v[228:229], off offset:128
	s_nop 0
	global_load_dword v229, v[230:231], off
	s_nop 0
	global_load_dword v230, v[230:231], off offset:128
	v_add_u32_e32 v208, 27, v225
	v_min_i32_e32 v208, 0x7fff, v208
	v_ashrrev_i32_e32 v208, 12, v208
	v_mul_hi_i32_i24_e32 v209, 0x3000, v208
	v_mul_i32_i24_e32 v208, 0x3000, v208
	v_lshl_add_u64 v[208:209], s[24:25], 0, v[208:209]
	v_lshl_add_u64 v[208:209], v[208:209], 0, s[18:19]
	v_lshl_add_u64 v[226:227], v[208:209], 0, v[180:181]
	global_load_dword v225, v[226:227], off
	s_nop 0
	global_load_dword v226, v[226:227], off offset:128
	v_mad_u64_u32 v[160:161], s[2:3], v183, s36, v[182:183]
	v_lshl_add_u32 v162, v160, 2, s34
	ds_write2_b32 v162, v112, v96 offset1:32
	v_mul_f32_e32 v96, v113, v232
	ds_write2_b32 v162, v96, v97 offset0:68 offset1:100
	v_mul_f32_e32 v96, v114, v232
	v_mul_f32_e32 v97, v98, v233
	ds_write2_b32 v162, v96, v97 offset0:136 offset1:168
	v_mul_f32_e32 v96, v115, v232
	v_mul_f32_e32 v97, v99, v233
	ds_write2_b32 v162, v96, v97 offset0:204 offset1:236
	s_waitcnt vmcnt(23)
	v_mul_f32_e32 v96, v116, v238
	s_waitcnt vmcnt(22)
	v_mul_f32_e32 v97, v100, v239
	v_add_u32_e32 v115, 0x800, v162
	ds_write2_b32 v115, v96, v97 offset0:32 offset1:64
	s_waitcnt vmcnt(21)
	v_mul_f32_e32 v96, v117, v240
	s_waitcnt vmcnt(20)
	v_mul_f32_e32 v97, v101, v241
	ds_write2_b32 v115, v96, v97 offset0:100 offset1:132
	s_waitcnt vmcnt(19)
	v_mul_f32_e32 v96, v118, v242
	s_waitcnt vmcnt(18)
	v_mul_f32_e32 v97, v102, v243
	ds_write2_b32 v115, v96, v97 offset0:168 offset1:200
	v_add_u32_e32 v116, 0xa00, v162
	v_add_u32_e32 v117, 0x1000, v162
	v_add_u32_e32 v118, 0x1400, v162
	v_ashrrev_i32_e32 v163, 4, v168
	v_and_b32_e32 v160, 15, v168
	v_mul_lo_u32 v161, v163, s37
	s_waitcnt vmcnt(17)
	v_mul_f32_e32 v96, v119, v234
	s_waitcnt vmcnt(16)
	v_mul_f32_e32 v97, v103, v235
	ds_write2_b32 v116, v96, v97 offset0:108 offset1:140
	s_waitcnt vmcnt(15)
	v_mul_f32_e32 v96, v120, v236
	s_waitcnt vmcnt(14)
	v_mul_f32_e32 v97, v104, v237
	ds_write2_b32 v117, v96, v97 offset0:64 offset1:96
	s_waitcnt vmcnt(13)
	v_mul_f32_e32 v96, v121, v244
	s_waitcnt vmcnt(12)
	v_mul_f32_e32 v97, v105, v245
	ds_write2_b32 v117, v96, v97 offset0:132 offset1:164
	s_waitcnt vmcnt(11)
	v_mul_f32_e32 v96, v122, v246
	s_waitcnt vmcnt(10)
	v_mul_f32_e32 v97, v106, v247
	ds_write2_b32 v117, v96, v97 offset0:200 offset1:232
	v_add_u32_e32 v119, 0x1800, v162
	v_add_u32_e32 v120, 0x1a00, v162
	v_lshl_add_u32 v164, v160, 4, s34
	v_lshlrev_b32_e32 v168, 2, v160
	v_add_u32_e32 v160, s55, v163
	v_add_u32_e32 v121, 0x1c00, v162
	v_cmp_gt_i32_e32 vcc, s38, v160
	v_add_u32_e32 v114, v164, v161
	v_ashrrev_i32_e32 v161, 31, v160
	s_waitcnt vmcnt(9)
	v_mul_f32_e32 v96, v123, v248
	s_waitcnt vmcnt(8)
	v_mul_f32_e32 v97, v107, v249
	ds_write2_b32 v118, v96, v97 offset0:12 offset1:44
	s_waitcnt vmcnt(7)
	v_mul_f32_e32 v96, v124, v250
	s_waitcnt vmcnt(6)
	v_mul_f32_e32 v97, v108, v251
	ds_write2_b32 v119, v96, v97 offset0:96 offset1:128
	s_waitcnt vmcnt(5)
	v_mul_f32_e32 v96, v125, v252
	s_waitcnt vmcnt(4)
	v_mul_f32_e32 v97, v109, v228
	ds_write2_b32 v119, v96, v97 offset0:164 offset1:196
	s_waitcnt vmcnt(3)
	v_mul_f32_e32 v96, v126, v229
	s_waitcnt vmcnt(2)
	v_mul_f32_e32 v97, v110, v230
	ds_write2_b32 v120, v96, v97 offset0:104 offset1:136
	s_waitcnt vmcnt(1)
	v_mul_f32_e32 v96, v127, v225
	s_waitcnt vmcnt(0)
	v_mul_f32_e32 v97, v111, v226
	ds_write2_b32 v121, v96, v97 offset0:44 offset1:76
	v_or_b32_e32 v96, s26, v168
	v_mov_b32_e32 v97, s27
	v_add_u32_e32 v128, 0, v160
	v_ashrrev_i32_e32 v129, 31, v128
	v_lshlrev_b64 v[128:129], 10, v[128:129]
	v_lshl_add_u64 v[128:129], v[128:129], 0, v[96:97]
	v_lshlrev_b64 v[128:129], 2, v[128:129]
	v_lshl_add_u64 v[128:129], s[16:17], 0, v[128:129]
	global_load_dwordx4 v[128:131], v[128:129], off
	v_add_u32_e32 v132, 4, v160
	v_ashrrev_i32_e32 v133, 31, v132
	v_lshlrev_b64 v[132:133], 10, v[132:133]
	v_lshl_add_u64 v[132:133], v[132:133], 0, v[96:97]
	v_lshlrev_b64 v[132:133], 2, v[132:133]
	v_lshl_add_u64 v[132:133], s[16:17], 0, v[132:133]
	global_load_dwordx4 v[132:135], v[132:133], off
	v_add_u32_e32 v136, 8, v160
	v_ashrrev_i32_e32 v137, 31, v136
	v_lshlrev_b64 v[136:137], 10, v[136:137]
	v_lshl_add_u64 v[136:137], v[136:137], 0, v[96:97]
	v_lshlrev_b64 v[136:137], 2, v[136:137]
	v_lshl_add_u64 v[136:137], s[16:17], 0, v[136:137]
	global_load_dwordx4 v[136:139], v[136:137], off
	v_add_u32_e32 v140, 12, v160
	v_ashrrev_i32_e32 v141, 31, v140
	v_lshlrev_b64 v[140:141], 10, v[140:141]
	v_lshl_add_u64 v[140:141], v[140:141], 0, v[96:97]
	v_lshlrev_b64 v[140:141], 2, v[140:141]
	v_lshl_add_u64 v[140:141], s[16:17], 0, v[140:141]
	global_load_dwordx4 v[140:143], v[140:141], off
	v_add_u32_e32 v144, 16, v160
	v_ashrrev_i32_e32 v145, 31, v144
	v_lshlrev_b64 v[144:145], 10, v[144:145]
	v_lshl_add_u64 v[144:145], v[144:145], 0, v[96:97]
	v_lshlrev_b64 v[144:145], 2, v[144:145]
	v_lshl_add_u64 v[144:145], s[16:17], 0, v[144:145]
	global_load_dwordx4 v[144:147], v[144:145], off
	v_add_u32_e32 v148, 20, v160
	v_ashrrev_i32_e32 v149, 31, v148
	v_lshlrev_b64 v[148:149], 10, v[148:149]
	v_lshl_add_u64 v[148:149], v[148:149], 0, v[96:97]
	v_lshlrev_b64 v[148:149], 2, v[148:149]
	v_lshl_add_u64 v[148:149], s[16:17], 0, v[148:149]
	global_load_dwordx4 v[148:151], v[148:149], off
	v_add_u32_e32 v152, 24, v160
	v_ashrrev_i32_e32 v153, 31, v152
	v_lshlrev_b64 v[152:153], 10, v[152:153]
	v_lshl_add_u64 v[152:153], v[152:153], 0, v[96:97]
	v_lshlrev_b64 v[152:153], 2, v[152:153]
	v_lshl_add_u64 v[152:153], s[16:17], 0, v[152:153]
	global_load_dwordx4 v[152:155], v[152:153], off
	v_add_u32_e32 v156, 28, v160
	v_ashrrev_i32_e32 v157, 31, v156
	v_lshlrev_b64 v[156:157], 10, v[156:157]
	v_lshl_add_u64 v[156:157], v[156:157], 0, v[96:97]
	v_lshlrev_b64 v[156:157], 2, v[156:157]
	v_lshl_add_u64 v[156:157], s[16:17], 0, v[156:157]
	global_load_dwordx4 v[156:159], v[156:157], off
	s_and_saveexec_b64 s[2:3], vcc
	s_cbranch_execz .LBB0_1281
	v_lshlrev_b64 v[98:99], 10, v[160:161]
	v_lshl_add_u64 v[98:99], v[98:99], 0, v[96:97]
	v_lshlrev_b64 v[106:107], 2, v[98:99]
	v_lshl_add_u64 v[98:99], s[16:17], 0, v[106:107]
	ds_read_b128 v[102:105], v114
	s_load_dwordx2 s[4:5], s[0:1], 0xb8
	s_waitcnt vmcnt(7) lgkmcnt(0)
	v_pk_add_f32 v[100:101], v[104:105], v[130:131]
	v_pk_add_f32 v[98:99], v[102:103], v[128:129]
	v_lshl_add_u64 v[102:103], s[4:5], 0, v[106:107]
	global_store_dwordx4 v[102:103], v[98:101], off

.LBB0_1460:
	v_mbcnt_hi_u32_b32 v192, -1, v210
	s_load_dwordx2 s[2:3], s[0:1], 0x158
	s_load_dwordx2 s[4:5], s[0:1], 0x100
	s_ashr_i32 s7, s6, 31
	v_mov_b32_e32 v1, v192
	s_and_b32 s7, s7, s42
	s_add_i32 s8, s7, s6
	v_add_u32_e32 v0, s70, v1
	v_ashrrev_i32_e32 v193, 3, v0
	v_readfirstlane_b32 s9, v0
	v_lshlrev_b32_e32 v0, 3, v1
	v_and_b32_e32 v0, 56, v0
	s_cmpk_lt_i32 s8, 0x480
	s_cselect_b64 s[6:7], -1, 0
	s_cmpk_gt_i32 s8, 0x47f
	v_lshlrev_b32_e32 v160, 1, v0
	v_add_u32_e32 v194, 64, v193
	s_cbranch_scc1 .LBB0_1462
	s_mul_hi_i32 s10, s8, 0x38e38e39
	s_lshr_b32 s11, s10, 31
	s_ashr_i32 s10, s10, 1
	s_add_i32 s10, s10, s11
	s_mul_i32 s11, s10, -9
	s_lshl_b32 s10, s10, 8
	v_add_u32_e32 v2, s10, v193
	v_min_i32_e32 v2, 0x7fff, v2
	v_ashrrev_i32_e32 v3, 31, v2
	v_lshlrev_b64 v[2:3], 11, v[2:3]
	s_add_i32 s11, s11, s8
	s_waitcnt lgkmcnt(0)
	v_lshl_add_u64 v[2:3], s[2:3], 0, v[2:3]
	v_mov_b32_e32 v161, 0
	s_lshl_b32 s11, s11, 8
	v_lshl_add_u64 v[2:3], v[2:3], 0, v[160:161]
	v_mbcnt_hi_u32_b32 v158, -1, v210
	s_and_b32 s90, s70, 0x40
	v_and_b32_e32 v159, 48, v158
	v_or_b32_e32 v159, s90, v159
	s_lshl_b32 s88, s70, 4
	s_lshl_b32 s92, s22, 4
	s_and_b32 s92, s92, 0x780
	s_mov_b32 s93, 0
	s_add_u32 m0, s88, 0
	v_lshl_add_u64 v[2:3], v[2:3], 0, s[92:93]
	v_xor_b32_e32 v2, v159, v2
	global_load_lds_dwordx4 v[2:3], off
	v_add_u32_e32 v2, s11, v193
	v_ashrrev_i32_e32 v3, 31, v2
	v_lshlrev_b64 v[2:3], 11, v[2:3]
	v_lshl_add_u64 v[2:3], s[4:5], 0, v[2:3]
	v_lshl_add_u64 v[2:3], v[2:3], 0, v[160:161]
	s_add_u32 m0, s88, 32768
	v_lshl_add_u64 v[2:3], v[2:3], 0, s[92:93]
	v_xor_b32_e32 v2, v159, v2
	global_load_lds_dwordx4 v[2:3], off
	v_add_u32_e32 v2, s10, v194
	v_min_i32_e32 v2, 0x7fff, v2
	v_ashrrev_i32_e32 v3, 31, v2
	v_lshlrev_b64 v[2:3], 11, v[2:3]
	v_lshl_add_u64 v[2:3], s[2:3], 0, v[2:3]
	v_lshl_add_u64 v[2:3], v[2:3], 0, v[160:161]
	s_add_u32 m0, s88, 8192
	v_lshl_add_u64 v[2:3], v[2:3], 0, s[92:93]
	v_xor_b32_e32 v2, v159, v2
	global_load_lds_dwordx4 v[2:3], off
	v_add_u32_e32 v2, s11, v194
	v_ashrrev_i32_e32 v3, 31, v2
	v_lshlrev_b64 v[2:3], 11, v[2:3]
	v_lshl_add_u64 v[2:3], s[4:5], 0, v[2:3]
	v_lshl_add_u64 v[2:3], v[2:3], 0, v[160:161]
	v_add_u32_e32 v4, 0x80, v193
	s_add_u32 m0, s88, 40960
	v_lshl_add_u64 v[2:3], v[2:3], 0, s[92:93]
	v_xor_b32_e32 v2, v159, v2
	global_load_lds_dwordx4 v[2:3], off
	v_add_u32_e32 v2, s10, v4
	v_min_i32_e32 v2, 0x7fff, v2
	v_ashrrev_i32_e32 v3, 31, v2
	v_lshlrev_b64 v[2:3], 11, v[2:3]
	v_lshl_add_u64 v[2:3], s[2:3], 0, v[2:3]
	v_lshl_add_u64 v[2:3], v[2:3], 0, v[160:161]
	s_add_u32 m0, s88, 16384
	v_lshl_add_u64 v[2:3], v[2:3], 0, s[92:93]
	v_xor_b32_e32 v2, v159, v2
	global_load_lds_dwordx4 v[2:3], off
	v_add_u32_e32 v2, s11, v4
	v_ashrrev_i32_e32 v3, 31, v2
	v_lshlrev_b64 v[2:3], 11, v[2:3]
	v_lshl_add_u64 v[2:3], s[4:5], 0, v[2:3]
	v_lshl_add_u64 v[2:3], v[2:3], 0, v[160:161]
	v_add_u32_e32 v4, 0xc0, v193
	s_add_u32 m0, s88, 49152
	v_lshl_add_u64 v[2:3], v[2:3], 0, s[92:93]
	v_xor_b32_e32 v2, v159, v2
	global_load_lds_dwordx4 v[2:3], off
	v_add_u32_e32 v2, s10, v4
	v_min_i32_e32 v2, 0x7fff, v2
	v_ashrrev_i32_e32 v3, 31, v2
	v_lshlrev_b64 v[2:3], 11, v[2:3]
	v_lshl_add_u64 v[2:3], s[2:3], 0, v[2:3]
	v_lshl_add_u64 v[2:3], v[2:3], 0, v[160:161]
	s_add_u32 m0, s88, 24576
	v_lshl_add_u64 v[2:3], v[2:3], 0, s[92:93]
	v_xor_b32_e32 v2, v159, v2
	global_load_lds_dwordx4 v[2:3], off
	v_add_u32_e32 v2, s11, v4
	v_ashrrev_i32_e32 v3, 31, v2
	v_lshlrev_b64 v[2:3], 11, v[2:3]
	v_lshl_add_u64 v[2:3], s[4:5], 0, v[2:3]
	v_lshl_add_u64 v[2:3], v[2:3], 0, v[160:161]
	s_add_u32 m0, s88, 57344
	v_lshl_add_u64 v[2:3], v[2:3], 0, s[92:93]
	v_xor_b32_e32 v2, v159, v2
	global_load_lds_dwordx4 v[2:3], off
	s_waitcnt vmcnt(0)

.LBB0_1466:
	s_mul_hi_i32 s2, s8, 0x38e38e39
	s_lshr_b32 s3, s2, 31
	s_ashr_i32 s4, s2, 1
	s_add_i32 s4, s4, s3
	s_lshl_b32 s77, s4, 8
	v_add_u32_e32 v0, s77, v193
	v_min_i32_e32 v0, 0x7fff, v0
	v_ashrrev_i32_e32 v1, 31, v0
	v_lshlrev_b64 v[0:1], 11, v[0:1]
	s_mul_i32 s2, s4, 0x900
	v_lshl_add_u64 v[172:173], v[168:169], 0, v[0:1]
	v_subrev_u32_e32 v0, s2, v201
	v_ashrrev_i32_e32 v1, 31, v0
	v_lshlrev_b64 v[0:1], 11, v[0:1]
	v_lshl_add_u64 v[180:181], v[170:171], 0, v[0:1]
	v_subrev_u32_e32 v0, s2, v202
	v_ashrrev_i32_e32 v1, 31, v0
	v_lshlrev_b64 v[0:1], 11, v[0:1]
	v_lshl_add_u64 v[182:183], v[170:171], 0, v[0:1]
	v_subrev_u32_e32 v0, s2, v203
	v_ashrrev_i32_e32 v1, 31, v0
	v_add_u32_e32 v2, s77, v194
	v_add_u32_e32 v4, s77, v163
	v_add_u32_e32 v6, s77, v196
	v_lshlrev_b64 v[0:1], 11, v[0:1]
	v_min_i32_e32 v2, 0x7fff, v2
	v_min_i32_e32 v4, 0x7fff, v4
	v_min_i32_e32 v6, 0x7fff, v6
	v_lshl_add_u64 v[184:185], v[170:171], 0, v[0:1]
	v_subrev_u32_e32 v0, s2, v204
	v_ashrrev_i32_e32 v3, 31, v2
	v_ashrrev_i32_e32 v5, 31, v4
	v_ashrrev_i32_e32 v7, 31, v6
	v_ashrrev_i32_e32 v1, 31, v0
	v_lshlrev_b64 v[2:3], 11, v[2:3]
	v_lshlrev_b64 v[4:5], 11, v[4:5]
	v_lshlrev_b64 v[6:7], 11, v[6:7]
	v_lshlrev_b64 v[0:1], 11, v[0:1]
	v_lshl_add_u64 v[174:175], v[168:169], 0, v[2:3]
	v_lshl_add_u64 v[176:177], v[168:169], 0, v[4:5]
	v_lshl_add_u64 v[178:179], v[168:169], 0, v[6:7]
	v_lshl_add_u64 v[186:187], v[170:171], 0, v[0:1]
	s_mov_b64 s[2:3], 0
	s_mov_b32 s5, s25
	v_mov_b32_e32 v0, 0
	v_mov_b32_e32 v1, v161
	v_mov_b32_e32 v2, v161
	v_mov_b32_e32 v3, v161
	v_mov_b32_e32 v4, v161
	v_mov_b32_e32 v5, v161
	v_mov_b32_e32 v6, v161
	v_mov_b32_e32 v7, v161
	v_mov_b32_e32 v8, v161
	v_mov_b32_e32 v9, v161
	v_mov_b32_e32 v10, v161
	v_mov_b32_e32 v11, v161
	v_mov_b32_e32 v12, v161
	v_mov_b32_e32 v13, v161
	v_mov_b32_e32 v14, v161
	v_mov_b32_e32 v15, v161
	v_mov_b32_e32 v16, 0
	v_mov_b32_e32 v17, v161
	v_mov_b32_e32 v18, v161
	v_mov_b32_e32 v19, v161
	v_mov_b32_e32 v20, v161
	v_mov_b32_e32 v21, v161
	v_mov_b32_e32 v22, v161
	v_mov_b32_e32 v23, v161
	v_mov_b32_e32 v24, v161
	v_mov_b32_e32 v25, v161
	v_mov_b32_e32 v26, v161
	v_mov_b32_e32 v27, v161
	v_mov_b32_e32 v28, v161
	v_mov_b32_e32 v29, v161
	v_mov_b32_e32 v30, v161
	v_mov_b32_e32 v31, v161
	v_mov_b32_e32 v32, 0
	v_mov_b32_e32 v33, v161
	v_mov_b32_e32 v34, v161
	v_mov_b32_e32 v35, v161
	v_mov_b32_e32 v36, v161
	v_mov_b32_e32 v37, v161
	v_mov_b32_e32 v38, v161
	v_mov_b32_e32 v39, v161
	v_mov_b32_e32 v40, v161
	v_mov_b32_e32 v41, v161
	v_mov_b32_e32 v42, v161
	v_mov_b32_e32 v43, v161
	v_mov_b32_e32 v44, v161
	v_mov_b32_e32 v45, v161
	v_mov_b32_e32 v46, v161
	v_mov_b32_e32 v47, v161
	v_mov_b32_e32 v48, 0
	v_mov_b32_e32 v49, v161
	v_mov_b32_e32 v50, v161
	v_mov_b32_e32 v51, v161
	v_mov_b32_e32 v52, v161
	v_mov_b32_e32 v53, v161
	v_mov_b32_e32 v54, v161
	v_mov_b32_e32 v55, v161
	v_mov_b32_e32 v56, v161
	v_mov_b32_e32 v57, v161
	v_mov_b32_e32 v58, v161
	v_mov_b32_e32 v59, v161
	v_mov_b32_e32 v60, v161
	v_mov_b32_e32 v61, v161
	v_mov_b32_e32 v62, v161
	v_mov_b32_e32 v63, v161
	v_mov_b32_e32 v64, 0
	v_mov_b32_e32 v65, v161
	v_mov_b32_e32 v66, v161
	v_mov_b32_e32 v67, v161
	v_mov_b32_e32 v68, v161
	v_mov_b32_e32 v69, v161
	v_mov_b32_e32 v70, v161
	v_mov_b32_e32 v71, v161
	v_mov_b32_e32 v72, v161
	v_mov_b32_e32 v73, v161
	v_mov_b32_e32 v74, v161
	v_mov_b32_e32 v75, v161
	v_mov_b32_e32 v76, v161
	v_mov_b32_e32 v77, v161
	v_mov_b32_e32 v78, v161
	v_mov_b32_e32 v79, v161
	v_mov_b32_e32 v80, 0
	v_mov_b32_e32 v81, v161
	v_mov_b32_e32 v82, v161
	v_mov_b32_e32 v83, v161
	v_mov_b32_e32 v84, v161
	v_mov_b32_e32 v85, v161
	v_mov_b32_e32 v86, v161
	v_mov_b32_e32 v87, v161
	v_mov_b32_e32 v88, v161
	v_mov_b32_e32 v89, v161
	v_mov_b32_e32 v90, v161
	v_mov_b32_e32 v91, v161
	v_mov_b32_e32 v92, v161
	v_mov_b32_e32 v93, v161
	v_mov_b32_e32 v94, v161
	v_mov_b32_e32 v95, v161
	v_mov_b32_e32 v96, 0
	v_mov_b32_e32 v97, v161
	v_mov_b32_e32 v98, v161
	v_mov_b32_e32 v99, v161
	v_mov_b32_e32 v100, v161
	v_mov_b32_e32 v101, v161
	v_mov_b32_e32 v102, v161
	v_mov_b32_e32 v103, v161
	v_mov_b32_e32 v104, v161
	v_mov_b32_e32 v105, v161
	v_mov_b32_e32 v106, v161
	v_mov_b32_e32 v107, v161
	v_mov_b32_e32 v108, v161
	v_mov_b32_e32 v109, v161
	v_mov_b32_e32 v110, v161
	v_mov_b32_e32 v111, v161
	v_mov_b32_e32 v112, 0
	v_mov_b32_e32 v113, v161
	v_mov_b32_e32 v114, v161
	v_mov_b32_e32 v115, v161
	v_mov_b32_e32 v116, v161
	v_mov_b32_e32 v117, v161
	v_mov_b32_e32 v118, v161
	v_mov_b32_e32 v119, v161
	v_mov_b32_e32 v120, v161
	v_mov_b32_e32 v121, v161
	v_mov_b32_e32 v122, v161
	v_mov_b32_e32 v123, v161
	v_mov_b32_e32 v124, v161
	v_mov_b32_e32 v125, v161
	v_mov_b32_e32 v126, v161
	v_mov_b32_e32 v127, v161
	v_mbcnt_hi_u32_b32 v128, -1, v210
	s_and_b32 s90, s70, 0x40
	v_and_b32_e32 v159, 48, v128
	v_or_b32_e32 v159, s90, v159
	v_and_b32_e32 v129, 31, v128
	v_lshrrev_b32_e32 v130, 5, v128
	v_bfe_u32 v131, v128, 1, 3
	v_lshlrev_b32_e32 v132, 7, v129
	s_lshr_b32 s91, s70, 7
	s_lshl_b32 s91, s91, 13
	s_lshl_b32 s90, s90, 8
	s_add_u32 s90, s90, 0x8000
	s_lshl_b32 s88, s70, 4
	s_mov_b32 s89, 0x10000
	s_lshl_b32 s92, s22, 4
	s_and_b32 s92, s92, 0x780
	s_mov_b32 s93, 0
	v_xor_b32_e32 v133, v130, v131
	v_lshl_add_u32 v133, v133, 4, v132
	v_add_u32_e32 v232, s91, v133
	v_add_u32_e32 v236, s90, v133
	v_or_b32_e32 v133, 2, v130
	v_xor_b32_e32 v133, v133, v131
	v_lshl_add_u32 v133, v133, 4, v132
	v_add_u32_e32 v233, s91, v133
	v_add_u32_e32 v237, s90, v133
	v_or_b32_e32 v133, 4, v130
	v_xor_b32_e32 v133, v133, v131
	v_lshl_add_u32 v133, v133, 4, v132
	v_add_u32_e32 v234, s91, v133
	v_add_u32_e32 v238, s90, v133
	v_or_b32_e32 v133, 6, v130
	v_xor_b32_e32 v133, v133, v131
	v_lshl_add_u32 v133, v133, 4, v132
	v_add_u32_e32 v235, s91, v133
	v_add_u32_e32 v239, s90, v133
	s_barrier
	ds_read_b128 v[188:191], v232
	ds_read_b128 v[216:219], v236
	ds_read_b128 v[212:215], v232 offset:4096
	ds_read_b128 v[220:223], v236 offset:4096
	ds_read_b128 v[224:227], v236 offset:8192
	ds_read_b128 v[228:231], v236 offset:12288
	s_add_u32 s94, s2, s92
	s_add_u32 s94, s94, 0x80
	s_and_b32 s94, s94, 0x780
	s_sub_u32 s94, s94, 0x80
	s_subb_u32 s95, 0, 0
	s_add_u32 s90, s88, s89
	s_add_u32 m0, s90, 0
	v_lshl_add_u64 v[152:153], v[172:173], 0, s[94:95]
	v_xor_b32_e32 v152, v159, v152
	global_load_lds_dwordx4 v[152:153], off
	s_add_u32 m0, s90, 32768
	v_lshl_add_u64 v[154:155], v[180:181], 0, s[94:95]
	v_xor_b32_e32 v154, v159, v154
	global_load_lds_dwordx4 v[154:155], off
	s_add_u32 m0, s90, 8192
	v_lshl_add_u64 v[156:157], v[174:175], 0, s[94:95]
	v_xor_b32_e32 v156, v159, v156
	global_load_lds_dwordx4 v[156:157], off
	s_add_u32 m0, s90, 40960
	v_lshl_add_u64 v[152:153], v[182:183], 0, s[94:95]
	v_xor_b32_e32 v152, v159, v152
	global_load_lds_dwordx4 v[152:153], off
	s_add_u32 m0, s90, 16384
	v_lshl_add_u64 v[154:155], v[176:177], 0, s[94:95]
	v_xor_b32_e32 v154, v159, v154
	global_load_lds_dwordx4 v[154:155], off
	s_add_u32 m0, s90, 49152
	v_lshl_add_u64 v[156:157], v[184:185], 0, s[94:95]
	v_xor_b32_e32 v156, v159, v156
	global_load_lds_dwordx4 v[156:157], off
	s_add_u32 m0, s90, 24576
	v_lshl_add_u64 v[152:153], v[178:179], 0, s[94:95]
	v_xor_b32_e32 v152, v159, v152
	global_load_lds_dwordx4 v[152:153], off
	s_add_u32 m0, s90, 57344
	v_lshl_add_u64 v[154:155], v[186:187], 0, s[94:95]
	v_xor_b32_e32 v154, v159, v154
	global_load_lds_dwordx4 v[154:155], off
	s_xor_b32 s89, s89, 0x10000

.LBB0_1470:
	ds_read_b128 v[128:131], v233
	ds_read_b128 v[136:139], v237
	ds_read_b128 v[132:135], v233 offset:4096
	ds_read_b128 v[140:143], v237 offset:4096
	ds_read_b128 v[144:147], v237 offset:8192
	ds_read_b128 v[148:151], v237 offset:12288
	s_waitcnt lgkmcnt(6)
	v_mfma_f32_32x32x16_bf16 v[112:127], v[188:191], v[216:219], v[112:127]
	v_mfma_f32_32x32x16_bf16 v[48:63], v[212:215], v[216:219], v[48:63]
	v_mfma_f32_32x32x16_bf16 v[96:111], v[188:191], v[220:223], v[96:111]
	v_mfma_f32_32x32x16_bf16 v[32:47], v[212:215], v[220:223], v[32:47]
	v_mfma_f32_32x32x16_bf16 v[80:95], v[188:191], v[224:227], v[80:95]
	v_mfma_f32_32x32x16_bf16 v[16:31], v[212:215], v[224:227], v[16:31]
	v_mfma_f32_32x32x16_bf16 v[64:79], v[188:191], v[228:231], v[64:79]
	v_mfma_f32_32x32x16_bf16 v[0:15], v[212:215], v[228:231], v[0:15]
	ds_read_b128 v[188:191], v234
	ds_read_b128 v[216:219], v238
	ds_read_b128 v[212:215], v234 offset:4096
	ds_read_b128 v[220:223], v238 offset:4096
	ds_read_b128 v[224:227], v238 offset:8192
	ds_read_b128 v[228:231], v238 offset:12288
	s_waitcnt lgkmcnt(6)
	v_mfma_f32_32x32x16_bf16 v[112:127], v[128:131], v[136:139], v[112:127]
	v_mfma_f32_32x32x16_bf16 v[48:63], v[132:135], v[136:139], v[48:63]
	v_mfma_f32_32x32x16_bf16 v[96:111], v[128:131], v[140:143], v[96:111]
	v_mfma_f32_32x32x16_bf16 v[32:47], v[132:135], v[140:143], v[32:47]
	v_mfma_f32_32x32x16_bf16 v[80:95], v[128:131], v[144:147], v[80:95]
	v_mfma_f32_32x32x16_bf16 v[16:31], v[132:135], v[144:147], v[16:31]
	v_mfma_f32_32x32x16_bf16 v[64:79], v[128:131], v[148:151], v[64:79]
	v_mfma_f32_32x32x16_bf16 v[0:15], v[132:135], v[148:151], v[0:15]
	ds_read_b128 v[128:131], v235
	ds_read_b128 v[136:139], v239
	ds_read_b128 v[132:135], v235 offset:4096
	ds_read_b128 v[140:143], v239 offset:4096
	ds_read_b128 v[144:147], v239 offset:8192
	ds_read_b128 v[148:151], v239 offset:12288
	s_waitcnt lgkmcnt(6)
	v_mfma_f32_32x32x16_bf16 v[112:127], v[188:191], v[216:219], v[112:127]
	v_mfma_f32_32x32x16_bf16 v[48:63], v[212:215], v[216:219], v[48:63]
	v_mfma_f32_32x32x16_bf16 v[96:111], v[188:191], v[220:223], v[96:111]
	v_mfma_f32_32x32x16_bf16 v[32:47], v[212:215], v[220:223], v[32:47]
	v_mfma_f32_32x32x16_bf16 v[80:95], v[188:191], v[224:227], v[80:95]
	v_mfma_f32_32x32x16_bf16 v[16:31], v[212:215], v[224:227], v[16:31]
	v_mfma_f32_32x32x16_bf16 v[64:79], v[188:191], v[228:231], v[64:79]
	v_mfma_f32_32x32x16_bf16 v[0:15], v[212:215], v[228:231], v[0:15]
	s_waitcnt vmcnt(0) lgkmcnt(0)
	s_barrier
	v_xor_b32_e32 v232, 0x10000, v232
	v_xor_b32_e32 v236, 0x10000, v236
	v_mfma_f32_32x32x16_bf16 v[112:127], v[128:131], v[136:139], v[112:127]
	v_xor_b32_e32 v233, 0x10000, v233
	v_xor_b32_e32 v237, 0x10000, v237
	v_mfma_f32_32x32x16_bf16 v[48:63], v[132:135], v[136:139], v[48:63]
	v_xor_b32_e32 v234, 0x10000, v234
	v_xor_b32_e32 v238, 0x10000, v238
	v_mfma_f32_32x32x16_bf16 v[96:111], v[128:131], v[140:143], v[96:111]
	v_xor_b32_e32 v235, 0x10000, v235
	v_xor_b32_e32 v239, 0x10000, v239
	v_mfma_f32_32x32x16_bf16 v[32:47], v[132:135], v[140:143], v[32:47]
	v_mfma_f32_32x32x16_bf16 v[80:95], v[128:131], v[144:147], v[80:95]
	v_mfma_f32_32x32x16_bf16 v[16:31], v[132:135], v[144:147], v[16:31]
	v_mfma_f32_32x32x16_bf16 v[64:79], v[128:131], v[148:151], v[64:79]
	v_mfma_f32_32x32x16_bf16 v[0:15], v[132:135], v[148:151], v[0:15]
	s_mul_i32 s2, s4, -9
	s_add_i32 s2, s2, s8
	s_lshl_b32 s2, s2, 8
	s_or_b32 s24, s2, s66
	s_ashr_i32 s58, s24, 6
	s_cmp_gt_i32 s58, 17
	s_cselect_b64 s[10:11], -1, 0
	s_cmp_gt_u32 s58, 19
	s_cselect_b64 s[2:3], -1, 0
	s_cmp_gt_i32 s58, 15
	s_cselect_b64 s[8:9], -1, 0
	s_cmp_lt_i32 s58, 16
	v_mov_b32_e32 v160, v195
	s_cselect_b64 s[4:5], -1, 0
	s_mov_b64 s[6:7], -1
	s_and_b64 vcc, exec, s[10:11]
	v_cndmask_b32_e64 v172, 0, 1, s[2:3]
	v_cmp_ne_u32_e64 s[2:3], 1, v172
	s_nop 3
	s_cbranch_vccz .LBB0_1474
	s_nop 3
	v_mov_b32_e32 v178, v112
	s_and_b64 vcc, exec, s[2:3]
	v_mov_b32_e32 v179, v96
	s_cbranch_vccnz .LBB0_1473
	v_mul_f32_e32 v172, 0xbfb8aa3b, v112
	v_mul_f32_e32 v173, 0xbfb8aa3b, v96
	v_exp_f32_e32 v172, v172
	v_exp_f32_e32 v173, v173
	v_add_f32_e32 v172, 1.0, v172
	v_add_f32_e32 v173, 1.0, v173
	v_rcp_f32_e32 v172, v172
	v_rcp_f32_e32 v173, v173
	s_nop 0
	v_pk_mul_f32 v[178:179], v[178:179], v[172:173]

.LBB0_1480:
	v_or_b32_e32 v173, 1, v209
	s_andn2_b64 vcc, exec, s[4:5]
	v_min_i32_e32 v178, 0x7fff, v173
	s_cbranch_vccnz .LBB0_1482
	v_ashrrev_i32_e32 v179, 31, v178
	v_lshlrev_b64 v[180:181], 8, v[178:179]
	v_mov_b32_e32 v173, v161
	s_waitcnt lgkmcnt(0)
	v_lshl_add_u64 v[180:181], s[4:5], 0, v[180:181]
	v_lshl_add_u64 v[180:181], v[180:181], 0, v[172:173]
	v_mov_b32_e32 v180, v130
	v_mov_b32_e32 v181, v131
	s_waitcnt vmcnt(0)
	v_pk_mul_f32 v[96:97], v[96:97], v[180:181] op_sel:[1,1] op_sel_hi:[1,0]
	s_nop 0
	v_pk_fma_f32 v[182:183], v[112:113], v[180:181], v[96:97] op_sel:[1,0,0] neg_lo:[0,0,1] neg_hi:[0,0,1]
	v_pk_fma_f32 v[96:97], v[112:113], v[180:181], v[96:97] op_sel:[1,0,0]
	s_nop 0
	v_mov_b32_e32 v183, v97
	v_pk_mul_f32 v[180:181], v[174:175], v[182:183] op_sel_hi:[0,1]

.LBB0_1486:
	v_or_b32_e32 v112, 2, v209
	s_andn2_b64 vcc, exec, s[4:5]
	v_min_i32_e32 v112, 0x7fff, v112
	s_cbranch_vccnz .LBB0_1488
	v_ashrrev_i32_e32 v113, 31, v112
	v_lshlrev_b64 v[96:97], 8, v[112:113]
	v_mov_b32_e32 v173, v161
	s_waitcnt lgkmcnt(0)
	v_lshl_add_u64 v[96:97], s[4:5], 0, v[96:97]
	v_lshl_add_u64 v[96:97], v[96:97], 0, v[172:173]
	v_mov_b32_e32 v96, v132
	v_mov_b32_e32 v97, v133
	s_waitcnt vmcnt(0)
	v_pk_mul_f32 v[180:181], v[98:99], v[96:97] op_sel:[0,1] op_sel_hi:[0,0]
	v_pk_fma_f32 v[182:183], v[114:115], v[96:97], v[180:181] neg_lo:[0,0,1] neg_hi:[0,0,1]
	v_pk_fma_f32 v[96:97], v[114:115], v[96:97], v[180:181] op_sel_hi:[0,1,1]
	v_mov_b32_e32 v183, v97
	v_pk_mul_f32 v[96:97], v[174:175], v[182:183] op_sel_hi:[0,1]

.LBB0_1492:
	v_or_b32_e32 v98, 3, v209
	s_andn2_b64 vcc, exec, s[4:5]
	v_min_i32_e32 v180, 0x7fff, v98
	s_cbranch_vccnz .LBB0_1494
	v_ashrrev_i32_e32 v181, 31, v180
	v_lshlrev_b64 v[96:97], 8, v[180:181]
	v_mov_b32_e32 v173, v161
	v_mov_b32_e32 v98, v99
	s_waitcnt lgkmcnt(0)
	v_lshl_add_u64 v[96:97], s[4:5], 0, v[96:97]
	v_lshl_add_u64 v[96:97], v[96:97], 0, v[172:173]
	v_mov_b32_e32 v96, v134
	v_mov_b32_e32 v97, v135
	v_mov_b32_e32 v114, v115
	s_waitcnt vmcnt(0)
	v_pk_mul_f32 v[98:99], v[98:99], v[96:97] op_sel:[0,1] op_sel_hi:[0,0]
	v_pk_fma_f32 v[182:183], v[114:115], v[96:97], v[98:99] op_sel_hi:[0,1,1] neg_lo:[0,0,1] neg_hi:[0,0,1]
	v_pk_fma_f32 v[96:97], v[114:115], v[96:97], v[98:99] op_sel_hi:[0,1,1]
	v_mov_b32_e32 v183, v97
	v_pk_mul_f32 v[96:97], v[174:175], v[182:183] op_sel_hi:[0,1]

.LBB0_1498:
	v_add_u32_e32 v98, 8, v209
	s_andn2_b64 vcc, exec, s[4:5]
	v_min_i32_e32 v114, 0x7fff, v98
	s_cbranch_vccnz .LBB0_1500
	v_ashrrev_i32_e32 v115, 31, v114
	v_lshlrev_b64 v[96:97], 8, v[114:115]
	v_mov_b32_e32 v173, v161
	s_waitcnt lgkmcnt(0)
	v_lshl_add_u64 v[96:97], s[4:5], 0, v[96:97]
	v_lshl_add_u64 v[96:97], v[96:97], 0, v[172:173]
	v_mov_b32_e32 v96, v136
	v_mov_b32_e32 v97, v137
	s_waitcnt vmcnt(0)
	v_pk_mul_f32 v[98:99], v[100:101], v[96:97] op_sel:[0,1] op_sel_hi:[0,0]
	v_pk_fma_f32 v[182:183], v[116:117], v[96:97], v[98:99] neg_lo:[0,0,1] neg_hi:[0,0,1]
	v_pk_fma_f32 v[96:97], v[116:117], v[96:97], v[98:99] op_sel_hi:[0,1,1]
	v_mov_b32_e32 v183, v97
	v_pk_mul_f32 v[96:97], v[174:175], v[182:183] op_sel_hi:[0,1]

.LBB0_1504:
	v_add_u32_e32 v98, 9, v209
	s_andn2_b64 vcc, exec, s[4:5]
	v_min_i32_e32 v182, 0x7fff, v98
	s_cbranch_vccnz .LBB0_1506
	v_ashrrev_i32_e32 v183, 31, v182
	v_lshlrev_b64 v[96:97], 8, v[182:183]
	v_mov_b32_e32 v173, v161
	v_mov_b32_e32 v98, v101
	s_waitcnt lgkmcnt(0)
	v_lshl_add_u64 v[96:97], s[4:5], 0, v[96:97]
	v_lshl_add_u64 v[96:97], v[96:97], 0, v[172:173]
	v_mov_b32_e32 v96, v138
	v_mov_b32_e32 v97, v139
	v_mov_b32_e32 v100, v117
	s_waitcnt vmcnt(0)
	v_pk_mul_f32 v[98:99], v[98:99], v[96:97] op_sel:[0,1] op_sel_hi:[0,0]
	v_pk_fma_f32 v[116:117], v[100:101], v[96:97], v[98:99] op_sel_hi:[0,1,1] neg_lo:[0,0,1] neg_hi:[0,0,1]
	v_pk_fma_f32 v[96:97], v[100:101], v[96:97], v[98:99] op_sel_hi:[0,1,1]
	v_mov_b32_e32 v117, v97
	v_pk_mul_f32 v[96:97], v[174:175], v[116:117] op_sel_hi:[0,1]

.LBB0_1510:
	v_add_u32_e32 v98, 10, v209
	s_andn2_b64 vcc, exec, s[4:5]
	v_min_i32_e32 v116, 0x7fff, v98
	s_cbranch_vccnz .LBB0_1512
	v_ashrrev_i32_e32 v117, 31, v116
	v_lshlrev_b64 v[96:97], 8, v[116:117]
	v_mov_b32_e32 v173, v161
	s_waitcnt lgkmcnt(0)
	v_lshl_add_u64 v[96:97], s[4:5], 0, v[96:97]
	v_lshl_add_u64 v[96:97], v[96:97], 0, v[172:173]
	v_mov_b32_e32 v96, v140
	v_mov_b32_e32 v97, v141
	s_waitcnt vmcnt(0)
	v_pk_mul_f32 v[98:99], v[102:103], v[96:97] op_sel:[0,1] op_sel_hi:[0,0]
	v_pk_fma_f32 v[100:101], v[118:119], v[96:97], v[98:99] neg_lo:[0,0,1] neg_hi:[0,0,1]
	v_pk_fma_f32 v[96:97], v[118:119], v[96:97], v[98:99] op_sel_hi:[0,1,1]
	v_mov_b32_e32 v101, v97
	v_pk_mul_f32 v[96:97], v[174:175], v[100:101] op_sel_hi:[0,1]

.LBB0_1516:
	v_add_u32_e32 v98, 11, v209
	s_andn2_b64 vcc, exec, s[4:5]
	v_min_i32_e32 v184, 0x7fff, v98
	s_cbranch_vccnz .LBB0_1518
	v_ashrrev_i32_e32 v185, 31, v184
	v_lshlrev_b64 v[96:97], 8, v[184:185]
	v_mov_b32_e32 v173, v161
	v_mov_b32_e32 v98, v103
	s_waitcnt lgkmcnt(0)
	v_lshl_add_u64 v[96:97], s[4:5], 0, v[96:97]
	v_lshl_add_u64 v[96:97], v[96:97], 0, v[172:173]
	v_mov_b32_e32 v96, v142
	v_mov_b32_e32 v97, v143
	v_mov_b32_e32 v100, v119
	s_waitcnt vmcnt(0)
	v_pk_mul_f32 v[98:99], v[98:99], v[96:97] op_sel:[0,1] op_sel_hi:[0,0]
	v_pk_fma_f32 v[102:103], v[100:101], v[96:97], v[98:99] op_sel_hi:[0,1,1] neg_lo:[0,0,1] neg_hi:[0,0,1]
	v_pk_fma_f32 v[96:97], v[100:101], v[96:97], v[98:99] op_sel_hi:[0,1,1]
	v_mov_b32_e32 v103, v97
	v_pk_mul_f32 v[96:97], v[174:175], v[102:103] op_sel_hi:[0,1]

.LBB0_1522:
	v_add_u32_e32 v98, 16, v209
	s_andn2_b64 vcc, exec, s[4:5]
	v_min_i32_e32 v118, 0x7fff, v98
	s_cbranch_vccnz .LBB0_1524
	v_ashrrev_i32_e32 v119, 31, v118
	v_lshlrev_b64 v[96:97], 8, v[118:119]
	v_mov_b32_e32 v173, v161
	s_waitcnt lgkmcnt(0)
	v_lshl_add_u64 v[96:97], s[4:5], 0, v[96:97]
	v_lshl_add_u64 v[96:97], v[96:97], 0, v[172:173]
	v_mov_b32_e32 v96, v144
	v_mov_b32_e32 v97, v145
	s_waitcnt vmcnt(0)
	v_pk_mul_f32 v[98:99], v[104:105], v[96:97] op_sel:[0,1] op_sel_hi:[0,0]
	v_pk_fma_f32 v[100:101], v[120:121], v[96:97], v[98:99] neg_lo:[0,0,1] neg_hi:[0,0,1]
	v_pk_fma_f32 v[96:97], v[120:121], v[96:97], v[98:99] op_sel_hi:[0,1,1]
	v_mov_b32_e32 v101, v97
	v_pk_mul_f32 v[96:97], v[174:175], v[100:101] op_sel_hi:[0,1]

.LBB0_1528:
	v_add_u32_e32 v98, 17, v209
	s_andn2_b64 vcc, exec, s[4:5]
	v_min_i32_e32 v186, 0x7fff, v98
	s_cbranch_vccnz .LBB0_1530
	v_ashrrev_i32_e32 v187, 31, v186
	v_lshlrev_b64 v[96:97], 8, v[186:187]
	v_mov_b32_e32 v173, v161
	v_mov_b32_e32 v98, v105
	s_waitcnt lgkmcnt(0)
	v_lshl_add_u64 v[96:97], s[4:5], 0, v[96:97]
	v_lshl_add_u64 v[96:97], v[96:97], 0, v[172:173]
	v_mov_b32_e32 v96, v146
	v_mov_b32_e32 v97, v147
	v_mov_b32_e32 v100, v121
	s_waitcnt vmcnt(0)
	v_pk_mul_f32 v[98:99], v[98:99], v[96:97] op_sel:[0,1] op_sel_hi:[0,0]
	v_pk_fma_f32 v[102:103], v[100:101], v[96:97], v[98:99] op_sel_hi:[0,1,1] neg_lo:[0,0,1] neg_hi:[0,0,1]
	v_pk_fma_f32 v[96:97], v[100:101], v[96:97], v[98:99] op_sel_hi:[0,1,1]
	v_mov_b32_e32 v103, v97
	v_pk_mul_f32 v[96:97], v[174:175], v[102:103] op_sel_hi:[0,1]

.LBB0_1534:
	v_add_u32_e32 v98, 18, v209
	s_andn2_b64 vcc, exec, s[4:5]
	v_min_i32_e32 v120, 0x7fff, v98
	s_cbranch_vccnz .LBB0_1536
	v_ashrrev_i32_e32 v121, 31, v120
	v_lshlrev_b64 v[96:97], 8, v[120:121]
	v_mov_b32_e32 v173, v161
	s_waitcnt lgkmcnt(0)
	v_lshl_add_u64 v[96:97], s[4:5], 0, v[96:97]
	v_lshl_add_u64 v[96:97], v[96:97], 0, v[172:173]
	v_mov_b32_e32 v96, v148
	v_mov_b32_e32 v97, v149
	s_waitcnt vmcnt(0)
	v_pk_mul_f32 v[98:99], v[106:107], v[96:97] op_sel:[0,1] op_sel_hi:[0,0]
	v_pk_fma_f32 v[100:101], v[122:123], v[96:97], v[98:99] neg_lo:[0,0,1] neg_hi:[0,0,1]
	v_pk_fma_f32 v[96:97], v[122:123], v[96:97], v[98:99] op_sel_hi:[0,1,1]
	v_mov_b32_e32 v101, v97
	v_pk_mul_f32 v[96:97], v[174:175], v[100:101] op_sel_hi:[0,1]

.LBB0_1540:
	v_add_u32_e32 v98, 19, v209
	s_andn2_b64 vcc, exec, s[4:5]
	v_min_i32_e32 v188, 0x7fff, v98
	s_cbranch_vccnz .LBB0_1542
	v_ashrrev_i32_e32 v189, 31, v188
	v_lshlrev_b64 v[96:97], 8, v[188:189]
	v_mov_b32_e32 v173, v161
	v_mov_b32_e32 v98, v107
	s_waitcnt lgkmcnt(0)
	v_lshl_add_u64 v[96:97], s[4:5], 0, v[96:97]
	v_lshl_add_u64 v[96:97], v[96:97], 0, v[172:173]
	v_mov_b32_e32 v96, v150
	v_mov_b32_e32 v97, v151
	v_mov_b32_e32 v100, v123
	s_waitcnt vmcnt(0)
	v_pk_mul_f32 v[98:99], v[98:99], v[96:97] op_sel:[0,1] op_sel_hi:[0,0]
	v_pk_fma_f32 v[102:103], v[100:101], v[96:97], v[98:99] op_sel_hi:[0,1,1] neg_lo:[0,0,1] neg_hi:[0,0,1]
	v_pk_fma_f32 v[96:97], v[100:101], v[96:97], v[98:99] op_sel_hi:[0,1,1]
	v_mov_b32_e32 v103, v97
	v_pk_mul_f32 v[96:97], v[174:175], v[102:103] op_sel_hi:[0,1]

.LBB0_1546:
	v_add_u32_e32 v98, 24, v209
	s_andn2_b64 vcc, exec, s[4:5]
	v_min_i32_e32 v122, 0x7fff, v98
	s_cbranch_vccnz .LBB0_1548
	v_ashrrev_i32_e32 v123, 31, v122
	v_lshlrev_b64 v[96:97], 8, v[122:123]
	v_mov_b32_e32 v173, v161
	s_waitcnt lgkmcnt(0)
	v_lshl_add_u64 v[96:97], s[4:5], 0, v[96:97]
	v_lshl_add_u64 v[96:97], v[96:97], 0, v[172:173]
	v_mov_b32_e32 v96, v152
	v_mov_b32_e32 v97, v153
	s_waitcnt vmcnt(0)
	v_pk_mul_f32 v[98:99], v[108:109], v[96:97] op_sel:[0,1] op_sel_hi:[0,0]
	v_pk_fma_f32 v[100:101], v[124:125], v[96:97], v[98:99] neg_lo:[0,0,1] neg_hi:[0,0,1]
	v_pk_fma_f32 v[96:97], v[124:125], v[96:97], v[98:99] op_sel_hi:[0,1,1]
	v_mov_b32_e32 v101, v97
	v_pk_mul_f32 v[96:97], v[174:175], v[100:101] op_sel_hi:[0,1]

.LBB0_1552:
	v_add_u32_e32 v98, 25, v209
	s_andn2_b64 vcc, exec, s[4:5]
	v_min_i32_e32 v190, 0x7fff, v98
	s_cbranch_vccnz .LBB0_1554
	v_ashrrev_i32_e32 v191, 31, v190
	v_lshlrev_b64 v[96:97], 8, v[190:191]
	v_mov_b32_e32 v173, v161
	v_mov_b32_e32 v98, v109
	s_waitcnt lgkmcnt(0)
	v_lshl_add_u64 v[96:97], s[4:5], 0, v[96:97]
	v_lshl_add_u64 v[96:97], v[96:97], 0, v[172:173]
	v_mov_b32_e32 v96, v154
	v_mov_b32_e32 v97, v155
	v_mov_b32_e32 v100, v125
	s_waitcnt vmcnt(0)
	v_pk_mul_f32 v[98:99], v[98:99], v[96:97] op_sel:[0,1] op_sel_hi:[0,0]
	v_pk_fma_f32 v[102:103], v[100:101], v[96:97], v[98:99] op_sel_hi:[0,1,1] neg_lo:[0,0,1] neg_hi:[0,0,1]
	v_pk_fma_f32 v[96:97], v[100:101], v[96:97], v[98:99] op_sel_hi:[0,1,1]
	v_mov_b32_e32 v103, v97
	v_pk_mul_f32 v[96:97], v[174:175], v[102:103] op_sel_hi:[0,1]

.LBB0_1558:
	v_add_u32_e32 v98, 26, v209
	s_andn2_b64 vcc, exec, s[4:5]
	v_min_i32_e32 v108, 0x7fff, v98
	s_cbranch_vccnz .LBB0_1560
	v_ashrrev_i32_e32 v109, 31, v108
	v_lshlrev_b64 v[96:97], 8, v[108:109]
	v_mov_b32_e32 v173, v161
	s_waitcnt lgkmcnt(0)
	v_lshl_add_u64 v[96:97], s[4:5], 0, v[96:97]
	v_lshl_add_u64 v[96:97], v[96:97], 0, v[172:173]
	v_mov_b32_e32 v96, v156
	v_mov_b32_e32 v97, v157
	s_waitcnt vmcnt(0)
	v_pk_mul_f32 v[98:99], v[110:111], v[96:97] op_sel:[0,1] op_sel_hi:[0,0]
	v_pk_fma_f32 v[100:101], v[126:127], v[96:97], v[98:99] neg_lo:[0,0,1] neg_hi:[0,0,1]
	v_pk_fma_f32 v[96:97], v[126:127], v[96:97], v[98:99] op_sel_hi:[0,1,1]
	v_mov_b32_e32 v101, v97
	v_pk_mul_f32 v[96:97], v[174:175], v[100:101] op_sel_hi:[0,1]

.LBB0_1564:
	v_add_u32_e32 v98, 27, v209
	s_andn2_b64 vcc, exec, s[4:5]
	v_min_i32_e32 v124, 0x7fff, v98
	s_cbranch_vccnz .LBB0_1566
	v_ashrrev_i32_e32 v125, 31, v124
	v_lshlrev_b64 v[96:97], 8, v[124:125]
	v_mov_b32_e32 v173, v161
	v_mov_b32_e32 v98, v111
	s_waitcnt lgkmcnt(0)
	v_lshl_add_u64 v[96:97], s[4:5], 0, v[96:97]
	v_lshl_add_u64 v[96:97], v[96:97], 0, v[172:173]
	v_mov_b32_e32 v96, v158
	v_mov_b32_e32 v97, v159
	v_mov_b32_e32 v100, v127
	s_waitcnt vmcnt(0)
	v_pk_mul_f32 v[98:99], v[98:99], v[96:97] op_sel:[0,1] op_sel_hi:[0,0]
	v_pk_fma_f32 v[102:103], v[100:101], v[96:97], v[98:99] op_sel_hi:[0,1,1] neg_lo:[0,0,1] neg_hi:[0,0,1]
	v_pk_fma_f32 v[96:97], v[100:101], v[96:97], v[98:99] op_sel_hi:[0,1,1]
	v_mov_b32_e32 v103, v97
	v_pk_mul_f32 v[96:97], v[174:175], v[102:103] op_sel_hi:[0,1]

.LBB0_1632:
	s_andn2_b64 vcc, exec, s[58:59]
	s_cbranch_vccnz .LBB0_1634
	v_ashrrev_i32_e32 v179, 31, v178
	v_lshlrev_b64 v[98:99], 8, v[178:179]
	v_mov_b32_e32 v173, v161
	s_waitcnt lgkmcnt(0)
	v_lshl_add_u64 v[98:99], s[58:59], 0, v[98:99]
	v_lshl_add_u64 v[98:99], v[98:99], 0, v[172:173]
	v_mov_b32_e32 v98, v130
	v_mov_b32_e32 v99, v131
	s_waitcnt vmcnt(0)
	v_pk_mul_f32 v[64:65], v[64:65], v[98:99] op_sel:[1,1] op_sel_hi:[1,0]
	s_nop 0
	v_pk_fma_f32 v[110:111], v[80:81], v[98:99], v[64:65] op_sel:[1,0,0] neg_lo:[0,0,1] neg_hi:[0,0,1]
	v_pk_fma_f32 v[64:65], v[80:81], v[98:99], v[64:65] op_sel:[1,0,0]
	s_nop 0
	v_mov_b32_e32 v111, v65
	v_pk_mul_f32 v[98:99], v[96:97], v[110:111] op_sel_hi:[0,1]

.LBB0_1638:
	s_andn2_b64 vcc, exec, s[58:59]
	s_cbranch_vccnz .LBB0_1640
	v_ashrrev_i32_e32 v113, 31, v112
	v_lshlrev_b64 v[64:65], 8, v[112:113]
	v_mov_b32_e32 v173, v161
	s_waitcnt lgkmcnt(0)
	v_lshl_add_u64 v[64:65], s[58:59], 0, v[64:65]
	v_lshl_add_u64 v[64:65], v[64:65], 0, v[172:173]
	v_mov_b32_e32 v64, v132
	v_mov_b32_e32 v65, v133
	s_waitcnt vmcnt(0)
	v_pk_mul_f32 v[80:81], v[66:67], v[64:65] op_sel:[0,1] op_sel_hi:[0,0]
	v_pk_fma_f32 v[98:99], v[82:83], v[64:65], v[80:81] neg_lo:[0,0,1] neg_hi:[0,0,1]
	v_pk_fma_f32 v[64:65], v[82:83], v[64:65], v[80:81] op_sel_hi:[0,1,1]
	v_mov_b32_e32 v99, v65
	v_pk_mul_f32 v[64:65], v[96:97], v[98:99] op_sel_hi:[0,1]

.LBB0_1644:
	s_andn2_b64 vcc, exec, s[58:59]
	s_cbranch_vccnz .LBB0_1646
	v_ashrrev_i32_e32 v181, 31, v180
	v_lshlrev_b64 v[64:65], 8, v[180:181]
	v_mov_b32_e32 v173, v161
	v_mov_b32_e32 v66, v67
	s_waitcnt lgkmcnt(0)
	v_lshl_add_u64 v[64:65], s[58:59], 0, v[64:65]
	v_lshl_add_u64 v[64:65], v[64:65], 0, v[172:173]
	v_mov_b32_e32 v64, v134
	v_mov_b32_e32 v65, v135
	v_mov_b32_e32 v80, v83
	s_waitcnt vmcnt(0)
	v_pk_mul_f32 v[66:67], v[66:67], v[64:65] op_sel:[0,1] op_sel_hi:[0,0]
	v_pk_fma_f32 v[82:83], v[80:81], v[64:65], v[66:67] op_sel_hi:[0,1,1] neg_lo:[0,0,1] neg_hi:[0,0,1]
	v_pk_fma_f32 v[64:65], v[80:81], v[64:65], v[66:67] op_sel_hi:[0,1,1]
	v_mov_b32_e32 v83, v65
	v_pk_mul_f32 v[64:65], v[96:97], v[82:83] op_sel_hi:[0,1]

.LBB0_1650:
	s_andn2_b64 vcc, exec, s[58:59]
	s_cbranch_vccnz .LBB0_1652
	v_ashrrev_i32_e32 v115, 31, v114
	v_lshlrev_b64 v[64:65], 8, v[114:115]
	v_mov_b32_e32 v173, v161
	s_waitcnt lgkmcnt(0)
	v_lshl_add_u64 v[64:65], s[58:59], 0, v[64:65]
	v_lshl_add_u64 v[64:65], v[64:65], 0, v[172:173]
	v_mov_b32_e32 v64, v136
	v_mov_b32_e32 v65, v137
	s_waitcnt vmcnt(0)
	v_pk_mul_f32 v[66:67], v[68:69], v[64:65] op_sel:[0,1] op_sel_hi:[0,0]
	v_pk_fma_f32 v[80:81], v[84:85], v[64:65], v[66:67] neg_lo:[0,0,1] neg_hi:[0,0,1]
	v_pk_fma_f32 v[64:65], v[84:85], v[64:65], v[66:67] op_sel_hi:[0,1,1]
	v_mov_b32_e32 v81, v65
	v_pk_mul_f32 v[64:65], v[96:97], v[80:81] op_sel_hi:[0,1]

.LBB0_1656:
	s_andn2_b64 vcc, exec, s[58:59]
	s_cbranch_vccnz .LBB0_1658
	v_ashrrev_i32_e32 v183, 31, v182
	v_lshlrev_b64 v[64:65], 8, v[182:183]
	v_mov_b32_e32 v173, v161
	v_mov_b32_e32 v66, v69
	s_waitcnt lgkmcnt(0)
	v_lshl_add_u64 v[64:65], s[58:59], 0, v[64:65]
	v_lshl_add_u64 v[64:65], v[64:65], 0, v[172:173]
	v_mov_b32_e32 v64, v138
	v_mov_b32_e32 v65, v139
	v_mov_b32_e32 v68, v85
	s_waitcnt vmcnt(0)
	v_pk_mul_f32 v[66:67], v[66:67], v[64:65] op_sel:[0,1] op_sel_hi:[0,0]
	v_pk_fma_f32 v[80:81], v[68:69], v[64:65], v[66:67] op_sel_hi:[0,1,1] neg_lo:[0,0,1] neg_hi:[0,0,1]
	v_pk_fma_f32 v[64:65], v[68:69], v[64:65], v[66:67] op_sel_hi:[0,1,1]
	v_mov_b32_e32 v81, v65
	v_pk_mul_f32 v[64:65], v[96:97], v[80:81] op_sel_hi:[0,1]

.LBB0_1662:
	s_andn2_b64 vcc, exec, s[58:59]
	s_cbranch_vccnz .LBB0_1664
	v_ashrrev_i32_e32 v117, 31, v116
	v_lshlrev_b64 v[64:65], 8, v[116:117]
	v_mov_b32_e32 v173, v161
	s_waitcnt lgkmcnt(0)
	v_lshl_add_u64 v[64:65], s[58:59], 0, v[64:65]
	v_lshl_add_u64 v[64:65], v[64:65], 0, v[172:173]
	v_mov_b32_e32 v64, v140
	v_mov_b32_e32 v65, v141
	s_waitcnt vmcnt(0)
	v_pk_mul_f32 v[66:67], v[70:71], v[64:65] op_sel:[0,1] op_sel_hi:[0,0]
	v_pk_fma_f32 v[68:69], v[86:87], v[64:65], v[66:67] neg_lo:[0,0,1] neg_hi:[0,0,1]
	v_pk_fma_f32 v[64:65], v[86:87], v[64:65], v[66:67] op_sel_hi:[0,1,1]
	v_mov_b32_e32 v69, v65
	v_pk_mul_f32 v[64:65], v[96:97], v[68:69] op_sel_hi:[0,1]

.LBB0_1668:
	s_andn2_b64 vcc, exec, s[58:59]
	s_cbranch_vccnz .LBB0_1670
	v_ashrrev_i32_e32 v185, 31, v184
	v_lshlrev_b64 v[64:65], 8, v[184:185]
	v_mov_b32_e32 v173, v161
	v_mov_b32_e32 v66, v71
	s_waitcnt lgkmcnt(0)
	v_lshl_add_u64 v[64:65], s[58:59], 0, v[64:65]
	v_lshl_add_u64 v[64:65], v[64:65], 0, v[172:173]
	v_mov_b32_e32 v64, v142
	v_mov_b32_e32 v65, v143
	v_mov_b32_e32 v68, v87
	s_waitcnt vmcnt(0)
	v_pk_mul_f32 v[66:67], v[66:67], v[64:65] op_sel:[0,1] op_sel_hi:[0,0]
	v_pk_fma_f32 v[70:71], v[68:69], v[64:65], v[66:67] op_sel_hi:[0,1,1] neg_lo:[0,0,1] neg_hi:[0,0,1]
	v_pk_fma_f32 v[64:65], v[68:69], v[64:65], v[66:67] op_sel_hi:[0,1,1]
	v_mov_b32_e32 v71, v65
	v_pk_mul_f32 v[64:65], v[96:97], v[70:71] op_sel_hi:[0,1]

.LBB0_1674:
	s_andn2_b64 vcc, exec, s[58:59]
	s_cbranch_vccnz .LBB0_1676
	v_ashrrev_i32_e32 v119, 31, v118
	v_lshlrev_b64 v[64:65], 8, v[118:119]
	v_mov_b32_e32 v173, v161
	s_waitcnt lgkmcnt(0)
	v_lshl_add_u64 v[64:65], s[58:59], 0, v[64:65]
	v_lshl_add_u64 v[64:65], v[64:65], 0, v[172:173]
	v_mov_b32_e32 v64, v144
	v_mov_b32_e32 v65, v145
	s_waitcnt vmcnt(0)
	v_pk_mul_f32 v[66:67], v[72:73], v[64:65] op_sel:[0,1] op_sel_hi:[0,0]
	v_pk_fma_f32 v[68:69], v[88:89], v[64:65], v[66:67] neg_lo:[0,0,1] neg_hi:[0,0,1]
	v_pk_fma_f32 v[64:65], v[88:89], v[64:65], v[66:67] op_sel_hi:[0,1,1]
	v_mov_b32_e32 v69, v65
	v_pk_mul_f32 v[64:65], v[96:97], v[68:69] op_sel_hi:[0,1]

.LBB0_1680:
	s_andn2_b64 vcc, exec, s[58:59]
	s_cbranch_vccnz .LBB0_1682
	v_ashrrev_i32_e32 v187, 31, v186
	v_lshlrev_b64 v[64:65], 8, v[186:187]
	v_mov_b32_e32 v173, v161
	v_mov_b32_e32 v66, v73
	s_waitcnt lgkmcnt(0)
	v_lshl_add_u64 v[64:65], s[58:59], 0, v[64:65]
	v_lshl_add_u64 v[64:65], v[64:65], 0, v[172:173]
	v_mov_b32_e32 v64, v146
	v_mov_b32_e32 v65, v147
	v_mov_b32_e32 v68, v89
	s_waitcnt vmcnt(0)
	v_pk_mul_f32 v[66:67], v[66:67], v[64:65] op_sel:[0,1] op_sel_hi:[0,0]
	v_pk_fma_f32 v[70:71], v[68:69], v[64:65], v[66:67] op_sel_hi:[0,1,1] neg_lo:[0,0,1] neg_hi:[0,0,1]
	v_pk_fma_f32 v[64:65], v[68:69], v[64:65], v[66:67] op_sel_hi:[0,1,1]
	v_mov_b32_e32 v71, v65
	v_pk_mul_f32 v[64:65], v[96:97], v[70:71] op_sel_hi:[0,1]

.LBB0_1686:
	s_andn2_b64 vcc, exec, s[58:59]
	s_cbranch_vccnz .LBB0_1688
	v_ashrrev_i32_e32 v121, 31, v120
	v_lshlrev_b64 v[64:65], 8, v[120:121]
	v_mov_b32_e32 v173, v161
	s_waitcnt lgkmcnt(0)
	v_lshl_add_u64 v[64:65], s[58:59], 0, v[64:65]
	v_lshl_add_u64 v[64:65], v[64:65], 0, v[172:173]
	v_mov_b32_e32 v64, v148
	v_mov_b32_e32 v65, v149
	s_waitcnt vmcnt(0)
	v_pk_mul_f32 v[66:67], v[74:75], v[64:65] op_sel:[0,1] op_sel_hi:[0,0]
	v_pk_fma_f32 v[68:69], v[90:91], v[64:65], v[66:67] neg_lo:[0,0,1] neg_hi:[0,0,1]
	v_pk_fma_f32 v[64:65], v[90:91], v[64:65], v[66:67] op_sel_hi:[0,1,1]
	v_mov_b32_e32 v69, v65
	v_pk_mul_f32 v[64:65], v[96:97], v[68:69] op_sel_hi:[0,1]

.LBB0_1692:
	s_andn2_b64 vcc, exec, s[58:59]
	s_cbranch_vccnz .LBB0_1694
	v_ashrrev_i32_e32 v189, 31, v188
	v_lshlrev_b64 v[64:65], 8, v[188:189]
	v_mov_b32_e32 v173, v161
	v_mov_b32_e32 v66, v75
	s_waitcnt lgkmcnt(0)
	v_lshl_add_u64 v[64:65], s[58:59], 0, v[64:65]
	v_lshl_add_u64 v[64:65], v[64:65], 0, v[172:173]
	v_mov_b32_e32 v64, v150
	v_mov_b32_e32 v65, v151
	v_mov_b32_e32 v68, v91
	s_waitcnt vmcnt(0)
	v_pk_mul_f32 v[66:67], v[66:67], v[64:65] op_sel:[0,1] op_sel_hi:[0,0]
	v_pk_fma_f32 v[70:71], v[68:69], v[64:65], v[66:67] op_sel_hi:[0,1,1] neg_lo:[0,0,1] neg_hi:[0,0,1]
	v_pk_fma_f32 v[64:65], v[68:69], v[64:65], v[66:67] op_sel_hi:[0,1,1]
	v_mov_b32_e32 v71, v65
	v_pk_mul_f32 v[64:65], v[96:97], v[70:71] op_sel_hi:[0,1]

.LBB0_1698:
	s_andn2_b64 vcc, exec, s[58:59]
	s_cbranch_vccnz .LBB0_1700
	v_ashrrev_i32_e32 v123, 31, v122
	v_lshlrev_b64 v[64:65], 8, v[122:123]
	v_mov_b32_e32 v173, v161
	s_waitcnt lgkmcnt(0)
	v_lshl_add_u64 v[64:65], s[58:59], 0, v[64:65]
	v_lshl_add_u64 v[64:65], v[64:65], 0, v[172:173]
	v_mov_b32_e32 v64, v152
	v_mov_b32_e32 v65, v153
	s_waitcnt vmcnt(0)
	v_pk_mul_f32 v[66:67], v[76:77], v[64:65] op_sel:[0,1] op_sel_hi:[0,0]
	v_pk_fma_f32 v[68:69], v[92:93], v[64:65], v[66:67] neg_lo:[0,0,1] neg_hi:[0,0,1]
	v_pk_fma_f32 v[64:65], v[92:93], v[64:65], v[66:67] op_sel_hi:[0,1,1]
	v_mov_b32_e32 v69, v65
	v_pk_mul_f32 v[64:65], v[96:97], v[68:69] op_sel_hi:[0,1]

.LBB0_1704:
	s_andn2_b64 vcc, exec, s[58:59]
	s_cbranch_vccnz .LBB0_1706
	v_ashrrev_i32_e32 v191, 31, v190
	v_lshlrev_b64 v[64:65], 8, v[190:191]
	v_mov_b32_e32 v173, v161
	v_mov_b32_e32 v66, v77
	s_waitcnt lgkmcnt(0)
	v_lshl_add_u64 v[64:65], s[58:59], 0, v[64:65]
	v_lshl_add_u64 v[64:65], v[64:65], 0, v[172:173]
	v_mov_b32_e32 v64, v154
	v_mov_b32_e32 v65, v155
	v_mov_b32_e32 v68, v93
	s_waitcnt vmcnt(0)
	v_pk_mul_f32 v[66:67], v[66:67], v[64:65] op_sel:[0,1] op_sel_hi:[0,0]
	v_pk_fma_f32 v[70:71], v[68:69], v[64:65], v[66:67] op_sel_hi:[0,1,1] neg_lo:[0,0,1] neg_hi:[0,0,1]
	v_pk_fma_f32 v[64:65], v[68:69], v[64:65], v[66:67] op_sel_hi:[0,1,1]
	v_mov_b32_e32 v71, v65
	v_pk_mul_f32 v[64:65], v[96:97], v[70:71] op_sel_hi:[0,1]

.LBB0_1710:
	s_andn2_b64 vcc, exec, s[58:59]
	s_cbranch_vccnz .LBB0_1712
	v_ashrrev_i32_e32 v109, 31, v108
	v_lshlrev_b64 v[64:65], 8, v[108:109]
	v_mov_b32_e32 v173, v161
	s_waitcnt lgkmcnt(0)
	v_lshl_add_u64 v[64:65], s[58:59], 0, v[64:65]
	v_lshl_add_u64 v[64:65], v[64:65], 0, v[172:173]
	v_mov_b32_e32 v64, v156
	v_mov_b32_e32 v65, v157
	s_waitcnt vmcnt(0)
	v_pk_mul_f32 v[66:67], v[78:79], v[64:65] op_sel:[0,1] op_sel_hi:[0,0]
	v_pk_fma_f32 v[68:69], v[94:95], v[64:65], v[66:67] neg_lo:[0,0,1] neg_hi:[0,0,1]
	v_pk_fma_f32 v[64:65], v[94:95], v[64:65], v[66:67] op_sel_hi:[0,1,1]
	v_mov_b32_e32 v69, v65
	v_pk_mul_f32 v[64:65], v[96:97], v[68:69] op_sel_hi:[0,1]

.LBB0_1716:
	s_andn2_b64 vcc, exec, s[58:59]
	s_cbranch_vccnz .LBB0_1718
	v_ashrrev_i32_e32 v125, 31, v124
	v_lshlrev_b64 v[64:65], 8, v[124:125]
	v_mov_b32_e32 v173, v161
	v_mov_b32_e32 v66, v79
	s_waitcnt lgkmcnt(0)
	v_lshl_add_u64 v[64:65], s[58:59], 0, v[64:65]
	v_lshl_add_u64 v[64:65], v[64:65], 0, v[172:173]
	v_mov_b32_e32 v64, v158
	v_mov_b32_e32 v65, v159
	v_mov_b32_e32 v68, v95
	s_waitcnt vmcnt(0)
	v_pk_mul_f32 v[66:67], v[66:67], v[64:65] op_sel:[0,1] op_sel_hi:[0,0]
	v_pk_fma_f32 v[70:71], v[68:69], v[64:65], v[66:67] op_sel_hi:[0,1,1] neg_lo:[0,0,1] neg_hi:[0,0,1]
	v_pk_fma_f32 v[64:65], v[68:69], v[64:65], v[66:67] op_sel_hi:[0,1,1]
	v_mov_b32_e32 v71, v65
	v_pk_mul_f32 v[64:65], v[96:97], v[70:71] op_sel_hi:[0,1]

.LBB0_1784:
	v_or_b32_e32 v64, 1, v80
	s_andn2_b64 vcc, exec, s[14:15]
	v_min_i32_e32 v64, 0x7fff, v64
	s_cbranch_vccnz .LBB0_1786
	v_ashrrev_i32_e32 v65, 31, v64
	v_lshlrev_b64 v[68:69], 8, v[64:65]
	v_mov_b32_e32 v173, v161
	s_waitcnt lgkmcnt(0)
	v_lshl_add_u64 v[68:69], s[14:15], 0, v[68:69]
	v_lshl_add_u64 v[68:69], v[68:69], 0, v[172:173]
	v_mov_b32_e32 v68, v130
	v_mov_b32_e32 v69, v131
	s_waitcnt vmcnt(0)
	v_pk_mul_f32 v[32:33], v[32:33], v[68:69] op_sel:[1,1] op_sel_hi:[1,0]
	s_nop 0
	v_pk_fma_f32 v[70:71], v[48:49], v[68:69], v[32:33] op_sel:[1,0,0] neg_lo:[0,0,1] neg_hi:[0,0,1]
	v_pk_fma_f32 v[32:33], v[48:49], v[68:69], v[32:33] op_sel:[1,0,0]
	s_nop 0
	v_mov_b32_e32 v71, v33
	v_pk_mul_f32 v[68:69], v[174:175], v[70:71] op_sel_hi:[0,1]

.LBB0_1790:
	v_or_b32_e32 v48, 2, v80
	s_andn2_b64 vcc, exec, s[14:15]
	v_min_i32_e32 v48, 0x7fff, v48
	s_cbranch_vccnz .LBB0_1792
	v_ashrrev_i32_e32 v49, 31, v48
	v_lshlrev_b64 v[32:33], 8, v[48:49]
	v_mov_b32_e32 v173, v161
	s_waitcnt lgkmcnt(0)
	v_lshl_add_u64 v[32:33], s[14:15], 0, v[32:33]
	v_lshl_add_u64 v[32:33], v[32:33], 0, v[172:173]
	v_mov_b32_e32 v32, v132
	v_mov_b32_e32 v33, v133
	s_waitcnt vmcnt(0)
	v_pk_mul_f32 v[68:69], v[34:35], v[32:33] op_sel:[0,1] op_sel_hi:[0,0]
	v_pk_fma_f32 v[70:71], v[50:51], v[32:33], v[68:69] neg_lo:[0,0,1] neg_hi:[0,0,1]
	v_pk_fma_f32 v[32:33], v[50:51], v[32:33], v[68:69] op_sel_hi:[0,1,1]
	v_mov_b32_e32 v71, v33
	v_pk_mul_f32 v[32:33], v[174:175], v[70:71] op_sel_hi:[0,1]

.LBB0_1796:
	v_or_b32_e32 v34, 3, v80
	s_andn2_b64 vcc, exec, s[14:15]
	v_min_i32_e32 v68, 0x7fff, v34
	s_cbranch_vccnz .LBB0_1798
	v_ashrrev_i32_e32 v69, 31, v68
	v_lshlrev_b64 v[32:33], 8, v[68:69]
	v_mov_b32_e32 v173, v161
	v_mov_b32_e32 v34, v35
	s_waitcnt lgkmcnt(0)
	v_lshl_add_u64 v[32:33], s[14:15], 0, v[32:33]
	v_lshl_add_u64 v[32:33], v[32:33], 0, v[172:173]
	v_mov_b32_e32 v32, v134
	v_mov_b32_e32 v33, v135
	v_mov_b32_e32 v50, v51
	s_waitcnt vmcnt(0)
	v_pk_mul_f32 v[34:35], v[34:35], v[32:33] op_sel:[0,1] op_sel_hi:[0,0]
	v_pk_fma_f32 v[70:71], v[50:51], v[32:33], v[34:35] op_sel_hi:[0,1,1] neg_lo:[0,0,1] neg_hi:[0,0,1]
	v_pk_fma_f32 v[32:33], v[50:51], v[32:33], v[34:35] op_sel_hi:[0,1,1]
	v_mov_b32_e32 v71, v33
	v_pk_mul_f32 v[32:33], v[174:175], v[70:71] op_sel_hi:[0,1]

.LBB0_1802:
	v_add_u32_e32 v34, 8, v80
	s_andn2_b64 vcc, exec, s[14:15]
	v_min_i32_e32 v50, 0x7fff, v34
	s_cbranch_vccnz .LBB0_1804
	v_ashrrev_i32_e32 v51, 31, v50
	v_lshlrev_b64 v[32:33], 8, v[50:51]
	v_mov_b32_e32 v173, v161
	s_waitcnt lgkmcnt(0)
	v_lshl_add_u64 v[32:33], s[14:15], 0, v[32:33]
	v_lshl_add_u64 v[32:33], v[32:33], 0, v[172:173]
	v_mov_b32_e32 v32, v136
	v_mov_b32_e32 v33, v137
	s_waitcnt vmcnt(0)
	v_pk_mul_f32 v[34:35], v[36:37], v[32:33] op_sel:[0,1] op_sel_hi:[0,0]
	v_pk_fma_f32 v[70:71], v[52:53], v[32:33], v[34:35] neg_lo:[0,0,1] neg_hi:[0,0,1]
	v_pk_fma_f32 v[32:33], v[52:53], v[32:33], v[34:35] op_sel_hi:[0,1,1]
	v_mov_b32_e32 v71, v33
	v_pk_mul_f32 v[32:33], v[174:175], v[70:71] op_sel_hi:[0,1]

.LBB0_1808:
	v_add_u32_e32 v34, 9, v80
	s_andn2_b64 vcc, exec, s[14:15]
	v_min_i32_e32 v70, 0x7fff, v34
	s_cbranch_vccnz .LBB0_1810
	v_ashrrev_i32_e32 v71, 31, v70
	v_lshlrev_b64 v[32:33], 8, v[70:71]
	v_mov_b32_e32 v173, v161
	v_mov_b32_e32 v34, v37
	s_waitcnt lgkmcnt(0)
	v_lshl_add_u64 v[32:33], s[14:15], 0, v[32:33]
	v_lshl_add_u64 v[32:33], v[32:33], 0, v[172:173]
	v_mov_b32_e32 v32, v138
	v_mov_b32_e32 v33, v139
	v_mov_b32_e32 v36, v53
	s_waitcnt vmcnt(0)
	v_pk_mul_f32 v[34:35], v[34:35], v[32:33] op_sel:[0,1] op_sel_hi:[0,0]
	v_pk_fma_f32 v[52:53], v[36:37], v[32:33], v[34:35] op_sel_hi:[0,1,1] neg_lo:[0,0,1] neg_hi:[0,0,1]
	v_pk_fma_f32 v[32:33], v[36:37], v[32:33], v[34:35] op_sel_hi:[0,1,1]
	v_mov_b32_e32 v53, v33
	v_pk_mul_f32 v[32:33], v[174:175], v[52:53] op_sel_hi:[0,1]

.LBB0_1814:
	v_add_u32_e32 v34, 10, v80
	s_andn2_b64 vcc, exec, s[14:15]
	v_min_i32_e32 v52, 0x7fff, v34
	s_cbranch_vccnz .LBB0_1816
	v_ashrrev_i32_e32 v53, 31, v52
	v_lshlrev_b64 v[32:33], 8, v[52:53]
	v_mov_b32_e32 v173, v161
	s_waitcnt lgkmcnt(0)
	v_lshl_add_u64 v[32:33], s[14:15], 0, v[32:33]
	v_lshl_add_u64 v[32:33], v[32:33], 0, v[172:173]
	v_mov_b32_e32 v32, v140
	v_mov_b32_e32 v33, v141
	s_waitcnt vmcnt(0)
	v_pk_mul_f32 v[34:35], v[38:39], v[32:33] op_sel:[0,1] op_sel_hi:[0,0]
	v_pk_fma_f32 v[36:37], v[54:55], v[32:33], v[34:35] neg_lo:[0,0,1] neg_hi:[0,0,1]
	v_pk_fma_f32 v[32:33], v[54:55], v[32:33], v[34:35] op_sel_hi:[0,1,1]
	v_mov_b32_e32 v37, v33
	v_pk_mul_f32 v[32:33], v[174:175], v[36:37] op_sel_hi:[0,1]

.LBB0_1820:
	v_add_u32_e32 v34, 11, v80
	s_andn2_b64 vcc, exec, s[14:15]
	v_min_i32_e32 v72, 0x7fff, v34
	s_cbranch_vccnz .LBB0_1822
	v_ashrrev_i32_e32 v73, 31, v72
	v_lshlrev_b64 v[32:33], 8, v[72:73]
	v_mov_b32_e32 v173, v161
	v_mov_b32_e32 v34, v39
	s_waitcnt lgkmcnt(0)
	v_lshl_add_u64 v[32:33], s[14:15], 0, v[32:33]
	v_lshl_add_u64 v[32:33], v[32:33], 0, v[172:173]
	v_mov_b32_e32 v32, v142
	v_mov_b32_e32 v33, v143
	v_mov_b32_e32 v36, v55
	s_waitcnt vmcnt(0)
	v_pk_mul_f32 v[34:35], v[34:35], v[32:33] op_sel:[0,1] op_sel_hi:[0,0]
	v_pk_fma_f32 v[38:39], v[36:37], v[32:33], v[34:35] op_sel_hi:[0,1,1] neg_lo:[0,0,1] neg_hi:[0,0,1]
	v_pk_fma_f32 v[32:33], v[36:37], v[32:33], v[34:35] op_sel_hi:[0,1,1]
	v_mov_b32_e32 v39, v33
	v_pk_mul_f32 v[32:33], v[174:175], v[38:39] op_sel_hi:[0,1]

.LBB0_1826:
	v_add_u32_e32 v34, 16, v80
	s_andn2_b64 vcc, exec, s[14:15]
	v_min_i32_e32 v54, 0x7fff, v34
	s_cbranch_vccnz .LBB0_1828
	v_ashrrev_i32_e32 v55, 31, v54
	v_lshlrev_b64 v[32:33], 8, v[54:55]
	v_mov_b32_e32 v173, v161
	s_waitcnt lgkmcnt(0)
	v_lshl_add_u64 v[32:33], s[14:15], 0, v[32:33]
	v_lshl_add_u64 v[32:33], v[32:33], 0, v[172:173]
	v_mov_b32_e32 v32, v144
	v_mov_b32_e32 v33, v145
	s_waitcnt vmcnt(0)
	v_pk_mul_f32 v[34:35], v[40:41], v[32:33] op_sel:[0,1] op_sel_hi:[0,0]
	v_pk_fma_f32 v[36:37], v[56:57], v[32:33], v[34:35] neg_lo:[0,0,1] neg_hi:[0,0,1]
	v_pk_fma_f32 v[32:33], v[56:57], v[32:33], v[34:35] op_sel_hi:[0,1,1]
	v_mov_b32_e32 v37, v33
	v_pk_mul_f32 v[32:33], v[174:175], v[36:37] op_sel_hi:[0,1]

.LBB0_1832:
	v_add_u32_e32 v34, 17, v80
	s_andn2_b64 vcc, exec, s[14:15]
	v_min_i32_e32 v74, 0x7fff, v34
	s_cbranch_vccnz .LBB0_1834
	v_ashrrev_i32_e32 v75, 31, v74
	v_lshlrev_b64 v[32:33], 8, v[74:75]
	v_mov_b32_e32 v173, v161
	v_mov_b32_e32 v34, v41
	s_waitcnt lgkmcnt(0)
	v_lshl_add_u64 v[32:33], s[14:15], 0, v[32:33]
	v_lshl_add_u64 v[32:33], v[32:33], 0, v[172:173]
	v_mov_b32_e32 v32, v146
	v_mov_b32_e32 v33, v147
	v_mov_b32_e32 v36, v57
	s_waitcnt vmcnt(0)
	v_pk_mul_f32 v[34:35], v[34:35], v[32:33] op_sel:[0,1] op_sel_hi:[0,0]
	v_pk_fma_f32 v[38:39], v[36:37], v[32:33], v[34:35] op_sel_hi:[0,1,1] neg_lo:[0,0,1] neg_hi:[0,0,1]
	v_pk_fma_f32 v[32:33], v[36:37], v[32:33], v[34:35] op_sel_hi:[0,1,1]
	v_mov_b32_e32 v39, v33
	v_pk_mul_f32 v[32:33], v[174:175], v[38:39] op_sel_hi:[0,1]

.LBB0_1838:
	v_add_u32_e32 v34, 18, v80
	s_andn2_b64 vcc, exec, s[14:15]
	v_min_i32_e32 v56, 0x7fff, v34
	s_cbranch_vccnz .LBB0_1840
	v_ashrrev_i32_e32 v57, 31, v56
	v_lshlrev_b64 v[32:33], 8, v[56:57]
	v_mov_b32_e32 v173, v161
	s_waitcnt lgkmcnt(0)
	v_lshl_add_u64 v[32:33], s[14:15], 0, v[32:33]
	v_lshl_add_u64 v[32:33], v[32:33], 0, v[172:173]
	v_mov_b32_e32 v32, v148
	v_mov_b32_e32 v33, v149
	s_waitcnt vmcnt(0)
	v_pk_mul_f32 v[34:35], v[42:43], v[32:33] op_sel:[0,1] op_sel_hi:[0,0]
	v_pk_fma_f32 v[36:37], v[58:59], v[32:33], v[34:35] neg_lo:[0,0,1] neg_hi:[0,0,1]
	v_pk_fma_f32 v[32:33], v[58:59], v[32:33], v[34:35] op_sel_hi:[0,1,1]
	v_mov_b32_e32 v37, v33
	v_pk_mul_f32 v[32:33], v[174:175], v[36:37] op_sel_hi:[0,1]

.LBB0_1844:
	v_add_u32_e32 v34, 19, v80
	s_andn2_b64 vcc, exec, s[14:15]
	v_min_i32_e32 v76, 0x7fff, v34
	s_cbranch_vccnz .LBB0_1846
	v_ashrrev_i32_e32 v77, 31, v76
	v_lshlrev_b64 v[32:33], 8, v[76:77]
	v_mov_b32_e32 v173, v161
	v_mov_b32_e32 v34, v43
	s_waitcnt lgkmcnt(0)
	v_lshl_add_u64 v[32:33], s[14:15], 0, v[32:33]
	v_lshl_add_u64 v[32:33], v[32:33], 0, v[172:173]
	v_mov_b32_e32 v32, v150
	v_mov_b32_e32 v33, v151
	v_mov_b32_e32 v36, v59
	s_waitcnt vmcnt(0)
	v_pk_mul_f32 v[34:35], v[34:35], v[32:33] op_sel:[0,1] op_sel_hi:[0,0]
	v_pk_fma_f32 v[38:39], v[36:37], v[32:33], v[34:35] op_sel_hi:[0,1,1] neg_lo:[0,0,1] neg_hi:[0,0,1]
	v_pk_fma_f32 v[32:33], v[36:37], v[32:33], v[34:35] op_sel_hi:[0,1,1]
	v_mov_b32_e32 v39, v33
	v_pk_mul_f32 v[32:33], v[174:175], v[38:39] op_sel_hi:[0,1]

.LBB0_1850:
	v_add_u32_e32 v34, 24, v80
	s_andn2_b64 vcc, exec, s[14:15]
	v_min_i32_e32 v58, 0x7fff, v34
	s_cbranch_vccnz .LBB0_1852
	v_ashrrev_i32_e32 v59, 31, v58
	v_lshlrev_b64 v[32:33], 8, v[58:59]
	v_mov_b32_e32 v173, v161
	s_waitcnt lgkmcnt(0)
	v_lshl_add_u64 v[32:33], s[14:15], 0, v[32:33]
	v_lshl_add_u64 v[32:33], v[32:33], 0, v[172:173]
	v_mov_b32_e32 v32, v152
	v_mov_b32_e32 v33, v153
	s_waitcnt vmcnt(0)
	v_pk_mul_f32 v[34:35], v[44:45], v[32:33] op_sel:[0,1] op_sel_hi:[0,0]
	v_pk_fma_f32 v[36:37], v[60:61], v[32:33], v[34:35] neg_lo:[0,0,1] neg_hi:[0,0,1]
	v_pk_fma_f32 v[32:33], v[60:61], v[32:33], v[34:35] op_sel_hi:[0,1,1]
	v_mov_b32_e32 v37, v33
	v_pk_mul_f32 v[32:33], v[174:175], v[36:37] op_sel_hi:[0,1]

.LBB0_1856:
	v_add_u32_e32 v34, 25, v80
	s_andn2_b64 vcc, exec, s[14:15]
	v_min_i32_e32 v78, 0x7fff, v34
	s_cbranch_vccnz .LBB0_1858
	v_ashrrev_i32_e32 v79, 31, v78
	v_lshlrev_b64 v[32:33], 8, v[78:79]
	v_mov_b32_e32 v173, v161
	v_mov_b32_e32 v34, v45
	s_waitcnt lgkmcnt(0)
	v_lshl_add_u64 v[32:33], s[14:15], 0, v[32:33]
	v_lshl_add_u64 v[32:33], v[32:33], 0, v[172:173]
	v_mov_b32_e32 v32, v154
	v_mov_b32_e32 v33, v155
	v_mov_b32_e32 v36, v61
	s_waitcnt vmcnt(0)
	v_pk_mul_f32 v[34:35], v[34:35], v[32:33] op_sel:[0,1] op_sel_hi:[0,0]
	v_pk_fma_f32 v[38:39], v[36:37], v[32:33], v[34:35] op_sel_hi:[0,1,1] neg_lo:[0,0,1] neg_hi:[0,0,1]
	v_pk_fma_f32 v[32:33], v[36:37], v[32:33], v[34:35] op_sel_hi:[0,1,1]
	v_mov_b32_e32 v39, v33
	v_pk_mul_f32 v[32:33], v[174:175], v[38:39] op_sel_hi:[0,1]

.LBB0_1862:
	v_add_u32_e32 v34, 26, v80
	s_andn2_b64 vcc, exec, s[14:15]
	v_min_i32_e32 v44, 0x7fff, v34
	s_cbranch_vccnz .LBB0_1864
	v_ashrrev_i32_e32 v45, 31, v44
	v_lshlrev_b64 v[32:33], 8, v[44:45]
	v_mov_b32_e32 v173, v161
	s_waitcnt lgkmcnt(0)
	v_lshl_add_u64 v[32:33], s[14:15], 0, v[32:33]
	v_lshl_add_u64 v[32:33], v[32:33], 0, v[172:173]
	v_mov_b32_e32 v32, v156
	v_mov_b32_e32 v33, v157
	s_waitcnt vmcnt(0)
	v_pk_mul_f32 v[34:35], v[46:47], v[32:33] op_sel:[0,1] op_sel_hi:[0,0]
	v_pk_fma_f32 v[36:37], v[62:63], v[32:33], v[34:35] neg_lo:[0,0,1] neg_hi:[0,0,1]
	v_pk_fma_f32 v[32:33], v[62:63], v[32:33], v[34:35] op_sel_hi:[0,1,1]
	v_mov_b32_e32 v37, v33
	v_pk_mul_f32 v[32:33], v[174:175], v[36:37] op_sel_hi:[0,1]

.LBB0_1868:
	v_add_u32_e32 v34, 27, v80
	s_andn2_b64 vcc, exec, s[6:7]
	v_min_i32_e32 v60, 0x7fff, v34
	s_cbranch_vccnz .LBB0_1870
	v_ashrrev_i32_e32 v61, 31, v60
	v_lshlrev_b64 v[32:33], 8, v[60:61]
	v_mov_b32_e32 v173, v161
	v_mov_b32_e32 v34, v47
	s_waitcnt lgkmcnt(0)
	v_lshl_add_u64 v[32:33], s[2:3], 0, v[32:33]
	v_lshl_add_u64 v[32:33], v[32:33], 0, v[172:173]
	v_mov_b32_e32 v32, v158
	v_mov_b32_e32 v33, v159
	v_mov_b32_e32 v36, v63
	s_waitcnt vmcnt(0)
	v_pk_mul_f32 v[34:35], v[34:35], v[32:33] op_sel:[0,1] op_sel_hi:[0,0]
	v_pk_fma_f32 v[38:39], v[36:37], v[32:33], v[34:35] op_sel_hi:[0,1,1] neg_lo:[0,0,1] neg_hi:[0,0,1]
	v_pk_fma_f32 v[32:33], v[36:37], v[32:33], v[34:35] op_sel_hi:[0,1,1]
	v_mov_b32_e32 v39, v33
	v_pk_mul_f32 v[32:33], v[174:175], v[38:39] op_sel_hi:[0,1]

.LBB0_1936:
	s_andn2_b64 vcc, exec, s[12:13]
	s_cbranch_vccnz .LBB0_1938
	v_ashrrev_i32_e32 v65, 31, v64
	v_lshlrev_b64 v[32:33], 8, v[64:65]
	v_mov_b32_e32 v173, v161
	s_waitcnt lgkmcnt(0)
	v_lshl_add_u64 v[32:33], s[12:13], 0, v[32:33]
	v_lshl_add_u64 v[32:33], v[32:33], 0, v[172:173]
	v_mov_b32_e32 v32, v130
	v_mov_b32_e32 v33, v131
	s_waitcnt vmcnt(0)
	v_pk_mul_f32 v[0:1], v[0:1], v[32:33] op_sel:[1,1] op_sel_hi:[1,0]
	s_nop 0
	v_pk_fma_f32 v[34:35], v[16:17], v[32:33], v[0:1] op_sel:[1,0,0] neg_lo:[0,0,1] neg_hi:[0,0,1]
	v_pk_fma_f32 v[0:1], v[16:17], v[32:33], v[0:1] op_sel:[1,0,0]
	s_nop 0
	v_mov_b32_e32 v35, v1
	v_pk_mul_f32 v[32:33], v[96:97], v[34:35] op_sel_hi:[0,1]

.LBB0_1942:
	s_andn2_b64 vcc, exec, s[12:13]
	s_cbranch_vccnz .LBB0_1944
	v_ashrrev_i32_e32 v49, 31, v48
	v_lshlrev_b64 v[0:1], 8, v[48:49]
	v_mov_b32_e32 v173, v161
	s_waitcnt lgkmcnt(0)
	v_lshl_add_u64 v[0:1], s[12:13], 0, v[0:1]
	v_lshl_add_u64 v[0:1], v[0:1], 0, v[172:173]
	v_mov_b32_e32 v0, v132
	v_mov_b32_e32 v1, v133
	s_waitcnt vmcnt(0)
	v_pk_mul_f32 v[16:17], v[2:3], v[0:1] op_sel:[0,1] op_sel_hi:[0,0]
	v_pk_fma_f32 v[32:33], v[18:19], v[0:1], v[16:17] neg_lo:[0,0,1] neg_hi:[0,0,1]
	v_pk_fma_f32 v[0:1], v[18:19], v[0:1], v[16:17] op_sel_hi:[0,1,1]
	v_mov_b32_e32 v33, v1
	v_pk_mul_f32 v[0:1], v[96:97], v[32:33] op_sel_hi:[0,1]

.LBB0_1948:
	s_andn2_b64 vcc, exec, s[12:13]
	s_cbranch_vccnz .LBB0_1950
	v_ashrrev_i32_e32 v69, 31, v68
	v_lshlrev_b64 v[0:1], 8, v[68:69]
	v_mov_b32_e32 v173, v161
	v_mov_b32_e32 v2, v3
	s_waitcnt lgkmcnt(0)
	v_lshl_add_u64 v[0:1], s[12:13], 0, v[0:1]
	v_lshl_add_u64 v[0:1], v[0:1], 0, v[172:173]
	v_mov_b32_e32 v0, v134
	v_mov_b32_e32 v1, v135
	v_mov_b32_e32 v16, v19
	s_waitcnt vmcnt(0)
	v_pk_mul_f32 v[2:3], v[2:3], v[0:1] op_sel:[0,1] op_sel_hi:[0,0]
	v_pk_fma_f32 v[18:19], v[16:17], v[0:1], v[2:3] op_sel_hi:[0,1,1] neg_lo:[0,0,1] neg_hi:[0,0,1]
	v_pk_fma_f32 v[0:1], v[16:17], v[0:1], v[2:3] op_sel_hi:[0,1,1]
	v_mov_b32_e32 v19, v1
	v_pk_mul_f32 v[0:1], v[96:97], v[18:19] op_sel_hi:[0,1]

.LBB0_1954:
	s_andn2_b64 vcc, exec, s[12:13]
	s_cbranch_vccnz .LBB0_1956
	v_ashrrev_i32_e32 v51, 31, v50
	v_lshlrev_b64 v[0:1], 8, v[50:51]
	v_mov_b32_e32 v173, v161
	s_waitcnt lgkmcnt(0)
	v_lshl_add_u64 v[0:1], s[12:13], 0, v[0:1]
	v_lshl_add_u64 v[0:1], v[0:1], 0, v[172:173]
	v_mov_b32_e32 v0, v136
	v_mov_b32_e32 v1, v137
	s_waitcnt vmcnt(0)
	v_pk_mul_f32 v[2:3], v[4:5], v[0:1] op_sel:[0,1] op_sel_hi:[0,0]
	v_pk_fma_f32 v[16:17], v[20:21], v[0:1], v[2:3] neg_lo:[0,0,1] neg_hi:[0,0,1]
	v_pk_fma_f32 v[0:1], v[20:21], v[0:1], v[2:3] op_sel_hi:[0,1,1]
	v_mov_b32_e32 v17, v1
	v_pk_mul_f32 v[0:1], v[96:97], v[16:17] op_sel_hi:[0,1]

.LBB0_1960:
	s_andn2_b64 vcc, exec, s[12:13]
	s_cbranch_vccnz .LBB0_1962
	v_ashrrev_i32_e32 v71, 31, v70
	v_lshlrev_b64 v[0:1], 8, v[70:71]
	v_mov_b32_e32 v173, v161
	v_mov_b32_e32 v2, v5
	s_waitcnt lgkmcnt(0)
	v_lshl_add_u64 v[0:1], s[12:13], 0, v[0:1]
	v_lshl_add_u64 v[0:1], v[0:1], 0, v[172:173]
	v_mov_b32_e32 v0, v138
	v_mov_b32_e32 v1, v139
	v_mov_b32_e32 v4, v21
	s_waitcnt vmcnt(0)
	v_pk_mul_f32 v[2:3], v[2:3], v[0:1] op_sel:[0,1] op_sel_hi:[0,0]
	v_pk_fma_f32 v[16:17], v[4:5], v[0:1], v[2:3] op_sel_hi:[0,1,1] neg_lo:[0,0,1] neg_hi:[0,0,1]
	v_pk_fma_f32 v[0:1], v[4:5], v[0:1], v[2:3] op_sel_hi:[0,1,1]
	v_mov_b32_e32 v17, v1
	v_pk_mul_f32 v[0:1], v[96:97], v[16:17] op_sel_hi:[0,1]

.LBB0_1966:
	s_andn2_b64 vcc, exec, s[12:13]
	s_cbranch_vccnz .LBB0_1968
	v_ashrrev_i32_e32 v53, 31, v52
	v_lshlrev_b64 v[0:1], 8, v[52:53]
	v_mov_b32_e32 v173, v161
	s_waitcnt lgkmcnt(0)
	v_lshl_add_u64 v[0:1], s[12:13], 0, v[0:1]
	v_lshl_add_u64 v[0:1], v[0:1], 0, v[172:173]
	v_mov_b32_e32 v0, v140
	v_mov_b32_e32 v1, v141
	s_waitcnt vmcnt(0)
	v_pk_mul_f32 v[2:3], v[6:7], v[0:1] op_sel:[0,1] op_sel_hi:[0,0]
	v_pk_fma_f32 v[4:5], v[22:23], v[0:1], v[2:3] neg_lo:[0,0,1] neg_hi:[0,0,1]
	v_pk_fma_f32 v[0:1], v[22:23], v[0:1], v[2:3] op_sel_hi:[0,1,1]
	v_mov_b32_e32 v5, v1
	v_pk_mul_f32 v[0:1], v[96:97], v[4:5] op_sel_hi:[0,1]

.LBB0_1972:
	s_andn2_b64 vcc, exec, s[12:13]
	s_cbranch_vccnz .LBB0_1974
	v_ashrrev_i32_e32 v73, 31, v72
	v_lshlrev_b64 v[0:1], 8, v[72:73]
	v_mov_b32_e32 v173, v161
	v_mov_b32_e32 v2, v7
	s_waitcnt lgkmcnt(0)
	v_lshl_add_u64 v[0:1], s[12:13], 0, v[0:1]
	v_lshl_add_u64 v[0:1], v[0:1], 0, v[172:173]
	v_mov_b32_e32 v0, v142
	v_mov_b32_e32 v1, v143
	v_mov_b32_e32 v4, v23
	s_waitcnt vmcnt(0)
	v_pk_mul_f32 v[2:3], v[2:3], v[0:1] op_sel:[0,1] op_sel_hi:[0,0]
	v_pk_fma_f32 v[6:7], v[4:5], v[0:1], v[2:3] op_sel_hi:[0,1,1] neg_lo:[0,0,1] neg_hi:[0,0,1]
	v_pk_fma_f32 v[0:1], v[4:5], v[0:1], v[2:3] op_sel_hi:[0,1,1]
	v_mov_b32_e32 v7, v1
	v_pk_mul_f32 v[0:1], v[96:97], v[6:7] op_sel_hi:[0,1]

.LBB0_1978:
	s_andn2_b64 vcc, exec, s[12:13]
	s_cbranch_vccnz .LBB0_1980
	v_ashrrev_i32_e32 v55, 31, v54
	v_lshlrev_b64 v[0:1], 8, v[54:55]
	v_mov_b32_e32 v173, v161
	s_waitcnt lgkmcnt(0)
	v_lshl_add_u64 v[0:1], s[12:13], 0, v[0:1]
	v_lshl_add_u64 v[0:1], v[0:1], 0, v[172:173]
	v_mov_b32_e32 v0, v144
	v_mov_b32_e32 v1, v145
	s_waitcnt vmcnt(0)
	v_pk_mul_f32 v[2:3], v[8:9], v[0:1] op_sel:[0,1] op_sel_hi:[0,0]
	v_pk_fma_f32 v[4:5], v[24:25], v[0:1], v[2:3] neg_lo:[0,0,1] neg_hi:[0,0,1]
	v_pk_fma_f32 v[0:1], v[24:25], v[0:1], v[2:3] op_sel_hi:[0,1,1]
	v_mov_b32_e32 v5, v1
	v_pk_mul_f32 v[0:1], v[96:97], v[4:5] op_sel_hi:[0,1]

.LBB0_1984:
	s_andn2_b64 vcc, exec, s[12:13]
	s_cbranch_vccnz .LBB0_1986
	v_ashrrev_i32_e32 v75, 31, v74
	v_lshlrev_b64 v[0:1], 8, v[74:75]
	v_mov_b32_e32 v173, v161
	v_mov_b32_e32 v2, v9
	s_waitcnt lgkmcnt(0)
	v_lshl_add_u64 v[0:1], s[12:13], 0, v[0:1]
	v_lshl_add_u64 v[0:1], v[0:1], 0, v[172:173]
	v_mov_b32_e32 v0, v146
	v_mov_b32_e32 v1, v147
	v_mov_b32_e32 v4, v25
	s_waitcnt vmcnt(0)
	v_pk_mul_f32 v[2:3], v[2:3], v[0:1] op_sel:[0,1] op_sel_hi:[0,0]
	v_pk_fma_f32 v[6:7], v[4:5], v[0:1], v[2:3] op_sel_hi:[0,1,1] neg_lo:[0,0,1] neg_hi:[0,0,1]
	v_pk_fma_f32 v[0:1], v[4:5], v[0:1], v[2:3] op_sel_hi:[0,1,1]
	v_mov_b32_e32 v7, v1
	v_pk_mul_f32 v[0:1], v[96:97], v[6:7] op_sel_hi:[0,1]

.LBB0_1990:
	s_andn2_b64 vcc, exec, s[12:13]
	s_cbranch_vccnz .LBB0_1992
	v_ashrrev_i32_e32 v57, 31, v56
	v_lshlrev_b64 v[0:1], 8, v[56:57]
	v_mov_b32_e32 v173, v161
	s_waitcnt lgkmcnt(0)
	v_lshl_add_u64 v[0:1], s[12:13], 0, v[0:1]
	v_lshl_add_u64 v[0:1], v[0:1], 0, v[172:173]
	v_mov_b32_e32 v0, v148
	v_mov_b32_e32 v1, v149
	s_waitcnt vmcnt(0)
	v_pk_mul_f32 v[2:3], v[10:11], v[0:1] op_sel:[0,1] op_sel_hi:[0,0]
	v_pk_fma_f32 v[4:5], v[26:27], v[0:1], v[2:3] neg_lo:[0,0,1] neg_hi:[0,0,1]
	v_pk_fma_f32 v[0:1], v[26:27], v[0:1], v[2:3] op_sel_hi:[0,1,1]
	v_mov_b32_e32 v5, v1
	v_pk_mul_f32 v[0:1], v[96:97], v[4:5] op_sel_hi:[0,1]

.LBB0_1996:
	s_andn2_b64 vcc, exec, s[12:13]
	s_cbranch_vccnz .LBB0_1998
	v_ashrrev_i32_e32 v77, 31, v76
	v_lshlrev_b64 v[0:1], 8, v[76:77]
	v_mov_b32_e32 v173, v161
	v_mov_b32_e32 v2, v11
	s_waitcnt lgkmcnt(0)
	v_lshl_add_u64 v[0:1], s[12:13], 0, v[0:1]
	v_lshl_add_u64 v[0:1], v[0:1], 0, v[172:173]
	v_mov_b32_e32 v0, v150
	v_mov_b32_e32 v1, v151
	v_mov_b32_e32 v4, v27
	s_waitcnt vmcnt(0)
	v_pk_mul_f32 v[2:3], v[2:3], v[0:1] op_sel:[0,1] op_sel_hi:[0,0]
	v_pk_fma_f32 v[6:7], v[4:5], v[0:1], v[2:3] op_sel_hi:[0,1,1] neg_lo:[0,0,1] neg_hi:[0,0,1]
	v_pk_fma_f32 v[0:1], v[4:5], v[0:1], v[2:3] op_sel_hi:[0,1,1]
	v_mov_b32_e32 v7, v1
	v_pk_mul_f32 v[0:1], v[96:97], v[6:7] op_sel_hi:[0,1]

.LBB0_2002:
	s_andn2_b64 vcc, exec, s[12:13]
	s_cbranch_vccnz .LBB0_2004
	v_ashrrev_i32_e32 v59, 31, v58
	v_lshlrev_b64 v[0:1], 8, v[58:59]
	v_mov_b32_e32 v173, v161
	s_waitcnt lgkmcnt(0)
	v_lshl_add_u64 v[0:1], s[12:13], 0, v[0:1]
	v_lshl_add_u64 v[0:1], v[0:1], 0, v[172:173]
	v_mov_b32_e32 v0, v152
	v_mov_b32_e32 v1, v153
	s_waitcnt vmcnt(0)
	v_pk_mul_f32 v[2:3], v[12:13], v[0:1] op_sel:[0,1] op_sel_hi:[0,0]
	v_pk_fma_f32 v[4:5], v[28:29], v[0:1], v[2:3] neg_lo:[0,0,1] neg_hi:[0,0,1]
	v_pk_fma_f32 v[0:1], v[28:29], v[0:1], v[2:3] op_sel_hi:[0,1,1]
	v_mov_b32_e32 v5, v1
	v_pk_mul_f32 v[0:1], v[96:97], v[4:5] op_sel_hi:[0,1]

.LBB0_2008:
	s_andn2_b64 vcc, exec, s[12:13]
	s_cbranch_vccnz .LBB0_2010
	v_ashrrev_i32_e32 v79, 31, v78
	v_lshlrev_b64 v[0:1], 8, v[78:79]
	v_mov_b32_e32 v173, v161
	v_mov_b32_e32 v2, v13
	s_waitcnt lgkmcnt(0)
	v_lshl_add_u64 v[0:1], s[12:13], 0, v[0:1]
	v_lshl_add_u64 v[0:1], v[0:1], 0, v[172:173]
	v_mov_b32_e32 v0, v154
	v_mov_b32_e32 v1, v155
	v_mov_b32_e32 v4, v29
	s_waitcnt vmcnt(0)
	v_pk_mul_f32 v[2:3], v[2:3], v[0:1] op_sel:[0,1] op_sel_hi:[0,0]
	v_pk_fma_f32 v[6:7], v[4:5], v[0:1], v[2:3] op_sel_hi:[0,1,1] neg_lo:[0,0,1] neg_hi:[0,0,1]
	v_pk_fma_f32 v[0:1], v[4:5], v[0:1], v[2:3] op_sel_hi:[0,1,1]
	v_mov_b32_e32 v7, v1
	v_pk_mul_f32 v[0:1], v[96:97], v[6:7] op_sel_hi:[0,1]

.LBB0_2014:
	s_andn2_b64 vcc, exec, s[12:13]
	s_cbranch_vccnz .LBB0_2016
	v_ashrrev_i32_e32 v45, 31, v44
	v_lshlrev_b64 v[0:1], 8, v[44:45]
	v_mov_b32_e32 v173, v161
	s_waitcnt lgkmcnt(0)
	v_lshl_add_u64 v[0:1], s[12:13], 0, v[0:1]
	v_lshl_add_u64 v[0:1], v[0:1], 0, v[172:173]
	v_mov_b32_e32 v0, v156
	v_mov_b32_e32 v1, v157
	s_waitcnt vmcnt(0)
	v_pk_mul_f32 v[2:3], v[14:15], v[0:1] op_sel:[0,1] op_sel_hi:[0,0]
	v_pk_fma_f32 v[4:5], v[30:31], v[0:1], v[2:3] neg_lo:[0,0,1] neg_hi:[0,0,1]
	v_pk_fma_f32 v[0:1], v[30:31], v[0:1], v[2:3] op_sel_hi:[0,1,1]
	v_mov_b32_e32 v5, v1
	v_pk_mul_f32 v[0:1], v[96:97], v[4:5] op_sel_hi:[0,1]

.LBB0_2020:
	s_andn2_b64 vcc, exec, s[8:9]
	s_cbranch_vccnz .LBB0_2022
	v_ashrrev_i32_e32 v61, 31, v60
	v_lshlrev_b64 v[0:1], 8, v[60:61]
	v_mov_b32_e32 v173, v161
	v_mov_b32_e32 v2, v15
	s_waitcnt lgkmcnt(0)
	v_lshl_add_u64 v[0:1], s[4:5], 0, v[0:1]
	v_lshl_add_u64 v[0:1], v[0:1], 0, v[172:173]
	v_mov_b32_e32 v0, v158
	v_mov_b32_e32 v1, v159
	v_mov_b32_e32 v4, v31
	s_waitcnt vmcnt(0)
	v_pk_mul_f32 v[2:3], v[2:3], v[0:1] op_sel:[0,1] op_sel_hi:[0,0]
	v_pk_fma_f32 v[6:7], v[4:5], v[0:1], v[2:3] op_sel_hi:[0,1,1] neg_lo:[0,0,1] neg_hi:[0,0,1]
	v_pk_fma_f32 v[0:1], v[4:5], v[0:1], v[2:3] op_sel_hi:[0,1,1]
	v_mov_b32_e32 v7, v1
	v_pk_mul_f32 v[0:1], v[96:97], v[6:7] op_sel_hi:[0,1]

.LBB0_2214:
	v_mbcnt_hi_u32_b32 v211, -1, v210
	s_load_dwordx2 s[2:3], s[0:1], 0x108
	s_load_dwordx2 s[4:5], s[0:1], 0x158
	s_ashr_i32 s7, s6, 31
	v_mov_b32_e32 v1, v211
	s_and_b32 s7, s7, s42
	s_add_i32 s54, s7, s6
	v_add_u32_e32 v0, s70, v1
	v_ashrrev_i32_e32 v212, 3, v0
	v_readfirstlane_b32 s8, v0
	v_lshlrev_b32_e32 v0, 3, v1
	v_and_b32_e32 v0, 56, v0
	s_cmpk_lt_i32 s54, 0x200
	s_cselect_b64 s[6:7], -1, 0
	s_cmpk_gt_i32 s54, 0x1ff
	v_lshlrev_b32_e32 v168, 1, v0
	v_add_u32_e32 v213, 64, v212
	s_cbranch_scc1 .LBB0_2216
	s_ashr_i32 s9, s54, 31
	s_lshr_b32 s9, s9, 30
	s_add_i32 s9, s54, s9
	s_ashr_i32 s9, s9, 2
	s_lshl_b32 s10, s9, 8
	v_add_u32_e32 v2, s10, v212
	v_min_i32_e32 v2, 0x7fff, v2
	v_ashrrev_i32_e32 v3, 31, v2
	v_lshlrev_b64 v[2:3], 11, v[2:3]
	s_lshl_b32 s9, s9, 10
	s_lshl_b32 s11, s54, 8
	s_waitcnt lgkmcnt(0)
	v_lshl_add_u64 v[2:3], s[4:5], 0, v[2:3]
	v_mov_b32_e32 v169, 0
	s_sub_i32 s9, s11, s9
	v_lshl_add_u64 v[2:3], v[2:3], 0, v[168:169]
	v_mbcnt_hi_u32_b32 v158, -1, v210
	s_and_b32 s90, s70, 0x40
	v_and_b32_e32 v159, 48, v158
	v_or_b32_e32 v159, s90, v159
	s_lshl_b32 s88, s70, 4
	s_lshl_b32 s92, s22, 4
	s_and_b32 s92, s92, 0x780
	s_mov_b32 s93, 0
	s_add_u32 m0, s88, 0
	v_lshl_add_u64 v[2:3], v[2:3], 0, s[92:93]
	v_xor_b32_e32 v2, v159, v2
	global_load_lds_dwordx4 v[2:3], off
	v_add_u32_e32 v2, s9, v212
	v_ashrrev_i32_e32 v3, 31, v2
	v_lshlrev_b64 v[2:3], 11, v[2:3]
	v_lshl_add_u64 v[2:3], s[2:3], 0, v[2:3]
	v_lshl_add_u64 v[2:3], v[2:3], 0, v[168:169]
	s_add_u32 m0, s88, 32768
	v_lshl_add_u64 v[2:3], v[2:3], 0, s[92:93]
	v_xor_b32_e32 v2, v159, v2
	global_load_lds_dwordx4 v[2:3], off
	v_add_u32_e32 v2, s10, v213
	v_min_i32_e32 v2, 0x7fff, v2
	v_ashrrev_i32_e32 v3, 31, v2
	v_lshlrev_b64 v[2:3], 11, v[2:3]
	v_lshl_add_u64 v[2:3], s[4:5], 0, v[2:3]
	v_lshl_add_u64 v[2:3], v[2:3], 0, v[168:169]
	s_add_u32 m0, s88, 8192
	v_lshl_add_u64 v[2:3], v[2:3], 0, s[92:93]
	v_xor_b32_e32 v2, v159, v2
	global_load_lds_dwordx4 v[2:3], off
	v_add_u32_e32 v2, s9, v213
	v_ashrrev_i32_e32 v3, 31, v2
	v_lshlrev_b64 v[2:3], 11, v[2:3]
	v_lshl_add_u64 v[2:3], s[2:3], 0, v[2:3]
	v_lshl_add_u64 v[2:3], v[2:3], 0, v[168:169]
	v_add_u32_e32 v4, 0x80, v212
	s_add_u32 m0, s88, 40960
	v_lshl_add_u64 v[2:3], v[2:3], 0, s[92:93]
	v_xor_b32_e32 v2, v159, v2
	global_load_lds_dwordx4 v[2:3], off
	v_add_u32_e32 v2, s10, v4
	v_min_i32_e32 v2, 0x7fff, v2
	v_ashrrev_i32_e32 v3, 31, v2
	v_lshlrev_b64 v[2:3], 11, v[2:3]
	v_lshl_add_u64 v[2:3], s[4:5], 0, v[2:3]
	v_lshl_add_u64 v[2:3], v[2:3], 0, v[168:169]
	s_add_u32 m0, s88, 16384
	v_lshl_add_u64 v[2:3], v[2:3], 0, s[92:93]
	v_xor_b32_e32 v2, v159, v2
	global_load_lds_dwordx4 v[2:3], off
	v_add_u32_e32 v2, s9, v4
	v_ashrrev_i32_e32 v3, 31, v2
	v_lshlrev_b64 v[2:3], 11, v[2:3]
	v_lshl_add_u64 v[2:3], s[2:3], 0, v[2:3]
	v_lshl_add_u64 v[2:3], v[2:3], 0, v[168:169]
	v_add_u32_e32 v4, 0xc0, v212
	s_add_u32 m0, s88, 49152
	v_lshl_add_u64 v[2:3], v[2:3], 0, s[92:93]
	v_xor_b32_e32 v2, v159, v2
	global_load_lds_dwordx4 v[2:3], off
	v_add_u32_e32 v2, s10, v4
	v_min_i32_e32 v2, 0x7fff, v2
	v_ashrrev_i32_e32 v3, 31, v2
	v_lshlrev_b64 v[2:3], 11, v[2:3]
	v_lshl_add_u64 v[2:3], s[4:5], 0, v[2:3]
	v_lshl_add_u64 v[2:3], v[2:3], 0, v[168:169]
	s_add_u32 m0, s88, 24576
	v_lshl_add_u64 v[2:3], v[2:3], 0, s[92:93]
	v_xor_b32_e32 v2, v159, v2
	global_load_lds_dwordx4 v[2:3], off
	v_add_u32_e32 v2, s9, v4
	v_ashrrev_i32_e32 v3, 31, v2
	v_lshlrev_b64 v[2:3], 11, v[2:3]
	v_lshl_add_u64 v[2:3], s[2:3], 0, v[2:3]
	v_lshl_add_u64 v[2:3], v[2:3], 0, v[168:169]
	s_add_u32 m0, s88, 57344
	v_lshl_add_u64 v[2:3], v[2:3], 0, s[92:93]
	v_xor_b32_e32 v2, v159, v2
	global_load_lds_dwordx4 v[2:3], off
	s_waitcnt vmcnt(0)

.LBB0_2223:
	ds_read_b128 v[128:131], v231
	ds_read_b128 v[136:139], v235
	ds_read_b128 v[132:135], v231 offset:4096
	ds_read_b128 v[140:143], v235 offset:4096
	ds_read_b128 v[144:147], v235 offset:8192
	ds_read_b128 v[148:151], v235 offset:12288
	s_waitcnt lgkmcnt(6)
	v_mfma_f32_32x32x16_bf16 v[112:127], v[188:191], v[196:199], v[112:127]
	v_mfma_f32_32x32x16_bf16 v[48:63], v[192:195], v[196:199], v[48:63]
	v_mfma_f32_32x32x16_bf16 v[96:111], v[188:191], v[200:203], v[96:111]
	v_mfma_f32_32x32x16_bf16 v[32:47], v[192:195], v[200:203], v[32:47]
	v_mfma_f32_32x32x16_bf16 v[80:95], v[188:191], v[204:207], v[80:95]
	v_mfma_f32_32x32x16_bf16 v[16:31], v[192:195], v[204:207], v[16:31]
	v_mfma_f32_32x32x16_bf16 v[64:79], v[188:191], v[226:229], v[64:79]
	v_mfma_f32_32x32x16_bf16 v[0:15], v[192:195], v[226:229], v[0:15]
	ds_read_b128 v[188:191], v232
	ds_read_b128 v[196:199], v236
	ds_read_b128 v[192:195], v232 offset:4096
	ds_read_b128 v[200:203], v236 offset:4096
	ds_read_b128 v[204:207], v236 offset:8192
	ds_read_b128 v[226:229], v236 offset:12288
	s_waitcnt lgkmcnt(6)
	v_mfma_f32_32x32x16_bf16 v[112:127], v[128:131], v[136:139], v[112:127]
	v_mfma_f32_32x32x16_bf16 v[48:63], v[132:135], v[136:139], v[48:63]
	v_mfma_f32_32x32x16_bf16 v[96:111], v[128:131], v[140:143], v[96:111]
	v_mfma_f32_32x32x16_bf16 v[32:47], v[132:135], v[140:143], v[32:47]
	v_mfma_f32_32x32x16_bf16 v[80:95], v[128:131], v[144:147], v[80:95]
	v_mfma_f32_32x32x16_bf16 v[16:31], v[132:135], v[144:147], v[16:31]
	v_mfma_f32_32x32x16_bf16 v[64:79], v[128:131], v[148:151], v[64:79]
	v_mfma_f32_32x32x16_bf16 v[0:15], v[132:135], v[148:151], v[0:15]
	ds_read_b128 v[128:131], v233
	ds_read_b128 v[136:139], v237
	ds_read_b128 v[132:135], v233 offset:4096
	ds_read_b128 v[140:143], v237 offset:4096
	ds_read_b128 v[144:147], v237 offset:8192
	ds_read_b128 v[148:151], v237 offset:12288
	s_waitcnt lgkmcnt(6)
	v_mfma_f32_32x32x16_bf16 v[112:127], v[188:191], v[196:199], v[112:127]
	v_mfma_f32_32x32x16_bf16 v[48:63], v[192:195], v[196:199], v[48:63]
	v_mfma_f32_32x32x16_bf16 v[96:111], v[188:191], v[200:203], v[96:111]
	v_mfma_f32_32x32x16_bf16 v[32:47], v[192:195], v[200:203], v[32:47]
	v_mfma_f32_32x32x16_bf16 v[80:95], v[188:191], v[204:207], v[80:95]
	v_mfma_f32_32x32x16_bf16 v[16:31], v[192:195], v[204:207], v[16:31]
	v_mfma_f32_32x32x16_bf16 v[64:79], v[188:191], v[226:229], v[64:79]
	v_mfma_f32_32x32x16_bf16 v[0:15], v[192:195], v[226:229], v[0:15]
	s_waitcnt vmcnt(0) lgkmcnt(0)
	s_barrier
	v_xor_b32_e32 v230, 0x10000, v230
	v_xor_b32_e32 v234, 0x10000, v234
	v_mfma_f32_32x32x16_bf16 v[112:127], v[128:131], v[136:139], v[112:127]
	v_xor_b32_e32 v231, 0x10000, v231
	v_xor_b32_e32 v235, 0x10000, v235
	v_mfma_f32_32x32x16_bf16 v[48:63], v[132:135], v[136:139], v[48:63]
	v_xor_b32_e32 v232, 0x10000, v232
	v_xor_b32_e32 v236, 0x10000, v236
	v_mfma_f32_32x32x16_bf16 v[96:111], v[128:131], v[140:143], v[96:111]
	v_xor_b32_e32 v233, 0x10000, v233
	v_xor_b32_e32 v237, 0x10000, v237
	v_mfma_f32_32x32x16_bf16 v[32:47], v[132:135], v[140:143], v[32:47]
	v_mfma_f32_32x32x16_bf16 v[80:95], v[128:131], v[144:147], v[80:95]
	v_mfma_f32_32x32x16_bf16 v[16:31], v[132:135], v[144:147], v[16:31]
	v_mfma_f32_32x32x16_bf16 v[64:79], v[128:131], v[148:151], v[64:79]
	v_mfma_f32_32x32x16_bf16 v[0:15], v[132:135], v[148:151], v[0:15]
	s_lshl_b32 s2, s5, 8
	s_sub_i32 s2, s2, s6
	v_mov_b32_e32 v168, v214
	s_add_i32 s55, s4, s30
	s_or_b32 s26, s2, s31
	s_ashr_i32 s27, s26, 31
	s_load_dwordx2 s[24:25], s[0:1], 0x140
	v_ashrrev_i32_e32 v180, 3, v168
	v_and_b32_e32 v183, -4, v180
	v_add_u32_e32 v225, s55, v183
	v_add_u32_e32 v190, 8, v225
	v_min_i32_e32 v190, 0x7fff, v190
	v_ashrrev_i32_e32 v190, 12, v190
	v_add_u32_e32 v190, 8, v190
	v_mul_hi_i32_i24_e32 v191, 0x3000, v190
	v_mul_i32_i24_e32 v190, 0x3000, v190
	v_min_i32_e32 v184, 0x7fff, v225
	v_ashrrev_i32_e32 v184, 12, v184
	v_and_b32_e32 v182, 31, v168
	v_add_u32_e32 v184, 8, v184
	v_or_b32_e32 v180, s26, v182
	v_mul_hi_i32_i24_e32 v185, 0x3000, v184
	v_mul_i32_i24_e32 v184, 0x3000, v184
	v_ashrrev_i32_e32 v181, 31, v180
	s_waitcnt lgkmcnt(0)
	v_lshl_add_u64 v[184:185], s[24:25], 0, v[184:185]
	v_lshl_add_u64 v[184:185], v[184:185], 0, s[18:19]
	v_lshlrev_b64 v[180:181], 2, v[180:181]
	v_lshl_add_u64 v[196:197], v[184:185], 0, v[180:181]
	v_lshl_add_u64 v[186:187], s[24:25], 0, v[190:191]
	v_add_u32_e32 v188, 9, v225
	v_add_u32_e32 v190, 10, v225
	v_min_i32_e32 v188, 0x7fff, v188
	v_min_i32_e32 v190, 0x7fff, v190
	v_ashrrev_i32_e32 v188, 12, v188
	v_ashrrev_i32_e32 v190, 12, v190
	v_add_u32_e32 v188, 8, v188
	v_add_u32_e32 v190, 8, v190
	v_mul_hi_i32_i24_e32 v189, 0x3000, v188
	v_mul_i32_i24_e32 v188, 0x3000, v188
	v_mul_hi_i32_i24_e32 v191, 0x3000, v190
	v_mul_i32_i24_e32 v190, 0x3000, v190
	v_lshl_add_u64 v[188:189], s[24:25], 0, v[188:189]
	v_lshl_add_u64 v[190:191], s[24:25], 0, v[190:191]
	v_lshl_add_u64 v[186:187], v[186:187], 0, s[18:19]
	v_lshl_add_u64 v[188:189], v[188:189], 0, s[18:19]
	v_lshl_add_u64 v[190:191], v[190:191], 0, s[18:19]
	v_lshl_add_u64 v[206:207], v[186:187], 0, v[180:181]
	v_add_u32_e32 v208, 18, v225
	v_min_i32_e32 v208, 0x7fff, v208
	v_ashrrev_i32_e32 v208, 12, v208
	v_add_u32_e32 v208, 8, v208
	v_mul_hi_i32_i24_e32 v209, 0x3000, v208
	v_mul_i32_i24_e32 v208, 0x3000, v208
	v_lshl_add_u64 v[208:209], s[24:25], 0, v[208:209]
	v_lshl_add_u64 v[202:203], v[188:189], 0, v[180:181]
	v_lshl_add_u64 v[204:205], v[190:191], 0, v[180:181]
	global_load_dword v232, v[196:197], off
	global_load_dword v233, v[196:197], off offset:128
	global_load_dword v242, v[206:207], off
	global_load_dword v243, v[206:207], off offset:128
	global_load_dword v244, v[202:203], off
	global_load_dword v245, v[202:203], off offset:128
	global_load_dword v246, v[204:205], off
	global_load_dword v247, v[204:205], off offset:128
	v_add_u32_e32 v196, 17, v225
	v_min_i32_e32 v196, 0x7fff, v196
	v_ashrrev_i32_e32 v196, 12, v196
	v_add_u32_e32 v196, 8, v196
	v_mul_hi_i32_i24_e32 v197, 0x3000, v196
	v_mul_i32_i24_e32 v196, 0x3000, v196
	v_lshl_add_u64 v[196:197], s[24:25], 0, v[196:197]
	v_lshl_add_u64 v[196:197], v[196:197], 0, s[18:19]
	v_lshl_add_u64 v[206:207], v[196:197], 0, v[180:181]
	s_waitcnt vmcnt(7)
	s_nop 5
	v_mul_f32_e32 v112, v112, v232
	v_add_u32_e32 v192, 11, v225
	v_add_u32_e32 v194, 16, v225
	v_min_i32_e32 v192, 0x7fff, v192
	v_min_i32_e32 v194, 0x7fff, v194
	v_ashrrev_i32_e32 v192, 12, v192
	v_ashrrev_i32_e32 v194, 12, v194
	v_add_u32_e32 v192, 8, v192
	v_add_u32_e32 v194, 8, v194
	v_mul_hi_i32_i24_e32 v193, 0x3000, v192
	v_mul_i32_i24_e32 v192, 0x3000, v192
	v_mul_hi_i32_i24_e32 v195, 0x3000, v194
	v_mul_i32_i24_e32 v194, 0x3000, v194
	v_lshl_add_u64 v[192:193], s[24:25], 0, v[192:193]
	v_lshl_add_u64 v[194:195], s[24:25], 0, v[194:195]
	v_lshl_add_u64 v[192:193], v[192:193], 0, s[18:19]
	v_lshl_add_u64 v[194:195], v[194:195], 0, s[18:19]
	v_lshl_add_u64 v[202:203], v[192:193], 0, v[180:181]
	v_lshl_add_u64 v[204:205], v[194:195], 0, v[180:181]
	s_waitcnt vmcnt(6)
	s_nop 5
	v_mul_f32_e32 v96, v96, v233
	v_mul_f32_e32 v97, v97, v233
	v_lshl_add_u64 v[198:199], v[208:209], 0, s[18:19]
	v_lshl_add_u64 v[200:201], v[198:199], 0, v[180:181]
	global_load_dword v234, v[202:203], off
	global_load_dword v235, v[202:203], off offset:128
	global_load_dword v236, v[204:205], off
	global_load_dword v237, v[204:205], off offset:128
	global_load_dword v238, v[206:207], off
	global_load_dword v239, v[206:207], off offset:128
	global_load_dword v240, v[200:201], off
	global_load_dword v241, v[200:201], off offset:128
	v_add_u32_e32 v200, 19, v225
	v_add_u32_e32 v204, 25, v225
	v_add_u32_e32 v206, 26, v225
	v_min_i32_e32 v200, 0x7fff, v200
	v_add_u32_e32 v202, 24, v225
	v_min_i32_e32 v204, 0x7fff, v204
	v_min_i32_e32 v206, 0x7fff, v206
	v_ashrrev_i32_e32 v200, 12, v200
	v_min_i32_e32 v202, 0x7fff, v202
	v_ashrrev_i32_e32 v204, 12, v204
	v_ashrrev_i32_e32 v206, 12, v206
	v_add_u32_e32 v200, 8, v200
	v_ashrrev_i32_e32 v202, 12, v202
	v_add_u32_e32 v204, 8, v204
	v_add_u32_e32 v206, 8, v206
	v_mul_hi_i32_i24_e32 v201, 0x3000, v200
	v_mul_i32_i24_e32 v200, 0x3000, v200
	v_add_u32_e32 v202, 8, v202
	v_mul_hi_i32_i24_e32 v205, 0x3000, v204
	v_mul_i32_i24_e32 v204, 0x3000, v204
	v_mul_hi_i32_i24_e32 v207, 0x3000, v206
	v_mul_i32_i24_e32 v206, 0x3000, v206
	v_lshl_add_u64 v[200:201], s[24:25], 0, v[200:201]
	v_mul_hi_i32_i24_e32 v203, 0x3000, v202
	v_mul_i32_i24_e32 v202, 0x3000, v202
	v_lshl_add_u64 v[204:205], s[24:25], 0, v[204:205]
	v_lshl_add_u64 v[206:207], s[24:25], 0, v[206:207]
	v_lshl_add_u64 v[200:201], v[200:201], 0, s[18:19]
	v_lshl_add_u64 v[202:203], s[24:25], 0, v[202:203]
	v_lshl_add_u64 v[204:205], v[204:205], 0, s[18:19]
	v_lshl_add_u64 v[206:207], v[206:207], 0, s[18:19]
	v_lshl_add_u64 v[208:209], v[200:201], 0, v[180:181]
	v_lshl_add_u64 v[202:203], v[202:203], 0, s[18:19]
	v_lshl_add_u64 v[228:229], v[204:205], 0, v[180:181]
	v_lshl_add_u64 v[230:231], v[206:207], 0, v[180:181]
	v_lshl_add_u64 v[226:227], v[202:203], 0, v[180:181]
	global_load_dword v248, v[208:209], off
	global_load_dword v249, v[208:209], off offset:128
	global_load_dword v250, v[226:227], off
	global_load_dword v251, v[226:227], off offset:128
	global_load_dword v252, v[228:229], off
	s_nop 0
	global_load_dword v228, v[228:229], off offset:128
	s_nop 0
	global_load_dword v229, v[230:231], off
	s_nop 0
	global_load_dword v230, v[230:231], off offset:128
	v_add_u32_e32 v208, 27, v225
	v_min_i32_e32 v208, 0x7fff, v208
	v_ashrrev_i32_e32 v208, 12, v208
	v_add_u32_e32 v208, 8, v208
	v_mul_hi_i32_i24_e32 v209, 0x3000, v208
	v_mul_i32_i24_e32 v208, 0x3000, v208
	v_lshl_add_u64 v[208:209], s[24:25], 0, v[208:209]
	v_lshl_add_u64 v[208:209], v[208:209], 0, s[18:19]
	v_lshl_add_u64 v[226:227], v[208:209], 0, v[180:181]
	global_load_dword v225, v[226:227], off
	s_nop 0
	global_load_dword v226, v[226:227], off offset:128
	v_mad_u64_u32 v[160:161], s[2:3], v183, s36, v[182:183]
	v_lshl_add_u32 v162, v160, 2, s34
	ds_write2_b32 v162, v112, v96 offset1:32
	v_mul_f32_e32 v96, v113, v232
	ds_write2_b32 v162, v96, v97 offset0:68 offset1:100
	v_mul_f32_e32 v96, v114, v232
	v_mul_f32_e32 v97, v98, v233
	ds_write2_b32 v162, v96, v97 offset0:136 offset1:168
	v_mul_f32_e32 v96, v115, v232
	v_mul_f32_e32 v97, v99, v233
	ds_write2_b32 v162, v96, v97 offset0:204 offset1:236
	s_waitcnt vmcnt(23)
	v_mul_f32_e32 v96, v116, v242
	s_waitcnt vmcnt(22)
	v_mul_f32_e32 v97, v100, v243
	v_add_u32_e32 v115, 0x800, v162
	ds_write2_b32 v115, v96, v97 offset0:32 offset1:64
	s_waitcnt vmcnt(21)
	v_mul_f32_e32 v96, v117, v244
	s_waitcnt vmcnt(20)
	v_mul_f32_e32 v97, v101, v245
	ds_write2_b32 v115, v96, v97 offset0:100 offset1:132
	s_waitcnt vmcnt(19)
	v_mul_f32_e32 v96, v118, v246
	s_waitcnt vmcnt(18)
	v_mul_f32_e32 v97, v102, v247
	ds_write2_b32 v115, v96, v97 offset0:168 offset1:200
	v_add_u32_e32 v116, 0xa00, v162
	v_add_u32_e32 v117, 0x1000, v162
	s_waitcnt vmcnt(17)
	v_mul_f32_e32 v96, v119, v234
	s_waitcnt vmcnt(16)
	v_mul_f32_e32 v97, v103, v235
	ds_write2_b32 v116, v96, v97 offset0:108 offset1:140
	s_waitcnt vmcnt(15)
	v_mul_f32_e32 v96, v120, v236
	s_waitcnt vmcnt(14)
	v_mul_f32_e32 v97, v104, v237
	ds_write2_b32 v117, v96, v97 offset0:64 offset1:96
	s_waitcnt vmcnt(13)
	v_mul_f32_e32 v96, v121, v238
	s_waitcnt vmcnt(12)
	v_mul_f32_e32 v97, v105, v239
	ds_write2_b32 v117, v96, v97 offset0:132 offset1:164
	s_waitcnt vmcnt(11)
	v_mul_f32_e32 v96, v122, v240
	s_waitcnt vmcnt(10)
	v_mul_f32_e32 v97, v106, v241
	ds_write2_b32 v117, v96, v97 offset0:200 offset1:232
	v_add_u32_e32 v118, 0x1400, v162
	v_add_u32_e32 v119, 0x1800, v162
	v_ashrrev_i32_e32 v163, 4, v168
	v_and_b32_e32 v160, 15, v168
	v_add_u32_e32 v120, 0x1a00, v162
	v_mul_lo_u32 v164, v163, s37
	v_lshl_add_u32 v165, v160, 4, s34
	v_lshlrev_b32_e32 v168, 2, v160
	v_add_u32_e32 v160, s55, v163
	v_add_u32_e32 v121, 0x1c00, v162
	v_cmp_gt_i32_e32 vcc, s38, v160
	v_ashrrev_i32_e32 v161, 31, v160
	v_add_u32_e32 v114, v165, v164
	s_waitcnt vmcnt(9)
	v_mul_f32_e32 v96, v123, v248
	s_waitcnt vmcnt(8)
	v_mul_f32_e32 v97, v107, v249
	ds_write2_b32 v118, v96, v97 offset0:12 offset1:44
	s_waitcnt vmcnt(7)
	v_mul_f32_e32 v96, v124, v250
	s_waitcnt vmcnt(6)
	v_mul_f32_e32 v97, v108, v251
	ds_write2_b32 v119, v96, v97 offset0:96 offset1:128
	s_waitcnt vmcnt(5)
	v_mul_f32_e32 v96, v125, v252
	s_waitcnt vmcnt(4)
	v_mul_f32_e32 v97, v109, v228
	ds_write2_b32 v119, v96, v97 offset0:164 offset1:196
	s_waitcnt vmcnt(3)
	v_mul_f32_e32 v96, v126, v229
	s_waitcnt vmcnt(2)
	v_mul_f32_e32 v97, v110, v230
	ds_write2_b32 v120, v96, v97 offset0:104 offset1:136
	s_waitcnt vmcnt(1)
	v_mul_f32_e32 v96, v127, v225
	s_waitcnt vmcnt(0)
	v_mul_f32_e32 v97, v111, v226
	ds_write2_b32 v121, v96, v97 offset0:44 offset1:76
	v_or_b32_e32 v96, s26, v168
	v_mov_b32_e32 v97, s27
	v_add_u32_e32 v128, 0, v160
	v_ashrrev_i32_e32 v129, 31, v128
	v_lshlrev_b64 v[128:129], 12, v[128:129]
	v_lshl_add_u64 v[128:129], s[16:17], 0, v[128:129]
	v_lshl_add_u64 v[128:129], v[96:97], 2, v[128:129]
	global_load_dwordx4 v[128:131], v[128:129], off
	v_add_u32_e32 v132, 4, v160
	v_ashrrev_i32_e32 v133, 31, v132
	v_lshlrev_b64 v[132:133], 12, v[132:133]
	v_lshl_add_u64 v[132:133], s[16:17], 0, v[132:133]
	v_lshl_add_u64 v[132:133], v[96:97], 2, v[132:133]
	global_load_dwordx4 v[132:135], v[132:133], off
	v_add_u32_e32 v136, 8, v160
	v_ashrrev_i32_e32 v137, 31, v136
	v_lshlrev_b64 v[136:137], 12, v[136:137]
	v_lshl_add_u64 v[136:137], s[16:17], 0, v[136:137]
	v_lshl_add_u64 v[136:137], v[96:97], 2, v[136:137]
	global_load_dwordx4 v[136:139], v[136:137], off
	v_add_u32_e32 v140, 12, v160
	v_ashrrev_i32_e32 v141, 31, v140
	v_lshlrev_b64 v[140:141], 12, v[140:141]
	v_lshl_add_u64 v[140:141], s[16:17], 0, v[140:141]
	v_lshl_add_u64 v[140:141], v[96:97], 2, v[140:141]
	global_load_dwordx4 v[140:143], v[140:141], off
	v_add_u32_e32 v144, 16, v160
	v_ashrrev_i32_e32 v145, 31, v144
	v_lshlrev_b64 v[144:145], 12, v[144:145]
	v_lshl_add_u64 v[144:145], s[16:17], 0, v[144:145]
	v_lshl_add_u64 v[144:145], v[96:97], 2, v[144:145]
	global_load_dwordx4 v[144:147], v[144:145], off
	v_add_u32_e32 v148, 20, v160
	v_ashrrev_i32_e32 v149, 31, v148
	v_lshlrev_b64 v[148:149], 12, v[148:149]
	v_lshl_add_u64 v[148:149], s[16:17], 0, v[148:149]
	v_lshl_add_u64 v[148:149], v[96:97], 2, v[148:149]
	global_load_dwordx4 v[148:151], v[148:149], off
	v_add_u32_e32 v152, 24, v160
	v_ashrrev_i32_e32 v153, 31, v152
	v_lshlrev_b64 v[152:153], 12, v[152:153]
	v_lshl_add_u64 v[152:153], s[16:17], 0, v[152:153]
	v_lshl_add_u64 v[152:153], v[96:97], 2, v[152:153]
	global_load_dwordx4 v[152:155], v[152:153], off
	v_add_u32_e32 v156, 28, v160
	v_ashrrev_i32_e32 v157, 31, v156
	v_lshlrev_b64 v[156:157], 12, v[156:157]
	v_lshl_add_u64 v[156:157], s[16:17], 0, v[156:157]
	v_lshl_add_u64 v[156:157], v[96:97], 2, v[156:157]
	global_load_dwordx4 v[156:159], v[156:157], off
	s_and_saveexec_b64 s[2:3], vcc
	s_cbranch_execz .LBB0_2225
	v_lshlrev_b64 v[98:99], 12, v[160:161]
	v_lshl_add_u64 v[98:99], s[16:17], 0, v[98:99]
	v_lshl_add_u64 v[106:107], v[96:97], 2, v[98:99]
	ds_read_b128 v[102:105], v114
	s_waitcnt vmcnt(7) lgkmcnt(0)
	v_pk_add_f32 v[100:101], v[104:105], v[130:131]
	v_pk_add_f32 v[98:99], v[102:103], v[128:129]
	global_store_dwordx4 v[106:107], v[98:101], off

.LBB0_2404:
	v_mbcnt_hi_u32_b32 v188, -1, v210
	s_load_dwordx2 s[2:3], s[0:1], 0x158
	s_load_dwordx2 s[4:5], s[0:1], 0x110
	s_ashr_i32 s7, s6, 31
	v_mov_b32_e32 v1, v188
	s_and_b32 s7, s7, s42
	s_add_i32 s82, s7, s6
	v_add_u32_e32 v0, s70, v1
	v_ashrrev_i32_e32 v189, 3, v0
	v_readfirstlane_b32 s8, v0
	v_lshlrev_b32_e32 v0, 3, v1
	v_and_b32_e32 v0, 56, v0
	s_cmpk_lt_i32 s82, 0x780
	s_cselect_b64 s[6:7], -1, 0
	s_cmpk_gt_i32 s82, 0x77f
	v_lshlrev_b32_e32 v160, 1, v0
	v_add_u32_e32 v190, 64, v189
	s_cbranch_scc1 .LBB0_2406
	s_mul_hi_i32 s9, s82, 0x88888889
	s_add_i32 s9, s9, s82
	s_lshr_b32 s10, s9, 31
	s_ashr_i32 s9, s9, 3
	s_add_i32 s9, s9, s10
	s_mul_i32 s10, s9, -15
	s_lshl_b32 s9, s9, 8
	v_add_u32_e32 v2, s9, v189
	v_min_i32_e32 v2, 0x7fff, v2
	v_ashrrev_i32_e32 v3, 31, v2
	v_lshlrev_b64 v[2:3], 11, v[2:3]
	s_add_i32 s10, s10, s82
	s_waitcnt lgkmcnt(0)
	v_lshl_add_u64 v[2:3], s[2:3], 0, v[2:3]
	v_mov_b32_e32 v161, 0
	s_lshl_b32 s10, s10, 8
	v_lshl_add_u64 v[2:3], v[2:3], 0, v[160:161]
	v_mbcnt_hi_u32_b32 v158, -1, v210
	s_and_b32 s90, s70, 0x40
	v_and_b32_e32 v159, 48, v158
	v_or_b32_e32 v159, s90, v159
	s_lshl_b32 s88, s70, 4
	s_lshl_b32 s92, s22, 4
	s_and_b32 s92, s92, 0x780
	s_mov_b32 s93, 0
	s_add_u32 m0, s88, 0
	v_lshl_add_u64 v[2:3], v[2:3], 0, s[92:93]
	v_xor_b32_e32 v2, v159, v2
	global_load_lds_dwordx4 v[2:3], off
	v_add_u32_e32 v2, s10, v189
	v_ashrrev_i32_e32 v3, 31, v2
	v_lshlrev_b64 v[2:3], 11, v[2:3]
	v_lshl_add_u64 v[2:3], s[4:5], 0, v[2:3]
	v_lshl_add_u64 v[2:3], v[2:3], 0, v[160:161]
	s_add_u32 m0, s88, 32768
	v_lshl_add_u64 v[2:3], v[2:3], 0, s[92:93]
	v_xor_b32_e32 v2, v159, v2
	global_load_lds_dwordx4 v[2:3], off
	v_add_u32_e32 v2, s9, v190
	v_min_i32_e32 v2, 0x7fff, v2
	v_ashrrev_i32_e32 v3, 31, v2
	v_lshlrev_b64 v[2:3], 11, v[2:3]
	v_lshl_add_u64 v[2:3], s[2:3], 0, v[2:3]
	v_lshl_add_u64 v[2:3], v[2:3], 0, v[160:161]
	s_add_u32 m0, s88, 8192
	v_lshl_add_u64 v[2:3], v[2:3], 0, s[92:93]
	v_xor_b32_e32 v2, v159, v2
	global_load_lds_dwordx4 v[2:3], off
	v_add_u32_e32 v2, s10, v190
	v_ashrrev_i32_e32 v3, 31, v2
	v_lshlrev_b64 v[2:3], 11, v[2:3]
	v_lshl_add_u64 v[2:3], s[4:5], 0, v[2:3]
	v_lshl_add_u64 v[2:3], v[2:3], 0, v[160:161]
	v_add_u32_e32 v4, 0x80, v189
	s_add_u32 m0, s88, 40960
	v_lshl_add_u64 v[2:3], v[2:3], 0, s[92:93]
	v_xor_b32_e32 v2, v159, v2
	global_load_lds_dwordx4 v[2:3], off
	v_add_u32_e32 v2, s9, v4
	v_min_i32_e32 v2, 0x7fff, v2
	v_ashrrev_i32_e32 v3, 31, v2
	v_lshlrev_b64 v[2:3], 11, v[2:3]
	v_lshl_add_u64 v[2:3], s[2:3], 0, v[2:3]
	v_lshl_add_u64 v[2:3], v[2:3], 0, v[160:161]
	s_add_u32 m0, s88, 16384
	v_lshl_add_u64 v[2:3], v[2:3], 0, s[92:93]
	v_xor_b32_e32 v2, v159, v2
	global_load_lds_dwordx4 v[2:3], off
	v_add_u32_e32 v2, s10, v4
	v_ashrrev_i32_e32 v3, 31, v2
	v_lshlrev_b64 v[2:3], 11, v[2:3]
	v_lshl_add_u64 v[2:3], s[4:5], 0, v[2:3]
	v_lshl_add_u64 v[2:3], v[2:3], 0, v[160:161]
	v_add_u32_e32 v4, 0xc0, v189
	s_add_u32 m0, s88, 49152
	v_lshl_add_u64 v[2:3], v[2:3], 0, s[92:93]
	v_xor_b32_e32 v2, v159, v2
	global_load_lds_dwordx4 v[2:3], off
	v_add_u32_e32 v2, s9, v4
	v_min_i32_e32 v2, 0x7fff, v2
	v_ashrrev_i32_e32 v3, 31, v2
	v_lshlrev_b64 v[2:3], 11, v[2:3]
	v_lshl_add_u64 v[2:3], s[2:3], 0, v[2:3]
	v_lshl_add_u64 v[2:3], v[2:3], 0, v[160:161]
	s_add_u32 m0, s88, 24576
	v_lshl_add_u64 v[2:3], v[2:3], 0, s[92:93]
	v_xor_b32_e32 v2, v159, v2
	global_load_lds_dwordx4 v[2:3], off
	v_add_u32_e32 v2, s10, v4
	v_ashrrev_i32_e32 v3, 31, v2
	v_lshlrev_b64 v[2:3], 11, v[2:3]
	v_lshl_add_u64 v[2:3], s[4:5], 0, v[2:3]
	v_lshl_add_u64 v[2:3], v[2:3], 0, v[160:161]
	s_add_u32 m0, s88, 57344
	v_lshl_add_u64 v[2:3], v[2:3], 0, s[92:93]
	v_xor_b32_e32 v2, v159, v2
	global_load_lds_dwordx4 v[2:3], off
	s_waitcnt vmcnt(0)

.LBB0_2409:
	s_mul_hi_i32 s2, s82, 0x88888889
	s_add_i32 s2, s2, s82
	s_lshr_b32 s3, s2, 31
	s_ashr_i32 s5, s2, 3
	s_add_i32 s5, s5, s3
	s_lshl_b32 s85, s5, 8
	s_waitcnt lgkmcnt(0)
	v_add_u32_e32 v0, s85, v189
	v_min_i32_e32 v0, 0x7fff, v0
	v_ashrrev_i32_e32 v1, 31, v0
	v_lshlrev_b64 v[0:1], 11, v[0:1]
	s_mul_i32 s2, s5, 0xf00
	v_lshl_add_u64 v[172:173], v[168:169], 0, v[0:1]
	v_subrev_u32_e32 v0, s2, v197
	v_ashrrev_i32_e32 v1, 31, v0
	v_lshlrev_b64 v[0:1], 11, v[0:1]
	v_lshl_add_u64 v[180:181], v[170:171], 0, v[0:1]
	v_subrev_u32_e32 v0, s2, v198
	v_ashrrev_i32_e32 v1, 31, v0
	v_lshlrev_b64 v[0:1], 11, v[0:1]
	v_lshl_add_u64 v[182:183], v[170:171], 0, v[0:1]
	v_subrev_u32_e32 v0, s2, v199
	v_ashrrev_i32_e32 v1, 31, v0
	v_add_u32_e32 v2, s85, v190
	v_add_u32_e32 v4, s85, v163
	v_add_u32_e32 v6, s85, v192
	v_lshlrev_b64 v[0:1], 11, v[0:1]
	v_min_i32_e32 v2, 0x7fff, v2
	v_min_i32_e32 v4, 0x7fff, v4
	v_min_i32_e32 v6, 0x7fff, v6
	v_lshl_add_u64 v[184:185], v[170:171], 0, v[0:1]
	v_subrev_u32_e32 v0, s2, v200
	v_ashrrev_i32_e32 v3, 31, v2
	v_ashrrev_i32_e32 v5, 31, v4
	v_ashrrev_i32_e32 v7, 31, v6
	v_ashrrev_i32_e32 v1, 31, v0
	v_lshlrev_b64 v[2:3], 11, v[2:3]
	v_lshlrev_b64 v[4:5], 11, v[4:5]
	v_lshlrev_b64 v[6:7], 11, v[6:7]
	v_lshlrev_b64 v[0:1], 11, v[0:1]
	s_mov_b32 s4, s82
	v_lshl_add_u64 v[174:175], v[168:169], 0, v[2:3]
	v_lshl_add_u64 v[176:177], v[168:169], 0, v[4:5]
	v_lshl_add_u64 v[178:179], v[168:169], 0, v[6:7]
	v_lshl_add_u64 v[186:187], v[170:171], 0, v[0:1]
	s_mov_b64 s[2:3], 0
	s_mov_b32 s6, s21
	v_mov_b32_e32 v0, 0
	v_mov_b32_e32 v1, v161
	v_mov_b32_e32 v2, v161
	v_mov_b32_e32 v3, v161
	v_mov_b32_e32 v4, v161
	v_mov_b32_e32 v5, v161
	v_mov_b32_e32 v6, v161
	v_mov_b32_e32 v7, v161
	v_mov_b32_e32 v8, v161
	v_mov_b32_e32 v9, v161
	v_mov_b32_e32 v10, v161
	v_mov_b32_e32 v11, v161
	v_mov_b32_e32 v12, v161
	v_mov_b32_e32 v13, v161
	v_mov_b32_e32 v14, v161
	v_mov_b32_e32 v15, v161
	v_mov_b32_e32 v16, 0
	v_mov_b32_e32 v17, v161
	v_mov_b32_e32 v18, v161
	v_mov_b32_e32 v19, v161
	v_mov_b32_e32 v20, v161
	v_mov_b32_e32 v21, v161
	v_mov_b32_e32 v22, v161
	v_mov_b32_e32 v23, v161
	v_mov_b32_e32 v24, v161
	v_mov_b32_e32 v25, v161
	v_mov_b32_e32 v26, v161
	v_mov_b32_e32 v27, v161
	v_mov_b32_e32 v28, v161
	v_mov_b32_e32 v29, v161
	v_mov_b32_e32 v30, v161
	v_mov_b32_e32 v31, v161
	v_mov_b32_e32 v32, 0
	v_mov_b32_e32 v33, v161
	v_mov_b32_e32 v34, v161
	v_mov_b32_e32 v35, v161
	v_mov_b32_e32 v36, v161
	v_mov_b32_e32 v37, v161
	v_mov_b32_e32 v38, v161
	v_mov_b32_e32 v39, v161
	v_mov_b32_e32 v40, v161
	v_mov_b32_e32 v41, v161
	v_mov_b32_e32 v42, v161
	v_mov_b32_e32 v43, v161
	v_mov_b32_e32 v44, v161
	v_mov_b32_e32 v45, v161
	v_mov_b32_e32 v46, v161
	v_mov_b32_e32 v47, v161
	v_mov_b32_e32 v48, 0
	v_mov_b32_e32 v49, v161
	v_mov_b32_e32 v50, v161
	v_mov_b32_e32 v51, v161
	v_mov_b32_e32 v52, v161
	v_mov_b32_e32 v53, v161
	v_mov_b32_e32 v54, v161
	v_mov_b32_e32 v55, v161
	v_mov_b32_e32 v56, v161
	v_mov_b32_e32 v57, v161
	v_mov_b32_e32 v58, v161
	v_mov_b32_e32 v59, v161
	v_mov_b32_e32 v60, v161
	v_mov_b32_e32 v61, v161
	v_mov_b32_e32 v62, v161
	v_mov_b32_e32 v63, v161
	v_mov_b32_e32 v64, 0
	v_mov_b32_e32 v65, v161
	v_mov_b32_e32 v66, v161
	v_mov_b32_e32 v67, v161
	v_mov_b32_e32 v68, v161
	v_mov_b32_e32 v69, v161
	v_mov_b32_e32 v70, v161
	v_mov_b32_e32 v71, v161
	v_mov_b32_e32 v72, v161
	v_mov_b32_e32 v73, v161
	v_mov_b32_e32 v74, v161
	v_mov_b32_e32 v75, v161
	v_mov_b32_e32 v76, v161
	v_mov_b32_e32 v77, v161
	v_mov_b32_e32 v78, v161
	v_mov_b32_e32 v79, v161
	v_mov_b32_e32 v80, 0
	v_mov_b32_e32 v81, v161
	v_mov_b32_e32 v82, v161
	v_mov_b32_e32 v83, v161
	v_mov_b32_e32 v84, v161
	v_mov_b32_e32 v85, v161
	v_mov_b32_e32 v86, v161
	v_mov_b32_e32 v87, v161
	v_mov_b32_e32 v88, v161
	v_mov_b32_e32 v89, v161
	v_mov_b32_e32 v90, v161
	v_mov_b32_e32 v91, v161
	v_mov_b32_e32 v92, v161
	v_mov_b32_e32 v93, v161
	v_mov_b32_e32 v94, v161
	v_mov_b32_e32 v95, v161
	v_mov_b32_e32 v96, 0
	v_mov_b32_e32 v97, v161
	v_mov_b32_e32 v98, v161
	v_mov_b32_e32 v99, v161
	v_mov_b32_e32 v100, v161
	v_mov_b32_e32 v101, v161
	v_mov_b32_e32 v102, v161
	v_mov_b32_e32 v103, v161
	v_mov_b32_e32 v104, v161
	v_mov_b32_e32 v105, v161
	v_mov_b32_e32 v106, v161
	v_mov_b32_e32 v107, v161
	v_mov_b32_e32 v108, v161
	v_mov_b32_e32 v109, v161
	v_mov_b32_e32 v110, v161
	v_mov_b32_e32 v111, v161
	v_mov_b32_e32 v112, 0
	v_mov_b32_e32 v113, v161
	v_mov_b32_e32 v114, v161
	v_mov_b32_e32 v115, v161
	v_mov_b32_e32 v116, v161
	v_mov_b32_e32 v117, v161
	v_mov_b32_e32 v118, v161
	v_mov_b32_e32 v119, v161
	v_mov_b32_e32 v120, v161
	v_mov_b32_e32 v121, v161
	v_mov_b32_e32 v122, v161
	v_mov_b32_e32 v123, v161
	v_mov_b32_e32 v124, v161
	v_mov_b32_e32 v125, v161
	v_mov_b32_e32 v126, v161
	v_mov_b32_e32 v127, v161
	v_mbcnt_hi_u32_b32 v128, -1, v210
	s_and_b32 s90, s70, 0x40
	v_and_b32_e32 v159, 48, v128
	v_or_b32_e32 v159, s90, v159
	v_and_b32_e32 v129, 31, v128
	v_lshrrev_b32_e32 v130, 5, v128
	v_bfe_u32 v131, v128, 1, 3
	v_lshlrev_b32_e32 v132, 7, v129
	s_lshr_b32 s91, s70, 7
	s_lshl_b32 s91, s91, 13
	s_lshl_b32 s90, s90, 8
	s_add_u32 s90, s90, 0x8000
	s_lshl_b32 s88, s70, 4
	s_mov_b32 s89, 0x10000
	s_lshl_b32 s92, s22, 4
	s_and_b32 s92, s92, 0x780
	s_mov_b32 s93, 0
	v_xor_b32_e32 v133, v130, v131
	v_lshl_add_u32 v133, v133, 4, v132
	v_add_u32_e32 v228, s91, v133
	v_add_u32_e32 v232, s90, v133
	v_or_b32_e32 v133, 2, v130
	v_xor_b32_e32 v133, v133, v131
	v_lshl_add_u32 v133, v133, 4, v132
	v_add_u32_e32 v229, s91, v133
	v_add_u32_e32 v233, s90, v133
	v_or_b32_e32 v133, 4, v130
	v_xor_b32_e32 v133, v133, v131
	v_lshl_add_u32 v133, v133, 4, v132
	v_add_u32_e32 v230, s91, v133
	v_add_u32_e32 v234, s90, v133
	v_or_b32_e32 v133, 6, v130
	v_xor_b32_e32 v133, v133, v131
	v_lshl_add_u32 v133, v133, 4, v132
	v_add_u32_e32 v231, s91, v133
	v_add_u32_e32 v235, s90, v133
	s_barrier
	ds_read_b128 v[202:205], v228
	ds_read_b128 v[212:215], v232
	ds_read_b128 v[206:209], v228 offset:4096
	ds_read_b128 v[216:219], v232 offset:4096
	ds_read_b128 v[220:223], v232 offset:8192
	ds_read_b128 v[224:227], v232 offset:12288
	s_add_u32 s94, s2, s92
	s_add_u32 s94, s94, 0x80
	s_and_b32 s94, s94, 0x780
	s_sub_u32 s94, s94, 0x80
	s_subb_u32 s95, 0, 0
	s_add_u32 s90, s88, s89
	s_add_u32 m0, s90, 0
	v_lshl_add_u64 v[152:153], v[172:173], 0, s[94:95]
	v_xor_b32_e32 v152, v159, v152
	global_load_lds_dwordx4 v[152:153], off
	s_add_u32 m0, s90, 32768
	v_lshl_add_u64 v[154:155], v[180:181], 0, s[94:95]
	v_xor_b32_e32 v154, v159, v154
	global_load_lds_dwordx4 v[154:155], off
	s_add_u32 m0, s90, 8192
	v_lshl_add_u64 v[156:157], v[174:175], 0, s[94:95]
	v_xor_b32_e32 v156, v159, v156
	global_load_lds_dwordx4 v[156:157], off
	s_add_u32 m0, s90, 40960
	v_lshl_add_u64 v[152:153], v[182:183], 0, s[94:95]
	v_xor_b32_e32 v152, v159, v152
	global_load_lds_dwordx4 v[152:153], off
	s_add_u32 m0, s90, 16384
	v_lshl_add_u64 v[154:155], v[176:177], 0, s[94:95]
	v_xor_b32_e32 v154, v159, v154
	global_load_lds_dwordx4 v[154:155], off
	s_add_u32 m0, s90, 49152
	v_lshl_add_u64 v[156:157], v[184:185], 0, s[94:95]
	v_xor_b32_e32 v156, v159, v156
	global_load_lds_dwordx4 v[156:157], off
	s_add_u32 m0, s90, 24576
	v_lshl_add_u64 v[152:153], v[178:179], 0, s[94:95]
	v_xor_b32_e32 v152, v159, v152
	global_load_lds_dwordx4 v[152:153], off
	s_add_u32 m0, s90, 57344
	v_lshl_add_u64 v[154:155], v[186:187], 0, s[94:95]
	v_xor_b32_e32 v154, v159, v154
	global_load_lds_dwordx4 v[154:155], off
	s_xor_b32 s89, s89, 0x10000

.LBB0_2413:
	ds_read_b128 v[128:131], v229
	ds_read_b128 v[136:139], v233
	ds_read_b128 v[132:135], v229 offset:4096
	ds_read_b128 v[140:143], v233 offset:4096
	ds_read_b128 v[144:147], v233 offset:8192
	ds_read_b128 v[148:151], v233 offset:12288
	s_waitcnt lgkmcnt(6)
	v_mfma_f32_32x32x16_bf16 v[112:127], v[202:205], v[212:215], v[112:127]
	v_mfma_f32_32x32x16_bf16 v[48:63], v[206:209], v[212:215], v[48:63]
	v_mfma_f32_32x32x16_bf16 v[96:111], v[202:205], v[216:219], v[96:111]
	v_mfma_f32_32x32x16_bf16 v[32:47], v[206:209], v[216:219], v[32:47]
	v_mfma_f32_32x32x16_bf16 v[80:95], v[202:205], v[220:223], v[80:95]
	v_mfma_f32_32x32x16_bf16 v[16:31], v[206:209], v[220:223], v[16:31]
	v_mfma_f32_32x32x16_bf16 v[64:79], v[202:205], v[224:227], v[64:79]
	v_mfma_f32_32x32x16_bf16 v[0:15], v[206:209], v[224:227], v[0:15]
	ds_read_b128 v[202:205], v230
	ds_read_b128 v[212:215], v234
	ds_read_b128 v[206:209], v230 offset:4096
	ds_read_b128 v[216:219], v234 offset:4096
	ds_read_b128 v[220:223], v234 offset:8192
	ds_read_b128 v[224:227], v234 offset:12288
	s_waitcnt lgkmcnt(6)
	v_mfma_f32_32x32x16_bf16 v[112:127], v[128:131], v[136:139], v[112:127]
	v_mfma_f32_32x32x16_bf16 v[48:63], v[132:135], v[136:139], v[48:63]
	v_mfma_f32_32x32x16_bf16 v[96:111], v[128:131], v[140:143], v[96:111]
	v_mfma_f32_32x32x16_bf16 v[32:47], v[132:135], v[140:143], v[32:47]
	v_mfma_f32_32x32x16_bf16 v[80:95], v[128:131], v[144:147], v[80:95]
	v_mfma_f32_32x32x16_bf16 v[16:31], v[132:135], v[144:147], v[16:31]
	v_mfma_f32_32x32x16_bf16 v[64:79], v[128:131], v[148:151], v[64:79]
	v_mfma_f32_32x32x16_bf16 v[0:15], v[132:135], v[148:151], v[0:15]
	ds_read_b128 v[128:131], v231
	ds_read_b128 v[136:139], v235
	ds_read_b128 v[132:135], v231 offset:4096
	ds_read_b128 v[140:143], v235 offset:4096
	ds_read_b128 v[144:147], v235 offset:8192
	ds_read_b128 v[148:151], v235 offset:12288
	s_waitcnt lgkmcnt(6)
	v_mfma_f32_32x32x16_bf16 v[112:127], v[202:205], v[212:215], v[112:127]
	v_mfma_f32_32x32x16_bf16 v[48:63], v[206:209], v[212:215], v[48:63]
	v_mfma_f32_32x32x16_bf16 v[96:111], v[202:205], v[216:219], v[96:111]
	v_mfma_f32_32x32x16_bf16 v[32:47], v[206:209], v[216:219], v[32:47]
	v_mfma_f32_32x32x16_bf16 v[80:95], v[202:205], v[220:223], v[80:95]
	v_mfma_f32_32x32x16_bf16 v[16:31], v[206:209], v[220:223], v[16:31]
	v_mfma_f32_32x32x16_bf16 v[64:79], v[202:205], v[224:227], v[64:79]
	v_mfma_f32_32x32x16_bf16 v[0:15], v[206:209], v[224:227], v[0:15]
	s_waitcnt vmcnt(0) lgkmcnt(0)
	s_barrier
	v_xor_b32_e32 v228, 0x10000, v228
	v_xor_b32_e32 v232, 0x10000, v232
	v_mfma_f32_32x32x16_bf16 v[112:127], v[128:131], v[136:139], v[112:127]
	v_xor_b32_e32 v229, 0x10000, v229
	v_xor_b32_e32 v233, 0x10000, v233
	v_mfma_f32_32x32x16_bf16 v[48:63], v[132:135], v[136:139], v[48:63]
	v_xor_b32_e32 v230, 0x10000, v230
	v_xor_b32_e32 v234, 0x10000, v234
	v_mfma_f32_32x32x16_bf16 v[96:111], v[128:131], v[140:143], v[96:111]
	v_xor_b32_e32 v231, 0x10000, v231
	v_xor_b32_e32 v235, 0x10000, v235
	v_mfma_f32_32x32x16_bf16 v[32:47], v[132:135], v[140:143], v[32:47]
	v_mfma_f32_32x32x16_bf16 v[80:95], v[128:131], v[144:147], v[80:95]
	v_mfma_f32_32x32x16_bf16 v[16:31], v[132:135], v[144:147], v[16:31]
	v_mfma_f32_32x32x16_bf16 v[64:79], v[128:131], v[148:151], v[64:79]
	v_mfma_f32_32x32x16_bf16 v[0:15], v[132:135], v[148:151], v[0:15]
	s_mul_i32 s2, s5, -15
	s_add_i32 s2, s2, s4
	s_lshl_b32 s2, s2, 8
	s_or_b32 s20, s2, s73
	s_add_i32 s85, s85, s72
	s_ashr_i32 s54, s20, 6
	s_cmp_gt_i32 s54, 15
	s_cselect_b64 s[4:5], -1, 0
	s_cmp_gt_u32 s54, 39
	s_cselect_b64 s[48:49], -1, 0
	s_cmp_gt_u32 s54, 55
	s_cselect_b64 s[38:39], -1, 0
	s_add_i32 s12, s54, -16
	s_lshr_b32 s83, s12, 2
	s_mov_b64 s[2:3], -1
	s_and_b64 vcc, exec, s[4:5]
	v_mov_b32_e32 v180, v191
	s_nop 0
	v_ashrrev_i32_e32 v203, 3, v180
	v_and_b32_e32 v204, -4, v203
	v_add_u32_e32 v181, s85, v204
	v_and_b32_e32 v176, 31, v180
	v_min_i32_e32 v172, 0x7fff, v181
	s_cbranch_vccz .LBB0_2427
	s_and_b64 vcc, exec, s[48:49]
	s_cbranch_vccz .LBB0_2420
	v_mul_f32_e32 v160, 0xbfb8aa3b, v112
	v_exp_f32_e32 v173, v160
	s_nop 0
	v_mul_f32_e32 v160, 0xbfb8aa3b, v96
	v_exp_f32_e32 v160, v160
	s_and_b64 vcc, exec, s[38:39]
	v_add_f32_e32 v173, 1.0, v173
	s_cbranch_vccz .LBB0_2417
	v_div_scale_f32 v174, s[2:3], v173, v173, 1.0
	v_rcp_f32_e32 v175, v174
	v_add_f32_e32 v177, 1.0, v160
	v_fma_f32 v178, -v174, v175, 1.0
	v_fmac_f32_e32 v175, v178, v175
	v_div_scale_f32 v178, vcc, 1.0, v173, 1.0
	v_mul_f32_e32 v179, v178, v175
	v_fma_f32 v182, -v174, v179, v178
	v_fmac_f32_e32 v179, v182, v175
	v_fma_f32 v174, -v174, v179, v178
	v_div_scale_f32 v178, s[2:3], v177, v177, 1.0
	v_rcp_f32_e32 v182, v178
	v_div_fmas_f32 v174, v174, v175, v179
	v_div_fixup_f32 v174, v174, v173, 1.0
	s_mov_b64 s[2:3], 0
	v_fma_f32 v175, -v178, v182, 1.0
	v_fmac_f32_e32 v182, v175, v182
	v_div_scale_f32 v175, vcc, 1.0, v177, 1.0
	v_mul_f32_e32 v179, v175, v182
	v_fma_f32 v183, -v178, v179, v175
	v_fmac_f32_e32 v179, v183, v182
	v_fma_f32 v175, -v178, v179, v175
	v_div_fmas_f32 v175, v175, v182, v179
	v_div_fixup_f32 v175, v175, v177, 1.0

.LBB0_4473:
	v_mbcnt_hi_u32_b32 v211, -1, v210
	s_load_dwordx2 s[2:3], s[0:1], 0x138
	s_load_dwordx2 s[4:5], s[0:1], 0x158
	s_ashr_i32 s7, s6, 31
	v_mov_b32_e32 v1, v211
	s_and_b32 s7, s7, s42
	s_waitcnt lgkmcnt(0)
	s_add_i32 s54, s7, s6
	v_add_u32_e32 v0, s70, v1
	v_ashrrev_i32_e32 v212, 3, v0
	v_readfirstlane_b32 s8, v0
	v_lshlrev_b32_e32 v0, 3, v1
	v_and_b32_e32 v0, 56, v0
	s_cmpk_lt_i32 s54, 0x200
	s_cselect_b64 s[6:7], -1, 0
	s_cmpk_gt_i32 s54, 0x1ff
	v_lshlrev_b32_e32 v168, 1, v0
	v_add_u32_e32 v213, 64, v212
	s_cbranch_scc1 .LBB0_4475
	s_ashr_i32 s9, s54, 31
	s_lshr_b32 s9, s9, 30
	s_add_i32 s9, s54, s9
	s_ashr_i32 s9, s9, 2
	s_lshl_b32 s10, s9, 8
	v_add_u32_e32 v2, s10, v212
	v_min_i32_e32 v2, 0x7fff, v2
	v_ashrrev_i32_e32 v3, 31, v2
	v_lshlrev_b64 v[2:3], 11, v[2:3]
	s_lshl_b32 s9, s9, 10
	s_lshl_b32 s11, s54, 8
	v_lshl_add_u64 v[2:3], s[4:5], 0, v[2:3]
	v_mov_b32_e32 v169, 0
	s_sub_i32 s9, s11, s9
	v_lshl_add_u64 v[2:3], v[2:3], 0, v[168:169]
	v_mbcnt_hi_u32_b32 v158, -1, v210
	s_and_b32 s90, s70, 0x40
	v_and_b32_e32 v159, 48, v158
	v_or_b32_e32 v159, s90, v159
	s_lshl_b32 s88, s70, 4
	s_lshl_b32 s92, s22, 4
	s_and_b32 s92, s92, 0x780
	s_mov_b32 s93, 0
	s_add_u32 m0, s88, 0
	v_lshl_add_u64 v[2:3], v[2:3], 0, s[92:93]
	v_xor_b32_e32 v2, v159, v2
	global_load_lds_dwordx4 v[2:3], off
	v_add_u32_e32 v2, s9, v212
	v_ashrrev_i32_e32 v3, 31, v2
	v_lshlrev_b64 v[2:3], 11, v[2:3]
	v_lshl_add_u64 v[2:3], s[2:3], 0, v[2:3]
	v_lshl_add_u64 v[2:3], v[2:3], 0, v[168:169]
	s_add_u32 m0, s88, 32768
	v_lshl_add_u64 v[2:3], v[2:3], 0, s[92:93]
	v_xor_b32_e32 v2, v159, v2
	global_load_lds_dwordx4 v[2:3], off
	v_add_u32_e32 v2, s10, v213
	v_min_i32_e32 v2, 0x7fff, v2
	v_ashrrev_i32_e32 v3, 31, v2
	v_lshlrev_b64 v[2:3], 11, v[2:3]
	v_lshl_add_u64 v[2:3], s[4:5], 0, v[2:3]
	v_lshl_add_u64 v[2:3], v[2:3], 0, v[168:169]
	s_add_u32 m0, s88, 8192
	v_lshl_add_u64 v[2:3], v[2:3], 0, s[92:93]
	v_xor_b32_e32 v2, v159, v2
	global_load_lds_dwordx4 v[2:3], off
	v_add_u32_e32 v2, s9, v213
	v_ashrrev_i32_e32 v3, 31, v2
	v_lshlrev_b64 v[2:3], 11, v[2:3]
	v_lshl_add_u64 v[2:3], s[2:3], 0, v[2:3]
	v_lshl_add_u64 v[2:3], v[2:3], 0, v[168:169]
	v_add_u32_e32 v4, 0x80, v212
	s_add_u32 m0, s88, 40960
	v_lshl_add_u64 v[2:3], v[2:3], 0, s[92:93]
	v_xor_b32_e32 v2, v159, v2
	global_load_lds_dwordx4 v[2:3], off
	v_add_u32_e32 v2, s10, v4
	v_min_i32_e32 v2, 0x7fff, v2
	v_ashrrev_i32_e32 v3, 31, v2
	v_lshlrev_b64 v[2:3], 11, v[2:3]
	v_lshl_add_u64 v[2:3], s[4:5], 0, v[2:3]
	v_lshl_add_u64 v[2:3], v[2:3], 0, v[168:169]
	s_add_u32 m0, s88, 16384
	v_lshl_add_u64 v[2:3], v[2:3], 0, s[92:93]
	v_xor_b32_e32 v2, v159, v2
	global_load_lds_dwordx4 v[2:3], off
	v_add_u32_e32 v2, s9, v4
	v_ashrrev_i32_e32 v3, 31, v2
	v_lshlrev_b64 v[2:3], 11, v[2:3]
	v_lshl_add_u64 v[2:3], s[2:3], 0, v[2:3]
	v_lshl_add_u64 v[2:3], v[2:3], 0, v[168:169]
	v_add_u32_e32 v4, 0xc0, v212
	s_add_u32 m0, s88, 49152
	v_lshl_add_u64 v[2:3], v[2:3], 0, s[92:93]
	v_xor_b32_e32 v2, v159, v2
	global_load_lds_dwordx4 v[2:3], off
	v_add_u32_e32 v2, s10, v4
	v_min_i32_e32 v2, 0x7fff, v2
	v_ashrrev_i32_e32 v3, 31, v2
	v_lshlrev_b64 v[2:3], 11, v[2:3]
	v_lshl_add_u64 v[2:3], s[4:5], 0, v[2:3]
	v_lshl_add_u64 v[2:3], v[2:3], 0, v[168:169]
	s_add_u32 m0, s88, 24576
	v_lshl_add_u64 v[2:3], v[2:3], 0, s[92:93]
	v_xor_b32_e32 v2, v159, v2
	global_load_lds_dwordx4 v[2:3], off
	v_add_u32_e32 v2, s9, v4
	v_ashrrev_i32_e32 v3, 31, v2
	v_lshlrev_b64 v[2:3], 11, v[2:3]
	v_lshl_add_u64 v[2:3], s[2:3], 0, v[2:3]
	v_lshl_add_u64 v[2:3], v[2:3], 0, v[168:169]
	s_add_u32 m0, s88, 57344
	v_lshl_add_u64 v[2:3], v[2:3], 0, s[92:93]
	v_xor_b32_e32 v2, v159, v2
	global_load_lds_dwordx4 v[2:3], off
	s_waitcnt vmcnt(0)

.LBB0_4478:
	s_ashr_i32 s2, s54, 31
	s_lshr_b32 s2, s2, 30
	s_add_i32 s2, s54, s2
	s_ashr_i32 s2, s2, 2
	s_lshl_b32 s4, s2, 8
	v_add_u32_e32 v0, s4, v212
	v_min_i32_e32 v0, 0x7fff, v0
	v_ashrrev_i32_e32 v1, 31, v0
	s_lshl_b32 s6, s2, 10
	v_lshlrev_b64 v[0:1], 11, v[0:1]
	v_lshl_add_u64 v[160:161], v[176:177], 0, v[0:1]
	v_subrev_u32_e32 v0, s6, v220
	v_ashrrev_i32_e32 v1, 31, v0
	v_lshlrev_b64 v[0:1], 11, v[0:1]
	v_lshl_add_u64 v[180:181], v[178:179], 0, v[0:1]
	v_subrev_u32_e32 v0, s6, v221
	v_ashrrev_i32_e32 v1, 31, v0
	v_lshlrev_b64 v[0:1], 11, v[0:1]
	v_lshl_add_u64 v[182:183], v[178:179], 0, v[0:1]
	v_subrev_u32_e32 v0, s6, v222
	v_ashrrev_i32_e32 v1, 31, v0
	v_add_u32_e32 v2, s4, v213
	v_add_u32_e32 v4, s4, v171
	v_add_u32_e32 v6, s4, v215
	v_lshlrev_b64 v[0:1], 11, v[0:1]
	v_min_i32_e32 v2, 0x7fff, v2
	v_min_i32_e32 v4, 0x7fff, v4
	v_min_i32_e32 v6, 0x7fff, v6
	v_lshl_add_u64 v[184:185], v[178:179], 0, v[0:1]
	v_subrev_u32_e32 v0, s6, v223
	v_ashrrev_i32_e32 v3, 31, v2
	v_ashrrev_i32_e32 v5, 31, v4
	v_ashrrev_i32_e32 v7, 31, v6
	v_ashrrev_i32_e32 v1, 31, v0
	v_lshlrev_b64 v[2:3], 11, v[2:3]
	v_lshlrev_b64 v[4:5], 11, v[4:5]
	v_lshlrev_b64 v[6:7], 11, v[6:7]
	v_lshlrev_b64 v[0:1], 11, v[0:1]
	s_mov_b32 s5, s54
	v_lshl_add_u64 v[162:163], v[176:177], 0, v[2:3]
	v_lshl_add_u64 v[164:165], v[176:177], 0, v[4:5]
	v_lshl_add_u64 v[166:167], v[176:177], 0, v[6:7]
	v_lshl_add_u64 v[186:187], v[178:179], 0, v[0:1]
	s_mov_b64 s[2:3], 0
	s_mov_b32 s7, 0
	v_mov_b32_e32 v0, 0
	v_mov_b32_e32 v1, v169
	v_mov_b32_e32 v2, v169
	v_mov_b32_e32 v3, v169
	v_mov_b32_e32 v4, v169
	v_mov_b32_e32 v5, v169
	v_mov_b32_e32 v6, v169
	v_mov_b32_e32 v7, v169
	v_mov_b32_e32 v8, v169
	v_mov_b32_e32 v9, v169
	v_mov_b32_e32 v10, v169
	v_mov_b32_e32 v11, v169
	v_mov_b32_e32 v12, v169
	v_mov_b32_e32 v13, v169
	v_mov_b32_e32 v14, v169
	v_mov_b32_e32 v15, v169
	v_mov_b32_e32 v16, 0
	v_mov_b32_e32 v17, v169
	v_mov_b32_e32 v18, v169
	v_mov_b32_e32 v19, v169
	v_mov_b32_e32 v20, v169
	v_mov_b32_e32 v21, v169
	v_mov_b32_e32 v22, v169
	v_mov_b32_e32 v23, v169
	v_mov_b32_e32 v24, v169
	v_mov_b32_e32 v25, v169
	v_mov_b32_e32 v26, v169
	v_mov_b32_e32 v27, v169
	v_mov_b32_e32 v28, v169
	v_mov_b32_e32 v29, v169
	v_mov_b32_e32 v30, v169
	v_mov_b32_e32 v31, v169
	v_mov_b32_e32 v32, 0
	v_mov_b32_e32 v33, v169
	v_mov_b32_e32 v34, v169
	v_mov_b32_e32 v35, v169
	v_mov_b32_e32 v36, v169
	v_mov_b32_e32 v37, v169
	v_mov_b32_e32 v38, v169
	v_mov_b32_e32 v39, v169
	v_mov_b32_e32 v40, v169
	v_mov_b32_e32 v41, v169
	v_mov_b32_e32 v42, v169
	v_mov_b32_e32 v43, v169
	v_mov_b32_e32 v44, v169
	v_mov_b32_e32 v45, v169
	v_mov_b32_e32 v46, v169
	v_mov_b32_e32 v47, v169
	v_mov_b32_e32 v48, 0
	v_mov_b32_e32 v49, v169
	v_mov_b32_e32 v50, v169
	v_mov_b32_e32 v51, v169
	v_mov_b32_e32 v52, v169
	v_mov_b32_e32 v53, v169
	v_mov_b32_e32 v54, v169
	v_mov_b32_e32 v55, v169
	v_mov_b32_e32 v56, v169
	v_mov_b32_e32 v57, v169
	v_mov_b32_e32 v58, v169
	v_mov_b32_e32 v59, v169
	v_mov_b32_e32 v60, v169
	v_mov_b32_e32 v61, v169
	v_mov_b32_e32 v62, v169
	v_mov_b32_e32 v63, v169
	v_mov_b32_e32 v64, 0
	v_mov_b32_e32 v65, v169
	v_mov_b32_e32 v66, v169
	v_mov_b32_e32 v67, v169
	v_mov_b32_e32 v68, v169
	v_mov_b32_e32 v69, v169
	v_mov_b32_e32 v70, v169
	v_mov_b32_e32 v71, v169
	v_mov_b32_e32 v72, v169
	v_mov_b32_e32 v73, v169
	v_mov_b32_e32 v74, v169
	v_mov_b32_e32 v75, v169
	v_mov_b32_e32 v76, v169
	v_mov_b32_e32 v77, v169
	v_mov_b32_e32 v78, v169
	v_mov_b32_e32 v79, v169
	v_mov_b32_e32 v80, 0
	v_mov_b32_e32 v81, v169
	v_mov_b32_e32 v82, v169
	v_mov_b32_e32 v83, v169
	v_mov_b32_e32 v84, v169
	v_mov_b32_e32 v85, v169
	v_mov_b32_e32 v86, v169
	v_mov_b32_e32 v87, v169
	v_mov_b32_e32 v88, v169
	v_mov_b32_e32 v89, v169
	v_mov_b32_e32 v90, v169
	v_mov_b32_e32 v91, v169
	v_mov_b32_e32 v92, v169
	v_mov_b32_e32 v93, v169
	v_mov_b32_e32 v94, v169
	v_mov_b32_e32 v95, v169
	s_waitcnt vmcnt(7)
	v_mov_b32_e32 v96, 0
	v_mov_b32_e32 v97, v169
	v_mov_b32_e32 v98, v169
	v_mov_b32_e32 v99, v169
	s_waitcnt vmcnt(6)
	v_mov_b32_e32 v100, v169
	v_mov_b32_e32 v101, v169
	v_mov_b32_e32 v102, v169
	v_mov_b32_e32 v103, v169
	s_waitcnt vmcnt(5)
	v_mov_b32_e32 v104, v169
	v_mov_b32_e32 v105, v169
	v_mov_b32_e32 v106, v169
	v_mov_b32_e32 v107, v169
	s_waitcnt vmcnt(4)
	v_mov_b32_e32 v108, v169
	v_mov_b32_e32 v109, v169
	v_mov_b32_e32 v110, v169
	v_mov_b32_e32 v111, v169
	s_waitcnt vmcnt(3)
	v_mov_b32_e32 v112, 0
	v_mov_b32_e32 v113, v169
	v_mov_b32_e32 v114, v169
	v_mov_b32_e32 v115, v169
	s_waitcnt vmcnt(2)
	v_mov_b32_e32 v116, v169
	v_mov_b32_e32 v117, v169
	v_mov_b32_e32 v118, v169
	v_mov_b32_e32 v119, v169
	s_waitcnt vmcnt(1)
	v_mov_b32_e32 v120, v169
	v_mov_b32_e32 v121, v169
	v_mov_b32_e32 v122, v169
	v_mov_b32_e32 v123, v169
	s_waitcnt vmcnt(0)
	v_mov_b32_e32 v124, v169
	v_mov_b32_e32 v125, v169
	v_mov_b32_e32 v126, v169
	v_mov_b32_e32 v127, v169
	v_mbcnt_hi_u32_b32 v128, -1, v210
	s_and_b32 s90, s70, 0x40
	v_and_b32_e32 v159, 48, v128
	v_or_b32_e32 v159, s90, v159
	v_and_b32_e32 v129, 31, v128
	v_lshrrev_b32_e32 v130, 5, v128
	v_bfe_u32 v131, v128, 1, 3
	v_lshlrev_b32_e32 v132, 7, v129
	s_lshr_b32 s91, s70, 7
	s_lshl_b32 s91, s91, 13
	s_lshl_b32 s90, s90, 8
	s_add_u32 s90, s90, 0x8000
	s_lshl_b32 s88, s70, 4
	s_mov_b32 s89, 0x10000
	s_lshl_b32 s92, s22, 4
	s_and_b32 s92, s92, 0x780
	s_mov_b32 s93, 0
	v_xor_b32_e32 v133, v130, v131
	v_lshl_add_u32 v133, v133, 4, v132
	v_add_u32_e32 v230, s91, v133
	v_add_u32_e32 v234, s90, v133
	v_or_b32_e32 v133, 2, v130
	v_xor_b32_e32 v133, v133, v131
	v_lshl_add_u32 v133, v133, 4, v132
	v_add_u32_e32 v231, s91, v133
	v_add_u32_e32 v235, s90, v133
	v_or_b32_e32 v133, 4, v130
	v_xor_b32_e32 v133, v133, v131
	v_lshl_add_u32 v133, v133, 4, v132
	v_add_u32_e32 v232, s91, v133
	v_add_u32_e32 v236, s90, v133
	v_or_b32_e32 v133, 6, v130
	v_xor_b32_e32 v133, v133, v131
	v_lshl_add_u32 v133, v133, 4, v132
	v_add_u32_e32 v233, s91, v133
	v_add_u32_e32 v237, s90, v133
	s_barrier
	ds_read_b128 v[188:191], v230
	ds_read_b128 v[196:199], v234
	ds_read_b128 v[192:195], v230 offset:4096
	ds_read_b128 v[200:203], v234 offset:4096
	ds_read_b128 v[204:207], v234 offset:8192
	ds_read_b128 v[226:229], v234 offset:12288
	s_add_u32 s94, s2, s92
	s_add_u32 s94, s94, 0x80
	s_and_b32 s94, s94, 0x780
	s_sub_u32 s94, s94, 0x80
	s_subb_u32 s95, 0, 0
	s_add_u32 s90, s88, s89
	s_add_u32 m0, s90, 0
	v_lshl_add_u64 v[152:153], v[160:161], 0, s[94:95]
	v_xor_b32_e32 v152, v159, v152
	global_load_lds_dwordx4 v[152:153], off
	s_add_u32 m0, s90, 32768
	v_lshl_add_u64 v[154:155], v[180:181], 0, s[94:95]
	v_xor_b32_e32 v154, v159, v154
	global_load_lds_dwordx4 v[154:155], off
	s_add_u32 m0, s90, 8192
	v_lshl_add_u64 v[156:157], v[162:163], 0, s[94:95]
	v_xor_b32_e32 v156, v159, v156
	global_load_lds_dwordx4 v[156:157], off
	s_add_u32 m0, s90, 40960
	v_lshl_add_u64 v[152:153], v[182:183], 0, s[94:95]
	v_xor_b32_e32 v152, v159, v152
	global_load_lds_dwordx4 v[152:153], off
	s_add_u32 m0, s90, 16384
	v_lshl_add_u64 v[154:155], v[164:165], 0, s[94:95]
	v_xor_b32_e32 v154, v159, v154
	global_load_lds_dwordx4 v[154:155], off
	s_add_u32 m0, s90, 49152
	v_lshl_add_u64 v[156:157], v[184:185], 0, s[94:95]
	v_xor_b32_e32 v156, v159, v156
	global_load_lds_dwordx4 v[156:157], off
	s_add_u32 m0, s90, 24576
	v_lshl_add_u64 v[152:153], v[166:167], 0, s[94:95]
	v_xor_b32_e32 v152, v159, v152
	global_load_lds_dwordx4 v[152:153], off
	s_add_u32 m0, s90, 57344
	v_lshl_add_u64 v[154:155], v[186:187], 0, s[94:95]
	v_xor_b32_e32 v154, v159, v154
	global_load_lds_dwordx4 v[154:155], off
	s_xor_b32 s89, s89, 0x10000

.LBB0_4482:
	ds_read_b128 v[128:131], v231
	ds_read_b128 v[136:139], v235
	ds_read_b128 v[132:135], v231 offset:4096
	ds_read_b128 v[140:143], v235 offset:4096
	ds_read_b128 v[144:147], v235 offset:8192
	ds_read_b128 v[148:151], v235 offset:12288
	s_waitcnt lgkmcnt(6)
	v_mfma_f32_32x32x16_bf16 v[112:127], v[188:191], v[196:199], v[112:127]
	v_mfma_f32_32x32x16_bf16 v[48:63], v[192:195], v[196:199], v[48:63]
	v_mfma_f32_32x32x16_bf16 v[96:111], v[188:191], v[200:203], v[96:111]
	v_mfma_f32_32x32x16_bf16 v[32:47], v[192:195], v[200:203], v[32:47]
	v_mfma_f32_32x32x16_bf16 v[80:95], v[188:191], v[204:207], v[80:95]
	v_mfma_f32_32x32x16_bf16 v[16:31], v[192:195], v[204:207], v[16:31]
	v_mfma_f32_32x32x16_bf16 v[64:79], v[188:191], v[226:229], v[64:79]
	v_mfma_f32_32x32x16_bf16 v[0:15], v[192:195], v[226:229], v[0:15]
	ds_read_b128 v[188:191], v232
	ds_read_b128 v[196:199], v236
	ds_read_b128 v[192:195], v232 offset:4096
	ds_read_b128 v[200:203], v236 offset:4096
	ds_read_b128 v[204:207], v236 offset:8192
	ds_read_b128 v[226:229], v236 offset:12288
	s_waitcnt lgkmcnt(6)
	v_mfma_f32_32x32x16_bf16 v[112:127], v[128:131], v[136:139], v[112:127]
	v_mfma_f32_32x32x16_bf16 v[48:63], v[132:135], v[136:139], v[48:63]
	v_mfma_f32_32x32x16_bf16 v[96:111], v[128:131], v[140:143], v[96:111]
	v_mfma_f32_32x32x16_bf16 v[32:47], v[132:135], v[140:143], v[32:47]
	v_mfma_f32_32x32x16_bf16 v[80:95], v[128:131], v[144:147], v[80:95]
	v_mfma_f32_32x32x16_bf16 v[16:31], v[132:135], v[144:147], v[16:31]
	v_mfma_f32_32x32x16_bf16 v[64:79], v[128:131], v[148:151], v[64:79]
	v_mfma_f32_32x32x16_bf16 v[0:15], v[132:135], v[148:151], v[0:15]
	ds_read_b128 v[128:131], v233
	ds_read_b128 v[136:139], v237
	ds_read_b128 v[132:135], v233 offset:4096
	ds_read_b128 v[140:143], v237 offset:4096
	ds_read_b128 v[144:147], v237 offset:8192
	ds_read_b128 v[148:151], v237 offset:12288
	s_waitcnt lgkmcnt(6)
	v_mfma_f32_32x32x16_bf16 v[112:127], v[188:191], v[196:199], v[112:127]
	v_mfma_f32_32x32x16_bf16 v[48:63], v[192:195], v[196:199], v[48:63]
	v_mfma_f32_32x32x16_bf16 v[96:111], v[188:191], v[200:203], v[96:111]
	v_mfma_f32_32x32x16_bf16 v[32:47], v[192:195], v[200:203], v[32:47]
	v_mfma_f32_32x32x16_bf16 v[80:95], v[188:191], v[204:207], v[80:95]
	v_mfma_f32_32x32x16_bf16 v[16:31], v[192:195], v[204:207], v[16:31]
	v_mfma_f32_32x32x16_bf16 v[64:79], v[188:191], v[226:229], v[64:79]
	v_mfma_f32_32x32x16_bf16 v[0:15], v[192:195], v[226:229], v[0:15]
	s_waitcnt vmcnt(0) lgkmcnt(0)
	s_barrier
	v_xor_b32_e32 v230, 0x10000, v230
	v_xor_b32_e32 v234, 0x10000, v234
	v_mfma_f32_32x32x16_bf16 v[112:127], v[128:131], v[136:139], v[112:127]
	v_xor_b32_e32 v231, 0x10000, v231
	v_xor_b32_e32 v235, 0x10000, v235
	v_mfma_f32_32x32x16_bf16 v[48:63], v[132:135], v[136:139], v[48:63]
	v_xor_b32_e32 v232, 0x10000, v232
	v_xor_b32_e32 v236, 0x10000, v236
	v_mfma_f32_32x32x16_bf16 v[96:111], v[128:131], v[140:143], v[96:111]
	v_xor_b32_e32 v233, 0x10000, v233
	v_xor_b32_e32 v237, 0x10000, v237
	v_mfma_f32_32x32x16_bf16 v[32:47], v[132:135], v[140:143], v[32:47]
	v_mfma_f32_32x32x16_bf16 v[80:95], v[128:131], v[144:147], v[80:95]
	v_mfma_f32_32x32x16_bf16 v[16:31], v[132:135], v[144:147], v[16:31]
	v_mfma_f32_32x32x16_bf16 v[64:79], v[128:131], v[148:151], v[64:79]
	v_mfma_f32_32x32x16_bf16 v[0:15], v[132:135], v[148:151], v[0:15]
	s_lshl_b32 s2, s5, 8
	s_sub_i32 s2, s2, s6
	v_mov_b32_e32 v168, v214
	s_add_i32 s55, s4, s30
	s_or_b32 s26, s2, s31
	s_ashr_i32 s27, s26, 31
	s_load_dwordx2 s[24:25], s[0:1], 0x140
	v_ashrrev_i32_e32 v180, 3, v168
	v_and_b32_e32 v183, -4, v180
	v_add_u32_e32 v225, s55, v183
	v_add_u32_e32 v190, 8, v225
	v_min_i32_e32 v190, 0x7fff, v190
	v_ashrrev_i32_e32 v190, 12, v190
	v_add_u32_e32 v190, 16, v190
	v_mul_hi_i32_i24_e32 v191, 0x3000, v190
	v_mul_i32_i24_e32 v190, 0x3000, v190
	v_min_i32_e32 v184, 0x7fff, v225
	v_ashrrev_i32_e32 v184, 12, v184
	v_and_b32_e32 v182, 31, v168
	v_add_u32_e32 v184, 16, v184
	v_or_b32_e32 v180, s26, v182
	v_mul_hi_i32_i24_e32 v185, 0x3000, v184
	v_mul_i32_i24_e32 v184, 0x3000, v184
	v_ashrrev_i32_e32 v181, 31, v180
	s_waitcnt lgkmcnt(0)
	v_lshl_add_u64 v[184:185], s[24:25], 0, v[184:185]
	v_lshl_add_u64 v[184:185], v[184:185], 0, s[18:19]
	v_lshlrev_b64 v[180:181], 2, v[180:181]
	v_lshl_add_u64 v[196:197], v[184:185], 0, v[180:181]
	v_lshl_add_u64 v[186:187], s[24:25], 0, v[190:191]
	v_add_u32_e32 v188, 9, v225
	v_add_u32_e32 v190, 10, v225
	v_min_i32_e32 v188, 0x7fff, v188
	v_min_i32_e32 v190, 0x7fff, v190
	v_ashrrev_i32_e32 v188, 12, v188
	v_ashrrev_i32_e32 v190, 12, v190
	v_add_u32_e32 v188, 16, v188
	v_add_u32_e32 v190, 16, v190
	v_mul_hi_i32_i24_e32 v189, 0x3000, v188
	v_mul_i32_i24_e32 v188, 0x3000, v188
	v_mul_hi_i32_i24_e32 v191, 0x3000, v190
	v_mul_i32_i24_e32 v190, 0x3000, v190
	v_lshl_add_u64 v[188:189], s[24:25], 0, v[188:189]
	v_lshl_add_u64 v[190:191], s[24:25], 0, v[190:191]
	v_lshl_add_u64 v[186:187], v[186:187], 0, s[18:19]
	v_lshl_add_u64 v[188:189], v[188:189], 0, s[18:19]
	v_lshl_add_u64 v[190:191], v[190:191], 0, s[18:19]
	v_lshl_add_u64 v[206:207], v[186:187], 0, v[180:181]
	v_add_u32_e32 v208, 18, v225
	v_min_i32_e32 v208, 0x7fff, v208
	v_ashrrev_i32_e32 v208, 12, v208
	v_add_u32_e32 v208, 16, v208
	v_mul_hi_i32_i24_e32 v209, 0x3000, v208
	v_mul_i32_i24_e32 v208, 0x3000, v208
	v_lshl_add_u64 v[208:209], s[24:25], 0, v[208:209]
	v_lshl_add_u64 v[202:203], v[188:189], 0, v[180:181]
	v_lshl_add_u64 v[204:205], v[190:191], 0, v[180:181]
	global_load_dword v232, v[196:197], off
	global_load_dword v233, v[196:197], off offset:128
	global_load_dword v242, v[206:207], off
	global_load_dword v243, v[206:207], off offset:128
	global_load_dword v244, v[202:203], off
	global_load_dword v245, v[202:203], off offset:128
	global_load_dword v246, v[204:205], off
	global_load_dword v247, v[204:205], off offset:128
	v_add_u32_e32 v196, 17, v225
	v_min_i32_e32 v196, 0x7fff, v196
	v_ashrrev_i32_e32 v196, 12, v196
	v_add_u32_e32 v196, 16, v196
	v_mul_hi_i32_i24_e32 v197, 0x3000, v196
	v_mul_i32_i24_e32 v196, 0x3000, v196
	v_lshl_add_u64 v[196:197], s[24:25], 0, v[196:197]
	v_lshl_add_u64 v[196:197], v[196:197], 0, s[18:19]
	v_lshl_add_u64 v[206:207], v[196:197], 0, v[180:181]
	s_waitcnt vmcnt(7)
	s_nop 5
	v_mul_f32_e32 v112, v112, v232
	v_add_u32_e32 v192, 11, v225
	v_add_u32_e32 v194, 16, v225
	v_min_i32_e32 v192, 0x7fff, v192
	v_min_i32_e32 v194, 0x7fff, v194
	v_ashrrev_i32_e32 v192, 12, v192
	v_ashrrev_i32_e32 v194, 12, v194
	v_add_u32_e32 v192, 16, v192
	v_add_u32_e32 v194, 16, v194
	v_mul_hi_i32_i24_e32 v193, 0x3000, v192
	v_mul_i32_i24_e32 v192, 0x3000, v192
	v_mul_hi_i32_i24_e32 v195, 0x3000, v194
	v_mul_i32_i24_e32 v194, 0x3000, v194
	v_lshl_add_u64 v[192:193], s[24:25], 0, v[192:193]
	v_lshl_add_u64 v[194:195], s[24:25], 0, v[194:195]
	v_lshl_add_u64 v[192:193], v[192:193], 0, s[18:19]
	v_lshl_add_u64 v[194:195], v[194:195], 0, s[18:19]
	v_lshl_add_u64 v[202:203], v[192:193], 0, v[180:181]
	v_lshl_add_u64 v[204:205], v[194:195], 0, v[180:181]
	s_waitcnt vmcnt(6)
	s_nop 5
	v_mul_f32_e32 v96, v96, v233
	v_mul_f32_e32 v97, v97, v233
	v_lshl_add_u64 v[198:199], v[208:209], 0, s[18:19]
	v_lshl_add_u64 v[200:201], v[198:199], 0, v[180:181]
	global_load_dword v234, v[202:203], off
	global_load_dword v235, v[202:203], off offset:128
	global_load_dword v236, v[204:205], off
	global_load_dword v237, v[204:205], off offset:128
	global_load_dword v238, v[206:207], off
	global_load_dword v239, v[206:207], off offset:128
	global_load_dword v240, v[200:201], off
	global_load_dword v241, v[200:201], off offset:128
	v_add_u32_e32 v200, 19, v225
	v_add_u32_e32 v204, 25, v225
	v_add_u32_e32 v206, 26, v225
	v_min_i32_e32 v200, 0x7fff, v200
	v_add_u32_e32 v202, 24, v225
	v_min_i32_e32 v204, 0x7fff, v204
	v_min_i32_e32 v206, 0x7fff, v206
	v_ashrrev_i32_e32 v200, 12, v200
	v_min_i32_e32 v202, 0x7fff, v202
	v_ashrrev_i32_e32 v204, 12, v204
	v_ashrrev_i32_e32 v206, 12, v206
	v_add_u32_e32 v200, 16, v200
	v_ashrrev_i32_e32 v202, 12, v202
	v_add_u32_e32 v204, 16, v204
	v_add_u32_e32 v206, 16, v206
	v_mul_hi_i32_i24_e32 v201, 0x3000, v200
	v_mul_i32_i24_e32 v200, 0x3000, v200
	v_add_u32_e32 v202, 16, v202
	v_mul_hi_i32_i24_e32 v205, 0x3000, v204
	v_mul_i32_i24_e32 v204, 0x3000, v204
	v_mul_hi_i32_i24_e32 v207, 0x3000, v206
	v_mul_i32_i24_e32 v206, 0x3000, v206
	v_lshl_add_u64 v[200:201], s[24:25], 0, v[200:201]
	v_mul_hi_i32_i24_e32 v203, 0x3000, v202
	v_mul_i32_i24_e32 v202, 0x3000, v202
	v_lshl_add_u64 v[204:205], s[24:25], 0, v[204:205]
	v_lshl_add_u64 v[206:207], s[24:25], 0, v[206:207]
	v_lshl_add_u64 v[200:201], v[200:201], 0, s[18:19]
	v_lshl_add_u64 v[202:203], s[24:25], 0, v[202:203]
	v_lshl_add_u64 v[204:205], v[204:205], 0, s[18:19]
	v_lshl_add_u64 v[206:207], v[206:207], 0, s[18:19]
	v_lshl_add_u64 v[208:209], v[200:201], 0, v[180:181]
	v_lshl_add_u64 v[202:203], v[202:203], 0, s[18:19]
	v_lshl_add_u64 v[228:229], v[204:205], 0, v[180:181]
	v_lshl_add_u64 v[230:231], v[206:207], 0, v[180:181]
	v_lshl_add_u64 v[226:227], v[202:203], 0, v[180:181]
	global_load_dword v248, v[208:209], off
	global_load_dword v249, v[208:209], off offset:128
	global_load_dword v250, v[226:227], off
	global_load_dword v251, v[226:227], off offset:128
	global_load_dword v252, v[228:229], off
	s_nop 0
	global_load_dword v228, v[228:229], off offset:128
	s_nop 0
	global_load_dword v229, v[230:231], off
	s_nop 0
	global_load_dword v230, v[230:231], off offset:128
	v_add_u32_e32 v208, 27, v225
	v_min_i32_e32 v208, 0x7fff, v208
	v_ashrrev_i32_e32 v208, 12, v208
	v_add_u32_e32 v208, 16, v208
	v_mul_hi_i32_i24_e32 v209, 0x3000, v208
	v_mul_i32_i24_e32 v208, 0x3000, v208
	v_lshl_add_u64 v[208:209], s[24:25], 0, v[208:209]
	v_lshl_add_u64 v[208:209], v[208:209], 0, s[18:19]
	v_lshl_add_u64 v[226:227], v[208:209], 0, v[180:181]
	global_load_dword v225, v[226:227], off
	s_nop 0
	global_load_dword v226, v[226:227], off offset:128
	v_mad_u64_u32 v[160:161], s[2:3], v183, s36, v[182:183]
	v_lshl_add_u32 v162, v160, 2, s34
	ds_write2_b32 v162, v112, v96 offset1:32
	v_mul_f32_e32 v96, v113, v232
	ds_write2_b32 v162, v96, v97 offset0:68 offset1:100
	v_mul_f32_e32 v96, v114, v232
	v_mul_f32_e32 v97, v98, v233
	ds_write2_b32 v162, v96, v97 offset0:136 offset1:168
	v_mul_f32_e32 v96, v115, v232
	v_mul_f32_e32 v97, v99, v233
	ds_write2_b32 v162, v96, v97 offset0:204 offset1:236
	s_waitcnt vmcnt(23)
	v_mul_f32_e32 v96, v116, v242
	s_waitcnt vmcnt(22)
	v_mul_f32_e32 v97, v100, v243
	v_add_u32_e32 v115, 0x800, v162
	ds_write2_b32 v115, v96, v97 offset0:32 offset1:64
	s_waitcnt vmcnt(21)
	v_mul_f32_e32 v96, v117, v244
	s_waitcnt vmcnt(20)
	v_mul_f32_e32 v97, v101, v245
	ds_write2_b32 v115, v96, v97 offset0:100 offset1:132
	s_waitcnt vmcnt(19)
	v_mul_f32_e32 v96, v118, v246
	s_waitcnt vmcnt(18)
	v_mul_f32_e32 v97, v102, v247
	ds_write2_b32 v115, v96, v97 offset0:168 offset1:200
	v_add_u32_e32 v116, 0xa00, v162
	v_add_u32_e32 v117, 0x1000, v162
	s_waitcnt vmcnt(17)
	v_mul_f32_e32 v96, v119, v234
	s_waitcnt vmcnt(16)
	v_mul_f32_e32 v97, v103, v235
	ds_write2_b32 v116, v96, v97 offset0:108 offset1:140
	s_waitcnt vmcnt(15)
	v_mul_f32_e32 v96, v120, v236
	s_waitcnt vmcnt(14)
	v_mul_f32_e32 v97, v104, v237
	ds_write2_b32 v117, v96, v97 offset0:64 offset1:96
	s_waitcnt vmcnt(13)
	v_mul_f32_e32 v96, v121, v238
	s_waitcnt vmcnt(12)
	v_mul_f32_e32 v97, v105, v239
	ds_write2_b32 v117, v96, v97 offset0:132 offset1:164
	s_waitcnt vmcnt(11)
	v_mul_f32_e32 v96, v122, v240
	s_waitcnt vmcnt(10)
	v_mul_f32_e32 v97, v106, v241
	ds_write2_b32 v117, v96, v97 offset0:200 offset1:232
	v_add_u32_e32 v118, 0x1400, v162
	v_add_u32_e32 v119, 0x1800, v162
	v_ashrrev_i32_e32 v163, 4, v168
	v_and_b32_e32 v160, 15, v168
	v_add_u32_e32 v120, 0x1a00, v162
	v_mul_lo_u32 v164, v163, s37
	v_lshl_add_u32 v165, v160, 4, s34
	v_lshlrev_b32_e32 v168, 2, v160
	v_add_u32_e32 v160, s55, v163
	v_add_u32_e32 v121, 0x1c00, v162
	v_cmp_gt_i32_e32 vcc, s38, v160
	v_ashrrev_i32_e32 v161, 31, v160
	v_add_u32_e32 v114, v165, v164
	s_waitcnt vmcnt(9)
	v_mul_f32_e32 v96, v123, v248
	s_waitcnt vmcnt(8)
	v_mul_f32_e32 v97, v107, v249
	ds_write2_b32 v118, v96, v97 offset0:12 offset1:44
	s_waitcnt vmcnt(7)
	v_mul_f32_e32 v96, v124, v250
	s_waitcnt vmcnt(6)
	v_mul_f32_e32 v97, v108, v251
	ds_write2_b32 v119, v96, v97 offset0:96 offset1:128
	s_waitcnt vmcnt(5)
	v_mul_f32_e32 v96, v125, v252
	s_waitcnt vmcnt(4)
	v_mul_f32_e32 v97, v109, v228
	ds_write2_b32 v119, v96, v97 offset0:164 offset1:196
	s_waitcnt vmcnt(3)
	v_mul_f32_e32 v96, v126, v229
	s_waitcnt vmcnt(2)
	v_mul_f32_e32 v97, v110, v230
	ds_write2_b32 v120, v96, v97 offset0:104 offset1:136
	s_waitcnt vmcnt(1)
	v_mul_f32_e32 v96, v127, v225
	s_waitcnt vmcnt(0)
	v_mul_f32_e32 v97, v111, v226
	ds_write2_b32 v121, v96, v97 offset0:44 offset1:76
	v_or_b32_e32 v96, s26, v168
	v_mov_b32_e32 v97, s27
	v_add_u32_e32 v128, 0, v160
	v_ashrrev_i32_e32 v129, 31, v128
	v_lshlrev_b64 v[128:129], 12, v[128:129]
	v_lshl_add_u64 v[128:129], s[16:17], 0, v[128:129]
	v_lshl_add_u64 v[128:129], v[96:97], 2, v[128:129]
	global_load_dwordx4 v[128:131], v[128:129], off
	v_add_u32_e32 v132, 4, v160
	v_ashrrev_i32_e32 v133, 31, v132
	v_lshlrev_b64 v[132:133], 12, v[132:133]
	v_lshl_add_u64 v[132:133], s[16:17], 0, v[132:133]
	v_lshl_add_u64 v[132:133], v[96:97], 2, v[132:133]
	global_load_dwordx4 v[132:135], v[132:133], off
	v_add_u32_e32 v136, 8, v160
	v_ashrrev_i32_e32 v137, 31, v136
	v_lshlrev_b64 v[136:137], 12, v[136:137]
	v_lshl_add_u64 v[136:137], s[16:17], 0, v[136:137]
	v_lshl_add_u64 v[136:137], v[96:97], 2, v[136:137]
	global_load_dwordx4 v[136:139], v[136:137], off
	v_add_u32_e32 v140, 12, v160
	v_ashrrev_i32_e32 v141, 31, v140
	v_lshlrev_b64 v[140:141], 12, v[140:141]
	v_lshl_add_u64 v[140:141], s[16:17], 0, v[140:141]
	v_lshl_add_u64 v[140:141], v[96:97], 2, v[140:141]
	global_load_dwordx4 v[140:143], v[140:141], off
	v_add_u32_e32 v144, 16, v160
	v_ashrrev_i32_e32 v145, 31, v144
	v_lshlrev_b64 v[144:145], 12, v[144:145]
	v_lshl_add_u64 v[144:145], s[16:17], 0, v[144:145]
	v_lshl_add_u64 v[144:145], v[96:97], 2, v[144:145]
	global_load_dwordx4 v[144:147], v[144:145], off
	v_add_u32_e32 v148, 20, v160
	v_ashrrev_i32_e32 v149, 31, v148
	v_lshlrev_b64 v[148:149], 12, v[148:149]
	v_lshl_add_u64 v[148:149], s[16:17], 0, v[148:149]
	v_lshl_add_u64 v[148:149], v[96:97], 2, v[148:149]
	global_load_dwordx4 v[148:151], v[148:149], off
	v_add_u32_e32 v152, 24, v160
	v_ashrrev_i32_e32 v153, 31, v152
	v_lshlrev_b64 v[152:153], 12, v[152:153]
	v_lshl_add_u64 v[152:153], s[16:17], 0, v[152:153]
	v_lshl_add_u64 v[152:153], v[96:97], 2, v[152:153]
	global_load_dwordx4 v[152:155], v[152:153], off
	v_add_u32_e32 v156, 28, v160
	v_ashrrev_i32_e32 v157, 31, v156
	v_lshlrev_b64 v[156:157], 12, v[156:157]
	v_lshl_add_u64 v[156:157], s[16:17], 0, v[156:157]
	v_lshl_add_u64 v[156:157], v[96:97], 2, v[156:157]
	global_load_dwordx4 v[156:159], v[156:157], off
	s_and_saveexec_b64 s[2:3], vcc
	s_cbranch_execz .LBB0_4484
	v_lshlrev_b64 v[98:99], 12, v[160:161]
	v_lshl_add_u64 v[98:99], s[16:17], 0, v[98:99]
	v_lshl_add_u64 v[106:107], v[96:97], 2, v[98:99]
	ds_read_b128 v[102:105], v114
	s_waitcnt vmcnt(7) lgkmcnt(0)
	v_pk_add_f32 v[100:101], v[104:105], v[130:131]
	v_pk_add_f32 v[98:99], v[102:103], v[128:129]
	global_store_dwordx4 v[106:107], v[98:101], off

.LBB0_4663:
	v_mbcnt_hi_u32_b32 v188, -1, v210
	s_load_dwordx2 s[2:3], s[0:1], 0x158
	s_load_dwordx2 s[4:5], s[0:1], 0xc8
	s_ashr_i32 s7, s6, 31
	v_mov_b32_e32 v1, v188
	s_and_b32 s7, s7, s42
	s_add_i32 s68, s7, s6
	v_add_u32_e32 v0, s70, v1
	v_ashrrev_i32_e32 v189, 3, v0
	v_readfirstlane_b32 s8, v0
	v_lshlrev_b32_e32 v0, 3, v1
	v_and_b32_e32 v0, 56, v0
	s_cmpk_lt_i32 s68, 0x300
	s_cselect_b64 s[6:7], -1, 0
	s_cmpk_gt_i32 s68, 0x2ff
	v_lshlrev_b32_e32 v160, 1, v0
	v_add_u32_e32 v190, 64, v189
	s_cbranch_scc1 .LBB0_4665
	s_mul_hi_i32 s9, s68, 0x2aaaaaab
	s_lshr_b32 s10, s9, 31
	s_add_i32 s9, s9, s10
	s_mul_i32 s10, s9, -6
	s_lshl_b32 s9, s9, 8
	v_add_u32_e32 v2, s9, v189
	v_min_i32_e32 v2, 0x7fff, v2
	v_ashrrev_i32_e32 v3, 31, v2
	v_lshlrev_b64 v[2:3], 11, v[2:3]
	s_add_i32 s10, s10, s68
	s_waitcnt lgkmcnt(0)
	v_lshl_add_u64 v[2:3], s[2:3], 0, v[2:3]
	v_mov_b32_e32 v161, 0
	s_lshl_b32 s10, s10, 8
	v_lshl_add_u64 v[2:3], v[2:3], 0, v[160:161]
	v_mbcnt_hi_u32_b32 v158, -1, v210
	s_and_b32 s90, s70, 0x40
	v_and_b32_e32 v159, 48, v158
	v_or_b32_e32 v159, s90, v159
	s_lshl_b32 s88, s70, 4
	s_lshl_b32 s92, s22, 4
	s_and_b32 s92, s92, 0x780
	s_mov_b32 s93, 0
	s_add_u32 m0, s88, 0
	v_lshl_add_u64 v[2:3], v[2:3], 0, s[92:93]
	v_xor_b32_e32 v2, v159, v2
	global_load_lds_dwordx4 v[2:3], off
	v_add_u32_e32 v2, s10, v189
	v_ashrrev_i32_e32 v3, 31, v2
	v_lshlrev_b64 v[2:3], 11, v[2:3]
	v_lshl_add_u64 v[2:3], s[4:5], 0, v[2:3]
	v_lshl_add_u64 v[2:3], v[2:3], 0, v[160:161]
	s_add_u32 m0, s88, 32768
	v_lshl_add_u64 v[2:3], v[2:3], 0, s[92:93]
	v_xor_b32_e32 v2, v159, v2
	global_load_lds_dwordx4 v[2:3], off
	v_add_u32_e32 v2, s9, v190
	v_min_i32_e32 v2, 0x7fff, v2
	v_ashrrev_i32_e32 v3, 31, v2
	v_lshlrev_b64 v[2:3], 11, v[2:3]
	v_lshl_add_u64 v[2:3], s[2:3], 0, v[2:3]
	v_lshl_add_u64 v[2:3], v[2:3], 0, v[160:161]
	s_add_u32 m0, s88, 8192
	v_lshl_add_u64 v[2:3], v[2:3], 0, s[92:93]
	v_xor_b32_e32 v2, v159, v2
	global_load_lds_dwordx4 v[2:3], off
	v_add_u32_e32 v2, s10, v190
	v_ashrrev_i32_e32 v3, 31, v2
	v_lshlrev_b64 v[2:3], 11, v[2:3]
	v_lshl_add_u64 v[2:3], s[4:5], 0, v[2:3]
	v_lshl_add_u64 v[2:3], v[2:3], 0, v[160:161]
	v_add_u32_e32 v4, 0x80, v189
	s_add_u32 m0, s88, 40960
	v_lshl_add_u64 v[2:3], v[2:3], 0, s[92:93]
	v_xor_b32_e32 v2, v159, v2
	global_load_lds_dwordx4 v[2:3], off
	v_add_u32_e32 v2, s9, v4
	v_min_i32_e32 v2, 0x7fff, v2
	v_ashrrev_i32_e32 v3, 31, v2
	v_lshlrev_b64 v[2:3], 11, v[2:3]
	v_lshl_add_u64 v[2:3], s[2:3], 0, v[2:3]
	v_lshl_add_u64 v[2:3], v[2:3], 0, v[160:161]
	s_add_u32 m0, s88, 16384
	v_lshl_add_u64 v[2:3], v[2:3], 0, s[92:93]
	v_xor_b32_e32 v2, v159, v2
	global_load_lds_dwordx4 v[2:3], off
	v_add_u32_e32 v2, s10, v4
	v_ashrrev_i32_e32 v3, 31, v2
	v_lshlrev_b64 v[2:3], 11, v[2:3]
	v_lshl_add_u64 v[2:3], s[4:5], 0, v[2:3]
	v_lshl_add_u64 v[2:3], v[2:3], 0, v[160:161]
	v_add_u32_e32 v4, 0xc0, v189
	s_add_u32 m0, s88, 49152
	v_lshl_add_u64 v[2:3], v[2:3], 0, s[92:93]
	v_xor_b32_e32 v2, v159, v2
	global_load_lds_dwordx4 v[2:3], off
	v_add_u32_e32 v2, s9, v4
	v_min_i32_e32 v2, 0x7fff, v2
	v_ashrrev_i32_e32 v3, 31, v2
	v_lshlrev_b64 v[2:3], 11, v[2:3]
	v_lshl_add_u64 v[2:3], s[2:3], 0, v[2:3]
	v_lshl_add_u64 v[2:3], v[2:3], 0, v[160:161]
	s_add_u32 m0, s88, 24576
	v_lshl_add_u64 v[2:3], v[2:3], 0, s[92:93]
	v_xor_b32_e32 v2, v159, v2
	global_load_lds_dwordx4 v[2:3], off
	v_add_u32_e32 v2, s10, v4
	v_ashrrev_i32_e32 v3, 31, v2
	v_lshlrev_b64 v[2:3], 11, v[2:3]
	v_lshl_add_u64 v[2:3], s[4:5], 0, v[2:3]
	v_lshl_add_u64 v[2:3], v[2:3], 0, v[160:161]
	s_add_u32 m0, s88, 57344
	v_lshl_add_u64 v[2:3], v[2:3], 0, s[92:93]
	v_xor_b32_e32 v2, v159, v2
	global_load_lds_dwordx4 v[2:3], off
	s_waitcnt vmcnt(0)

.LBB0_4668:
	s_mul_hi_i32 s5, s68, 0x2aaaaaab
	s_lshr_b32 s2, s5, 31
	s_add_i32 s5, s5, s2
	s_lshl_b32 s69, s5, 8
	s_waitcnt lgkmcnt(0)
	v_add_u32_e32 v0, s69, v189
	v_min_i32_e32 v0, 0x7fff, v0
	v_ashrrev_i32_e32 v1, 31, v0
	v_lshlrev_b64 v[0:1], 11, v[0:1]
	s_mul_i32 s2, s5, 0x600
	v_lshl_add_u64 v[172:173], v[168:169], 0, v[0:1]
	v_subrev_u32_e32 v0, s2, v200
	v_ashrrev_i32_e32 v1, 31, v0
	v_lshlrev_b64 v[0:1], 11, v[0:1]
	v_lshl_add_u64 v[180:181], v[170:171], 0, v[0:1]
	v_subrev_u32_e32 v0, s2, v201
	v_ashrrev_i32_e32 v1, 31, v0
	v_lshlrev_b64 v[0:1], 11, v[0:1]
	v_lshl_add_u64 v[182:183], v[170:171], 0, v[0:1]
	v_subrev_u32_e32 v0, s2, v202
	v_ashrrev_i32_e32 v1, 31, v0
	v_add_u32_e32 v2, s69, v190
	v_add_u32_e32 v4, s69, v163
	v_add_u32_e32 v6, s69, v192
	v_lshlrev_b64 v[0:1], 11, v[0:1]
	v_min_i32_e32 v2, 0x7fff, v2
	v_min_i32_e32 v4, 0x7fff, v4
	v_min_i32_e32 v6, 0x7fff, v6
	v_lshl_add_u64 v[184:185], v[170:171], 0, v[0:1]
	v_subrev_u32_e32 v0, s2, v203
	v_ashrrev_i32_e32 v3, 31, v2
	v_ashrrev_i32_e32 v5, 31, v4
	v_ashrrev_i32_e32 v7, 31, v6
	v_ashrrev_i32_e32 v1, 31, v0
	v_lshlrev_b64 v[2:3], 11, v[2:3]
	v_lshlrev_b64 v[4:5], 11, v[4:5]
	v_lshlrev_b64 v[6:7], 11, v[6:7]
	v_lshlrev_b64 v[0:1], 11, v[0:1]
	s_mov_b32 s4, s68
	v_lshl_add_u64 v[174:175], v[168:169], 0, v[2:3]
	v_lshl_add_u64 v[176:177], v[168:169], 0, v[4:5]
	v_lshl_add_u64 v[178:179], v[168:169], 0, v[6:7]
	v_lshl_add_u64 v[186:187], v[170:171], 0, v[0:1]
	s_mov_b64 s[2:3], 0
	s_mov_b32 s6, s25
	v_mov_b32_e32 v0, v161
	v_mov_b32_e32 v1, v161
	v_mov_b32_e32 v2, v161
	v_mov_b32_e32 v3, v161
	v_mov_b32_e32 v4, v161
	v_mov_b32_e32 v5, v161
	v_mov_b32_e32 v6, v161
	v_mov_b32_e32 v7, v161
	v_mov_b32_e32 v8, v161
	v_mov_b32_e32 v9, v161
	v_mov_b32_e32 v10, v161
	v_mov_b32_e32 v11, v161
	v_mov_b32_e32 v12, v161
	v_mov_b32_e32 v13, v161
	v_mov_b32_e32 v14, v161
	v_mov_b32_e32 v15, v161
	v_mov_b32_e32 v16, v161
	v_mov_b32_e32 v17, v161
	v_mov_b32_e32 v18, v161
	v_mov_b32_e32 v19, v161
	v_mov_b32_e32 v20, v161
	v_mov_b32_e32 v21, v161
	v_mov_b32_e32 v22, v161
	v_mov_b32_e32 v23, v161
	v_mov_b32_e32 v24, v161
	v_mov_b32_e32 v25, v161
	v_mov_b32_e32 v26, v161
	v_mov_b32_e32 v27, v161
	v_mov_b32_e32 v28, v161
	v_mov_b32_e32 v29, v161
	v_mov_b32_e32 v30, v161
	v_mov_b32_e32 v31, v161
	v_mov_b32_e32 v32, v161
	v_mov_b32_e32 v33, v161
	v_mov_b32_e32 v34, v161
	v_mov_b32_e32 v35, v161
	v_mov_b32_e32 v36, v161
	v_mov_b32_e32 v37, v161
	v_mov_b32_e32 v38, v161
	v_mov_b32_e32 v39, v161
	v_mov_b32_e32 v40, v161
	v_mov_b32_e32 v41, v161
	v_mov_b32_e32 v42, v161
	v_mov_b32_e32 v43, v161
	v_mov_b32_e32 v44, v161
	v_mov_b32_e32 v45, v161
	v_mov_b32_e32 v46, v161
	v_mov_b32_e32 v47, v161
	v_mov_b32_e32 v48, v161
	v_mov_b32_e32 v49, v161
	v_mov_b32_e32 v50, v161
	v_mov_b32_e32 v51, v161
	v_mov_b32_e32 v52, v161
	v_mov_b32_e32 v53, v161
	v_mov_b32_e32 v54, v161
	v_mov_b32_e32 v55, v161
	v_mov_b32_e32 v56, v161
	v_mov_b32_e32 v57, v161
	v_mov_b32_e32 v58, v161
	v_mov_b32_e32 v59, v161
	v_mov_b32_e32 v60, v161
	v_mov_b32_e32 v61, v161
	v_mov_b32_e32 v62, v161
	v_mov_b32_e32 v63, v161
	v_mov_b32_e32 v64, v161
	v_mov_b32_e32 v65, v161
	v_mov_b32_e32 v66, v161
	v_mov_b32_e32 v67, v161
	v_mov_b32_e32 v68, v161
	v_mov_b32_e32 v69, v161
	v_mov_b32_e32 v70, v161
	v_mov_b32_e32 v71, v161
	v_mov_b32_e32 v72, v161
	v_mov_b32_e32 v73, v161
	v_mov_b32_e32 v74, v161
	v_mov_b32_e32 v75, v161
	v_mov_b32_e32 v76, v161
	v_mov_b32_e32 v77, v161
	v_mov_b32_e32 v78, v161
	v_mov_b32_e32 v79, v161
	v_mov_b32_e32 v80, v161
	v_mov_b32_e32 v81, v161
	v_mov_b32_e32 v82, v161
	v_mov_b32_e32 v83, v161
	v_mov_b32_e32 v84, v161
	v_mov_b32_e32 v85, v161
	v_mov_b32_e32 v86, v161
	v_mov_b32_e32 v87, v161
	v_mov_b32_e32 v88, v161
	v_mov_b32_e32 v89, v161
	v_mov_b32_e32 v90, v161
	v_mov_b32_e32 v91, v161
	v_mov_b32_e32 v92, v161
	v_mov_b32_e32 v93, v161
	v_mov_b32_e32 v94, v161
	v_mov_b32_e32 v95, v161
	s_waitcnt vmcnt(7)
	v_mov_b32_e32 v96, v161
	v_mov_b32_e32 v97, v161
	v_mov_b32_e32 v98, v161
	v_mov_b32_e32 v99, v161
	s_waitcnt vmcnt(6)
	v_mov_b32_e32 v100, v161
	v_mov_b32_e32 v101, v161
	v_mov_b32_e32 v102, v161
	v_mov_b32_e32 v103, v161
	s_waitcnt vmcnt(5)
	v_mov_b32_e32 v104, v161
	v_mov_b32_e32 v105, v161
	v_mov_b32_e32 v106, v161
	v_mov_b32_e32 v107, v161
	s_waitcnt vmcnt(4)
	v_mov_b32_e32 v108, v161
	v_mov_b32_e32 v109, v161
	v_mov_b32_e32 v110, v161
	v_mov_b32_e32 v111, v161
	s_waitcnt vmcnt(3)
	v_mov_b32_e32 v112, v161
	v_mov_b32_e32 v113, v161
	v_mov_b32_e32 v114, v161
	v_mov_b32_e32 v115, v161
	s_waitcnt vmcnt(2)
	v_mov_b32_e32 v116, v161
	v_mov_b32_e32 v117, v161
	v_mov_b32_e32 v118, v161
	v_mov_b32_e32 v119, v161
	s_waitcnt vmcnt(1)
	v_mov_b32_e32 v120, v161
	v_mov_b32_e32 v121, v161
	v_mov_b32_e32 v122, v161
	v_mov_b32_e32 v123, v161
	s_waitcnt vmcnt(0)
	v_mov_b32_e32 v124, v161
	v_mov_b32_e32 v125, v161
	v_mov_b32_e32 v126, v161
	v_mov_b32_e32 v127, v161
	v_mbcnt_hi_u32_b32 v128, -1, v210
	s_and_b32 s90, s70, 0x40
	v_and_b32_e32 v159, 48, v128
	v_or_b32_e32 v159, s90, v159
	v_and_b32_e32 v129, 31, v128
	v_lshrrev_b32_e32 v130, 5, v128
	v_bfe_u32 v131, v128, 1, 3
	v_lshlrev_b32_e32 v132, 7, v129
	s_lshr_b32 s91, s70, 7
	s_lshl_b32 s91, s91, 13
	s_lshl_b32 s90, s90, 8
	s_add_u32 s90, s90, 0x8000
	s_lshl_b32 s88, s70, 4
	s_mov_b32 s89, 0x10000
	s_lshl_b32 s92, s22, 4
	s_and_b32 s92, s92, 0x780
	s_mov_b32 s93, 0
	v_xor_b32_e32 v133, v130, v131
	v_lshl_add_u32 v133, v133, 4, v132
	v_add_u32_e32 v232, s91, v133
	v_add_u32_e32 v236, s90, v133
	v_or_b32_e32 v133, 2, v130
	v_xor_b32_e32 v133, v133, v131
	v_lshl_add_u32 v133, v133, 4, v132
	v_add_u32_e32 v233, s91, v133
	v_add_u32_e32 v237, s90, v133
	v_or_b32_e32 v133, 4, v130
	v_xor_b32_e32 v133, v133, v131
	v_lshl_add_u32 v133, v133, 4, v132
	v_add_u32_e32 v234, s91, v133
	v_add_u32_e32 v238, s90, v133
	v_or_b32_e32 v133, 6, v130
	v_xor_b32_e32 v133, v133, v131
	v_lshl_add_u32 v133, v133, 4, v132
	v_add_u32_e32 v235, s91, v133
	v_add_u32_e32 v239, s90, v133
	s_barrier
	ds_read_b128 v[206:209], v232
	ds_read_b128 v[216:219], v236
	ds_read_b128 v[212:215], v232 offset:4096
	ds_read_b128 v[220:223], v236 offset:4096
	ds_read_b128 v[224:227], v236 offset:8192
	ds_read_b128 v[228:231], v236 offset:12288
	s_add_u32 s94, s2, s92
	s_add_u32 s94, s94, 0x80
	s_and_b32 s94, s94, 0x780
	s_sub_u32 s94, s94, 0x80
	s_subb_u32 s95, 0, 0
	s_add_u32 s90, s88, s89
	s_add_u32 m0, s90, 0
	v_lshl_add_u64 v[152:153], v[172:173], 0, s[94:95]
	v_xor_b32_e32 v152, v159, v152
	global_load_lds_dwordx4 v[152:153], off
	s_add_u32 m0, s90, 32768
	v_lshl_add_u64 v[154:155], v[180:181], 0, s[94:95]
	v_xor_b32_e32 v154, v159, v154
	global_load_lds_dwordx4 v[154:155], off
	s_add_u32 m0, s90, 8192
	v_lshl_add_u64 v[156:157], v[174:175], 0, s[94:95]
	v_xor_b32_e32 v156, v159, v156
	global_load_lds_dwordx4 v[156:157], off
	s_add_u32 m0, s90, 40960
	v_lshl_add_u64 v[152:153], v[182:183], 0, s[94:95]
	v_xor_b32_e32 v152, v159, v152
	global_load_lds_dwordx4 v[152:153], off
	s_add_u32 m0, s90, 16384
	v_lshl_add_u64 v[154:155], v[176:177], 0, s[94:95]
	v_xor_b32_e32 v154, v159, v154
	global_load_lds_dwordx4 v[154:155], off
	s_add_u32 m0, s90, 49152
	v_lshl_add_u64 v[156:157], v[184:185], 0, s[94:95]
	v_xor_b32_e32 v156, v159, v156
	global_load_lds_dwordx4 v[156:157], off
	s_add_u32 m0, s90, 24576
	v_lshl_add_u64 v[152:153], v[178:179], 0, s[94:95]
	v_xor_b32_e32 v152, v159, v152
	global_load_lds_dwordx4 v[152:153], off
	s_add_u32 m0, s90, 57344
	v_lshl_add_u64 v[154:155], v[186:187], 0, s[94:95]
	v_xor_b32_e32 v154, v159, v154
	global_load_lds_dwordx4 v[154:155], off
	s_xor_b32 s89, s89, 0x10000

.LBB0_5635:
	v_mbcnt_hi_u32_b32 v211, -1, v210
	s_load_dwordx2 s[2:3], s[0:1], 0xf8
	s_load_dwordx2 s[4:5], s[0:1], 0x158
	s_ashr_i32 s7, s6, 31
	v_mov_b32_e32 v1, v211
	s_and_b32 s7, s7, s42
	s_add_i32 s54, s7, s6
	v_add_u32_e32 v0, s70, v1
	v_ashrrev_i32_e32 v212, 3, v0
	v_readfirstlane_b32 s8, v0
	v_lshlrev_b32_e32 v0, 3, v1
	v_and_b32_e32 v0, 56, v0
	s_cmpk_lt_i32 s54, 0x200
	s_cselect_b64 s[6:7], -1, 0
	s_cmpk_gt_i32 s54, 0x1ff
	v_lshlrev_b32_e32 v168, 1, v0
	v_add_u32_e32 v213, 64, v212
	s_cbranch_scc1 .LBB0_5637
	s_ashr_i32 s9, s54, 31
	s_lshr_b32 s9, s9, 30
	s_add_i32 s9, s54, s9
	s_ashr_i32 s9, s9, 2
	s_lshl_b32 s10, s9, 8
	v_add_u32_e32 v2, s10, v212
	v_min_i32_e32 v2, 0x7fff, v2
	v_ashrrev_i32_e32 v3, 31, v2
	v_lshlrev_b64 v[2:3], 11, v[2:3]
	s_lshl_b32 s9, s9, 10
	s_lshl_b32 s11, s54, 8
	s_waitcnt lgkmcnt(0)
	v_lshl_add_u64 v[2:3], s[4:5], 0, v[2:3]
	v_mov_b32_e32 v169, 0
	s_sub_i32 s9, s11, s9
	v_lshl_add_u64 v[2:3], v[2:3], 0, v[168:169]
	v_mbcnt_hi_u32_b32 v158, -1, v210
	s_and_b32 s90, s70, 0x40
	v_and_b32_e32 v159, 48, v158
	v_or_b32_e32 v159, s90, v159
	s_lshl_b32 s88, s70, 4
	s_lshl_b32 s92, s22, 4
	s_and_b32 s92, s92, 0x780
	s_mov_b32 s93, 0
	s_add_u32 m0, s88, 0
	v_lshl_add_u64 v[2:3], v[2:3], 0, s[92:93]
	v_xor_b32_e32 v2, v159, v2
	global_load_lds_dwordx4 v[2:3], off
	v_add_u32_e32 v2, s9, v212
	v_ashrrev_i32_e32 v3, 31, v2
	v_lshlrev_b64 v[2:3], 11, v[2:3]
	v_lshl_add_u64 v[2:3], s[2:3], 0, v[2:3]
	v_lshl_add_u64 v[2:3], v[2:3], 0, v[168:169]
	s_add_u32 m0, s88, 32768
	v_lshl_add_u64 v[2:3], v[2:3], 0, s[92:93]
	v_xor_b32_e32 v2, v159, v2
	global_load_lds_dwordx4 v[2:3], off
	v_add_u32_e32 v2, s10, v213
	v_min_i32_e32 v2, 0x7fff, v2
	v_ashrrev_i32_e32 v3, 31, v2
	v_lshlrev_b64 v[2:3], 11, v[2:3]
	v_lshl_add_u64 v[2:3], s[4:5], 0, v[2:3]
	v_lshl_add_u64 v[2:3], v[2:3], 0, v[168:169]
	s_add_u32 m0, s88, 8192
	v_lshl_add_u64 v[2:3], v[2:3], 0, s[92:93]
	v_xor_b32_e32 v2, v159, v2
	global_load_lds_dwordx4 v[2:3], off
	v_add_u32_e32 v2, s9, v213
	v_ashrrev_i32_e32 v3, 31, v2
	v_lshlrev_b64 v[2:3], 11, v[2:3]
	v_lshl_add_u64 v[2:3], s[2:3], 0, v[2:3]
	v_lshl_add_u64 v[2:3], v[2:3], 0, v[168:169]
	v_add_u32_e32 v4, 0x80, v212
	s_add_u32 m0, s88, 40960
	v_lshl_add_u64 v[2:3], v[2:3], 0, s[92:93]
	v_xor_b32_e32 v2, v159, v2
	global_load_lds_dwordx4 v[2:3], off
	v_add_u32_e32 v2, s10, v4
	v_min_i32_e32 v2, 0x7fff, v2
	v_ashrrev_i32_e32 v3, 31, v2
	v_lshlrev_b64 v[2:3], 11, v[2:3]
	v_lshl_add_u64 v[2:3], s[4:5], 0, v[2:3]
	v_lshl_add_u64 v[2:3], v[2:3], 0, v[168:169]
	s_add_u32 m0, s88, 16384
	v_lshl_add_u64 v[2:3], v[2:3], 0, s[92:93]
	v_xor_b32_e32 v2, v159, v2
	global_load_lds_dwordx4 v[2:3], off
	v_add_u32_e32 v2, s9, v4
	v_ashrrev_i32_e32 v3, 31, v2
	v_lshlrev_b64 v[2:3], 11, v[2:3]
	v_lshl_add_u64 v[2:3], s[2:3], 0, v[2:3]
	v_lshl_add_u64 v[2:3], v[2:3], 0, v[168:169]
	v_add_u32_e32 v4, 0xc0, v212
	s_add_u32 m0, s88, 49152
	v_lshl_add_u64 v[2:3], v[2:3], 0, s[92:93]
	v_xor_b32_e32 v2, v159, v2
	global_load_lds_dwordx4 v[2:3], off
	v_add_u32_e32 v2, s10, v4
	v_min_i32_e32 v2, 0x7fff, v2
	v_ashrrev_i32_e32 v3, 31, v2
	v_lshlrev_b64 v[2:3], 11, v[2:3]
	v_lshl_add_u64 v[2:3], s[4:5], 0, v[2:3]
	v_lshl_add_u64 v[2:3], v[2:3], 0, v[168:169]
	s_add_u32 m0, s88, 24576
	v_lshl_add_u64 v[2:3], v[2:3], 0, s[92:93]
	v_xor_b32_e32 v2, v159, v2
	global_load_lds_dwordx4 v[2:3], off
	v_add_u32_e32 v2, s9, v4
	v_ashrrev_i32_e32 v3, 31, v2
	v_lshlrev_b64 v[2:3], 11, v[2:3]
	v_lshl_add_u64 v[2:3], s[2:3], 0, v[2:3]
	v_lshl_add_u64 v[2:3], v[2:3], 0, v[168:169]
	s_add_u32 m0, s88, 57344
	v_lshl_add_u64 v[2:3], v[2:3], 0, s[92:93]
	v_xor_b32_e32 v2, v159, v2
	global_load_lds_dwordx4 v[2:3], off
	s_waitcnt vmcnt(0)

.LBB0_5644:
	ds_read_b128 v[128:131], v231
	ds_read_b128 v[136:139], v235
	ds_read_b128 v[132:135], v231 offset:4096
	ds_read_b128 v[140:143], v235 offset:4096
	ds_read_b128 v[144:147], v235 offset:8192
	ds_read_b128 v[148:151], v235 offset:12288
	s_waitcnt lgkmcnt(6)
	v_mfma_f32_32x32x16_bf16 v[112:127], v[188:191], v[196:199], v[112:127]
	v_mfma_f32_32x32x16_bf16 v[48:63], v[192:195], v[196:199], v[48:63]
	v_mfma_f32_32x32x16_bf16 v[96:111], v[188:191], v[200:203], v[96:111]
	v_mfma_f32_32x32x16_bf16 v[32:47], v[192:195], v[200:203], v[32:47]
	v_mfma_f32_32x32x16_bf16 v[80:95], v[188:191], v[204:207], v[80:95]
	v_mfma_f32_32x32x16_bf16 v[16:31], v[192:195], v[204:207], v[16:31]
	v_mfma_f32_32x32x16_bf16 v[64:79], v[188:191], v[226:229], v[64:79]
	v_mfma_f32_32x32x16_bf16 v[0:15], v[192:195], v[226:229], v[0:15]
	ds_read_b128 v[188:191], v232
	ds_read_b128 v[196:199], v236
	ds_read_b128 v[192:195], v232 offset:4096
	ds_read_b128 v[200:203], v236 offset:4096
	ds_read_b128 v[204:207], v236 offset:8192
	ds_read_b128 v[226:229], v236 offset:12288
	s_waitcnt lgkmcnt(6)
	v_mfma_f32_32x32x16_bf16 v[112:127], v[128:131], v[136:139], v[112:127]
	v_mfma_f32_32x32x16_bf16 v[48:63], v[132:135], v[136:139], v[48:63]
	v_mfma_f32_32x32x16_bf16 v[96:111], v[128:131], v[140:143], v[96:111]
	v_mfma_f32_32x32x16_bf16 v[32:47], v[132:135], v[140:143], v[32:47]
	v_mfma_f32_32x32x16_bf16 v[80:95], v[128:131], v[144:147], v[80:95]
	v_mfma_f32_32x32x16_bf16 v[16:31], v[132:135], v[144:147], v[16:31]
	v_mfma_f32_32x32x16_bf16 v[64:79], v[128:131], v[148:151], v[64:79]
	v_mfma_f32_32x32x16_bf16 v[0:15], v[132:135], v[148:151], v[0:15]
	ds_read_b128 v[128:131], v233
	ds_read_b128 v[136:139], v237
	ds_read_b128 v[132:135], v233 offset:4096
	ds_read_b128 v[140:143], v237 offset:4096
	ds_read_b128 v[144:147], v237 offset:8192
	ds_read_b128 v[148:151], v237 offset:12288
	s_waitcnt lgkmcnt(6)
	v_mfma_f32_32x32x16_bf16 v[112:127], v[188:191], v[196:199], v[112:127]
	v_mfma_f32_32x32x16_bf16 v[48:63], v[192:195], v[196:199], v[48:63]
	v_mfma_f32_32x32x16_bf16 v[96:111], v[188:191], v[200:203], v[96:111]
	v_mfma_f32_32x32x16_bf16 v[32:47], v[192:195], v[200:203], v[32:47]
	v_mfma_f32_32x32x16_bf16 v[80:95], v[188:191], v[204:207], v[80:95]
	v_mfma_f32_32x32x16_bf16 v[16:31], v[192:195], v[204:207], v[16:31]
	v_mfma_f32_32x32x16_bf16 v[64:79], v[188:191], v[226:229], v[64:79]
	v_mfma_f32_32x32x16_bf16 v[0:15], v[192:195], v[226:229], v[0:15]
	s_waitcnt vmcnt(0) lgkmcnt(0)
	s_barrier
	v_xor_b32_e32 v230, 0x10000, v230
	v_xor_b32_e32 v234, 0x10000, v234
	v_mfma_f32_32x32x16_bf16 v[112:127], v[128:131], v[136:139], v[112:127]
	v_xor_b32_e32 v231, 0x10000, v231
	v_xor_b32_e32 v235, 0x10000, v235
	v_mfma_f32_32x32x16_bf16 v[48:63], v[132:135], v[136:139], v[48:63]
	v_xor_b32_e32 v232, 0x10000, v232
	v_xor_b32_e32 v236, 0x10000, v236
	v_mfma_f32_32x32x16_bf16 v[96:111], v[128:131], v[140:143], v[96:111]
	v_xor_b32_e32 v233, 0x10000, v233
	v_xor_b32_e32 v237, 0x10000, v237
	v_mfma_f32_32x32x16_bf16 v[32:47], v[132:135], v[140:143], v[32:47]
	v_mfma_f32_32x32x16_bf16 v[80:95], v[128:131], v[144:147], v[80:95]
	v_mfma_f32_32x32x16_bf16 v[16:31], v[132:135], v[144:147], v[16:31]
	v_mfma_f32_32x32x16_bf16 v[64:79], v[128:131], v[148:151], v[64:79]
	v_mfma_f32_32x32x16_bf16 v[0:15], v[132:135], v[148:151], v[0:15]
	s_lshl_b32 s2, s5, 8
	s_sub_i32 s2, s2, s6
	v_mov_b32_e32 v168, v214
	s_add_i32 s55, s4, s30
	s_or_b32 s26, s2, s31
	s_ashr_i32 s27, s26, 31
	s_load_dwordx2 s[24:25], s[0:1], 0x140
	v_ashrrev_i32_e32 v180, 3, v168
	v_and_b32_e32 v183, -4, v180
	v_add_u32_e32 v225, s55, v183
	v_add_u32_e32 v190, 8, v225
	v_min_i32_e32 v190, 0x7fff, v190
	v_ashrrev_i32_e32 v190, 12, v190
	v_add_u32_e32 v190, 24, v190
	v_mul_hi_i32_i24_e32 v191, 0x3000, v190
	v_mul_i32_i24_e32 v190, 0x3000, v190
	v_min_i32_e32 v184, 0x7fff, v225
	v_ashrrev_i32_e32 v184, 12, v184
	v_and_b32_e32 v182, 31, v168
	v_add_u32_e32 v184, 24, v184
	v_or_b32_e32 v180, s26, v182
	v_mul_hi_i32_i24_e32 v185, 0x3000, v184
	v_mul_i32_i24_e32 v184, 0x3000, v184
	v_ashrrev_i32_e32 v181, 31, v180
	s_waitcnt lgkmcnt(0)
	v_lshl_add_u64 v[184:185], s[24:25], 0, v[184:185]
	v_lshl_add_u64 v[184:185], v[184:185], 0, s[18:19]
	v_lshlrev_b64 v[180:181], 2, v[180:181]
	v_lshl_add_u64 v[196:197], v[184:185], 0, v[180:181]
	v_lshl_add_u64 v[186:187], s[24:25], 0, v[190:191]
	v_add_u32_e32 v188, 9, v225
	v_add_u32_e32 v190, 10, v225
	v_min_i32_e32 v188, 0x7fff, v188
	v_min_i32_e32 v190, 0x7fff, v190
	v_ashrrev_i32_e32 v188, 12, v188
	v_ashrrev_i32_e32 v190, 12, v190
	v_add_u32_e32 v188, 24, v188
	v_add_u32_e32 v190, 24, v190
	v_mul_hi_i32_i24_e32 v189, 0x3000, v188
	v_mul_i32_i24_e32 v188, 0x3000, v188
	v_mul_hi_i32_i24_e32 v191, 0x3000, v190
	v_mul_i32_i24_e32 v190, 0x3000, v190
	v_lshl_add_u64 v[188:189], s[24:25], 0, v[188:189]
	v_lshl_add_u64 v[190:191], s[24:25], 0, v[190:191]
	v_lshl_add_u64 v[186:187], v[186:187], 0, s[18:19]
	v_lshl_add_u64 v[188:189], v[188:189], 0, s[18:19]
	v_lshl_add_u64 v[190:191], v[190:191], 0, s[18:19]
	v_lshl_add_u64 v[206:207], v[186:187], 0, v[180:181]
	v_add_u32_e32 v208, 18, v225
	v_min_i32_e32 v208, 0x7fff, v208
	v_ashrrev_i32_e32 v208, 12, v208
	v_add_u32_e32 v208, 24, v208
	v_mul_hi_i32_i24_e32 v209, 0x3000, v208
	v_mul_i32_i24_e32 v208, 0x3000, v208
	v_lshl_add_u64 v[208:209], s[24:25], 0, v[208:209]
	v_lshl_add_u64 v[202:203], v[188:189], 0, v[180:181]
	v_lshl_add_u64 v[204:205], v[190:191], 0, v[180:181]
	global_load_dword v232, v[196:197], off
	global_load_dword v233, v[196:197], off offset:128
	global_load_dword v242, v[206:207], off
	global_load_dword v243, v[206:207], off offset:128
	global_load_dword v244, v[202:203], off
	global_load_dword v245, v[202:203], off offset:128
	global_load_dword v246, v[204:205], off
	global_load_dword v247, v[204:205], off offset:128
	v_add_u32_e32 v196, 17, v225
	v_min_i32_e32 v196, 0x7fff, v196
	v_ashrrev_i32_e32 v196, 12, v196
	v_add_u32_e32 v196, 24, v196
	v_mul_hi_i32_i24_e32 v197, 0x3000, v196
	v_mul_i32_i24_e32 v196, 0x3000, v196
	v_lshl_add_u64 v[196:197], s[24:25], 0, v[196:197]
	v_lshl_add_u64 v[196:197], v[196:197], 0, s[18:19]
	v_lshl_add_u64 v[206:207], v[196:197], 0, v[180:181]
	s_waitcnt vmcnt(7)
	s_nop 5
	v_mul_f32_e32 v112, v112, v232
	v_add_u32_e32 v192, 11, v225
	v_add_u32_e32 v194, 16, v225
	v_min_i32_e32 v192, 0x7fff, v192
	v_min_i32_e32 v194, 0x7fff, v194
	v_ashrrev_i32_e32 v192, 12, v192
	v_ashrrev_i32_e32 v194, 12, v194
	v_add_u32_e32 v192, 24, v192
	v_add_u32_e32 v194, 24, v194
	v_mul_hi_i32_i24_e32 v193, 0x3000, v192
	v_mul_i32_i24_e32 v192, 0x3000, v192
	v_mul_hi_i32_i24_e32 v195, 0x3000, v194
	v_mul_i32_i24_e32 v194, 0x3000, v194
	v_lshl_add_u64 v[192:193], s[24:25], 0, v[192:193]
	v_lshl_add_u64 v[194:195], s[24:25], 0, v[194:195]
	v_lshl_add_u64 v[192:193], v[192:193], 0, s[18:19]
	v_lshl_add_u64 v[194:195], v[194:195], 0, s[18:19]
	v_lshl_add_u64 v[202:203], v[192:193], 0, v[180:181]
	v_lshl_add_u64 v[204:205], v[194:195], 0, v[180:181]
	s_waitcnt vmcnt(6)
	s_nop 5
	v_mul_f32_e32 v96, v96, v233
	v_mul_f32_e32 v97, v97, v233
	v_lshl_add_u64 v[198:199], v[208:209], 0, s[18:19]
	v_lshl_add_u64 v[200:201], v[198:199], 0, v[180:181]
	global_load_dword v234, v[202:203], off
	global_load_dword v235, v[202:203], off offset:128
	global_load_dword v236, v[204:205], off
	global_load_dword v237, v[204:205], off offset:128
	global_load_dword v238, v[206:207], off
	global_load_dword v239, v[206:207], off offset:128
	global_load_dword v240, v[200:201], off
	global_load_dword v241, v[200:201], off offset:128
	v_add_u32_e32 v200, 19, v225
	v_add_u32_e32 v204, 25, v225
	v_add_u32_e32 v206, 26, v225
	v_min_i32_e32 v200, 0x7fff, v200
	v_add_u32_e32 v202, 24, v225
	v_min_i32_e32 v204, 0x7fff, v204
	v_min_i32_e32 v206, 0x7fff, v206
	v_ashrrev_i32_e32 v200, 12, v200
	v_min_i32_e32 v202, 0x7fff, v202
	v_ashrrev_i32_e32 v204, 12, v204
	v_ashrrev_i32_e32 v206, 12, v206
	v_add_u32_e32 v200, 24, v200
	v_ashrrev_i32_e32 v202, 12, v202
	v_add_u32_e32 v204, 24, v204
	v_add_u32_e32 v206, 24, v206
	v_mul_hi_i32_i24_e32 v201, 0x3000, v200
	v_mul_i32_i24_e32 v200, 0x3000, v200
	v_add_u32_e32 v202, 24, v202
	v_mul_hi_i32_i24_e32 v205, 0x3000, v204
	v_mul_i32_i24_e32 v204, 0x3000, v204
	v_mul_hi_i32_i24_e32 v207, 0x3000, v206
	v_mul_i32_i24_e32 v206, 0x3000, v206
	v_lshl_add_u64 v[200:201], s[24:25], 0, v[200:201]
	v_mul_hi_i32_i24_e32 v203, 0x3000, v202
	v_mul_i32_i24_e32 v202, 0x3000, v202
	v_lshl_add_u64 v[204:205], s[24:25], 0, v[204:205]
	v_lshl_add_u64 v[206:207], s[24:25], 0, v[206:207]
	v_lshl_add_u64 v[200:201], v[200:201], 0, s[18:19]
	v_lshl_add_u64 v[202:203], s[24:25], 0, v[202:203]
	v_lshl_add_u64 v[204:205], v[204:205], 0, s[18:19]
	v_lshl_add_u64 v[206:207], v[206:207], 0, s[18:19]
	v_lshl_add_u64 v[208:209], v[200:201], 0, v[180:181]
	v_lshl_add_u64 v[202:203], v[202:203], 0, s[18:19]
	v_lshl_add_u64 v[228:229], v[204:205], 0, v[180:181]
	v_lshl_add_u64 v[230:231], v[206:207], 0, v[180:181]
	v_lshl_add_u64 v[226:227], v[202:203], 0, v[180:181]
	global_load_dword v248, v[208:209], off
	global_load_dword v249, v[208:209], off offset:128
	global_load_dword v250, v[226:227], off
	global_load_dword v251, v[226:227], off offset:128
	global_load_dword v252, v[228:229], off
	s_nop 0
	global_load_dword v228, v[228:229], off offset:128
	s_nop 0
	global_load_dword v229, v[230:231], off
	s_nop 0
	global_load_dword v230, v[230:231], off offset:128
	v_add_u32_e32 v208, 27, v225
	v_min_i32_e32 v208, 0x7fff, v208
	v_ashrrev_i32_e32 v208, 12, v208
	v_add_u32_e32 v208, 24, v208
	v_mul_hi_i32_i24_e32 v209, 0x3000, v208
	v_mul_i32_i24_e32 v208, 0x3000, v208
	v_lshl_add_u64 v[208:209], s[24:25], 0, v[208:209]
	v_lshl_add_u64 v[208:209], v[208:209], 0, s[18:19]
	v_lshl_add_u64 v[226:227], v[208:209], 0, v[180:181]
	global_load_dword v225, v[226:227], off
	s_nop 0
	global_load_dword v226, v[226:227], off offset:128
	v_mad_u64_u32 v[160:161], s[2:3], v183, s36, v[182:183]
	v_lshl_add_u32 v162, v160, 2, s34
	ds_write2_b32 v162, v112, v96 offset1:32
	v_mul_f32_e32 v96, v113, v232
	ds_write2_b32 v162, v96, v97 offset0:68 offset1:100
	v_mul_f32_e32 v96, v114, v232
	v_mul_f32_e32 v97, v98, v233
	ds_write2_b32 v162, v96, v97 offset0:136 offset1:168
	v_mul_f32_e32 v96, v115, v232
	v_mul_f32_e32 v97, v99, v233
	ds_write2_b32 v162, v96, v97 offset0:204 offset1:236
	s_waitcnt vmcnt(23)
	v_mul_f32_e32 v96, v116, v242
	s_waitcnt vmcnt(22)
	v_mul_f32_e32 v97, v100, v243
	v_add_u32_e32 v115, 0x800, v162
	ds_write2_b32 v115, v96, v97 offset0:32 offset1:64
	s_waitcnt vmcnt(21)
	v_mul_f32_e32 v96, v117, v244
	s_waitcnt vmcnt(20)
	v_mul_f32_e32 v97, v101, v245
	ds_write2_b32 v115, v96, v97 offset0:100 offset1:132
	s_waitcnt vmcnt(19)
	v_mul_f32_e32 v96, v118, v246
	s_waitcnt vmcnt(18)
	v_mul_f32_e32 v97, v102, v247
	ds_write2_b32 v115, v96, v97 offset0:168 offset1:200
	v_add_u32_e32 v116, 0xa00, v162
	v_add_u32_e32 v117, 0x1000, v162
	s_waitcnt vmcnt(17)
	v_mul_f32_e32 v96, v119, v234
	s_waitcnt vmcnt(16)
	v_mul_f32_e32 v97, v103, v235
	ds_write2_b32 v116, v96, v97 offset0:108 offset1:140
	s_waitcnt vmcnt(15)
	v_mul_f32_e32 v96, v120, v236
	s_waitcnt vmcnt(14)
	v_mul_f32_e32 v97, v104, v237
	ds_write2_b32 v117, v96, v97 offset0:64 offset1:96
	s_waitcnt vmcnt(13)
	v_mul_f32_e32 v96, v121, v238
	s_waitcnt vmcnt(12)
	v_mul_f32_e32 v97, v105, v239
	ds_write2_b32 v117, v96, v97 offset0:132 offset1:164
	s_waitcnt vmcnt(11)
	v_mul_f32_e32 v96, v122, v240
	s_waitcnt vmcnt(10)
	v_mul_f32_e32 v97, v106, v241
	ds_write2_b32 v117, v96, v97 offset0:200 offset1:232
	v_add_u32_e32 v118, 0x1400, v162
	v_add_u32_e32 v119, 0x1800, v162
	v_ashrrev_i32_e32 v163, 4, v168
	v_and_b32_e32 v160, 15, v168
	v_add_u32_e32 v120, 0x1a00, v162
	v_mul_lo_u32 v164, v163, s37
	v_lshl_add_u32 v165, v160, 4, s34
	v_lshlrev_b32_e32 v168, 2, v160
	v_add_u32_e32 v160, s55, v163
	v_add_u32_e32 v121, 0x1c00, v162
	v_cmp_gt_i32_e32 vcc, s38, v160
	v_ashrrev_i32_e32 v161, 31, v160
	v_add_u32_e32 v114, v165, v164
	s_waitcnt vmcnt(9)
	v_mul_f32_e32 v96, v123, v248
	s_waitcnt vmcnt(8)
	v_mul_f32_e32 v97, v107, v249
	ds_write2_b32 v118, v96, v97 offset0:12 offset1:44
	s_waitcnt vmcnt(7)
	v_mul_f32_e32 v96, v124, v250
	s_waitcnt vmcnt(6)
	v_mul_f32_e32 v97, v108, v251
	ds_write2_b32 v119, v96, v97 offset0:96 offset1:128
	s_waitcnt vmcnt(5)
	v_mul_f32_e32 v96, v125, v252
	s_waitcnt vmcnt(4)
	v_mul_f32_e32 v97, v109, v228
	ds_write2_b32 v119, v96, v97 offset0:164 offset1:196
	s_waitcnt vmcnt(3)
	v_mul_f32_e32 v96, v126, v229
	s_waitcnt vmcnt(2)
	v_mul_f32_e32 v97, v110, v230
	ds_write2_b32 v120, v96, v97 offset0:104 offset1:136
	s_waitcnt vmcnt(1)
	v_mul_f32_e32 v96, v127, v225
	s_waitcnt vmcnt(0)
	v_mul_f32_e32 v97, v111, v226
	ds_write2_b32 v121, v96, v97 offset0:44 offset1:76
	v_or_b32_e32 v96, s26, v168
	v_mov_b32_e32 v97, s27
	v_add_u32_e32 v128, 0, v160
	v_ashrrev_i32_e32 v129, 31, v128
	v_lshlrev_b64 v[128:129], 12, v[128:129]
	v_lshl_add_u64 v[128:129], s[16:17], 0, v[128:129]
	v_lshl_add_u64 v[128:129], v[96:97], 2, v[128:129]
	global_load_dwordx4 v[128:131], v[128:129], off
	v_add_u32_e32 v132, 4, v160
	v_ashrrev_i32_e32 v133, 31, v132
	v_lshlrev_b64 v[132:133], 12, v[132:133]
	v_lshl_add_u64 v[132:133], s[16:17], 0, v[132:133]
	v_lshl_add_u64 v[132:133], v[96:97], 2, v[132:133]
	global_load_dwordx4 v[132:135], v[132:133], off
	v_add_u32_e32 v136, 8, v160
	v_ashrrev_i32_e32 v137, 31, v136
	v_lshlrev_b64 v[136:137], 12, v[136:137]
	v_lshl_add_u64 v[136:137], s[16:17], 0, v[136:137]
	v_lshl_add_u64 v[136:137], v[96:97], 2, v[136:137]
	global_load_dwordx4 v[136:139], v[136:137], off
	v_add_u32_e32 v140, 12, v160
	v_ashrrev_i32_e32 v141, 31, v140
	v_lshlrev_b64 v[140:141], 12, v[140:141]
	v_lshl_add_u64 v[140:141], s[16:17], 0, v[140:141]
	v_lshl_add_u64 v[140:141], v[96:97], 2, v[140:141]
	global_load_dwordx4 v[140:143], v[140:141], off
	v_add_u32_e32 v144, 16, v160
	v_ashrrev_i32_e32 v145, 31, v144
	v_lshlrev_b64 v[144:145], 12, v[144:145]
	v_lshl_add_u64 v[144:145], s[16:17], 0, v[144:145]
	v_lshl_add_u64 v[144:145], v[96:97], 2, v[144:145]
	global_load_dwordx4 v[144:147], v[144:145], off
	v_add_u32_e32 v148, 20, v160
	v_ashrrev_i32_e32 v149, 31, v148
	v_lshlrev_b64 v[148:149], 12, v[148:149]
	v_lshl_add_u64 v[148:149], s[16:17], 0, v[148:149]
	v_lshl_add_u64 v[148:149], v[96:97], 2, v[148:149]
	global_load_dwordx4 v[148:151], v[148:149], off
	v_add_u32_e32 v152, 24, v160
	v_ashrrev_i32_e32 v153, 31, v152
	v_lshlrev_b64 v[152:153], 12, v[152:153]
	v_lshl_add_u64 v[152:153], s[16:17], 0, v[152:153]
	v_lshl_add_u64 v[152:153], v[96:97], 2, v[152:153]
	global_load_dwordx4 v[152:155], v[152:153], off
	v_add_u32_e32 v156, 28, v160
	v_ashrrev_i32_e32 v157, 31, v156
	v_lshlrev_b64 v[156:157], 12, v[156:157]
	v_lshl_add_u64 v[156:157], s[16:17], 0, v[156:157]
	v_lshl_add_u64 v[156:157], v[96:97], 2, v[156:157]
	global_load_dwordx4 v[156:159], v[156:157], off
	s_and_saveexec_b64 s[2:3], vcc
	s_cbranch_execz .LBB0_5646
	v_lshlrev_b64 v[98:99], 12, v[160:161]
	v_lshl_add_u64 v[98:99], s[16:17], 0, v[98:99]
	v_lshl_add_u64 v[106:107], v[96:97], 2, v[98:99]
	ds_read_b128 v[102:105], v114
	s_waitcnt vmcnt(7) lgkmcnt(0)
	v_pk_add_f32 v[100:101], v[104:105], v[130:131]
	v_pk_add_f32 v[98:99], v[102:103], v[128:129]
	global_store_dwordx4 v[106:107], v[98:101], off
